# merged 4-double-phase GEMM loops + peeled first K-iteration (srcC=0 MFMAs, no accumulator zeroing block, relaxed waits only there) + phase-0 via XCD barrier + parallel counter loads
# speedup vs baseline: 1.0202x; 1.0065x over previous
.LBB0_30:
	s_add_u32 s10, s52, 0x100
	s_addc_u32 s11, s53, 0
	s_mov_b32 s12, -2
	s_waitcnt lgkmcnt(0)
	s_add_u32 s46, s50, 0x100
	s_addc_u32 s47, s51, 0
	s_add_i32 s6, 0, 0x10000
	v_add_u32_e32 v146, s6, v206
	ds_read_b128 v[128:131], v146
	ds_read_b128 v[132:135], v146 offset:1024
	ds_read_b128 v[136:139], v146 offset:2048
	ds_read_b128 v[146:149], v146 offset:3072
	s_cmp_eq_u32 s12, 40
	s_cselect_b32 s53, s31, s47
	s_cselect_b32 s52, s30, s46
	s_cselect_b32 s49, s35, s11
	s_cselect_b32 s48, s34, s10
	v_lshl_add_u64 v[214:215], s[50:51], 0, v[158:159]
	s_add_i32 m0, s58, 0xc000
	ds_read_b128 v[162:165], v208
	ds_read_b128 v[166:169], v208 offset:1024
	ds_read_b128 v[170:173], v208 offset:2048
	ds_read_b128 v[174:177], v208 offset:3072
	ds_read_b128 v[178:181], v208 offset:4096
	ds_read_b128 v[182:185], v208 offset:5120
	ds_read_b128 v[194:197], v208 offset:6144
	ds_read_b128 v[210:213], v208 offset:7168
	global_load_lds_dwordx4 v[214:215], off
	v_lshl_add_u64 v[214:215], s[50:51], 0, v[160:161]
	s_add_i32 m0, s58, 0xe000
	s_nop 0
	global_load_lds_dwordx4 v[214:215], off
	s_add_i32 s19, 0, 0x14000
	v_add_u32_e32 v192, s19, v206
	ds_read_b128 v[214:217], v192
	ds_read_b128 v[218:221], v192 offset:1024
	ds_read_b128 v[222:225], v192 offset:2048
	ds_read_b128 v[226:229], v192 offset:3072
	s_waitcnt vmcnt(40)
	s_cmp_lg_u32 s100, 0
	s_cbranch_scc1 .Lm4ap_31
	s_waitcnt vmcnt(8)
.Lm4ap_31:
	s_waitcnt lgkmcnt(0)
	s_barrier
	s_setprio 1
	v_mfma_f32_16x16x32_bf16 v[124:127], v[128:131], v[162:165], 0
	v_mfma_f32_16x16x32_bf16 v[120:123], v[136:139], v[162:165], 0
	v_mfma_f32_16x16x32_bf16 v[108:111], v[128:131], v[170:173], 0
	v_mfma_f32_16x16x32_bf16 v[104:107], v[136:139], v[170:173], 0
	v_mfma_f32_16x16x32_bf16 v[96:99], v[128:131], v[178:181], 0
	v_mfma_f32_16x16x32_bf16 v[88:91], v[136:139], v[178:181], 0
	v_mfma_f32_16x16x32_bf16 v[84:87], v[128:131], v[194:197], 0
	v_mfma_f32_16x16x32_bf16 v[80:83], v[136:139], v[194:197], 0
	v_mfma_f32_16x16x32_bf16 v[124:127], v[132:135], v[166:169], v[124:127]
	v_mfma_f32_16x16x32_bf16 v[120:123], v[146:149], v[166:169], v[120:123]
	v_mfma_f32_16x16x32_bf16 v[108:111], v[132:135], v[174:177], v[108:111]
	v_mfma_f32_16x16x32_bf16 v[104:107], v[146:149], v[174:177], v[104:107]
	v_mfma_f32_16x16x32_bf16 v[96:99], v[132:135], v[182:185], v[96:99]
	v_mfma_f32_16x16x32_bf16 v[88:91], v[146:149], v[182:185], v[88:91]
	v_mfma_f32_16x16x32_bf16 v[84:87], v[132:135], v[210:213], v[84:87]
	v_mfma_f32_16x16x32_bf16 v[80:83], v[146:149], v[210:213], v[80:83]
	v_mfma_f32_16x16x32_bf16 v[116:119], v[214:217], v[162:165], 0
	v_mfma_f32_16x16x32_bf16 v[112:115], v[222:225], v[162:165], 0
	v_mfma_f32_16x16x32_bf16 v[100:103], v[214:217], v[170:173], 0
	v_mfma_f32_16x16x32_bf16 v[92:95], v[222:225], v[170:173], 0
	v_mfma_f32_16x16x32_bf16 v[76:79], v[214:217], v[178:181], 0
	v_mfma_f32_16x16x32_bf16 v[72:75], v[222:225], v[178:181], 0
	v_mfma_f32_16x16x32_bf16 v[68:71], v[214:217], v[194:197], 0
	v_mfma_f32_16x16x32_bf16 v[64:67], v[222:225], v[194:197], 0
	v_mfma_f32_16x16x32_bf16 v[116:119], v[218:221], v[166:169], v[116:119]
	v_mfma_f32_16x16x32_bf16 v[112:115], v[226:229], v[166:169], v[112:115]
	v_mfma_f32_16x16x32_bf16 v[100:103], v[218:221], v[174:177], v[100:103]
	v_mfma_f32_16x16x32_bf16 v[92:95], v[226:229], v[174:177], v[92:95]
	v_mfma_f32_16x16x32_bf16 v[76:79], v[218:221], v[182:185], v[76:79]
	v_mfma_f32_16x16x32_bf16 v[72:75], v[226:229], v[182:185], v[72:75]
	v_mfma_f32_16x16x32_bf16 v[68:71], v[218:221], v[210:213], v[68:71]
	v_mfma_f32_16x16x32_bf16 v[64:67], v[226:229], v[210:213], v[64:67]
	s_setprio 0
	s_barrier
	s_add_i32 s6, s6, s57
	v_lshl_add_u64 v[230:231], s[48:49], 0, v[140:141]
	s_mov_b32 m0, s6
	s_nop 0
	global_load_lds_dwordx4 v[230:231], off
	v_lshl_add_u64 v[232:233], s[48:49], 0, v[150:151]
	s_add_i32 m0, s6, 0x2000
	s_nop 0
	global_load_lds_dwordx4 v[232:233], off
	s_mov_b32 m0, s58
	v_lshl_add_u64 v[234:235], s[52:53], 0, v[154:155]
	ds_read_b128 v[162:165], v208 offset:16384
	ds_read_b128 v[166:169], v208 offset:17408
	ds_read_b128 v[170:173], v208 offset:18432
	ds_read_b128 v[174:177], v208 offset:19456
	ds_read_b128 v[178:181], v208 offset:20480
	ds_read_b128 v[182:185], v208 offset:21504
	ds_read_b128 v[194:197], v208 offset:22528
	ds_read_b128 v[210:213], v208 offset:23552
	global_load_lds_dwordx4 v[234:235], off
	v_lshl_add_u64 v[236:237], s[52:53], 0, v[152:153]
	s_mov_b32 m0, s59
	s_nop 0
	global_load_lds_dwordx4 v[236:237], off
	s_add_u32 s50, s48, 0xb0000
	s_addc_u32 s51, s49, 0
	s_add_i32 s6, s19, s57
	v_lshl_add_u64 v[250:251], s[50:51], 0, v[140:141]
	s_mov_b32 m0, s6
	s_nop 0
	global_load_lds_dwordx4 v[250:251], off
	v_lshl_add_u64 v[250:251], s[50:51], 0, v[150:151]
	s_add_i32 m0, s6, 0x2000
	s_nop 0
	global_load_lds_dwordx4 v[250:251], off
	s_waitcnt vmcnt(40)
	s_cmp_lg_u32 s100, 0
	s_cbranch_scc1 .Lm4bp_31
	s_waitcnt vmcnt(8)
.Lm4bp_31:
	s_waitcnt lgkmcnt(0)
	s_mov_b32 s100, 0
	s_barrier
	s_setprio 1
	v_mfma_f32_16x16x32_bf16 v[60:63], v[128:131], v[162:165], 0
	v_mfma_f32_16x16x32_bf16 v[56:59], v[136:139], v[162:165], 0
	v_mfma_f32_16x16x32_bf16 v[48:51], v[128:131], v[170:173], 0
	v_mfma_f32_16x16x32_bf16 v[40:43], v[136:139], v[170:173], 0
	v_mfma_f32_16x16x32_bf16 v[32:35], v[128:131], v[178:181], 0
	v_mfma_f32_16x16x32_bf16 v[24:27], v[136:139], v[178:181], 0
	v_mfma_f32_16x16x32_bf16 v[16:19], v[128:131], v[194:197], 0
	v_mfma_f32_16x16x32_bf16 v[8:11], v[136:139], v[194:197], 0
	v_mfma_f32_16x16x32_bf16 v[60:63], v[132:135], v[166:169], v[60:63]
	v_mfma_f32_16x16x32_bf16 v[56:59], v[146:149], v[166:169], v[56:59]
	v_mfma_f32_16x16x32_bf16 v[48:51], v[132:135], v[174:177], v[48:51]
	v_mfma_f32_16x16x32_bf16 v[40:43], v[146:149], v[174:177], v[40:43]
	v_mfma_f32_16x16x32_bf16 v[32:35], v[132:135], v[182:185], v[32:35]
	v_mfma_f32_16x16x32_bf16 v[24:27], v[146:149], v[182:185], v[24:27]
	v_mfma_f32_16x16x32_bf16 v[16:19], v[132:135], v[210:213], v[16:19]
	v_mfma_f32_16x16x32_bf16 v[8:11], v[146:149], v[210:213], v[8:11]
	v_mfma_f32_16x16x32_bf16 v[52:55], v[214:217], v[162:165], 0
	v_mfma_f32_16x16x32_bf16 v[44:47], v[222:225], v[162:165], 0
	v_mfma_f32_16x16x32_bf16 v[36:39], v[214:217], v[170:173], 0
	v_mfma_f32_16x16x32_bf16 v[28:31], v[222:225], v[170:173], 0
	v_mfma_f32_16x16x32_bf16 v[20:23], v[214:217], v[178:181], 0
	v_mfma_f32_16x16x32_bf16 v[12:15], v[222:225], v[178:181], 0
	v_mfma_f32_16x16x32_bf16 v[4:7], v[214:217], v[194:197], 0
	v_mfma_f32_16x16x32_bf16 v[0:3], v[222:225], v[194:197], 0
	v_mfma_f32_16x16x32_bf16 v[52:55], v[218:221], v[166:169], v[52:55]
	v_mfma_f32_16x16x32_bf16 v[44:47], v[226:229], v[166:169], v[44:47]
	v_mfma_f32_16x16x32_bf16 v[36:39], v[218:221], v[174:177], v[36:39]
	v_mfma_f32_16x16x32_bf16 v[28:31], v[226:229], v[174:177], v[28:31]
	v_mfma_f32_16x16x32_bf16 v[20:23], v[218:221], v[182:185], v[20:23]
	v_mfma_f32_16x16x32_bf16 v[12:15], v[226:229], v[182:185], v[12:15]
	v_mfma_f32_16x16x32_bf16 v[4:7], v[218:221], v[210:213], v[4:7]
	v_mfma_f32_16x16x32_bf16 v[0:3], v[226:229], v[210:213], v[0:3]
	s_setprio 0
	s_barrier
	s_add_i32 s6, 0, 0x18000
	v_add_u32_e32 v146, s6, v206
	ds_read_b128 v[128:131], v146
	ds_read_b128 v[132:135], v146 offset:1024
	ds_read_b128 v[136:139], v146 offset:2048
	ds_read_b128 v[146:149], v146 offset:3072
	s_add_u32 s50, s52, 0xb0000
	s_addc_u32 s51, s53, 0
	s_mov_b32 m0, s68
	v_lshl_add_u64 v[214:215], s[50:51], 0, v[154:155]
	ds_read_b128 v[162:165], v208 offset:32768
	ds_read_b128 v[166:169], v208 offset:33792
	ds_read_b128 v[170:173], v208 offset:34816
	ds_read_b128 v[174:177], v208 offset:35840
	ds_read_b128 v[178:181], v208 offset:36864
	ds_read_b128 v[182:185], v208 offset:37888
	ds_read_b128 v[194:197], v208 offset:38912
	ds_read_b128 v[210:213], v208 offset:39936
	global_load_lds_dwordx4 v[214:215], off
	v_lshl_add_u64 v[214:215], s[50:51], 0, v[152:153]
	s_mov_b32 m0, s69
	s_nop 0
	global_load_lds_dwordx4 v[214:215], off
	s_add_i32 s19, 0, 0x1c000
	v_add_u32_e32 v192, s19, v206
	ds_read_b128 v[214:217], v192
	ds_read_b128 v[218:221], v192 offset:1024
	ds_read_b128 v[222:225], v192 offset:2048
	ds_read_b128 v[226:229], v192 offset:3072
	s_waitcnt vmcnt(8)
	s_waitcnt lgkmcnt(0)
	s_barrier
	s_setprio 1
	v_mfma_f32_16x16x32_bf16 v[124:127], v[128:131], v[162:165], v[124:127]
	v_mfma_f32_16x16x32_bf16 v[120:123], v[136:139], v[162:165], v[120:123]
	v_mfma_f32_16x16x32_bf16 v[108:111], v[128:131], v[170:173], v[108:111]
	v_mfma_f32_16x16x32_bf16 v[104:107], v[136:139], v[170:173], v[104:107]
	v_mfma_f32_16x16x32_bf16 v[96:99], v[128:131], v[178:181], v[96:99]
	v_mfma_f32_16x16x32_bf16 v[88:91], v[136:139], v[178:181], v[88:91]
	v_mfma_f32_16x16x32_bf16 v[84:87], v[128:131], v[194:197], v[84:87]
	v_mfma_f32_16x16x32_bf16 v[80:83], v[136:139], v[194:197], v[80:83]
	v_mfma_f32_16x16x32_bf16 v[124:127], v[132:135], v[166:169], v[124:127]
	v_mfma_f32_16x16x32_bf16 v[120:123], v[146:149], v[166:169], v[120:123]
	v_mfma_f32_16x16x32_bf16 v[108:111], v[132:135], v[174:177], v[108:111]
	v_mfma_f32_16x16x32_bf16 v[104:107], v[146:149], v[174:177], v[104:107]
	v_mfma_f32_16x16x32_bf16 v[96:99], v[132:135], v[182:185], v[96:99]
	v_mfma_f32_16x16x32_bf16 v[88:91], v[146:149], v[182:185], v[88:91]
	v_mfma_f32_16x16x32_bf16 v[84:87], v[132:135], v[210:213], v[84:87]
	v_mfma_f32_16x16x32_bf16 v[80:83], v[146:149], v[210:213], v[80:83]
	v_mfma_f32_16x16x32_bf16 v[116:119], v[214:217], v[162:165], v[116:119]
	v_mfma_f32_16x16x32_bf16 v[112:115], v[222:225], v[162:165], v[112:115]
	v_mfma_f32_16x16x32_bf16 v[100:103], v[214:217], v[170:173], v[100:103]
	v_mfma_f32_16x16x32_bf16 v[92:95], v[222:225], v[170:173], v[92:95]
	v_mfma_f32_16x16x32_bf16 v[76:79], v[214:217], v[178:181], v[76:79]
	v_mfma_f32_16x16x32_bf16 v[72:75], v[222:225], v[178:181], v[72:75]
	v_mfma_f32_16x16x32_bf16 v[68:71], v[214:217], v[194:197], v[68:71]
	v_mfma_f32_16x16x32_bf16 v[64:67], v[222:225], v[194:197], v[64:67]
	v_mfma_f32_16x16x32_bf16 v[116:119], v[218:221], v[166:169], v[116:119]
	v_mfma_f32_16x16x32_bf16 v[112:115], v[226:229], v[166:169], v[112:115]
	v_mfma_f32_16x16x32_bf16 v[100:103], v[218:221], v[174:177], v[100:103]
	v_mfma_f32_16x16x32_bf16 v[92:95], v[226:229], v[174:177], v[92:95]
	v_mfma_f32_16x16x32_bf16 v[76:79], v[218:221], v[182:185], v[76:79]
	v_mfma_f32_16x16x32_bf16 v[72:75], v[226:229], v[182:185], v[72:75]
	v_mfma_f32_16x16x32_bf16 v[68:71], v[218:221], v[210:213], v[68:71]
	v_mfma_f32_16x16x32_bf16 v[64:67], v[226:229], v[210:213], v[64:67]
	s_setprio 0
	s_barrier
	s_add_i32 s6, s6, s57
	v_lshl_add_u64 v[230:231], v[230:231], 0, s[36:37]
	s_mov_b32 m0, s6
	s_nop 0
	global_load_lds_dwordx4 v[230:231], off
	v_lshl_add_u64 v[230:231], v[232:233], 0, s[36:37]
	s_add_i32 m0, s6, 0x2000
	s_nop 0
	global_load_lds_dwordx4 v[230:231], off
	s_mov_b32 m0, s70
	v_lshl_add_u64 v[230:231], v[234:235], 0, s[36:37]
	ds_read_b128 v[162:165], v208 offset:49152
	ds_read_b128 v[166:169], v208 offset:50176
	ds_read_b128 v[170:173], v208 offset:51200
	ds_read_b128 v[174:177], v208 offset:52224
	ds_read_b128 v[178:181], v208 offset:53248
	ds_read_b128 v[182:185], v208 offset:54272
	ds_read_b128 v[194:197], v208 offset:55296
	ds_read_b128 v[210:213], v208 offset:56320
	global_load_lds_dwordx4 v[230:231], off
	v_lshl_add_u64 v[230:231], v[236:237], 0, s[36:37]
	s_mov_b32 m0, s71
	s_nop 0
	global_load_lds_dwordx4 v[230:231], off
	s_add_u32 s48, s48, 0xb0080
	s_addc_u32 s49, s49, 0
	s_add_i32 s6, s19, s57
	v_lshl_add_u64 v[250:251], s[48:49], 0, v[140:141]
	s_mov_b32 m0, s6
	s_nop 0
	global_load_lds_dwordx4 v[250:251], off
	v_lshl_add_u64 v[250:251], s[48:49], 0, v[150:151]
	s_add_i32 m0, s6, 0x2000
	s_nop 0
	global_load_lds_dwordx4 v[250:251], off
	s_waitcnt vmcnt(8)
	s_waitcnt lgkmcnt(0)
	s_barrier
	s_setprio 1
	v_mfma_f32_16x16x32_bf16 v[60:63], v[128:131], v[162:165], v[60:63]
	v_mfma_f32_16x16x32_bf16 v[56:59], v[136:139], v[162:165], v[56:59]
	v_mfma_f32_16x16x32_bf16 v[48:51], v[128:131], v[170:173], v[48:51]
	v_mfma_f32_16x16x32_bf16 v[40:43], v[136:139], v[170:173], v[40:43]
	v_mfma_f32_16x16x32_bf16 v[32:35], v[128:131], v[178:181], v[32:35]
	v_mfma_f32_16x16x32_bf16 v[24:27], v[136:139], v[178:181], v[24:27]
	v_mfma_f32_16x16x32_bf16 v[16:19], v[128:131], v[194:197], v[16:19]
	v_mfma_f32_16x16x32_bf16 v[8:11], v[136:139], v[194:197], v[8:11]
	v_mfma_f32_16x16x32_bf16 v[60:63], v[132:135], v[166:169], v[60:63]
	v_mfma_f32_16x16x32_bf16 v[56:59], v[146:149], v[166:169], v[56:59]
	v_mfma_f32_16x16x32_bf16 v[48:51], v[132:135], v[174:177], v[48:51]
	v_mfma_f32_16x16x32_bf16 v[40:43], v[146:149], v[174:177], v[40:43]
	v_mfma_f32_16x16x32_bf16 v[32:35], v[132:135], v[182:185], v[32:35]
	v_mfma_f32_16x16x32_bf16 v[24:27], v[146:149], v[182:185], v[24:27]
	v_mfma_f32_16x16x32_bf16 v[16:19], v[132:135], v[210:213], v[16:19]
	v_mfma_f32_16x16x32_bf16 v[8:11], v[146:149], v[210:213], v[8:11]
	v_mfma_f32_16x16x32_bf16 v[52:55], v[214:217], v[162:165], v[52:55]
	v_mfma_f32_16x16x32_bf16 v[44:47], v[222:225], v[162:165], v[44:47]
	v_mfma_f32_16x16x32_bf16 v[36:39], v[214:217], v[170:173], v[36:39]
	v_mfma_f32_16x16x32_bf16 v[28:31], v[222:225], v[170:173], v[28:31]
	v_mfma_f32_16x16x32_bf16 v[20:23], v[214:217], v[178:181], v[20:23]
	v_mfma_f32_16x16x32_bf16 v[12:15], v[222:225], v[178:181], v[12:15]
	v_mfma_f32_16x16x32_bf16 v[4:7], v[214:217], v[194:197], v[4:7]
	v_mfma_f32_16x16x32_bf16 v[0:3], v[222:225], v[194:197], v[0:3]
	v_mfma_f32_16x16x32_bf16 v[52:55], v[218:221], v[166:169], v[52:55]
	v_mfma_f32_16x16x32_bf16 v[44:47], v[226:229], v[166:169], v[44:47]
	v_mfma_f32_16x16x32_bf16 v[36:39], v[218:221], v[174:177], v[36:39]
	v_mfma_f32_16x16x32_bf16 v[28:31], v[226:229], v[174:177], v[28:31]
	v_mfma_f32_16x16x32_bf16 v[20:23], v[218:221], v[182:185], v[20:23]
	v_mfma_f32_16x16x32_bf16 v[12:15], v[226:229], v[182:185], v[12:15]
	v_mfma_f32_16x16x32_bf16 v[4:7], v[218:221], v[210:213], v[4:7]
	v_mfma_f32_16x16x32_bf16 v[0:3], v[226:229], v[210:213], v[0:3]
	s_setprio 0
	s_add_i32 s12, s12, 2
	s_add_u32 s10, s10, 0x100
	s_addc_u32 s11, s11, 0
	s_cmp_gt_u32 s12, 41
	s_mov_b64 s[50:51], s[46:47]
	s_barrier
.LBB0_31:
	s_add_u32 s46, s50, 0x100
	s_addc_u32 s47, s51, 0
	s_add_i32 s6, 0, 0x10000
	v_add_u32_e32 v146, s6, v206
	ds_read_b128 v[128:131], v146
	ds_read_b128 v[132:135], v146 offset:1024
	ds_read_b128 v[136:139], v146 offset:2048
	ds_read_b128 v[146:149], v146 offset:3072
	s_cmp_eq_u32 s12, 40
	s_cselect_b32 s53, s31, s47
	s_cselect_b32 s52, s30, s46
	s_cselect_b32 s49, s35, s11
	s_cselect_b32 s48, s34, s10
	v_lshl_add_u64 v[214:215], s[50:51], 0, v[158:159]
	s_add_i32 m0, s58, 0xc000
	ds_read_b128 v[162:165], v208
	ds_read_b128 v[166:169], v208 offset:1024
	ds_read_b128 v[170:173], v208 offset:2048
	ds_read_b128 v[174:177], v208 offset:3072
	ds_read_b128 v[178:181], v208 offset:4096
	ds_read_b128 v[182:185], v208 offset:5120
	ds_read_b128 v[194:197], v208 offset:6144
	ds_read_b128 v[210:213], v208 offset:7168
	global_load_lds_dwordx4 v[214:215], off
	v_lshl_add_u64 v[214:215], s[50:51], 0, v[160:161]
	s_add_i32 m0, s58, 0xe000
	s_nop 0
	global_load_lds_dwordx4 v[214:215], off
	s_add_i32 s19, 0, 0x14000
	v_add_u32_e32 v192, s19, v206
	ds_read_b128 v[214:217], v192
	ds_read_b128 v[218:221], v192 offset:1024
	ds_read_b128 v[222:225], v192 offset:2048
	ds_read_b128 v[226:229], v192 offset:3072
	s_waitcnt vmcnt(8)
	s_waitcnt lgkmcnt(0)
	s_barrier
	s_setprio 1
	v_mfma_f32_16x16x32_bf16 v[124:127], v[128:131], v[162:165], v[124:127]
	v_mfma_f32_16x16x32_bf16 v[120:123], v[136:139], v[162:165], v[120:123]
	v_mfma_f32_16x16x32_bf16 v[108:111], v[128:131], v[170:173], v[108:111]
	v_mfma_f32_16x16x32_bf16 v[104:107], v[136:139], v[170:173], v[104:107]
	v_mfma_f32_16x16x32_bf16 v[96:99], v[128:131], v[178:181], v[96:99]
	v_mfma_f32_16x16x32_bf16 v[88:91], v[136:139], v[178:181], v[88:91]
	v_mfma_f32_16x16x32_bf16 v[84:87], v[128:131], v[194:197], v[84:87]
	v_mfma_f32_16x16x32_bf16 v[80:83], v[136:139], v[194:197], v[80:83]
	v_mfma_f32_16x16x32_bf16 v[124:127], v[132:135], v[166:169], v[124:127]
	v_mfma_f32_16x16x32_bf16 v[120:123], v[146:149], v[166:169], v[120:123]
	v_mfma_f32_16x16x32_bf16 v[108:111], v[132:135], v[174:177], v[108:111]
	v_mfma_f32_16x16x32_bf16 v[104:107], v[146:149], v[174:177], v[104:107]
	v_mfma_f32_16x16x32_bf16 v[96:99], v[132:135], v[182:185], v[96:99]
	v_mfma_f32_16x16x32_bf16 v[88:91], v[146:149], v[182:185], v[88:91]
	v_mfma_f32_16x16x32_bf16 v[84:87], v[132:135], v[210:213], v[84:87]
	v_mfma_f32_16x16x32_bf16 v[80:83], v[146:149], v[210:213], v[80:83]
	v_mfma_f32_16x16x32_bf16 v[116:119], v[214:217], v[162:165], v[116:119]
	v_mfma_f32_16x16x32_bf16 v[112:115], v[222:225], v[162:165], v[112:115]
	v_mfma_f32_16x16x32_bf16 v[100:103], v[214:217], v[170:173], v[100:103]
	v_mfma_f32_16x16x32_bf16 v[92:95], v[222:225], v[170:173], v[92:95]
	v_mfma_f32_16x16x32_bf16 v[76:79], v[214:217], v[178:181], v[76:79]
	v_mfma_f32_16x16x32_bf16 v[72:75], v[222:225], v[178:181], v[72:75]
	v_mfma_f32_16x16x32_bf16 v[68:71], v[214:217], v[194:197], v[68:71]
	v_mfma_f32_16x16x32_bf16 v[64:67], v[222:225], v[194:197], v[64:67]
	v_mfma_f32_16x16x32_bf16 v[116:119], v[218:221], v[166:169], v[116:119]
	v_mfma_f32_16x16x32_bf16 v[112:115], v[226:229], v[166:169], v[112:115]
	v_mfma_f32_16x16x32_bf16 v[100:103], v[218:221], v[174:177], v[100:103]
	v_mfma_f32_16x16x32_bf16 v[92:95], v[226:229], v[174:177], v[92:95]
	v_mfma_f32_16x16x32_bf16 v[76:79], v[218:221], v[182:185], v[76:79]
	v_mfma_f32_16x16x32_bf16 v[72:75], v[226:229], v[182:185], v[72:75]
	v_mfma_f32_16x16x32_bf16 v[68:71], v[218:221], v[210:213], v[68:71]
	v_mfma_f32_16x16x32_bf16 v[64:67], v[226:229], v[210:213], v[64:67]
	s_setprio 0
	s_barrier
	s_add_i32 s6, s6, s57
	v_lshl_add_u64 v[230:231], s[48:49], 0, v[140:141]
	s_mov_b32 m0, s6
	s_nop 0
	global_load_lds_dwordx4 v[230:231], off
	v_lshl_add_u64 v[232:233], s[48:49], 0, v[150:151]
	s_add_i32 m0, s6, 0x2000
	s_nop 0
	global_load_lds_dwordx4 v[232:233], off
	s_mov_b32 m0, s58
	v_lshl_add_u64 v[234:235], s[52:53], 0, v[154:155]
	ds_read_b128 v[162:165], v208 offset:16384
	ds_read_b128 v[166:169], v208 offset:17408
	ds_read_b128 v[170:173], v208 offset:18432
	ds_read_b128 v[174:177], v208 offset:19456
	ds_read_b128 v[178:181], v208 offset:20480
	ds_read_b128 v[182:185], v208 offset:21504
	ds_read_b128 v[194:197], v208 offset:22528
	ds_read_b128 v[210:213], v208 offset:23552
	global_load_lds_dwordx4 v[234:235], off
	v_lshl_add_u64 v[236:237], s[52:53], 0, v[152:153]
	s_mov_b32 m0, s59
	s_nop 0
	global_load_lds_dwordx4 v[236:237], off
	s_add_u32 s50, s48, 0xb0000
	s_addc_u32 s51, s49, 0
	s_add_i32 s6, s19, s57
	v_lshl_add_u64 v[250:251], s[50:51], 0, v[140:141]
	s_mov_b32 m0, s6
	s_nop 0
	global_load_lds_dwordx4 v[250:251], off
	v_lshl_add_u64 v[250:251], s[50:51], 0, v[150:151]
	s_add_i32 m0, s6, 0x2000
	s_nop 0
	global_load_lds_dwordx4 v[250:251], off
	s_waitcnt vmcnt(8)
	s_waitcnt lgkmcnt(0)
	s_barrier
	s_setprio 1
	v_mfma_f32_16x16x32_bf16 v[60:63], v[128:131], v[162:165], v[60:63]
	v_mfma_f32_16x16x32_bf16 v[56:59], v[136:139], v[162:165], v[56:59]
	v_mfma_f32_16x16x32_bf16 v[48:51], v[128:131], v[170:173], v[48:51]
	v_mfma_f32_16x16x32_bf16 v[40:43], v[136:139], v[170:173], v[40:43]
	v_mfma_f32_16x16x32_bf16 v[32:35], v[128:131], v[178:181], v[32:35]
	v_mfma_f32_16x16x32_bf16 v[24:27], v[136:139], v[178:181], v[24:27]
	v_mfma_f32_16x16x32_bf16 v[16:19], v[128:131], v[194:197], v[16:19]
	v_mfma_f32_16x16x32_bf16 v[8:11], v[136:139], v[194:197], v[8:11]
	v_mfma_f32_16x16x32_bf16 v[60:63], v[132:135], v[166:169], v[60:63]
	v_mfma_f32_16x16x32_bf16 v[56:59], v[146:149], v[166:169], v[56:59]
	v_mfma_f32_16x16x32_bf16 v[48:51], v[132:135], v[174:177], v[48:51]
	v_mfma_f32_16x16x32_bf16 v[40:43], v[146:149], v[174:177], v[40:43]
	v_mfma_f32_16x16x32_bf16 v[32:35], v[132:135], v[182:185], v[32:35]
	v_mfma_f32_16x16x32_bf16 v[24:27], v[146:149], v[182:185], v[24:27]
	v_mfma_f32_16x16x32_bf16 v[16:19], v[132:135], v[210:213], v[16:19]
	v_mfma_f32_16x16x32_bf16 v[8:11], v[146:149], v[210:213], v[8:11]
	v_mfma_f32_16x16x32_bf16 v[52:55], v[214:217], v[162:165], v[52:55]
	v_mfma_f32_16x16x32_bf16 v[44:47], v[222:225], v[162:165], v[44:47]
	v_mfma_f32_16x16x32_bf16 v[36:39], v[214:217], v[170:173], v[36:39]
	v_mfma_f32_16x16x32_bf16 v[28:31], v[222:225], v[170:173], v[28:31]
	v_mfma_f32_16x16x32_bf16 v[20:23], v[214:217], v[178:181], v[20:23]
	v_mfma_f32_16x16x32_bf16 v[12:15], v[222:225], v[178:181], v[12:15]
	v_mfma_f32_16x16x32_bf16 v[4:7], v[214:217], v[194:197], v[4:7]
	v_mfma_f32_16x16x32_bf16 v[0:3], v[222:225], v[194:197], v[0:3]
	v_mfma_f32_16x16x32_bf16 v[52:55], v[218:221], v[166:169], v[52:55]
	v_mfma_f32_16x16x32_bf16 v[44:47], v[226:229], v[166:169], v[44:47]
	v_mfma_f32_16x16x32_bf16 v[36:39], v[218:221], v[174:177], v[36:39]
	v_mfma_f32_16x16x32_bf16 v[28:31], v[226:229], v[174:177], v[28:31]
	v_mfma_f32_16x16x32_bf16 v[20:23], v[218:221], v[182:185], v[20:23]
	v_mfma_f32_16x16x32_bf16 v[12:15], v[226:229], v[182:185], v[12:15]
	v_mfma_f32_16x16x32_bf16 v[4:7], v[218:221], v[210:213], v[4:7]
	v_mfma_f32_16x16x32_bf16 v[0:3], v[226:229], v[210:213], v[0:3]
	s_setprio 0
	s_barrier
	s_add_i32 s6, 0, 0x18000
	v_add_u32_e32 v146, s6, v206
	ds_read_b128 v[128:131], v146
	ds_read_b128 v[132:135], v146 offset:1024
	ds_read_b128 v[136:139], v146 offset:2048
	ds_read_b128 v[146:149], v146 offset:3072
	s_add_u32 s50, s52, 0xb0000
	s_addc_u32 s51, s53, 0
	s_mov_b32 m0, s68
	v_lshl_add_u64 v[214:215], s[50:51], 0, v[154:155]
	ds_read_b128 v[162:165], v208 offset:32768
	ds_read_b128 v[166:169], v208 offset:33792
	ds_read_b128 v[170:173], v208 offset:34816
	ds_read_b128 v[174:177], v208 offset:35840
	ds_read_b128 v[178:181], v208 offset:36864
	ds_read_b128 v[182:185], v208 offset:37888
	ds_read_b128 v[194:197], v208 offset:38912
	ds_read_b128 v[210:213], v208 offset:39936
	global_load_lds_dwordx4 v[214:215], off
	v_lshl_add_u64 v[214:215], s[50:51], 0, v[152:153]
	s_mov_b32 m0, s69
	s_nop 0
	global_load_lds_dwordx4 v[214:215], off
	s_add_i32 s19, 0, 0x1c000
	v_add_u32_e32 v192, s19, v206
	ds_read_b128 v[214:217], v192
	ds_read_b128 v[218:221], v192 offset:1024
	ds_read_b128 v[222:225], v192 offset:2048
	ds_read_b128 v[226:229], v192 offset:3072
	s_waitcnt vmcnt(8)
	s_waitcnt lgkmcnt(0)
	s_barrier
	s_setprio 1
	v_mfma_f32_16x16x32_bf16 v[124:127], v[128:131], v[162:165], v[124:127]
	v_mfma_f32_16x16x32_bf16 v[120:123], v[136:139], v[162:165], v[120:123]
	v_mfma_f32_16x16x32_bf16 v[108:111], v[128:131], v[170:173], v[108:111]
	v_mfma_f32_16x16x32_bf16 v[104:107], v[136:139], v[170:173], v[104:107]
	v_mfma_f32_16x16x32_bf16 v[96:99], v[128:131], v[178:181], v[96:99]
	v_mfma_f32_16x16x32_bf16 v[88:91], v[136:139], v[178:181], v[88:91]
	v_mfma_f32_16x16x32_bf16 v[84:87], v[128:131], v[194:197], v[84:87]
	v_mfma_f32_16x16x32_bf16 v[80:83], v[136:139], v[194:197], v[80:83]
	v_mfma_f32_16x16x32_bf16 v[124:127], v[132:135], v[166:169], v[124:127]
	v_mfma_f32_16x16x32_bf16 v[120:123], v[146:149], v[166:169], v[120:123]
	v_mfma_f32_16x16x32_bf16 v[108:111], v[132:135], v[174:177], v[108:111]
	v_mfma_f32_16x16x32_bf16 v[104:107], v[146:149], v[174:177], v[104:107]
	v_mfma_f32_16x16x32_bf16 v[96:99], v[132:135], v[182:185], v[96:99]
	v_mfma_f32_16x16x32_bf16 v[88:91], v[146:149], v[182:185], v[88:91]
	v_mfma_f32_16x16x32_bf16 v[84:87], v[132:135], v[210:213], v[84:87]
	v_mfma_f32_16x16x32_bf16 v[80:83], v[146:149], v[210:213], v[80:83]
	v_mfma_f32_16x16x32_bf16 v[116:119], v[214:217], v[162:165], v[116:119]
	v_mfma_f32_16x16x32_bf16 v[112:115], v[222:225], v[162:165], v[112:115]
	v_mfma_f32_16x16x32_bf16 v[100:103], v[214:217], v[170:173], v[100:103]
	v_mfma_f32_16x16x32_bf16 v[92:95], v[222:225], v[170:173], v[92:95]
	v_mfma_f32_16x16x32_bf16 v[76:79], v[214:217], v[178:181], v[76:79]
	v_mfma_f32_16x16x32_bf16 v[72:75], v[222:225], v[178:181], v[72:75]
	v_mfma_f32_16x16x32_bf16 v[68:71], v[214:217], v[194:197], v[68:71]
	v_mfma_f32_16x16x32_bf16 v[64:67], v[222:225], v[194:197], v[64:67]
	v_mfma_f32_16x16x32_bf16 v[116:119], v[218:221], v[166:169], v[116:119]
	v_mfma_f32_16x16x32_bf16 v[112:115], v[226:229], v[166:169], v[112:115]
	v_mfma_f32_16x16x32_bf16 v[100:103], v[218:221], v[174:177], v[100:103]
	v_mfma_f32_16x16x32_bf16 v[92:95], v[226:229], v[174:177], v[92:95]
	v_mfma_f32_16x16x32_bf16 v[76:79], v[218:221], v[182:185], v[76:79]
	v_mfma_f32_16x16x32_bf16 v[72:75], v[226:229], v[182:185], v[72:75]
	v_mfma_f32_16x16x32_bf16 v[68:71], v[218:221], v[210:213], v[68:71]
	v_mfma_f32_16x16x32_bf16 v[64:67], v[226:229], v[210:213], v[64:67]
	s_setprio 0
	s_barrier
	s_add_i32 s6, s6, s57
	v_lshl_add_u64 v[230:231], v[230:231], 0, s[36:37]
	s_mov_b32 m0, s6
	s_nop 0
	global_load_lds_dwordx4 v[230:231], off
	v_lshl_add_u64 v[230:231], v[232:233], 0, s[36:37]
	s_add_i32 m0, s6, 0x2000
	s_nop 0
	global_load_lds_dwordx4 v[230:231], off
	s_mov_b32 m0, s70
	v_lshl_add_u64 v[230:231], v[234:235], 0, s[36:37]
	ds_read_b128 v[162:165], v208 offset:49152
	ds_read_b128 v[166:169], v208 offset:50176
	ds_read_b128 v[170:173], v208 offset:51200
	ds_read_b128 v[174:177], v208 offset:52224
	ds_read_b128 v[178:181], v208 offset:53248
	ds_read_b128 v[182:185], v208 offset:54272
	ds_read_b128 v[194:197], v208 offset:55296
	ds_read_b128 v[210:213], v208 offset:56320
	global_load_lds_dwordx4 v[230:231], off
	v_lshl_add_u64 v[230:231], v[236:237], 0, s[36:37]
	s_mov_b32 m0, s71
	s_nop 0
	global_load_lds_dwordx4 v[230:231], off
	s_add_u32 s48, s48, 0xb0080
	s_addc_u32 s49, s49, 0
	s_add_i32 s6, s19, s57
	v_lshl_add_u64 v[250:251], s[48:49], 0, v[140:141]
	s_mov_b32 m0, s6
	s_nop 0
	global_load_lds_dwordx4 v[250:251], off
	v_lshl_add_u64 v[250:251], s[48:49], 0, v[150:151]
	s_add_i32 m0, s6, 0x2000
	s_nop 0
	global_load_lds_dwordx4 v[250:251], off
	s_waitcnt vmcnt(8)
	s_waitcnt lgkmcnt(0)
	s_barrier
	s_setprio 1
	v_mfma_f32_16x16x32_bf16 v[60:63], v[128:131], v[162:165], v[60:63]
	v_mfma_f32_16x16x32_bf16 v[56:59], v[136:139], v[162:165], v[56:59]
	v_mfma_f32_16x16x32_bf16 v[48:51], v[128:131], v[170:173], v[48:51]
	v_mfma_f32_16x16x32_bf16 v[40:43], v[136:139], v[170:173], v[40:43]
	v_mfma_f32_16x16x32_bf16 v[32:35], v[128:131], v[178:181], v[32:35]
	v_mfma_f32_16x16x32_bf16 v[24:27], v[136:139], v[178:181], v[24:27]
	v_mfma_f32_16x16x32_bf16 v[16:19], v[128:131], v[194:197], v[16:19]
	v_mfma_f32_16x16x32_bf16 v[8:11], v[136:139], v[194:197], v[8:11]
	v_mfma_f32_16x16x32_bf16 v[60:63], v[132:135], v[166:169], v[60:63]
	v_mfma_f32_16x16x32_bf16 v[56:59], v[146:149], v[166:169], v[56:59]
	v_mfma_f32_16x16x32_bf16 v[48:51], v[132:135], v[174:177], v[48:51]
	v_mfma_f32_16x16x32_bf16 v[40:43], v[146:149], v[174:177], v[40:43]
	v_mfma_f32_16x16x32_bf16 v[32:35], v[132:135], v[182:185], v[32:35]
	v_mfma_f32_16x16x32_bf16 v[24:27], v[146:149], v[182:185], v[24:27]
	v_mfma_f32_16x16x32_bf16 v[16:19], v[132:135], v[210:213], v[16:19]
	v_mfma_f32_16x16x32_bf16 v[8:11], v[146:149], v[210:213], v[8:11]
	v_mfma_f32_16x16x32_bf16 v[52:55], v[214:217], v[162:165], v[52:55]
	v_mfma_f32_16x16x32_bf16 v[44:47], v[222:225], v[162:165], v[44:47]
	v_mfma_f32_16x16x32_bf16 v[36:39], v[214:217], v[170:173], v[36:39]
	v_mfma_f32_16x16x32_bf16 v[28:31], v[222:225], v[170:173], v[28:31]
	v_mfma_f32_16x16x32_bf16 v[20:23], v[214:217], v[178:181], v[20:23]
	v_mfma_f32_16x16x32_bf16 v[12:15], v[222:225], v[178:181], v[12:15]
	v_mfma_f32_16x16x32_bf16 v[4:7], v[214:217], v[194:197], v[4:7]
	v_mfma_f32_16x16x32_bf16 v[0:3], v[222:225], v[194:197], v[0:3]
	v_mfma_f32_16x16x32_bf16 v[52:55], v[218:221], v[166:169], v[52:55]
	v_mfma_f32_16x16x32_bf16 v[44:47], v[226:229], v[166:169], v[44:47]
	v_mfma_f32_16x16x32_bf16 v[36:39], v[218:221], v[174:177], v[36:39]
	v_mfma_f32_16x16x32_bf16 v[28:31], v[226:229], v[174:177], v[28:31]
	v_mfma_f32_16x16x32_bf16 v[20:23], v[218:221], v[182:185], v[20:23]
	v_mfma_f32_16x16x32_bf16 v[12:15], v[226:229], v[182:185], v[12:15]
	v_mfma_f32_16x16x32_bf16 v[4:7], v[218:221], v[210:213], v[4:7]
	v_mfma_f32_16x16x32_bf16 v[0:3], v[226:229], v[210:213], v[0:3]
	s_setprio 0
	s_add_i32 s12, s12, 2
	s_add_u32 s10, s10, 0x100
	s_addc_u32 s11, s11, 0
	s_cmp_gt_u32 s12, 41
	s_mov_b64 s[50:51], s[46:47]
	s_barrier
	s_cbranch_scc0 .LBB0_31
	s_mov_b32 s100, 1
	s_ashr_i32 s39, s38, 31
	v_lshl_or_b32 v128, s81, 8, v207
	s_lshl_b64 s[10:11], s[38:39], 8
	v_ashrrev_i32_e32 v129, 31, v128
	v_lshl_add_u64 v[168:169], s[10:11], 0, v[156:157]
	v_lshlrev_b64 v[170:171], 1, v[128:129]
	v_lshl_add_u64 v[174:175], s[4:5], 0, v[170:171]
	v_lshlrev_b64 v[172:173], 11, v[168:169]
	v_lshl_add_u64 v[128:129], v[174:175], 0, v[172:173]
	global_load_dwordx4 v[146:149], v[128:129], off
	global_load_dwordx4 v[182:185], v[128:129], off offset:256
	v_or_b32_e32 v166, 16, v168
	v_mov_b32_e32 v167, v169
	v_lshlrev_b64 v[176:177], 11, v[166:167]
	v_lshl_add_u64 v[128:129], v[174:175], 0, v[176:177]
	global_load_dwordx4 v[194:197], v[128:129], off
	global_load_dwordx4 v[210:213], v[128:129], off offset:256
	v_or_b32_e32 v164, 32, v168
	v_mov_b32_e32 v165, v169
	v_or_b32_e32 v162, 48, v168
	v_mov_b32_e32 v163, v169
	v_lshlrev_b64 v[180:181], 11, v[164:165]
	v_lshlrev_b64 v[178:179], 11, v[162:163]
	v_lshl_add_u64 v[128:129], v[174:175], 0, v[180:181]
	v_lshl_add_u64 v[130:131], v[174:175], 0, v[178:179]
	global_load_dwordx4 v[214:217], v[128:129], off
	global_load_dwordx4 v[136:139], v[128:129], off offset:256
	global_load_dwordx4 v[132:135], v[130:131], off
	s_nop 0
	global_load_dwordx4 v[128:131], v[130:131], off offset:256
	s_mov_b64 s[10:11], 0x90
	v_lshl_add_u64 v[172:173], s[28:29], 0, v[172:173]
	v_lshl_add_u64 v[172:173], v[172:173], 0, v[170:171]
	s_waitcnt vmcnt(0)
	v_lshlrev_b32_e32 v218, 16, v146
	v_and_b32_e32 v219, 0xffff0000, v146
	v_lshlrev_b32_e32 v220, 16, v148
	v_and_b32_e32 v221, 0xffff0000, v148
	v_lshlrev_b32_e32 v146, 16, v147
	v_and_b32_e32 v147, 0xffff0000, v147
	v_lshlrev_b32_e32 v222, 16, v182
	v_and_b32_e32 v223, 0xffff0000, v182
	v_lshlrev_b32_e32 v224, 16, v184
	v_and_b32_e32 v225, 0xffff0000, v184
	v_lshlrev_b32_e32 v182, 16, v183
	v_and_b32_e32 v183, 0xffff0000, v183
	v_pk_fma_f32 v[124:125], v[124:125], 0.5, v[218:219] op_sel_hi:[1,0,1]
	v_pk_fma_f32 v[120:121], v[120:121], 0.5, v[220:221] op_sel_hi:[1,0,1]
	v_pk_fma_f32 v[126:127], v[126:127], 0.5, v[146:147] op_sel_hi:[1,0,1]
	v_pk_fma_f32 v[116:117], v[116:117], 0.5, v[222:223] op_sel_hi:[1,0,1]
	v_pk_fma_f32 v[146:147], v[112:113], 0.5, v[224:225] op_sel_hi:[1,0,1]
	v_pk_fma_f32 v[118:119], v[118:119], 0.5, v[182:183] op_sel_hi:[1,0,1]
	v_pk_mul_f32 v[220:221], v[124:125], v[124:125]
	v_pk_mul_f32 v[222:223], v[126:127], v[126:127]
	v_cvt_pk_bf16_f32 v112, v124, v125
	v_cvt_pk_bf16_f32 v113, v126, v127
	v_pk_mul_f32 v[124:125], v[116:117], v[116:117]
	v_pk_mul_f32 v[126:127], v[118:119], v[118:119]
	v_pk_mul_f32 v[228:229], v[146:147], v[146:147]
	v_cvt_pk_bf16_f32 v116, v116, v117
	v_cvt_pk_bf16_f32 v117, v118, v119
	v_cvt_pk_bf16_f32 v118, v146, v147
	v_add_f32_e32 v146, v220, v221
	v_add_f32_e32 v146, v222, v146
	v_lshlrev_b32_e32 v148, 16, v149
	v_and_b32_e32 v149, 0xffff0000, v149
	v_pk_mul_f32 v[224:225], v[120:121], v[120:121]
	v_add_f32_e32 v146, v223, v146
	v_pk_fma_f32 v[122:123], v[122:123], 0.5, v[148:149] op_sel_hi:[1,0,1]
	v_add_f32_e32 v146, v224, v146
	v_pk_mul_f32 v[226:227], v[122:123], v[122:123]
	v_add_f32_e32 v146, v225, v146
	v_add_f32_e32 v146, v226, v146
	v_add_f32_e32 v146, v227, v146
	v_add_f32_e32 v124, v124, v146
	v_add_f32_e32 v124, v125, v124
	v_add_f32_e32 v124, v126, v124
	v_lshlrev_b32_e32 v184, 16, v185
	v_and_b32_e32 v185, 0xffff0000, v185
	v_add_f32_e32 v124, v127, v124
	v_pk_fma_f32 v[148:149], v[114:115], 0.5, v[184:185] op_sel_hi:[1,0,1]
	v_add_f32_e32 v124, v228, v124
	v_pk_mul_f32 v[230:231], v[148:149], v[148:149]
	v_add_f32_e32 v124, v229, v124
	v_add_f32_e32 v124, v230, v124
	v_add_f32_e32 v209, v231, v124
	v_lshlrev_b32_e32 v124, 16, v212
	v_and_b32_e32 v125, 0xffff0000, v212
	v_pk_fma_f32 v[124:125], v[92:93], 0.5, v[124:125] op_sel_hi:[1,0,1]
	v_lshlrev_b32_e32 v92, 16, v211
	v_and_b32_e32 v93, 0xffff0000, v211
	v_pk_fma_f32 v[102:103], v[102:103], 0.5, v[92:93] op_sel_hi:[1,0,1]
	v_lshlrev_b32_e32 v92, 16, v213
	v_and_b32_e32 v93, 0xffff0000, v213
	v_pk_fma_f32 v[126:127], v[94:95], 0.5, v[92:93] op_sel_hi:[1,0,1]
	v_lshlrev_b32_e32 v92, 16, v214
	v_and_b32_e32 v93, 0xffff0000, v214
	v_pk_fma_f32 v[92:93], v[96:97], 0.5, v[92:93] op_sel_hi:[1,0,1]
	v_lshlrev_b32_e32 v96, 16, v217
	v_and_b32_e32 v97, 0xffff0000, v217
	v_lshlrev_b32_e32 v94, 16, v216
	v_and_b32_e32 v95, 0xffff0000, v216
	v_pk_fma_f32 v[90:91], v[90:91], 0.5, v[96:97] op_sel_hi:[1,0,1]
	v_lshlrev_b32_e32 v96, 16, v136
	v_and_b32_e32 v97, 0xffff0000, v136
	v_lshlrev_b32_e32 v182, 16, v194
	v_and_b32_e32 v183, 0xffff0000, v194
	v_pk_fma_f32 v[88:89], v[88:89], 0.5, v[94:95] op_sel_hi:[1,0,1]
	v_lshlrev_b32_e32 v94, 16, v215
	v_and_b32_e32 v95, 0xffff0000, v215
	v_pk_fma_f32 v[96:97], v[76:77], 0.5, v[96:97] op_sel_hi:[1,0,1]
	v_lshl_add_u64 v[76:77], v[168:169], 0, s[36:37]
	v_lshlrev_b32_e32 v184, 16, v196
	v_and_b32_e32 v185, 0xffff0000, v196
	v_cvt_pk_bf16_f32 v114, v120, v121
	v_pk_fma_f32 v[120:121], v[108:109], 0.5, v[182:183] op_sel_hi:[1,0,1]
	v_pk_fma_f32 v[94:95], v[98:99], 0.5, v[94:95] op_sel_hi:[1,0,1]
	v_lshlrev_b64 v[182:183], 11, v[76:77]
	v_lshlrev_b32_e32 v98, 16, v138
	v_and_b32_e32 v99, 0xffff0000, v138
	v_pk_fma_f32 v[108:109], v[104:105], 0.5, v[184:185] op_sel_hi:[1,0,1]
	v_lshl_add_u64 v[184:185], v[174:175], 0, v[182:183]
	v_pk_fma_f32 v[98:99], v[72:73], 0.5, v[98:99] op_sel_hi:[1,0,1]
	v_lshlrev_b32_e32 v72, 16, v137
	v_and_b32_e32 v73, 0xffff0000, v137
	v_lshlrev_b32_e32 v218, 16, v210
	v_and_b32_e32 v219, 0xffff0000, v210
	global_load_dwordx4 v[210:213], v[184:185], off
	v_pk_fma_f32 v[136:137], v[78:79], 0.5, v[72:73] op_sel_hi:[1,0,1]
	v_lshlrev_b32_e32 v72, 16, v139
	v_and_b32_e32 v73, 0xffff0000, v139
	v_pk_fma_f32 v[138:139], v[74:75], 0.5, v[72:73] op_sel_hi:[1,0,1]
	v_lshlrev_b32_e32 v72, 16, v132
	v_and_b32_e32 v73, 0xffff0000, v132
	v_pk_fma_f32 v[74:75], v[84:85], 0.5, v[72:73] op_sel_hi:[1,0,1]
	v_lshlrev_b32_e32 v72, 16, v134
	v_and_b32_e32 v73, 0xffff0000, v134
	v_pk_fma_f32 v[78:79], v[80:81], 0.5, v[72:73] op_sel_hi:[1,0,1]
	v_lshlrev_b32_e32 v72, 16, v133
	v_and_b32_e32 v73, 0xffff0000, v133
	v_pk_fma_f32 v[100:101], v[100:101], 0.5, v[218:219] op_sel_hi:[1,0,1]
	global_load_dwordx4 v[218:221], v[184:185], off offset:256
	v_pk_fma_f32 v[80:81], v[86:87], 0.5, v[72:73] op_sel_hi:[1,0,1]
	v_lshlrev_b32_e32 v72, 16, v135
	v_and_b32_e32 v73, 0xffff0000, v135
	v_pk_fma_f32 v[82:83], v[82:83], 0.5, v[72:73] op_sel_hi:[1,0,1]
	v_lshl_add_u64 v[72:73], v[168:169], 0, s[10:11]
	v_lshlrev_b64 v[132:133], 11, v[72:73]
	v_lshl_add_u64 v[134:135], v[174:175], 0, v[132:133]
	v_lshlrev_b32_e32 v84, 16, v128
	v_and_b32_e32 v85, 0xffff0000, v128
	global_load_dwordx4 v[226:229], v[134:135], off
	global_load_dwordx4 v[234:237], v[134:135], off offset:256
	v_pk_fma_f32 v[84:85], v[68:69], 0.5, v[84:85] op_sel_hi:[1,0,1]
	v_lshlrev_b32_e32 v68, 16, v130
	v_and_b32_e32 v69, 0xffff0000, v130
	v_pk_fma_f32 v[86:87], v[64:65], 0.5, v[68:69] op_sel_hi:[1,0,1]
	v_lshlrev_b32_e32 v64, 16, v129
	v_and_b32_e32 v65, 0xffff0000, v129
	s_mov_b64 s[10:11], 0xa0
	v_pk_fma_f32 v[128:129], v[70:71], 0.5, v[64:65] op_sel_hi:[1,0,1]
	v_lshl_add_u64 v[70:71], v[168:169], 0, s[10:11]
	s_mov_b64 s[10:11], 0xb0
	v_lshlrev_b32_e32 v64, 16, v131
	v_and_b32_e32 v65, 0xffff0000, v131
	v_lshlrev_b64 v[134:135], 11, v[70:71]
	v_lshl_add_u64 v[68:69], v[168:169], 0, s[10:11]
	v_pk_fma_f32 v[130:131], v[66:67], 0.5, v[64:65] op_sel_hi:[1,0,1]
	v_lshl_add_u64 v[64:65], v[174:175], 0, v[134:135]
	v_lshlrev_b64 v[184:185], 11, v[68:69]
	global_load_dwordx4 v[238:241], v[64:65], off
	global_load_dwordx4 v[242:245], v[64:65], off offset:256
	v_lshl_add_u64 v[64:65], v[174:175], 0, v[184:185]
	global_load_dwordx4 v[246:249], v[64:65], off
	s_nop 0
	global_load_dwordx4 v[64:67], v[64:65], off offset:256
	v_lshlrev_b32_e32 v194, 16, v195
	v_and_b32_e32 v195, 0xffff0000, v195
	v_lshlrev_b32_e32 v196, 16, v197
	v_and_b32_e32 v197, 0xffff0000, v197
	v_cvt_pk_bf16_f32 v115, v122, v123
	v_cvt_pk_bf16_f32 v119, v148, v149
	v_pk_fma_f32 v[122:123], v[110:111], 0.5, v[194:195] op_sel_hi:[1,0,1]
	v_pk_fma_f32 v[110:111], v[106:107], 0.5, v[196:197] op_sel_hi:[1,0,1]
	global_store_dwordx4 v[172:173], v[112:115], off
	global_store_dwordx4 v[172:173], v[116:119], off offset:256
	v_cvt_pk_bf16_f32 v104, v120, v121
	v_lshl_add_u64 v[112:113], s[28:29], 0, v[176:177]
	v_cvt_pk_bf16_f32 v105, v122, v123
	v_cvt_pk_bf16_f32 v106, v108, v109
	v_cvt_pk_bf16_f32 v107, v110, v111
	v_lshl_add_u64 v[112:113], v[112:113], 0, v[170:171]
	v_cvt_pk_bf16_f32 v146, v100, v101
	v_cvt_pk_bf16_f32 v147, v102, v103
	v_cvt_pk_bf16_f32 v148, v124, v125
	v_cvt_pk_bf16_f32 v149, v126, v127
	global_store_dwordx4 v[112:113], v[104:107], off
	global_store_dwordx4 v[112:113], v[146:149], off offset:256
	v_cvt_pk_bf16_f32 v194, v92, v93
	v_lshl_add_u64 v[104:105], s[28:29], 0, v[180:181]
	v_cvt_pk_bf16_f32 v195, v94, v95
	v_cvt_pk_bf16_f32 v196, v88, v89
	v_cvt_pk_bf16_f32 v197, v90, v91
	v_lshl_add_u64 v[104:105], v[104:105], 0, v[170:171]
	v_cvt_pk_bf16_f32 v214, v96, v97
	v_cvt_pk_bf16_f32 v215, v136, v137
	v_cvt_pk_bf16_f32 v216, v98, v99
	v_cvt_pk_bf16_f32 v217, v138, v139
	global_store_dwordx4 v[104:105], v[194:197], off
	global_store_dwordx4 v[104:105], v[214:217], off offset:256
	v_lshl_add_u64 v[104:105], s[28:29], 0, v[178:179]
	v_cvt_pk_bf16_f32 v222, v74, v75
	v_cvt_pk_bf16_f32 v223, v80, v81
	v_cvt_pk_bf16_f32 v224, v78, v79
	v_cvt_pk_bf16_f32 v225, v82, v83
	v_lshl_add_u64 v[104:105], v[104:105], 0, v[170:171]
	v_cvt_pk_bf16_f32 v230, v84, v85
	v_cvt_pk_bf16_f32 v231, v128, v129
	v_cvt_pk_bf16_f32 v232, v86, v87
	v_cvt_pk_bf16_f32 v233, v130, v131
	global_store_dwordx4 v[104:105], v[222:225], off
	global_store_dwordx4 v[104:105], v[230:233], off offset:256
	s_waitcnt vmcnt(0)
	v_lshlrev_b32_e32 v104, 16, v210
	v_and_b32_e32 v105, 0xffff0000, v210
	v_pk_fma_f32 v[60:61], v[60:61], 0.5, v[104:105] op_sel_hi:[1,0,1]
	v_lshlrev_b32_e32 v104, 16, v212
	v_and_b32_e32 v105, 0xffff0000, v212
	v_pk_fma_f32 v[56:57], v[56:57], 0.5, v[104:105] op_sel_hi:[1,0,1]
	v_lshlrev_b32_e32 v104, 16, v211
	v_and_b32_e32 v105, 0xffff0000, v211
	v_pk_fma_f32 v[62:63], v[62:63], 0.5, v[104:105] op_sel_hi:[1,0,1]
	v_lshlrev_b32_e32 v104, 16, v213
	v_and_b32_e32 v105, 0xffff0000, v213
	v_pk_fma_f32 v[58:59], v[58:59], 0.5, v[104:105] op_sel_hi:[1,0,1]
	v_lshlrev_b32_e32 v104, 16, v218
	v_and_b32_e32 v105, 0xffff0000, v218
	v_pk_fma_f32 v[52:53], v[52:53], 0.5, v[104:105] op_sel_hi:[1,0,1]
	v_lshlrev_b32_e32 v104, 16, v220
	v_and_b32_e32 v105, 0xffff0000, v220
	v_pk_fma_f32 v[104:105], v[44:45], 0.5, v[104:105] op_sel_hi:[1,0,1]
	v_lshlrev_b32_e32 v44, 16, v219
	v_and_b32_e32 v45, 0xffff0000, v219
	v_pk_fma_f32 v[54:55], v[54:55], 0.5, v[44:45] op_sel_hi:[1,0,1]
	v_lshlrev_b32_e32 v44, 16, v221
	v_and_b32_e32 v45, 0xffff0000, v221
	v_pk_fma_f32 v[106:107], v[46:47], 0.5, v[44:45] op_sel_hi:[1,0,1]
	v_lshlrev_b32_e32 v44, 16, v226
	v_and_b32_e32 v45, 0xffff0000, v226
	v_pk_fma_f32 v[44:45], v[48:49], 0.5, v[44:45] op_sel_hi:[1,0,1]
	v_lshlrev_b32_e32 v48, 16, v229
	v_and_b32_e32 v49, 0xffff0000, v229
	v_pk_fma_f32 v[42:43], v[42:43], 0.5, v[48:49] op_sel_hi:[1,0,1]
	v_lshlrev_b32_e32 v48, 16, v234
	v_and_b32_e32 v49, 0xffff0000, v234
	v_pk_fma_f32 v[36:37], v[36:37], 0.5, v[48:49] op_sel_hi:[1,0,1]
	v_lshlrev_b32_e32 v48, 16, v236
	v_and_b32_e32 v49, 0xffff0000, v236
	v_lshlrev_b32_e32 v46, 16, v228
	v_and_b32_e32 v47, 0xffff0000, v228
	v_pk_fma_f32 v[48:49], v[28:29], 0.5, v[48:49] op_sel_hi:[1,0,1]
	v_lshlrev_b32_e32 v28, 16, v235
	v_and_b32_e32 v29, 0xffff0000, v235
	v_pk_fma_f32 v[40:41], v[40:41], 0.5, v[46:47] op_sel_hi:[1,0,1]
	v_lshlrev_b32_e32 v46, 16, v227
	v_and_b32_e32 v47, 0xffff0000, v227
	v_pk_fma_f32 v[38:39], v[38:39], 0.5, v[28:29] op_sel_hi:[1,0,1]
	v_lshlrev_b32_e32 v28, 16, v237
	v_and_b32_e32 v29, 0xffff0000, v237
	v_pk_fma_f32 v[46:47], v[50:51], 0.5, v[46:47] op_sel_hi:[1,0,1]
	v_pk_fma_f32 v[50:51], v[30:31], 0.5, v[28:29] op_sel_hi:[1,0,1]
	v_lshlrev_b32_e32 v28, 16, v238
	v_and_b32_e32 v29, 0xffff0000, v238
	v_lshlrev_b32_e32 v180, 16, v64
	v_and_b32_e32 v181, 0xffff0000, v64
	v_pk_fma_f32 v[28:29], v[32:33], 0.5, v[28:29] op_sel_hi:[1,0,1]
	v_lshlrev_b32_e32 v32, 16, v241
	v_and_b32_e32 v33, 0xffff0000, v241
	v_pk_fma_f32 v[4:5], v[4:5], 0.5, v[180:181] op_sel_hi:[1,0,1]
	v_lshlrev_b32_e32 v180, 16, v66
	v_and_b32_e32 v181, 0xffff0000, v66
	v_pk_fma_f32 v[26:27], v[26:27], 0.5, v[32:33] op_sel_hi:[1,0,1]
	v_lshlrev_b32_e32 v32, 16, v242
	v_and_b32_e32 v33, 0xffff0000, v242
	v_pk_fma_f32 v[0:1], v[0:1], 0.5, v[180:181] op_sel_hi:[1,0,1]
	v_lshl_add_u64 v[180:181], s[28:29], 0, v[182:183]
	v_cvt_pk_bf16_f32 v112, v60, v61
	v_cvt_pk_bf16_f32 v113, v62, v63
	v_cvt_pk_bf16_f32 v114, v56, v57
	v_cvt_pk_bf16_f32 v115, v58, v59
	v_pk_fma_f32 v[20:21], v[20:21], 0.5, v[32:33] op_sel_hi:[1,0,1]
	v_lshlrev_b32_e32 v32, 16, v244
	v_and_b32_e32 v33, 0xffff0000, v244
	v_lshl_add_u64 v[180:181], v[180:181], 0, v[170:171]
	v_cvt_pk_bf16_f32 v116, v52, v53
	v_cvt_pk_bf16_f32 v117, v54, v55
	v_cvt_pk_bf16_f32 v118, v104, v105
	v_cvt_pk_bf16_f32 v119, v106, v107
	v_lshlrev_b32_e32 v30, 16, v240
	v_and_b32_e32 v31, 0xffff0000, v240
	v_pk_fma_f32 v[32:33], v[12:13], 0.5, v[32:33] op_sel_hi:[1,0,1]
	v_lshlrev_b32_e32 v12, 16, v243
	v_and_b32_e32 v13, 0xffff0000, v243
	global_store_dwordx4 v[180:181], v[112:115], off
	global_store_dwordx4 v[180:181], v[116:119], off offset:256
	v_cvt_pk_bf16_f32 v146, v44, v45
	v_lshl_add_u64 v[112:113], s[28:29], 0, v[132:133]
	v_cvt_pk_bf16_f32 v147, v46, v47
	v_cvt_pk_bf16_f32 v148, v40, v41
	v_cvt_pk_bf16_f32 v149, v42, v43
	v_pk_fma_f32 v[24:25], v[24:25], 0.5, v[30:31] op_sel_hi:[1,0,1]
	v_lshlrev_b32_e32 v30, 16, v239
	v_and_b32_e32 v31, 0xffff0000, v239
	v_pk_fma_f32 v[22:23], v[22:23], 0.5, v[12:13] op_sel_hi:[1,0,1]
	v_lshlrev_b32_e32 v12, 16, v245
	v_and_b32_e32 v13, 0xffff0000, v245
	v_lshl_add_u64 v[112:113], v[112:113], 0, v[170:171]
	v_cvt_pk_bf16_f32 v172, v36, v37
	v_cvt_pk_bf16_f32 v173, v38, v39
	v_cvt_pk_bf16_f32 v174, v48, v49
	v_cvt_pk_bf16_f32 v175, v50, v51
	v_pk_fma_f32 v[30:31], v[34:35], 0.5, v[30:31] op_sel_hi:[1,0,1]
	v_pk_fma_f32 v[34:35], v[14:15], 0.5, v[12:13] op_sel_hi:[1,0,1]
	v_lshlrev_b32_e32 v12, 16, v246
	v_and_b32_e32 v13, 0xffff0000, v246
	v_lshlrev_b32_e32 v14, 16, v248
	v_and_b32_e32 v15, 0xffff0000, v248
	global_store_dwordx4 v[112:113], v[146:149], off
	global_store_dwordx4 v[112:113], v[172:175], off offset:256
	v_lshl_add_u64 v[112:113], s[28:29], 0, v[134:135]
	v_cvt_pk_bf16_f32 v176, v28, v29
	v_cvt_pk_bf16_f32 v177, v30, v31
	v_cvt_pk_bf16_f32 v178, v24, v25
	v_cvt_pk_bf16_f32 v179, v26, v27
	v_pk_fma_f32 v[12:13], v[16:17], 0.5, v[12:13] op_sel_hi:[1,0,1]
	v_pk_fma_f32 v[8:9], v[8:9], 0.5, v[14:15] op_sel_hi:[1,0,1]
	v_lshlrev_b32_e32 v14, 16, v247
	v_and_b32_e32 v15, 0xffff0000, v247
	v_lshlrev_b32_e32 v16, 16, v249
	v_and_b32_e32 v17, 0xffff0000, v249
	v_lshlrev_b32_e32 v64, 16, v65
	v_and_b32_e32 v65, 0xffff0000, v65
	v_lshl_add_u64 v[112:113], v[112:113], 0, v[170:171]
	v_cvt_pk_bf16_f32 v194, v20, v21
	v_cvt_pk_bf16_f32 v195, v22, v23
	v_cvt_pk_bf16_f32 v196, v32, v33
	v_cvt_pk_bf16_f32 v197, v34, v35
	v_pk_fma_f32 v[14:15], v[18:19], 0.5, v[14:15] op_sel_hi:[1,0,1]
	v_pk_fma_f32 v[10:11], v[10:11], 0.5, v[16:17] op_sel_hi:[1,0,1]
	v_pk_fma_f32 v[6:7], v[6:7], 0.5, v[64:65] op_sel_hi:[1,0,1]
	v_lshlrev_b32_e32 v64, 16, v67
	v_and_b32_e32 v65, 0xffff0000, v67
	global_store_dwordx4 v[112:113], v[176:179], off
	global_store_dwordx4 v[112:113], v[194:197], off offset:256
	v_lshl_add_u64 v[112:113], s[28:29], 0, v[184:185]
	v_cvt_pk_bf16_f32 v16, v12, v13
	v_cvt_pk_bf16_f32 v17, v14, v15
	v_cvt_pk_bf16_f32 v18, v8, v9
	v_cvt_pk_bf16_f32 v19, v10, v11
	v_pk_fma_f32 v[2:3], v[2:3], 0.5, v[64:65] op_sel_hi:[1,0,1]
	v_lshl_add_u64 v[112:113], v[112:113], 0, v[170:171]
	v_cvt_pk_bf16_f32 v64, v4, v5
	v_cvt_pk_bf16_f32 v65, v6, v7
	v_cvt_pk_bf16_f32 v66, v0, v1
	v_cvt_pk_bf16_f32 v67, v2, v3
	global_store_dwordx4 v[112:113], v[16:19], off
	global_store_dwordx4 v[112:113], v[64:67], off offset:256
	s_lshl_b32 s10, s81, 2
	v_and_b32_e32 v17, 64, v188
	v_xor_b32_e32 v16, 16, v188
	v_add_u32_e32 v17, 64, v17
	v_cmp_lt_i32_e32 vcc, v16, v17
	v_xor_b32_e32 v18, 32, v188
	s_ashr_i32 s11, s10, 31
	v_cndmask_b32_e32 v16, v188, v16, vcc
	v_lshlrev_b32_e32 v16, 2, v16
	ds_bpermute_b32 v19, v16, v209
	v_cmp_lt_i32_e32 vcc, v18, v17
	s_lshl_b64 s[10:11], s[10:11], 2
	s_add_u32 s38, s73, s10
	v_cndmask_b32_e32 v17, v188, v18, vcc
	v_lshlrev_b32_e32 v17, 2, v17
	s_waitcnt lgkmcnt(0)
	v_add_f32_e32 v18, v209, v19
	ds_bpermute_b32 v19, v17, v18
	s_addc_u32 s39, s74, s11
	s_and_saveexec_b64 s[46:47], s[42:43]
	s_cbranch_execz .LBB0_34
	s_waitcnt lgkmcnt(0)
	v_add_f32_e32 v64, v18, v19
	v_lshlrev_b64 v[18:19], 6, v[168:169]
	v_lshl_add_u64 v[18:19], s[38:39], 0, v[18:19]
	global_store_dword v[18:19], v64, off

.LBB0_72:
	s_add_u32 s28, s28, 0x3290000
	v_and_b32_e32 v15, 15, v8
	v_lshrrev_b32_e32 v8, 1, v8
	s_addc_u32 s29, s29, 0
	v_and_b32_e32 v8, 24, v8
	s_lshl_b32 s10, s10, 5
	v_lshlrev_b32_e32 v16, 1, v8
	v_lshlrev_b32_e32 v17, 2, v15
	s_and_b32 s19, s10, 0x60
	s_add_i32 m0, s68, 0x18000
	v_lshl_add_u64 v[6:7], v[6:7], 0, s[36:37]
	s_lshl_b32 s12, s6, 6
	v_lshl_or_b32 v16, v15, 6, v16
	s_lshl_b32 s11, s6, 13
	v_and_b32_e32 v18, 32, v17
	s_lshl_b32 s10, s19, 7
	s_waitcnt vmcnt(0)
	s_barrier
	global_load_lds_dwordx4 v[6:7], off
	v_lshl_add_u64 v[4:5], v[4:5], 0, s[36:37]
	s_add_i32 m0, s68, 0x1a000
	s_add_i32 s72, s68, 0x8000
	s_add_i32 s73, s68, 0xa000
	v_bitop3_b32 v154, v16, s10, v18 bitop3:0xde
	global_load_lds_dwordx4 v[4:5], off
	v_lshl_add_u64 v[2:3], v[2:3], 0, s[36:37]
	s_mov_b32 m0, s72
	s_add_u32 s10, s50, 0x40080
	v_bitop3_b32 v19, v16, s11, v18 bitop3:0xde
	global_load_lds_dwordx4 v[2:3], off
	v_lshl_add_u64 v[0:1], v[0:1], 0, s[36:37]
	s_mov_b32 m0, s73
	s_addc_u32 s11, s51, 0
	global_load_lds_dwordx4 v[0:1], off
	s_add_i32 m0, s68, 0x1c000
	v_lshl_add_u64 v[0:1], s[10:11], 0, v[140:141]
	global_load_lds_dwordx4 v[0:1], off
	v_lshl_add_u64 v[0:1], s[10:11], 0, v[132:133]
	s_add_i32 m0, s68, 0x1e000
	s_lshl_b32 s6, s6, 8
	global_load_lds_dwordx4 v[0:1], off
	v_lshlrev_b32_e32 v0, 14, v9
	v_and_b32_e32 v0, 0xffff8000, v0
	v_lshl_add_u32 v0, v10, 11, v0
	v_and_b32_e32 v1, 1, v9
	v_lshl_or_b32 v0, v1, 6, v0
	v_lshl_add_u32 v136, v11, 1, v0
	v_lshlrev_b32_e32 v0, 14, v12
	v_and_b32_e32 v0, 0xffff8000, v0
	s_add_i32 s6, s6, 0
	v_lshl_add_u32 v0, v13, 11, v0
	v_and_b32_e32 v1, 1, v12
	s_waitcnt vmcnt(6)
	s_add_i32 s6, s6, 0x22000
	v_lshl_or_b32 v0, v1, 6, v0
	v_add_u32_e32 v155, s6, v17
	s_ashr_i32 s6, s12, 31
	v_lshl_add_u32 v138, v14, 1, v0
	v_or_b32_e32 v134, s12, v15
	v_mov_b32_e32 v135, s6
	v_or_b32_e32 v156, s19, v8
	v_mov_b32_e32 v137, v141
	v_mov_b32_e32 v139, v141
	s_mov_b32 s75, 0
	v_add_u32_e32 v157, 0, v19
	v_readlane_b32 s74, v253, 49
	v_readlane_b32 s30, v254, 0
	s_barrier
	v_readlane_b32 s31, v254, 1
	s_mov_b32 s100, 0
	s_branch .LBB0_74
.LBB0_73:
	s_mov_b32 s74, s38
	s_mov_b32 s30, s34
	s_mov_b64 s[26:27], s[48:49]
	s_mov_b32 s75, s80
	s_andn2_b64 vcc, exec, s[42:43]
	s_mov_b64 s[50:51], s[46:47]
	s_cbranch_vccz .LBB0_80

.LBB0_76:
	s_add_u32 s10, s50, 0x100
	s_addc_u32 s11, s51, 0
	s_ashr_i32 s35, s34, 31
	s_lshl_b64 s[46:47], s[34:35], 19
	s_add_u32 s48, s33, s46
	s_addc_u32 s49, s41, s47
	s_and_b64 s[46:47], s[44:45], exec
	s_cselect_b32 s12, s49, s27
	s_cselect_b32 s31, s48, s26
	s_ashr_i32 s39, s38, 31
	s_lshl_b64 s[46:47], s[38:39], 19
	s_add_u32 s46, s57, s46
	s_addc_u32 s47, s58, s47
	s_and_b64 s[52:53], s[44:45], exec
	s_cselect_b32 s35, s47, s51
	s_cselect_b32 s39, s46, s50
	s_add_u32 s50, s26, 0x40080
	s_addc_u32 s51, s27, 0
	v_lshl_add_u64 v[150:151], s[50:51], 0, v[136:137]
	v_lshl_add_u64 v[152:153], s[50:51], 0, v[138:139]
	s_mov_b32 s81, -2
	s_mov_b64 s[50:51], 0
	s_add_u32 s6, s26, s50
	s_addc_u32 s19, s27, s51
	s_add_u32 s6, s6, 0x100
	s_addc_u32 s19, s19, 0
	s_add_u32 s23, s10, s50
	s_addc_u32 s52, s11, s51
	s_add_i32 s82, 0, 0x10000
	v_add_u32_e32 v146, s82, v154
	ds_read_b128 v[158:161], v146
	ds_read_b128 v[162:165], v146 offset:1024
	ds_read_b128 v[166:169], v146 offset:2048
	ds_read_b128 v[170:173], v146 offset:3072
	s_cmpk_eq_i32 s50, 0x700
	s_cselect_b32 s55, s12, s19
	s_cselect_b32 s54, s31, s6
	s_cselect_b32 s53, s35, s52
	s_cselect_b32 s52, s39, s23
	v_lshl_add_u64 v[146:147], v[150:151], 0, s[50:51]
	s_add_i32 m0, s68, 0xc000
	ds_read_b128 v[174:177], v157
	ds_read_b128 v[178:181], v157 offset:1024
	ds_read_b128 v[182:185], v157 offset:2048
	ds_read_b128 v[206:209], v157 offset:3072
	ds_read_b128 v[210:213], v157 offset:4096
	ds_read_b128 v[214:217], v157 offset:5120
	ds_read_b128 v[218:221], v157 offset:6144
	ds_read_b128 v[222:225], v157 offset:7168
	global_load_lds_dwordx4 v[146:147], off
	v_lshl_add_u64 v[146:147], v[152:153], 0, s[50:51]
	s_add_i32 m0, s68, 0xe000
	s_nop 0
	global_load_lds_dwordx4 v[146:147], off
	s_add_i32 s6, 0, 0x14000
	v_add_u32_e32 v146, s6, v154
	ds_read_b128 v[226:229], v146
	ds_read_b128 v[230:233], v146 offset:1024
	ds_read_b128 v[234:237], v146 offset:2048
	ds_read_b128 v[238:241], v146 offset:3072
	s_waitcnt vmcnt(16)
	s_cmp_lg_u32 s100, 0
	s_cbranch_scc1 .Lm4ap_77
	s_waitcnt vmcnt(8)
.Lm4ap_77:
	s_waitcnt lgkmcnt(0)
	s_barrier
	s_setprio 1
	v_mfma_f32_16x16x32_bf16 v[124:127], v[158:161], v[174:177], 0
	v_mfma_f32_16x16x32_bf16 v[120:123], v[166:169], v[174:177], 0
	v_mfma_f32_16x16x32_bf16 v[116:119], v[158:161], v[182:185], 0
	v_mfma_f32_16x16x32_bf16 v[112:115], v[166:169], v[182:185], 0
	v_mfma_f32_16x16x32_bf16 v[108:111], v[158:161], v[210:213], 0
	v_mfma_f32_16x16x32_bf16 v[104:107], v[166:169], v[210:213], 0
	v_mfma_f32_16x16x32_bf16 v[100:103], v[158:161], v[218:221], 0
	v_mfma_f32_16x16x32_bf16 v[96:99], v[166:169], v[218:221], 0
	v_mfma_f32_16x16x32_bf16 v[124:127], v[162:165], v[178:181], v[124:127]
	v_mfma_f32_16x16x32_bf16 v[120:123], v[170:173], v[178:181], v[120:123]
	v_mfma_f32_16x16x32_bf16 v[116:119], v[162:165], v[206:209], v[116:119]
	v_mfma_f32_16x16x32_bf16 v[112:115], v[170:173], v[206:209], v[112:115]
	v_mfma_f32_16x16x32_bf16 v[108:111], v[162:165], v[214:217], v[108:111]
	v_mfma_f32_16x16x32_bf16 v[104:107], v[170:173], v[214:217], v[104:107]
	v_mfma_f32_16x16x32_bf16 v[100:103], v[162:165], v[222:225], v[100:103]
	v_mfma_f32_16x16x32_bf16 v[96:99], v[170:173], v[222:225], v[96:99]
	v_mfma_f32_16x16x32_bf16 v[92:95], v[226:229], v[174:177], 0
	v_mfma_f32_16x16x32_bf16 v[88:91], v[234:237], v[174:177], 0
	v_mfma_f32_16x16x32_bf16 v[84:87], v[226:229], v[182:185], 0
	v_mfma_f32_16x16x32_bf16 v[80:83], v[234:237], v[182:185], 0
	v_mfma_f32_16x16x32_bf16 v[76:79], v[226:229], v[210:213], 0
	v_mfma_f32_16x16x32_bf16 v[72:75], v[234:237], v[210:213], 0
	v_mfma_f32_16x16x32_bf16 v[68:71], v[226:229], v[218:221], 0
	v_mfma_f32_16x16x32_bf16 v[64:67], v[234:237], v[218:221], 0
	v_mfma_f32_16x16x32_bf16 v[92:95], v[230:233], v[178:181], v[92:95]
	v_mfma_f32_16x16x32_bf16 v[88:91], v[238:241], v[178:181], v[88:91]
	v_mfma_f32_16x16x32_bf16 v[84:87], v[230:233], v[206:209], v[84:87]
	v_mfma_f32_16x16x32_bf16 v[80:83], v[238:241], v[206:209], v[80:83]
	v_mfma_f32_16x16x32_bf16 v[76:79], v[230:233], v[214:217], v[76:79]
	v_mfma_f32_16x16x32_bf16 v[72:75], v[238:241], v[214:217], v[72:75]
	v_mfma_f32_16x16x32_bf16 v[68:71], v[230:233], v[222:225], v[68:71]
	v_mfma_f32_16x16x32_bf16 v[64:67], v[238:241], v[222:225], v[64:67]
	s_setprio 0
	s_barrier
	s_add_i32 s19, s82, s59
	v_lshl_add_u64 v[146:147], s[52:53], 0, v[140:141]
	s_mov_b32 m0, s19
	v_lshl_add_u64 v[148:149], s[52:53], 0, v[132:133]
	global_load_lds_dwordx4 v[146:147], off
	s_add_i32 m0, s19, 0x2000
	s_nop 0
	global_load_lds_dwordx4 v[148:149], off
	s_mov_b32 m0, s68
	v_lshl_add_u64 v[194:195], s[54:55], 0, v[128:129]
	ds_read_b128 v[174:177], v157 offset:16384
	ds_read_b128 v[178:181], v157 offset:17408
	ds_read_b128 v[182:185], v157 offset:18432
	ds_read_b128 v[206:209], v157 offset:19456
	ds_read_b128 v[210:213], v157 offset:20480
	ds_read_b128 v[214:217], v157 offset:21504
	ds_read_b128 v[218:221], v157 offset:22528
	ds_read_b128 v[222:225], v157 offset:23552
	global_load_lds_dwordx4 v[194:195], off
	v_lshl_add_u64 v[196:197], s[54:55], 0, v[130:131]
	s_mov_b32 m0, s69
	s_nop 0
	global_load_lds_dwordx4 v[196:197], off
	s_add_u32 s82, s52, 0x40000
	s_addc_u32 s83, s53, 0
	s_add_i32 s6, s6, s59
	v_lshl_add_u64 v[250:251], s[82:83], 0, v[140:141]
	s_mov_b32 m0, s6
	s_nop 0
	global_load_lds_dwordx4 v[250:251], off
	v_lshl_add_u64 v[250:251], s[82:83], 0, v[132:133]
	s_add_i32 m0, s6, 0x2000
	s_nop 0
	global_load_lds_dwordx4 v[250:251], off
	s_waitcnt vmcnt(16)
	s_cmp_lg_u32 s100, 0
	s_cbranch_scc1 .Lm4bp_77
	s_waitcnt vmcnt(8)
.Lm4bp_77:
	s_waitcnt lgkmcnt(0)
	s_mov_b32 s100, 0
	s_barrier
	s_setprio 1
	v_mfma_f32_16x16x32_bf16 v[60:63], v[158:161], v[174:177], 0
	v_mfma_f32_16x16x32_bf16 v[56:59], v[166:169], v[174:177], 0
	v_mfma_f32_16x16x32_bf16 v[52:55], v[158:161], v[182:185], 0
	v_mfma_f32_16x16x32_bf16 v[48:51], v[166:169], v[182:185], 0
	v_mfma_f32_16x16x32_bf16 v[44:47], v[158:161], v[210:213], 0
	v_mfma_f32_16x16x32_bf16 v[40:43], v[166:169], v[210:213], 0
	v_mfma_f32_16x16x32_bf16 v[36:39], v[158:161], v[218:221], 0
	v_mfma_f32_16x16x32_bf16 v[32:35], v[166:169], v[218:221], 0
	v_mfma_f32_16x16x32_bf16 v[60:63], v[162:165], v[178:181], v[60:63]
	v_mfma_f32_16x16x32_bf16 v[56:59], v[170:173], v[178:181], v[56:59]
	v_mfma_f32_16x16x32_bf16 v[52:55], v[162:165], v[206:209], v[52:55]
	v_mfma_f32_16x16x32_bf16 v[48:51], v[170:173], v[206:209], v[48:51]
	v_mfma_f32_16x16x32_bf16 v[44:47], v[162:165], v[214:217], v[44:47]
	v_mfma_f32_16x16x32_bf16 v[40:43], v[170:173], v[214:217], v[40:43]
	v_mfma_f32_16x16x32_bf16 v[36:39], v[162:165], v[222:225], v[36:39]
	v_mfma_f32_16x16x32_bf16 v[32:35], v[170:173], v[222:225], v[32:35]
	v_mfma_f32_16x16x32_bf16 v[28:31], v[226:229], v[174:177], 0
	v_mfma_f32_16x16x32_bf16 v[24:27], v[234:237], v[174:177], 0
	v_mfma_f32_16x16x32_bf16 v[20:23], v[226:229], v[182:185], 0
	v_mfma_f32_16x16x32_bf16 v[16:19], v[234:237], v[182:185], 0
	v_mfma_f32_16x16x32_bf16 v[12:15], v[226:229], v[210:213], 0
	v_mfma_f32_16x16x32_bf16 v[8:11], v[234:237], v[210:213], 0
	v_mfma_f32_16x16x32_bf16 v[4:7], v[226:229], v[218:221], 0
	v_mfma_f32_16x16x32_bf16 v[0:3], v[234:237], v[218:221], 0
	v_mfma_f32_16x16x32_bf16 v[28:31], v[230:233], v[178:181], v[28:31]
	v_mfma_f32_16x16x32_bf16 v[24:27], v[238:241], v[178:181], v[24:27]
	v_mfma_f32_16x16x32_bf16 v[20:23], v[230:233], v[206:209], v[20:23]
	v_mfma_f32_16x16x32_bf16 v[16:19], v[238:241], v[206:209], v[16:19]
	v_mfma_f32_16x16x32_bf16 v[12:15], v[230:233], v[214:217], v[12:15]
	v_mfma_f32_16x16x32_bf16 v[8:11], v[238:241], v[214:217], v[8:11]
	v_mfma_f32_16x16x32_bf16 v[4:7], v[230:233], v[222:225], v[4:7]
	v_mfma_f32_16x16x32_bf16 v[0:3], v[238:241], v[222:225], v[0:3]
	s_setprio 0
	s_barrier
	s_add_i32 s6, 0, 0x18000
	v_add_u32_e32 v170, s6, v154
	ds_read_b128 v[158:161], v170
	ds_read_b128 v[162:165], v170 offset:1024
	ds_read_b128 v[166:169], v170 offset:2048
	ds_read_b128 v[170:173], v170 offset:3072
	s_add_u32 s54, s54, 0x40000
	s_addc_u32 s55, s55, 0
	s_mov_b32 m0, s70
	v_lshl_add_u64 v[226:227], s[54:55], 0, v[128:129]
	ds_read_b128 v[174:177], v157 offset:32768
	ds_read_b128 v[178:181], v157 offset:33792
	ds_read_b128 v[182:185], v157 offset:34816
	ds_read_b128 v[206:209], v157 offset:35840
	ds_read_b128 v[210:213], v157 offset:36864
	ds_read_b128 v[214:217], v157 offset:37888
	ds_read_b128 v[218:221], v157 offset:38912
	ds_read_b128 v[222:225], v157 offset:39936
	global_load_lds_dwordx4 v[226:227], off
	v_lshl_add_u64 v[226:227], s[54:55], 0, v[130:131]
	s_mov_b32 m0, s71
	s_nop 0
	global_load_lds_dwordx4 v[226:227], off
	s_add_i32 s19, 0, 0x1c000
	v_add_u32_e32 v192, s19, v154
	ds_read_b128 v[226:229], v192
	ds_read_b128 v[230:233], v192 offset:1024
	ds_read_b128 v[234:237], v192 offset:2048
	ds_read_b128 v[238:241], v192 offset:3072
	s_waitcnt vmcnt(8)
	s_waitcnt lgkmcnt(0)
	s_barrier
	s_setprio 1
	v_mfma_f32_16x16x32_bf16 v[124:127], v[158:161], v[174:177], v[124:127]
	v_mfma_f32_16x16x32_bf16 v[120:123], v[166:169], v[174:177], v[120:123]
	v_mfma_f32_16x16x32_bf16 v[116:119], v[158:161], v[182:185], v[116:119]
	v_mfma_f32_16x16x32_bf16 v[112:115], v[166:169], v[182:185], v[112:115]
	v_mfma_f32_16x16x32_bf16 v[108:111], v[158:161], v[210:213], v[108:111]
	v_mfma_f32_16x16x32_bf16 v[104:107], v[166:169], v[210:213], v[104:107]
	v_mfma_f32_16x16x32_bf16 v[100:103], v[158:161], v[218:221], v[100:103]
	v_mfma_f32_16x16x32_bf16 v[96:99], v[166:169], v[218:221], v[96:99]
	v_mfma_f32_16x16x32_bf16 v[124:127], v[162:165], v[178:181], v[124:127]
	v_mfma_f32_16x16x32_bf16 v[120:123], v[170:173], v[178:181], v[120:123]
	v_mfma_f32_16x16x32_bf16 v[116:119], v[162:165], v[206:209], v[116:119]
	v_mfma_f32_16x16x32_bf16 v[112:115], v[170:173], v[206:209], v[112:115]
	v_mfma_f32_16x16x32_bf16 v[108:111], v[162:165], v[214:217], v[108:111]
	v_mfma_f32_16x16x32_bf16 v[104:107], v[170:173], v[214:217], v[104:107]
	v_mfma_f32_16x16x32_bf16 v[100:103], v[162:165], v[222:225], v[100:103]
	v_mfma_f32_16x16x32_bf16 v[96:99], v[170:173], v[222:225], v[96:99]
	v_mfma_f32_16x16x32_bf16 v[92:95], v[226:229], v[174:177], v[92:95]
	v_mfma_f32_16x16x32_bf16 v[88:91], v[234:237], v[174:177], v[88:91]
	v_mfma_f32_16x16x32_bf16 v[84:87], v[226:229], v[182:185], v[84:87]
	v_mfma_f32_16x16x32_bf16 v[80:83], v[234:237], v[182:185], v[80:83]
	v_mfma_f32_16x16x32_bf16 v[76:79], v[226:229], v[210:213], v[76:79]
	v_mfma_f32_16x16x32_bf16 v[72:75], v[234:237], v[210:213], v[72:75]
	v_mfma_f32_16x16x32_bf16 v[68:71], v[226:229], v[218:221], v[68:71]
	v_mfma_f32_16x16x32_bf16 v[64:67], v[234:237], v[218:221], v[64:67]
	v_mfma_f32_16x16x32_bf16 v[92:95], v[230:233], v[178:181], v[92:95]
	v_mfma_f32_16x16x32_bf16 v[88:91], v[238:241], v[178:181], v[88:91]
	v_mfma_f32_16x16x32_bf16 v[84:87], v[230:233], v[206:209], v[84:87]
	v_mfma_f32_16x16x32_bf16 v[80:83], v[238:241], v[206:209], v[80:83]
	v_mfma_f32_16x16x32_bf16 v[76:79], v[230:233], v[214:217], v[76:79]
	v_mfma_f32_16x16x32_bf16 v[72:75], v[238:241], v[214:217], v[72:75]
	v_mfma_f32_16x16x32_bf16 v[68:71], v[230:233], v[222:225], v[68:71]
	v_mfma_f32_16x16x32_bf16 v[64:67], v[238:241], v[222:225], v[64:67]
	s_setprio 0
	s_barrier
	s_add_i32 s6, s6, s59
	v_lshl_add_u64 v[146:147], v[146:147], 0, s[36:37]
	s_mov_b32 m0, s6
	s_nop 0
	global_load_lds_dwordx4 v[146:147], off
	v_lshl_add_u64 v[146:147], v[148:149], 0, s[36:37]
	s_add_i32 m0, s6, 0x2000
	s_nop 0
	global_load_lds_dwordx4 v[146:147], off
	s_mov_b32 m0, s72
	v_lshl_add_u64 v[146:147], v[194:195], 0, s[36:37]
	ds_read_b128 v[174:177], v157 offset:49152
	ds_read_b128 v[178:181], v157 offset:50176
	ds_read_b128 v[182:185], v157 offset:51200
	ds_read_b128 v[206:209], v157 offset:52224
	ds_read_b128 v[210:213], v157 offset:53248
	ds_read_b128 v[214:217], v157 offset:54272
	ds_read_b128 v[218:221], v157 offset:55296
	ds_read_b128 v[222:225], v157 offset:56320
	global_load_lds_dwordx4 v[146:147], off
	v_lshl_add_u64 v[146:147], v[196:197], 0, s[36:37]
	s_mov_b32 m0, s73
	s_nop 0
	global_load_lds_dwordx4 v[146:147], off
	s_add_u32 s52, s52, 0x40080
	s_addc_u32 s53, s53, 0
	s_add_i32 s6, s19, s59
	v_lshl_add_u64 v[146:147], s[52:53], 0, v[140:141]
	s_mov_b32 m0, s6
	s_nop 0
	global_load_lds_dwordx4 v[146:147], off
	v_lshl_add_u64 v[146:147], s[52:53], 0, v[132:133]
	s_add_i32 m0, s6, 0x2000
	s_nop 0
	global_load_lds_dwordx4 v[146:147], off
	s_waitcnt vmcnt(8)
	s_waitcnt lgkmcnt(0)
	s_barrier
	s_setprio 1
	v_mfma_f32_16x16x32_bf16 v[60:63], v[158:161], v[174:177], v[60:63]
	v_mfma_f32_16x16x32_bf16 v[56:59], v[166:169], v[174:177], v[56:59]
	v_mfma_f32_16x16x32_bf16 v[52:55], v[158:161], v[182:185], v[52:55]
	v_mfma_f32_16x16x32_bf16 v[48:51], v[166:169], v[182:185], v[48:51]
	v_mfma_f32_16x16x32_bf16 v[44:47], v[158:161], v[210:213], v[44:47]
	v_mfma_f32_16x16x32_bf16 v[40:43], v[166:169], v[210:213], v[40:43]
	v_mfma_f32_16x16x32_bf16 v[36:39], v[158:161], v[218:221], v[36:39]
	v_mfma_f32_16x16x32_bf16 v[32:35], v[166:169], v[218:221], v[32:35]
	v_mfma_f32_16x16x32_bf16 v[60:63], v[162:165], v[178:181], v[60:63]
	v_mfma_f32_16x16x32_bf16 v[56:59], v[170:173], v[178:181], v[56:59]
	v_mfma_f32_16x16x32_bf16 v[52:55], v[162:165], v[206:209], v[52:55]
	v_mfma_f32_16x16x32_bf16 v[48:51], v[170:173], v[206:209], v[48:51]
	v_mfma_f32_16x16x32_bf16 v[44:47], v[162:165], v[214:217], v[44:47]
	v_mfma_f32_16x16x32_bf16 v[40:43], v[170:173], v[214:217], v[40:43]
	v_mfma_f32_16x16x32_bf16 v[36:39], v[162:165], v[222:225], v[36:39]
	v_mfma_f32_16x16x32_bf16 v[32:35], v[170:173], v[222:225], v[32:35]
	v_mfma_f32_16x16x32_bf16 v[28:31], v[226:229], v[174:177], v[28:31]
	v_mfma_f32_16x16x32_bf16 v[24:27], v[234:237], v[174:177], v[24:27]
	v_mfma_f32_16x16x32_bf16 v[20:23], v[226:229], v[182:185], v[20:23]
	v_mfma_f32_16x16x32_bf16 v[16:19], v[234:237], v[182:185], v[16:19]
	v_mfma_f32_16x16x32_bf16 v[12:15], v[226:229], v[210:213], v[12:15]
	v_mfma_f32_16x16x32_bf16 v[8:11], v[234:237], v[210:213], v[8:11]
	v_mfma_f32_16x16x32_bf16 v[4:7], v[226:229], v[218:221], v[4:7]
	v_mfma_f32_16x16x32_bf16 v[0:3], v[234:237], v[218:221], v[0:3]
	v_mfma_f32_16x16x32_bf16 v[28:31], v[230:233], v[178:181], v[28:31]
	v_mfma_f32_16x16x32_bf16 v[24:27], v[238:241], v[178:181], v[24:27]
	v_mfma_f32_16x16x32_bf16 v[20:23], v[230:233], v[206:209], v[20:23]
	v_mfma_f32_16x16x32_bf16 v[16:19], v[238:241], v[206:209], v[16:19]
	v_mfma_f32_16x16x32_bf16 v[12:15], v[230:233], v[214:217], v[12:15]
	v_mfma_f32_16x16x32_bf16 v[8:11], v[238:241], v[214:217], v[8:11]
	v_mfma_f32_16x16x32_bf16 v[4:7], v[230:233], v[222:225], v[4:7]
	v_mfma_f32_16x16x32_bf16 v[0:3], v[238:241], v[222:225], v[0:3]
	s_setprio 0
	s_add_i32 s81, s81, 2
	s_add_u32 s50, s50, 0x100
	s_addc_u32 s51, s51, 0
	s_cmp_gt_u32 s81, 13
	s_barrier
.LBB0_77:
	s_add_u32 s6, s26, s50
	s_addc_u32 s19, s27, s51
	s_add_u32 s6, s6, 0x100
	s_addc_u32 s19, s19, 0
	s_add_u32 s23, s10, s50
	s_addc_u32 s52, s11, s51
	s_add_i32 s82, 0, 0x10000
	v_add_u32_e32 v146, s82, v154
	ds_read_b128 v[158:161], v146
	ds_read_b128 v[162:165], v146 offset:1024
	ds_read_b128 v[166:169], v146 offset:2048
	ds_read_b128 v[170:173], v146 offset:3072
	s_cmpk_eq_i32 s50, 0x700
	s_cselect_b32 s55, s12, s19
	s_cselect_b32 s54, s31, s6
	s_cselect_b32 s53, s35, s52
	s_cselect_b32 s52, s39, s23
	v_lshl_add_u64 v[146:147], v[150:151], 0, s[50:51]
	s_add_i32 m0, s68, 0xc000
	ds_read_b128 v[174:177], v157
	ds_read_b128 v[178:181], v157 offset:1024
	ds_read_b128 v[182:185], v157 offset:2048
	ds_read_b128 v[206:209], v157 offset:3072
	ds_read_b128 v[210:213], v157 offset:4096
	ds_read_b128 v[214:217], v157 offset:5120
	ds_read_b128 v[218:221], v157 offset:6144
	ds_read_b128 v[222:225], v157 offset:7168
	global_load_lds_dwordx4 v[146:147], off
	v_lshl_add_u64 v[146:147], v[152:153], 0, s[50:51]
	s_add_i32 m0, s68, 0xe000
	s_nop 0
	global_load_lds_dwordx4 v[146:147], off
	s_add_i32 s6, 0, 0x14000
	v_add_u32_e32 v146, s6, v154
	ds_read_b128 v[226:229], v146
	ds_read_b128 v[230:233], v146 offset:1024
	ds_read_b128 v[234:237], v146 offset:2048
	ds_read_b128 v[238:241], v146 offset:3072
	s_waitcnt vmcnt(8)
	s_waitcnt lgkmcnt(0)
	s_barrier
	s_setprio 1
	v_mfma_f32_16x16x32_bf16 v[124:127], v[158:161], v[174:177], v[124:127]
	v_mfma_f32_16x16x32_bf16 v[120:123], v[166:169], v[174:177], v[120:123]
	v_mfma_f32_16x16x32_bf16 v[116:119], v[158:161], v[182:185], v[116:119]
	v_mfma_f32_16x16x32_bf16 v[112:115], v[166:169], v[182:185], v[112:115]
	v_mfma_f32_16x16x32_bf16 v[108:111], v[158:161], v[210:213], v[108:111]
	v_mfma_f32_16x16x32_bf16 v[104:107], v[166:169], v[210:213], v[104:107]
	v_mfma_f32_16x16x32_bf16 v[100:103], v[158:161], v[218:221], v[100:103]
	v_mfma_f32_16x16x32_bf16 v[96:99], v[166:169], v[218:221], v[96:99]
	v_mfma_f32_16x16x32_bf16 v[124:127], v[162:165], v[178:181], v[124:127]
	v_mfma_f32_16x16x32_bf16 v[120:123], v[170:173], v[178:181], v[120:123]
	v_mfma_f32_16x16x32_bf16 v[116:119], v[162:165], v[206:209], v[116:119]
	v_mfma_f32_16x16x32_bf16 v[112:115], v[170:173], v[206:209], v[112:115]
	v_mfma_f32_16x16x32_bf16 v[108:111], v[162:165], v[214:217], v[108:111]
	v_mfma_f32_16x16x32_bf16 v[104:107], v[170:173], v[214:217], v[104:107]
	v_mfma_f32_16x16x32_bf16 v[100:103], v[162:165], v[222:225], v[100:103]
	v_mfma_f32_16x16x32_bf16 v[96:99], v[170:173], v[222:225], v[96:99]
	v_mfma_f32_16x16x32_bf16 v[92:95], v[226:229], v[174:177], v[92:95]
	v_mfma_f32_16x16x32_bf16 v[88:91], v[234:237], v[174:177], v[88:91]
	v_mfma_f32_16x16x32_bf16 v[84:87], v[226:229], v[182:185], v[84:87]
	v_mfma_f32_16x16x32_bf16 v[80:83], v[234:237], v[182:185], v[80:83]
	v_mfma_f32_16x16x32_bf16 v[76:79], v[226:229], v[210:213], v[76:79]
	v_mfma_f32_16x16x32_bf16 v[72:75], v[234:237], v[210:213], v[72:75]
	v_mfma_f32_16x16x32_bf16 v[68:71], v[226:229], v[218:221], v[68:71]
	v_mfma_f32_16x16x32_bf16 v[64:67], v[234:237], v[218:221], v[64:67]
	v_mfma_f32_16x16x32_bf16 v[92:95], v[230:233], v[178:181], v[92:95]
	v_mfma_f32_16x16x32_bf16 v[88:91], v[238:241], v[178:181], v[88:91]
	v_mfma_f32_16x16x32_bf16 v[84:87], v[230:233], v[206:209], v[84:87]
	v_mfma_f32_16x16x32_bf16 v[80:83], v[238:241], v[206:209], v[80:83]
	v_mfma_f32_16x16x32_bf16 v[76:79], v[230:233], v[214:217], v[76:79]
	v_mfma_f32_16x16x32_bf16 v[72:75], v[238:241], v[214:217], v[72:75]
	v_mfma_f32_16x16x32_bf16 v[68:71], v[230:233], v[222:225], v[68:71]
	v_mfma_f32_16x16x32_bf16 v[64:67], v[238:241], v[222:225], v[64:67]
	s_setprio 0
	s_barrier
	s_add_i32 s19, s82, s59
	v_lshl_add_u64 v[146:147], s[52:53], 0, v[140:141]
	s_mov_b32 m0, s19
	v_lshl_add_u64 v[148:149], s[52:53], 0, v[132:133]
	global_load_lds_dwordx4 v[146:147], off
	s_add_i32 m0, s19, 0x2000
	s_nop 0
	global_load_lds_dwordx4 v[148:149], off
	s_mov_b32 m0, s68
	v_lshl_add_u64 v[194:195], s[54:55], 0, v[128:129]
	ds_read_b128 v[174:177], v157 offset:16384
	ds_read_b128 v[178:181], v157 offset:17408
	ds_read_b128 v[182:185], v157 offset:18432
	ds_read_b128 v[206:209], v157 offset:19456
	ds_read_b128 v[210:213], v157 offset:20480
	ds_read_b128 v[214:217], v157 offset:21504
	ds_read_b128 v[218:221], v157 offset:22528
	ds_read_b128 v[222:225], v157 offset:23552
	global_load_lds_dwordx4 v[194:195], off
	v_lshl_add_u64 v[196:197], s[54:55], 0, v[130:131]
	s_mov_b32 m0, s69
	s_nop 0
	global_load_lds_dwordx4 v[196:197], off
	s_add_u32 s82, s52, 0x40000
	s_addc_u32 s83, s53, 0
	s_add_i32 s6, s6, s59
	v_lshl_add_u64 v[250:251], s[82:83], 0, v[140:141]
	s_mov_b32 m0, s6
	s_nop 0
	global_load_lds_dwordx4 v[250:251], off
	v_lshl_add_u64 v[250:251], s[82:83], 0, v[132:133]
	s_add_i32 m0, s6, 0x2000
	s_nop 0
	global_load_lds_dwordx4 v[250:251], off
	s_waitcnt vmcnt(8)
	s_waitcnt lgkmcnt(0)
	s_barrier
	s_setprio 1
	v_mfma_f32_16x16x32_bf16 v[60:63], v[158:161], v[174:177], v[60:63]
	v_mfma_f32_16x16x32_bf16 v[56:59], v[166:169], v[174:177], v[56:59]
	v_mfma_f32_16x16x32_bf16 v[52:55], v[158:161], v[182:185], v[52:55]
	v_mfma_f32_16x16x32_bf16 v[48:51], v[166:169], v[182:185], v[48:51]
	v_mfma_f32_16x16x32_bf16 v[44:47], v[158:161], v[210:213], v[44:47]
	v_mfma_f32_16x16x32_bf16 v[40:43], v[166:169], v[210:213], v[40:43]
	v_mfma_f32_16x16x32_bf16 v[36:39], v[158:161], v[218:221], v[36:39]
	v_mfma_f32_16x16x32_bf16 v[32:35], v[166:169], v[218:221], v[32:35]
	v_mfma_f32_16x16x32_bf16 v[60:63], v[162:165], v[178:181], v[60:63]
	v_mfma_f32_16x16x32_bf16 v[56:59], v[170:173], v[178:181], v[56:59]
	v_mfma_f32_16x16x32_bf16 v[52:55], v[162:165], v[206:209], v[52:55]
	v_mfma_f32_16x16x32_bf16 v[48:51], v[170:173], v[206:209], v[48:51]
	v_mfma_f32_16x16x32_bf16 v[44:47], v[162:165], v[214:217], v[44:47]
	v_mfma_f32_16x16x32_bf16 v[40:43], v[170:173], v[214:217], v[40:43]
	v_mfma_f32_16x16x32_bf16 v[36:39], v[162:165], v[222:225], v[36:39]
	v_mfma_f32_16x16x32_bf16 v[32:35], v[170:173], v[222:225], v[32:35]
	v_mfma_f32_16x16x32_bf16 v[28:31], v[226:229], v[174:177], v[28:31]
	v_mfma_f32_16x16x32_bf16 v[24:27], v[234:237], v[174:177], v[24:27]
	v_mfma_f32_16x16x32_bf16 v[20:23], v[226:229], v[182:185], v[20:23]
	v_mfma_f32_16x16x32_bf16 v[16:19], v[234:237], v[182:185], v[16:19]
	v_mfma_f32_16x16x32_bf16 v[12:15], v[226:229], v[210:213], v[12:15]
	v_mfma_f32_16x16x32_bf16 v[8:11], v[234:237], v[210:213], v[8:11]
	v_mfma_f32_16x16x32_bf16 v[4:7], v[226:229], v[218:221], v[4:7]
	v_mfma_f32_16x16x32_bf16 v[0:3], v[234:237], v[218:221], v[0:3]
	v_mfma_f32_16x16x32_bf16 v[28:31], v[230:233], v[178:181], v[28:31]
	v_mfma_f32_16x16x32_bf16 v[24:27], v[238:241], v[178:181], v[24:27]
	v_mfma_f32_16x16x32_bf16 v[20:23], v[230:233], v[206:209], v[20:23]
	v_mfma_f32_16x16x32_bf16 v[16:19], v[238:241], v[206:209], v[16:19]
	v_mfma_f32_16x16x32_bf16 v[12:15], v[230:233], v[214:217], v[12:15]
	v_mfma_f32_16x16x32_bf16 v[8:11], v[238:241], v[214:217], v[8:11]
	v_mfma_f32_16x16x32_bf16 v[4:7], v[230:233], v[222:225], v[4:7]
	v_mfma_f32_16x16x32_bf16 v[0:3], v[238:241], v[222:225], v[0:3]
	s_setprio 0
	s_barrier
	s_add_i32 s6, 0, 0x18000
	v_add_u32_e32 v170, s6, v154
	ds_read_b128 v[158:161], v170
	ds_read_b128 v[162:165], v170 offset:1024
	ds_read_b128 v[166:169], v170 offset:2048
	ds_read_b128 v[170:173], v170 offset:3072
	s_add_u32 s54, s54, 0x40000
	s_addc_u32 s55, s55, 0
	s_mov_b32 m0, s70
	v_lshl_add_u64 v[226:227], s[54:55], 0, v[128:129]
	ds_read_b128 v[174:177], v157 offset:32768
	ds_read_b128 v[178:181], v157 offset:33792
	ds_read_b128 v[182:185], v157 offset:34816
	ds_read_b128 v[206:209], v157 offset:35840
	ds_read_b128 v[210:213], v157 offset:36864
	ds_read_b128 v[214:217], v157 offset:37888
	ds_read_b128 v[218:221], v157 offset:38912
	ds_read_b128 v[222:225], v157 offset:39936
	global_load_lds_dwordx4 v[226:227], off
	v_lshl_add_u64 v[226:227], s[54:55], 0, v[130:131]
	s_mov_b32 m0, s71
	s_nop 0
	global_load_lds_dwordx4 v[226:227], off
	s_add_i32 s19, 0, 0x1c000
	v_add_u32_e32 v192, s19, v154
	ds_read_b128 v[226:229], v192
	ds_read_b128 v[230:233], v192 offset:1024
	ds_read_b128 v[234:237], v192 offset:2048
	ds_read_b128 v[238:241], v192 offset:3072
	s_waitcnt vmcnt(8)
	s_waitcnt lgkmcnt(0)
	s_barrier
	s_setprio 1
	v_mfma_f32_16x16x32_bf16 v[124:127], v[158:161], v[174:177], v[124:127]
	v_mfma_f32_16x16x32_bf16 v[120:123], v[166:169], v[174:177], v[120:123]
	v_mfma_f32_16x16x32_bf16 v[116:119], v[158:161], v[182:185], v[116:119]
	v_mfma_f32_16x16x32_bf16 v[112:115], v[166:169], v[182:185], v[112:115]
	v_mfma_f32_16x16x32_bf16 v[108:111], v[158:161], v[210:213], v[108:111]
	v_mfma_f32_16x16x32_bf16 v[104:107], v[166:169], v[210:213], v[104:107]
	v_mfma_f32_16x16x32_bf16 v[100:103], v[158:161], v[218:221], v[100:103]
	v_mfma_f32_16x16x32_bf16 v[96:99], v[166:169], v[218:221], v[96:99]
	v_mfma_f32_16x16x32_bf16 v[124:127], v[162:165], v[178:181], v[124:127]
	v_mfma_f32_16x16x32_bf16 v[120:123], v[170:173], v[178:181], v[120:123]
	v_mfma_f32_16x16x32_bf16 v[116:119], v[162:165], v[206:209], v[116:119]
	v_mfma_f32_16x16x32_bf16 v[112:115], v[170:173], v[206:209], v[112:115]
	v_mfma_f32_16x16x32_bf16 v[108:111], v[162:165], v[214:217], v[108:111]
	v_mfma_f32_16x16x32_bf16 v[104:107], v[170:173], v[214:217], v[104:107]
	v_mfma_f32_16x16x32_bf16 v[100:103], v[162:165], v[222:225], v[100:103]
	v_mfma_f32_16x16x32_bf16 v[96:99], v[170:173], v[222:225], v[96:99]
	v_mfma_f32_16x16x32_bf16 v[92:95], v[226:229], v[174:177], v[92:95]
	v_mfma_f32_16x16x32_bf16 v[88:91], v[234:237], v[174:177], v[88:91]
	v_mfma_f32_16x16x32_bf16 v[84:87], v[226:229], v[182:185], v[84:87]
	v_mfma_f32_16x16x32_bf16 v[80:83], v[234:237], v[182:185], v[80:83]
	v_mfma_f32_16x16x32_bf16 v[76:79], v[226:229], v[210:213], v[76:79]
	v_mfma_f32_16x16x32_bf16 v[72:75], v[234:237], v[210:213], v[72:75]
	v_mfma_f32_16x16x32_bf16 v[68:71], v[226:229], v[218:221], v[68:71]
	v_mfma_f32_16x16x32_bf16 v[64:67], v[234:237], v[218:221], v[64:67]
	v_mfma_f32_16x16x32_bf16 v[92:95], v[230:233], v[178:181], v[92:95]
	v_mfma_f32_16x16x32_bf16 v[88:91], v[238:241], v[178:181], v[88:91]
	v_mfma_f32_16x16x32_bf16 v[84:87], v[230:233], v[206:209], v[84:87]
	v_mfma_f32_16x16x32_bf16 v[80:83], v[238:241], v[206:209], v[80:83]
	v_mfma_f32_16x16x32_bf16 v[76:79], v[230:233], v[214:217], v[76:79]
	v_mfma_f32_16x16x32_bf16 v[72:75], v[238:241], v[214:217], v[72:75]
	v_mfma_f32_16x16x32_bf16 v[68:71], v[230:233], v[222:225], v[68:71]
	v_mfma_f32_16x16x32_bf16 v[64:67], v[238:241], v[222:225], v[64:67]
	s_setprio 0
	s_barrier
	s_add_i32 s6, s6, s59
	v_lshl_add_u64 v[146:147], v[146:147], 0, s[36:37]
	s_mov_b32 m0, s6
	s_nop 0
	global_load_lds_dwordx4 v[146:147], off
	v_lshl_add_u64 v[146:147], v[148:149], 0, s[36:37]
	s_add_i32 m0, s6, 0x2000
	s_nop 0
	global_load_lds_dwordx4 v[146:147], off
	s_mov_b32 m0, s72
	v_lshl_add_u64 v[146:147], v[194:195], 0, s[36:37]
	ds_read_b128 v[174:177], v157 offset:49152
	ds_read_b128 v[178:181], v157 offset:50176
	ds_read_b128 v[182:185], v157 offset:51200
	ds_read_b128 v[206:209], v157 offset:52224
	ds_read_b128 v[210:213], v157 offset:53248
	ds_read_b128 v[214:217], v157 offset:54272
	ds_read_b128 v[218:221], v157 offset:55296
	ds_read_b128 v[222:225], v157 offset:56320
	global_load_lds_dwordx4 v[146:147], off
	v_lshl_add_u64 v[146:147], v[196:197], 0, s[36:37]
	s_mov_b32 m0, s73
	s_nop 0
	global_load_lds_dwordx4 v[146:147], off
	s_add_u32 s52, s52, 0x40080
	s_addc_u32 s53, s53, 0
	s_add_i32 s6, s19, s59
	v_lshl_add_u64 v[146:147], s[52:53], 0, v[140:141]
	s_mov_b32 m0, s6
	s_nop 0
	global_load_lds_dwordx4 v[146:147], off
	v_lshl_add_u64 v[146:147], s[52:53], 0, v[132:133]
	s_add_i32 m0, s6, 0x2000
	s_nop 0
	global_load_lds_dwordx4 v[146:147], off
	s_waitcnt vmcnt(8)
	s_waitcnt lgkmcnt(0)
	s_barrier
	s_setprio 1
	v_mfma_f32_16x16x32_bf16 v[60:63], v[158:161], v[174:177], v[60:63]
	v_mfma_f32_16x16x32_bf16 v[56:59], v[166:169], v[174:177], v[56:59]
	v_mfma_f32_16x16x32_bf16 v[52:55], v[158:161], v[182:185], v[52:55]
	v_mfma_f32_16x16x32_bf16 v[48:51], v[166:169], v[182:185], v[48:51]
	v_mfma_f32_16x16x32_bf16 v[44:47], v[158:161], v[210:213], v[44:47]
	v_mfma_f32_16x16x32_bf16 v[40:43], v[166:169], v[210:213], v[40:43]
	v_mfma_f32_16x16x32_bf16 v[36:39], v[158:161], v[218:221], v[36:39]
	v_mfma_f32_16x16x32_bf16 v[32:35], v[166:169], v[218:221], v[32:35]
	v_mfma_f32_16x16x32_bf16 v[60:63], v[162:165], v[178:181], v[60:63]
	v_mfma_f32_16x16x32_bf16 v[56:59], v[170:173], v[178:181], v[56:59]
	v_mfma_f32_16x16x32_bf16 v[52:55], v[162:165], v[206:209], v[52:55]
	v_mfma_f32_16x16x32_bf16 v[48:51], v[170:173], v[206:209], v[48:51]
	v_mfma_f32_16x16x32_bf16 v[44:47], v[162:165], v[214:217], v[44:47]
	v_mfma_f32_16x16x32_bf16 v[40:43], v[170:173], v[214:217], v[40:43]
	v_mfma_f32_16x16x32_bf16 v[36:39], v[162:165], v[222:225], v[36:39]
	v_mfma_f32_16x16x32_bf16 v[32:35], v[170:173], v[222:225], v[32:35]
	v_mfma_f32_16x16x32_bf16 v[28:31], v[226:229], v[174:177], v[28:31]
	v_mfma_f32_16x16x32_bf16 v[24:27], v[234:237], v[174:177], v[24:27]
	v_mfma_f32_16x16x32_bf16 v[20:23], v[226:229], v[182:185], v[20:23]
	v_mfma_f32_16x16x32_bf16 v[16:19], v[234:237], v[182:185], v[16:19]
	v_mfma_f32_16x16x32_bf16 v[12:15], v[226:229], v[210:213], v[12:15]
	v_mfma_f32_16x16x32_bf16 v[8:11], v[234:237], v[210:213], v[8:11]
	v_mfma_f32_16x16x32_bf16 v[4:7], v[226:229], v[218:221], v[4:7]
	v_mfma_f32_16x16x32_bf16 v[0:3], v[234:237], v[218:221], v[0:3]
	v_mfma_f32_16x16x32_bf16 v[28:31], v[230:233], v[178:181], v[28:31]
	v_mfma_f32_16x16x32_bf16 v[24:27], v[238:241], v[178:181], v[24:27]
	v_mfma_f32_16x16x32_bf16 v[20:23], v[230:233], v[206:209], v[20:23]
	v_mfma_f32_16x16x32_bf16 v[16:19], v[238:241], v[206:209], v[16:19]
	v_mfma_f32_16x16x32_bf16 v[12:15], v[230:233], v[214:217], v[12:15]
	v_mfma_f32_16x16x32_bf16 v[8:11], v[238:241], v[214:217], v[8:11]
	v_mfma_f32_16x16x32_bf16 v[4:7], v[230:233], v[222:225], v[4:7]
	v_mfma_f32_16x16x32_bf16 v[0:3], v[238:241], v[222:225], v[0:3]
	s_setprio 0
	s_add_i32 s81, s81, 2
	s_add_u32 s50, s50, 0x100
	s_addc_u32 s51, s51, 0
	s_cmp_gt_u32 s81, 13
	s_barrier
	s_cbranch_scc0 .LBB0_77
	s_mov_b32 s100, 1
	v_lshl_add_u32 v158, s75, 10, v155
	ds_read2_b32 v[146:147], v158 offset1:16
	s_add_u32 s50, s10, 0xffffff00
	s_addc_u32 s51, s11, -1
	s_ashr_i32 s31, s30, 31
	s_lshl_b64 s[10:11], s[30:31], 8
	s_waitcnt lgkmcnt(0)
	v_pk_mul_f32 v[148:149], v[124:125], v[146:147] op_sel_hi:[1,0]
	v_lshl_add_u64 v[152:153], v[134:135], 0, s[10:11]
	v_mul_f32_e32 v159, 0xbfb8aa3b, v148
	v_exp_f32_e32 v159, v159
	s_movk_i32 s6, 0x1600
	v_lshl_or_b32 v150, s74, 7, v156
	v_ashrrev_i32_e32 v151, 31, v150
	v_add_f32_e32 v159, 1.0, v159
	v_rcp_f32_e32 v160, v159
	v_mul_f32_e32 v159, 0xbfb8aa3b, v149
	v_exp_f32_e32 v159, v159
	s_nop 0
	v_add_f32_e32 v159, 1.0, v159
	v_rcp_f32_e32 v161, v159
	s_nop 0
	v_pk_mul_f32 v[148:149], v[148:149], v[160:161]
	v_pk_mul_f32 v[160:161], v[92:93], v[146:147] op_sel_hi:[1,0]
	s_nop 0
	v_pk_mul_f32 v[148:149], v[160:161], v[148:149]
	v_pk_mul_f32 v[160:161], v[126:127], v[146:147] op_sel_hi:[1,0]
	s_nop 0
	v_mul_f32_e32 v159, 0xbfb8aa3b, v160
	v_exp_f32_e32 v159, v159
	s_nop 0
	v_add_f32_e32 v159, 1.0, v159
	v_rcp_f32_e32 v162, v159
	v_mul_f32_e32 v159, 0xbfb8aa3b, v161
	v_exp_f32_e32 v159, v159
	s_nop 0
	v_add_f32_e32 v159, 1.0, v159
	v_rcp_f32_e32 v163, v159
	s_nop 0
	v_pk_mul_f32 v[160:161], v[160:161], v[162:163]
	v_pk_mul_f32 v[162:163], v[94:95], v[146:147] op_sel_hi:[1,0]
	s_nop 0
	v_pk_mul_f32 v[162:163], v[162:163], v[160:161]
	v_pk_mul_f32 v[160:161], v[120:121], v[146:147] op_sel_hi:[1,0]
	s_nop 0
	v_mul_f32_e32 v159, 0xbfb8aa3b, v160
	v_exp_f32_e32 v159, v159
	s_nop 0
	v_add_f32_e32 v159, 1.0, v159
	v_rcp_f32_e32 v164, v159
	v_mul_f32_e32 v159, 0xbfb8aa3b, v161
	v_exp_f32_e32 v159, v159
	s_nop 0
	v_add_f32_e32 v159, 1.0, v159
	v_rcp_f32_e32 v165, v159
	s_nop 0
	v_pk_mul_f32 v[160:161], v[160:161], v[164:165]
	v_pk_mul_f32 v[164:165], v[88:89], v[146:147] op_sel_hi:[1,0]
	s_nop 0
	v_pk_mul_f32 v[164:165], v[164:165], v[160:161]
	v_pk_mul_f32 v[160:161], v[122:123], v[146:147] op_sel_hi:[1,0]
	s_nop 0
	v_mul_f32_e32 v159, 0xbfb8aa3b, v160
	v_exp_f32_e32 v159, v159
	s_nop 0
	v_add_f32_e32 v159, 1.0, v159
	v_rcp_f32_e32 v166, v159
	v_mul_f32_e32 v159, 0xbfb8aa3b, v161
	v_exp_f32_e32 v159, v159
	s_nop 0
	v_add_f32_e32 v159, 1.0, v159
	v_rcp_f32_e32 v167, v159
	s_nop 0
	v_pk_mul_f32 v[160:161], v[160:161], v[166:167]
	v_pk_mul_f32 v[166:167], v[90:91], v[146:147] op_sel_hi:[1,0]
	s_nop 0
	v_pk_mul_f32 v[166:167], v[166:167], v[160:161]
	v_cvt_pk_bf16_f32 v160, v148, v149
	v_mov_b64_e32 v[148:149], s[28:29]
	v_mad_u64_u32 v[148:149], s[10:11], v152, s6, v[148:149]
	v_mov_b32_e32 v146, v149
	v_mad_u64_u32 v[152:153], s[10:11], v153, s6, v[146:147]
	v_mov_b32_e32 v149, v152
	v_mov_b32_e32 v146, v147
	v_lshl_add_u64 v[150:151], v[150:151], 1, v[148:149]
	v_pk_mul_f32 v[148:149], v[116:117], v[146:147] op_sel_hi:[1,0]
	v_cvt_pk_bf16_f32 v161, v162, v163
	v_mul_f32_e32 v147, 0xbfb8aa3b, v148
	v_exp_f32_e32 v147, v147
	v_cvt_pk_bf16_f32 v162, v164, v165
	v_cvt_pk_bf16_f32 v163, v166, v167
	global_store_dwordx4 v[150:151], v[160:163], off
	v_add_f32_e32 v147, 1.0, v147
	v_rcp_f32_e32 v152, v147
	v_mul_f32_e32 v147, 0xbfb8aa3b, v149
	v_exp_f32_e32 v147, v147
	s_mov_b32 s6, 0x16000
	v_add_f32_e32 v147, 1.0, v147
	v_rcp_f32_e32 v153, v147
	s_nop 0
	v_pk_mul_f32 v[148:149], v[148:149], v[152:153]
	v_pk_mul_f32 v[152:153], v[84:85], v[146:147] op_sel_hi:[1,0]
	s_nop 0
	v_pk_mul_f32 v[148:149], v[152:153], v[148:149]
	v_pk_mul_f32 v[152:153], v[118:119], v[146:147] op_sel_hi:[1,0]
	s_nop 0
	v_mul_f32_e32 v147, 0xbfb8aa3b, v152
	v_exp_f32_e32 v147, v147
	s_nop 0
	v_add_f32_e32 v147, 1.0, v147
	v_rcp_f32_e32 v160, v147
	v_mul_f32_e32 v147, 0xbfb8aa3b, v153
	v_exp_f32_e32 v147, v147
	s_nop 0
	v_add_f32_e32 v147, 1.0, v147
	v_rcp_f32_e32 v161, v147
	s_nop 0
	v_pk_mul_f32 v[152:153], v[152:153], v[160:161]
	v_pk_mul_f32 v[160:161], v[86:87], v[146:147] op_sel_hi:[1,0]
	s_nop 0
	v_pk_mul_f32 v[152:153], v[160:161], v[152:153]
	v_pk_mul_f32 v[160:161], v[112:113], v[146:147] op_sel_hi:[1,0]
	s_nop 0
	v_mul_f32_e32 v147, 0xbfb8aa3b, v160
	v_exp_f32_e32 v147, v147
	s_nop 0
	v_add_f32_e32 v147, 1.0, v147
	v_rcp_f32_e32 v162, v147
	v_mul_f32_e32 v147, 0xbfb8aa3b, v161
	v_exp_f32_e32 v147, v147
	s_nop 0
	v_add_f32_e32 v147, 1.0, v147
	v_rcp_f32_e32 v163, v147
	s_nop 0
	v_pk_mul_f32 v[160:161], v[160:161], v[162:163]
	v_pk_mul_f32 v[162:163], v[80:81], v[146:147] op_sel_hi:[1,0]
	s_nop 0
	v_pk_mul_f32 v[162:163], v[162:163], v[160:161]
	v_pk_mul_f32 v[160:161], v[114:115], v[146:147] op_sel_hi:[1,0]
	v_cvt_pk_bf16_f32 v162, v162, v163
	v_mul_f32_e32 v147, 0xbfb8aa3b, v160
	v_exp_f32_e32 v147, v147
	s_nop 0
	v_add_f32_e32 v147, 1.0, v147
	v_rcp_f32_e32 v164, v147
	v_mul_f32_e32 v147, 0xbfb8aa3b, v161
	v_exp_f32_e32 v147, v147
	s_nop 0
	v_add_f32_e32 v147, 1.0, v147
	v_rcp_f32_e32 v165, v147
	v_pk_mul_f32 v[146:147], v[82:83], v[146:147] op_sel_hi:[1,0]
	v_pk_mul_f32 v[160:161], v[160:161], v[164:165]
	s_nop 0
	v_pk_mul_f32 v[146:147], v[146:147], v[160:161]
	v_cvt_pk_bf16_f32 v160, v148, v149
	v_cvt_pk_bf16_f32 v163, v146, v147
	v_add_co_u32_e32 v146, vcc, s6, v150
	v_cvt_pk_bf16_f32 v161, v152, v153
	s_nop 0
	v_addc_co_u32_e32 v147, vcc, 0, v151, vcc
	global_store_dwordx4 v[146:147], v[160:163], off
	ds_read2_b32 v[146:147], v158 offset0:32 offset1:48
	s_mov_b32 s6, 0x2c000
	s_waitcnt lgkmcnt(0)
	v_pk_mul_f32 v[148:149], v[108:109], v[146:147] op_sel_hi:[1,0]
	s_nop 0
	v_mul_f32_e32 v152, 0xbfb8aa3b, v148
	v_mul_f32_e32 v153, 0xbfb8aa3b, v149
	v_exp_f32_e32 v152, v152
	v_exp_f32_e32 v153, v153
	v_add_f32_e32 v152, 1.0, v152
	v_add_f32_e32 v153, 1.0, v153
	v_rcp_f32_e32 v152, v152
	v_rcp_f32_e32 v153, v153
	s_nop 0
	v_pk_mul_f32 v[148:149], v[148:149], v[152:153]
	v_pk_mul_f32 v[152:153], v[76:77], v[146:147] op_sel_hi:[1,0]
	s_nop 0
	v_pk_mul_f32 v[148:149], v[152:153], v[148:149]
	v_pk_mul_f32 v[152:153], v[110:111], v[146:147] op_sel_hi:[1,0]
	s_nop 0
	v_mul_f32_e32 v159, 0xbfb8aa3b, v152
	v_exp_f32_e32 v159, v159
	s_nop 0
	v_add_f32_e32 v159, 1.0, v159
	v_rcp_f32_e32 v160, v159
	v_mul_f32_e32 v159, 0xbfb8aa3b, v153
	v_exp_f32_e32 v159, v159
	s_nop 0
	v_add_f32_e32 v159, 1.0, v159
	v_rcp_f32_e32 v161, v159
	s_nop 0
	v_pk_mul_f32 v[152:153], v[152:153], v[160:161]
	v_pk_mul_f32 v[160:161], v[78:79], v[146:147] op_sel_hi:[1,0]
	s_nop 0
	v_pk_mul_f32 v[152:153], v[160:161], v[152:153]
	v_pk_mul_f32 v[160:161], v[104:105], v[146:147] op_sel_hi:[1,0]
	s_nop 0
	v_mul_f32_e32 v159, 0xbfb8aa3b, v160
	v_exp_f32_e32 v159, v159
	s_nop 0
	v_add_f32_e32 v159, 1.0, v159
	v_rcp_f32_e32 v162, v159
	v_mul_f32_e32 v159, 0xbfb8aa3b, v161
	v_exp_f32_e32 v159, v159
	s_nop 0
	v_add_f32_e32 v159, 1.0, v159
	v_rcp_f32_e32 v163, v159
	s_nop 0
	v_pk_mul_f32 v[160:161], v[160:161], v[162:163]
	v_pk_mul_f32 v[162:163], v[72:73], v[146:147] op_sel_hi:[1,0]
	s_nop 0
	v_pk_mul_f32 v[162:163], v[162:163], v[160:161]
	v_pk_mul_f32 v[160:161], v[106:107], v[146:147] op_sel_hi:[1,0]
	v_cvt_pk_bf16_f32 v162, v162, v163
	v_mul_f32_e32 v159, 0xbfb8aa3b, v160
	v_exp_f32_e32 v159, v159
	s_nop 0
	v_add_f32_e32 v159, 1.0, v159
	v_rcp_f32_e32 v164, v159
	v_mul_f32_e32 v159, 0xbfb8aa3b, v161
	v_exp_f32_e32 v159, v159
	s_nop 0
	v_add_f32_e32 v159, 1.0, v159
	v_rcp_f32_e32 v165, v159
	s_nop 0
	v_pk_mul_f32 v[160:161], v[160:161], v[164:165]
	v_pk_mul_f32 v[164:165], v[74:75], v[146:147] op_sel_hi:[1,0]
	v_mov_b32_e32 v146, v147
	v_pk_mul_f32 v[164:165], v[164:165], v[160:161]
	v_cvt_pk_bf16_f32 v160, v148, v149
	v_add_co_u32_e32 v148, vcc, s6, v150
	v_cvt_pk_bf16_f32 v161, v152, v153
	v_cvt_pk_bf16_f32 v163, v164, v165
	v_addc_co_u32_e32 v149, vcc, 0, v151, vcc
	global_store_dwordx4 v[148:149], v[160:163], off
	v_pk_mul_f32 v[148:149], v[100:101], v[146:147] op_sel_hi:[1,0]
	s_mov_b32 s6, 0x42000
	v_mul_f32_e32 v147, 0xbfb8aa3b, v148
	v_exp_f32_e32 v147, v147
	s_nop 0
	v_add_f32_e32 v147, 1.0, v147
	v_rcp_f32_e32 v152, v147
	v_mul_f32_e32 v147, 0xbfb8aa3b, v149
	v_exp_f32_e32 v147, v147
	s_nop 0
	v_add_f32_e32 v147, 1.0, v147
	v_rcp_f32_e32 v153, v147
	s_nop 0
	v_pk_mul_f32 v[148:149], v[148:149], v[152:153]
	v_pk_mul_f32 v[152:153], v[68:69], v[146:147] op_sel_hi:[1,0]
	s_nop 0
	v_pk_mul_f32 v[148:149], v[152:153], v[148:149]
	v_pk_mul_f32 v[152:153], v[102:103], v[146:147] op_sel_hi:[1,0]
	s_nop 0
	v_mul_f32_e32 v147, 0xbfb8aa3b, v152
	v_exp_f32_e32 v147, v147
	s_nop 0
	v_add_f32_e32 v147, 1.0, v147
	v_rcp_f32_e32 v160, v147
	v_mul_f32_e32 v147, 0xbfb8aa3b, v153
	v_exp_f32_e32 v147, v147
	s_nop 0
	v_add_f32_e32 v147, 1.0, v147
	v_rcp_f32_e32 v161, v147
	s_nop 0
	v_pk_mul_f32 v[152:153], v[152:153], v[160:161]
	v_pk_mul_f32 v[160:161], v[70:71], v[146:147] op_sel_hi:[1,0]
	s_nop 0
	v_pk_mul_f32 v[152:153], v[160:161], v[152:153]
	v_pk_mul_f32 v[160:161], v[96:97], v[146:147] op_sel_hi:[1,0]
	s_nop 0
	v_mul_f32_e32 v147, 0xbfb8aa3b, v160
	v_exp_f32_e32 v147, v147
	s_nop 0
	v_add_f32_e32 v147, 1.0, v147
	v_rcp_f32_e32 v162, v147
	v_mul_f32_e32 v147, 0xbfb8aa3b, v161
	v_exp_f32_e32 v147, v147
	s_nop 0
	v_add_f32_e32 v147, 1.0, v147
	v_rcp_f32_e32 v163, v147
	s_nop 0
	v_pk_mul_f32 v[160:161], v[160:161], v[162:163]
	v_pk_mul_f32 v[162:163], v[64:65], v[146:147] op_sel_hi:[1,0]
	s_nop 0
	v_pk_mul_f32 v[162:163], v[162:163], v[160:161]
	v_pk_mul_f32 v[160:161], v[98:99], v[146:147] op_sel_hi:[1,0]
	v_cvt_pk_bf16_f32 v162, v162, v163
	v_mul_f32_e32 v147, 0xbfb8aa3b, v160
	v_exp_f32_e32 v147, v147
	s_nop 0
	v_add_f32_e32 v147, 1.0, v147
	v_rcp_f32_e32 v164, v147
	v_mul_f32_e32 v147, 0xbfb8aa3b, v161
	v_exp_f32_e32 v147, v147
	s_nop 0
	v_add_f32_e32 v147, 1.0, v147
	v_rcp_f32_e32 v165, v147
	v_pk_mul_f32 v[146:147], v[66:67], v[146:147] op_sel_hi:[1,0]
	v_pk_mul_f32 v[160:161], v[160:161], v[164:165]
	s_nop 0
	v_pk_mul_f32 v[146:147], v[146:147], v[160:161]
	v_cvt_pk_bf16_f32 v160, v148, v149
	v_cvt_pk_bf16_f32 v163, v146, v147
	v_add_co_u32_e32 v146, vcc, s6, v150
	v_cvt_pk_bf16_f32 v161, v152, v153
	s_nop 0
	v_addc_co_u32_e32 v147, vcc, 0, v151, vcc
	global_store_dwordx4 v[146:147], v[160:163], off
	ds_read2_b32 v[146:147], v158 offset0:128 offset1:144
	s_mov_b32 s6, 0xb0000
	s_waitcnt lgkmcnt(0)
	v_pk_mul_f32 v[148:149], v[60:61], v[146:147] op_sel_hi:[1,0]
	s_nop 0
	v_mul_f32_e32 v152, 0xbfb8aa3b, v148
	v_mul_f32_e32 v153, 0xbfb8aa3b, v149
	v_exp_f32_e32 v152, v152
	v_exp_f32_e32 v153, v153
	v_add_f32_e32 v152, 1.0, v152
	v_add_f32_e32 v153, 1.0, v153
	v_rcp_f32_e32 v152, v152
	v_rcp_f32_e32 v153, v153
	s_nop 0
	v_pk_mul_f32 v[148:149], v[148:149], v[152:153]
	v_pk_mul_f32 v[152:153], v[28:29], v[146:147] op_sel_hi:[1,0]
	s_nop 0
	v_pk_mul_f32 v[148:149], v[152:153], v[148:149]
	v_pk_mul_f32 v[152:153], v[62:63], v[146:147] op_sel_hi:[1,0]
	s_nop 0
	v_mul_f32_e32 v159, 0xbfb8aa3b, v152
	v_exp_f32_e32 v159, v159
	s_nop 0
	v_add_f32_e32 v159, 1.0, v159
	v_rcp_f32_e32 v160, v159
	v_mul_f32_e32 v159, 0xbfb8aa3b, v153
	v_exp_f32_e32 v159, v159
	s_nop 0
	v_add_f32_e32 v159, 1.0, v159
	v_rcp_f32_e32 v161, v159
	s_nop 0
	v_pk_mul_f32 v[152:153], v[152:153], v[160:161]
	v_pk_mul_f32 v[160:161], v[30:31], v[146:147] op_sel_hi:[1,0]
	s_nop 0
	v_pk_mul_f32 v[152:153], v[160:161], v[152:153]
	v_pk_mul_f32 v[160:161], v[56:57], v[146:147] op_sel_hi:[1,0]
	s_nop 0
	v_mul_f32_e32 v159, 0xbfb8aa3b, v160
	v_exp_f32_e32 v159, v159
	s_nop 0
	v_add_f32_e32 v159, 1.0, v159
	v_rcp_f32_e32 v162, v159
	v_mul_f32_e32 v159, 0xbfb8aa3b, v161
	v_exp_f32_e32 v159, v159
	s_nop 0
	v_add_f32_e32 v159, 1.0, v159
	v_rcp_f32_e32 v163, v159
	s_nop 0
	v_pk_mul_f32 v[160:161], v[160:161], v[162:163]
	v_pk_mul_f32 v[162:163], v[24:25], v[146:147] op_sel_hi:[1,0]
	s_nop 0
	v_pk_mul_f32 v[162:163], v[162:163], v[160:161]
	v_pk_mul_f32 v[160:161], v[58:59], v[146:147] op_sel_hi:[1,0]
	v_cvt_pk_bf16_f32 v162, v162, v163
	v_mul_f32_e32 v159, 0xbfb8aa3b, v160
	v_exp_f32_e32 v159, v159
	s_nop 0
	v_add_f32_e32 v159, 1.0, v159
	v_rcp_f32_e32 v164, v159
	v_mul_f32_e32 v159, 0xbfb8aa3b, v161
	v_exp_f32_e32 v159, v159
	s_nop 0
	v_add_f32_e32 v159, 1.0, v159
	v_rcp_f32_e32 v165, v159
	s_nop 0
	v_pk_mul_f32 v[160:161], v[160:161], v[164:165]
	v_pk_mul_f32 v[164:165], v[26:27], v[146:147] op_sel_hi:[1,0]
	v_mov_b32_e32 v146, v147
	v_pk_mul_f32 v[164:165], v[164:165], v[160:161]
	v_cvt_pk_bf16_f32 v160, v148, v149
	v_add_co_u32_e32 v148, vcc, s6, v150
	v_cvt_pk_bf16_f32 v161, v152, v153
	v_cvt_pk_bf16_f32 v163, v164, v165
	v_addc_co_u32_e32 v149, vcc, 0, v151, vcc
	global_store_dwordx4 v[148:149], v[160:163], off
	v_pk_mul_f32 v[148:149], v[52:53], v[146:147] op_sel_hi:[1,0]
	s_mov_b32 s6, 0xc6000
	v_mul_f32_e32 v147, 0xbfb8aa3b, v148
	v_exp_f32_e32 v147, v147
	s_nop 0
	v_add_f32_e32 v147, 1.0, v147
	v_rcp_f32_e32 v152, v147
	v_mul_f32_e32 v147, 0xbfb8aa3b, v149
	v_exp_f32_e32 v147, v147
	s_nop 0
	v_add_f32_e32 v147, 1.0, v147
	v_rcp_f32_e32 v153, v147
	s_nop 0
	v_pk_mul_f32 v[148:149], v[148:149], v[152:153]
	v_pk_mul_f32 v[152:153], v[20:21], v[146:147] op_sel_hi:[1,0]
	s_nop 0
	v_pk_mul_f32 v[148:149], v[152:153], v[148:149]
	v_pk_mul_f32 v[152:153], v[54:55], v[146:147] op_sel_hi:[1,0]
	s_nop 0
	v_mul_f32_e32 v147, 0xbfb8aa3b, v152
	v_exp_f32_e32 v147, v147
	s_nop 0
	v_add_f32_e32 v147, 1.0, v147
	v_rcp_f32_e32 v160, v147
	v_mul_f32_e32 v147, 0xbfb8aa3b, v153
	v_exp_f32_e32 v147, v147
	s_nop 0
	v_add_f32_e32 v147, 1.0, v147
	v_rcp_f32_e32 v161, v147
	s_nop 0
	v_pk_mul_f32 v[152:153], v[152:153], v[160:161]
	v_pk_mul_f32 v[160:161], v[22:23], v[146:147] op_sel_hi:[1,0]
	s_nop 0
	v_pk_mul_f32 v[152:153], v[160:161], v[152:153]
	v_pk_mul_f32 v[160:161], v[48:49], v[146:147] op_sel_hi:[1,0]
	s_nop 0
	v_mul_f32_e32 v147, 0xbfb8aa3b, v160
	v_exp_f32_e32 v147, v147
	s_nop 0
	v_add_f32_e32 v147, 1.0, v147
	v_rcp_f32_e32 v162, v147
	v_mul_f32_e32 v147, 0xbfb8aa3b, v161
	v_exp_f32_e32 v147, v147
	s_nop 0
	v_add_f32_e32 v147, 1.0, v147
	v_rcp_f32_e32 v163, v147
	s_nop 0
	v_pk_mul_f32 v[160:161], v[160:161], v[162:163]
	v_pk_mul_f32 v[162:163], v[16:17], v[146:147] op_sel_hi:[1,0]
	s_nop 0
	v_pk_mul_f32 v[162:163], v[162:163], v[160:161]
	v_pk_mul_f32 v[160:161], v[50:51], v[146:147] op_sel_hi:[1,0]
	v_cvt_pk_bf16_f32 v162, v162, v163
	v_mul_f32_e32 v147, 0xbfb8aa3b, v160
	v_exp_f32_e32 v147, v147
	s_nop 0
	v_add_f32_e32 v147, 1.0, v147
	v_rcp_f32_e32 v164, v147
	v_mul_f32_e32 v147, 0xbfb8aa3b, v161
	v_exp_f32_e32 v147, v147
	s_nop 0
	v_add_f32_e32 v147, 1.0, v147
	v_rcp_f32_e32 v165, v147
	v_pk_mul_f32 v[146:147], v[18:19], v[146:147] op_sel_hi:[1,0]
	v_pk_mul_f32 v[160:161], v[160:161], v[164:165]
	s_nop 0
	v_pk_mul_f32 v[146:147], v[146:147], v[160:161]
	v_cvt_pk_bf16_f32 v160, v148, v149
	v_cvt_pk_bf16_f32 v163, v146, v147
	v_add_co_u32_e32 v146, vcc, s6, v150
	v_cvt_pk_bf16_f32 v161, v152, v153
	s_nop 0
	v_addc_co_u32_e32 v147, vcc, 0, v151, vcc
	global_store_dwordx4 v[146:147], v[160:163], off
	ds_read2_b32 v[146:147], v158 offset0:160 offset1:176
	s_mov_b32 s6, 0xdc000
	s_waitcnt lgkmcnt(0)
	v_pk_mul_f32 v[148:149], v[44:45], v[146:147] op_sel_hi:[1,0]
	s_nop 0
	v_mul_f32_e32 v152, 0xbfb8aa3b, v148
	v_mul_f32_e32 v153, 0xbfb8aa3b, v149
	v_exp_f32_e32 v152, v152
	v_exp_f32_e32 v153, v153
	v_add_f32_e32 v152, 1.0, v152
	v_add_f32_e32 v153, 1.0, v153
	v_rcp_f32_e32 v152, v152
	v_rcp_f32_e32 v153, v153
	s_nop 0
	v_pk_mul_f32 v[148:149], v[148:149], v[152:153]
	v_pk_mul_f32 v[152:153], v[12:13], v[146:147] op_sel_hi:[1,0]
	s_nop 0
	v_pk_mul_f32 v[148:149], v[152:153], v[148:149]
	v_pk_mul_f32 v[152:153], v[46:47], v[146:147] op_sel_hi:[1,0]
	s_nop 0
	v_mul_f32_e32 v158, 0xbfb8aa3b, v152
	v_mul_f32_e32 v159, 0xbfb8aa3b, v153
	v_exp_f32_e32 v158, v158
	v_exp_f32_e32 v159, v159
	v_add_f32_e32 v158, 1.0, v158
	v_add_f32_e32 v159, 1.0, v159
	v_rcp_f32_e32 v158, v158
	v_rcp_f32_e32 v159, v159
	s_nop 0
	v_pk_mul_f32 v[152:153], v[152:153], v[158:159]
	v_pk_mul_f32 v[158:159], v[14:15], v[146:147] op_sel_hi:[1,0]
	s_nop 0
	v_pk_mul_f32 v[152:153], v[158:159], v[152:153]
	v_pk_mul_f32 v[158:159], v[40:41], v[146:147] op_sel_hi:[1,0]
	s_nop 0
	v_mul_f32_e32 v160, 0xbfb8aa3b, v158
	v_mul_f32_e32 v161, 0xbfb8aa3b, v159
	v_exp_f32_e32 v160, v160
	v_exp_f32_e32 v161, v161
	v_add_f32_e32 v160, 1.0, v160
	v_add_f32_e32 v161, 1.0, v161
	v_rcp_f32_e32 v160, v160
	v_rcp_f32_e32 v161, v161
	s_nop 0
	v_pk_mul_f32 v[158:159], v[158:159], v[160:161]
	v_pk_mul_f32 v[160:161], v[8:9], v[146:147] op_sel_hi:[1,0]
	s_nop 0
	v_pk_mul_f32 v[160:161], v[160:161], v[158:159]
	v_pk_mul_f32 v[158:159], v[42:43], v[146:147] op_sel_hi:[1,0]
	v_cvt_pk_bf16_f32 v160, v160, v161
	v_mul_f32_e32 v162, 0xbfb8aa3b, v158
	v_mul_f32_e32 v163, 0xbfb8aa3b, v159
	v_exp_f32_e32 v162, v162
	v_exp_f32_e32 v163, v163
	v_add_f32_e32 v162, 1.0, v162
	v_add_f32_e32 v163, 1.0, v163
	v_rcp_f32_e32 v162, v162
	v_rcp_f32_e32 v163, v163
	s_nop 0
	v_pk_mul_f32 v[158:159], v[158:159], v[162:163]
	v_pk_mul_f32 v[162:163], v[10:11], v[146:147] op_sel_hi:[1,0]
	v_mov_b32_e32 v146, v147
	v_pk_mul_f32 v[162:163], v[162:163], v[158:159]
	v_cvt_pk_bf16_f32 v158, v148, v149
	v_add_co_u32_e32 v148, vcc, s6, v150
	v_cvt_pk_bf16_f32 v159, v152, v153
	v_cvt_pk_bf16_f32 v161, v162, v163
	v_addc_co_u32_e32 v149, vcc, 0, v151, vcc
	global_store_dwordx4 v[148:149], v[158:161], off
	v_pk_mul_f32 v[148:149], v[36:37], v[146:147] op_sel_hi:[1,0]
	s_nop 0
	v_mul_f32_e32 v147, 0xbfb8aa3b, v148
	v_exp_f32_e32 v147, v147
	s_nop 0
	v_add_f32_e32 v147, 1.0, v147
	v_rcp_f32_e32 v152, v147
	v_mul_f32_e32 v147, 0xbfb8aa3b, v149
	v_exp_f32_e32 v147, v147
	s_nop 0
	v_add_f32_e32 v147, 1.0, v147
	v_rcp_f32_e32 v153, v147
	s_nop 0
	v_pk_mul_f32 v[148:149], v[148:149], v[152:153]
	v_pk_mul_f32 v[152:153], v[4:5], v[146:147] op_sel_hi:[1,0]
	s_nop 0
	v_pk_mul_f32 v[148:149], v[152:153], v[148:149]
	v_pk_mul_f32 v[152:153], v[38:39], v[146:147] op_sel_hi:[1,0]
	s_nop 0
	v_mul_f32_e32 v147, 0xbfb8aa3b, v152
	v_exp_f32_e32 v147, v147
	s_nop 0
	v_add_f32_e32 v147, 1.0, v147
	v_rcp_f32_e32 v158, v147
	v_mul_f32_e32 v147, 0xbfb8aa3b, v153
	v_exp_f32_e32 v147, v147
	s_nop 0
	v_add_f32_e32 v147, 1.0, v147
	v_rcp_f32_e32 v159, v147
	s_nop 0
	v_pk_mul_f32 v[152:153], v[152:153], v[158:159]
	v_pk_mul_f32 v[158:159], v[6:7], v[146:147] op_sel_hi:[1,0]
	s_nop 0
	v_pk_mul_f32 v[152:153], v[158:159], v[152:153]
	v_pk_mul_f32 v[158:159], v[32:33], v[146:147] op_sel_hi:[1,0]
	s_nop 0
	v_mul_f32_e32 v147, 0xbfb8aa3b, v158
	v_exp_f32_e32 v147, v147
	s_nop 0
	v_add_f32_e32 v147, 1.0, v147
	v_rcp_f32_e32 v160, v147
	v_mul_f32_e32 v147, 0xbfb8aa3b, v159
	v_exp_f32_e32 v147, v147
	s_nop 0
	v_add_f32_e32 v147, 1.0, v147
	v_rcp_f32_e32 v161, v147
	s_nop 0
	v_pk_mul_f32 v[158:159], v[158:159], v[160:161]
	v_pk_mul_f32 v[160:161], v[0:1], v[146:147] op_sel_hi:[1,0]
	s_nop 0
	v_pk_mul_f32 v[160:161], v[160:161], v[158:159]
	v_pk_mul_f32 v[158:159], v[34:35], v[146:147] op_sel_hi:[1,0]
	v_cvt_pk_bf16_f32 v160, v160, v161
	v_mul_f32_e32 v147, 0xbfb8aa3b, v158
	v_exp_f32_e32 v147, v147
	s_nop 0
	v_add_f32_e32 v147, 1.0, v147
	v_rcp_f32_e32 v162, v147
	v_mul_f32_e32 v147, 0xbfb8aa3b, v159
	v_exp_f32_e32 v147, v147
	s_nop 0
	v_add_f32_e32 v147, 1.0, v147
	v_rcp_f32_e32 v163, v147
	v_pk_mul_f32 v[146:147], v[2:3], v[146:147] op_sel_hi:[1,0]
	v_pk_mul_f32 v[158:159], v[158:159], v[162:163]
	s_nop 0
	v_pk_mul_f32 v[146:147], v[146:147], v[158:159]
	v_cvt_pk_bf16_f32 v158, v148, v149
	v_cvt_pk_bf16_f32 v161, v146, v147
	v_add_co_u32_e32 v146, vcc, 0xf2000, v150
	v_cvt_pk_bf16_f32 v159, v152, v153
	s_nop 0
	v_addc_co_u32_e32 v147, vcc, 0, v151, vcc
	s_andn2_b64 vcc, exec, s[44:45]
	global_store_dwordx4 v[146:147], v[158:161], off
	s_cbranch_vccz .LBB0_73
	s_mov_b64 s[46:47], s[50:51]
	s_andn2_b64 vcc, exec, s[42:43]
	s_mov_b64 s[50:51], s[46:47]
	s_cbranch_vccnz .LBB0_74

.LBB0_102:
	s_add_u32 s54, s54, 0x40080
	s_addc_u32 s55, s55, 0
	s_add_u32 s10, s58, 0x100
	s_addc_u32 s11, s59, 0
	s_mov_b32 s12, -2
	s_waitcnt lgkmcnt(0)
	s_add_u32 s6, s54, 0xfffc0080
	s_addc_u32 s19, s55, -1
	s_add_i32 s23, 0, 0x10000
	v_add_u32_e32 v146, s23, v206
	ds_read_b128 v[128:131], v146
	ds_read_b128 v[132:135], v146 offset:1024
	ds_read_b128 v[136:139], v146 offset:2048
	ds_read_b128 v[146:149], v146 offset:3072
	s_cmp_eq_u32 s12, 12
	s_cselect_b32 s69, s47, s19
	s_cselect_b32 s68, s46, s6
	s_cselect_b32 s59, s49, s11
	s_cselect_b32 s58, s48, s10
	v_lshl_add_u64 v[192:193], s[54:55], 0, v[158:159]
	s_add_i32 m0, s72, 0xc000
	ds_read_b128 v[162:165], v208
	ds_read_b128 v[166:169], v208 offset:1024
	ds_read_b128 v[170:173], v208 offset:2048
	ds_read_b128 v[174:177], v208 offset:3072
	ds_read_b128 v[178:181], v208 offset:4096
	ds_read_b128 v[182:185], v208 offset:5120
	ds_read_b128 v[194:197], v208 offset:6144
	ds_read_b128 v[210:213], v208 offset:7168
	global_load_lds_dwordx4 v[192:193], off
	v_lshl_add_u64 v[192:193], s[54:55], 0, v[160:161]
	s_add_i32 m0, s72, 0xe000
	s_nop 0
	global_load_lds_dwordx4 v[192:193], off
	s_add_i32 s6, 0, 0x14000
	v_add_u32_e32 v192, s6, v206
	ds_read_b128 v[214:217], v192
	ds_read_b128 v[218:221], v192 offset:1024
	ds_read_b128 v[222:225], v192 offset:2048
	ds_read_b128 v[226:229], v192 offset:3072
	s_waitcnt vmcnt(40)
	s_cmp_lg_u32 s100, 0
	s_cbranch_scc1 .Lm4ap_103
	s_waitcnt vmcnt(8)
.Lm4ap_103:
	s_waitcnt lgkmcnt(0)
	s_barrier
	s_setprio 1
	v_mfma_f32_16x16x32_bf16 v[124:127], v[128:131], v[162:165], 0
	v_mfma_f32_16x16x32_bf16 v[120:123], v[136:139], v[162:165], 0
	v_mfma_f32_16x16x32_bf16 v[108:111], v[128:131], v[170:173], 0
	v_mfma_f32_16x16x32_bf16 v[104:107], v[136:139], v[170:173], 0
	v_mfma_f32_16x16x32_bf16 v[96:99], v[128:131], v[178:181], 0
	v_mfma_f32_16x16x32_bf16 v[88:91], v[136:139], v[178:181], 0
	v_mfma_f32_16x16x32_bf16 v[84:87], v[128:131], v[194:197], 0
	v_mfma_f32_16x16x32_bf16 v[80:83], v[136:139], v[194:197], 0
	v_mfma_f32_16x16x32_bf16 v[124:127], v[132:135], v[166:169], v[124:127]
	v_mfma_f32_16x16x32_bf16 v[120:123], v[146:149], v[166:169], v[120:123]
	v_mfma_f32_16x16x32_bf16 v[108:111], v[132:135], v[174:177], v[108:111]
	v_mfma_f32_16x16x32_bf16 v[104:107], v[146:149], v[174:177], v[104:107]
	v_mfma_f32_16x16x32_bf16 v[96:99], v[132:135], v[182:185], v[96:99]
	v_mfma_f32_16x16x32_bf16 v[88:91], v[146:149], v[182:185], v[88:91]
	v_mfma_f32_16x16x32_bf16 v[84:87], v[132:135], v[210:213], v[84:87]
	v_mfma_f32_16x16x32_bf16 v[80:83], v[146:149], v[210:213], v[80:83]
	v_mfma_f32_16x16x32_bf16 v[116:119], v[214:217], v[162:165], 0
	v_mfma_f32_16x16x32_bf16 v[112:115], v[222:225], v[162:165], 0
	v_mfma_f32_16x16x32_bf16 v[100:103], v[214:217], v[170:173], 0
	v_mfma_f32_16x16x32_bf16 v[92:95], v[222:225], v[170:173], 0
	v_mfma_f32_16x16x32_bf16 v[76:79], v[214:217], v[178:181], 0
	v_mfma_f32_16x16x32_bf16 v[72:75], v[222:225], v[178:181], 0
	v_mfma_f32_16x16x32_bf16 v[68:71], v[214:217], v[194:197], 0
	v_mfma_f32_16x16x32_bf16 v[64:67], v[222:225], v[194:197], 0
	v_mfma_f32_16x16x32_bf16 v[116:119], v[218:221], v[166:169], v[116:119]
	v_mfma_f32_16x16x32_bf16 v[112:115], v[226:229], v[166:169], v[112:115]
	v_mfma_f32_16x16x32_bf16 v[100:103], v[218:221], v[174:177], v[100:103]
	v_mfma_f32_16x16x32_bf16 v[92:95], v[226:229], v[174:177], v[92:95]
	v_mfma_f32_16x16x32_bf16 v[76:79], v[218:221], v[182:185], v[76:79]
	v_mfma_f32_16x16x32_bf16 v[72:75], v[226:229], v[182:185], v[72:75]
	v_mfma_f32_16x16x32_bf16 v[68:71], v[218:221], v[210:213], v[68:71]
	v_mfma_f32_16x16x32_bf16 v[64:67], v[226:229], v[210:213], v[64:67]
	s_setprio 0
	s_barrier
	s_add_i32 s19, s23, s71
	v_lshl_add_u64 v[192:193], s[58:59], 0, v[140:141]
	s_mov_b32 m0, s19
	v_lshl_add_u64 v[230:231], s[58:59], 0, v[150:151]
	global_load_lds_dwordx4 v[192:193], off
	s_add_i32 m0, s19, 0x2000
	s_nop 0
	global_load_lds_dwordx4 v[230:231], off
	s_mov_b32 m0, s72
	v_lshl_add_u64 v[232:233], s[68:69], 0, v[154:155]
	ds_read_b128 v[162:165], v208 offset:16384
	ds_read_b128 v[166:169], v208 offset:17408
	ds_read_b128 v[170:173], v208 offset:18432
	ds_read_b128 v[174:177], v208 offset:19456
	ds_read_b128 v[178:181], v208 offset:20480
	ds_read_b128 v[182:185], v208 offset:21504
	ds_read_b128 v[194:197], v208 offset:22528
	ds_read_b128 v[210:213], v208 offset:23552
	global_load_lds_dwordx4 v[232:233], off
	v_lshl_add_u64 v[234:235], s[68:69], 0, v[152:153]
	s_mov_b32 m0, s73
	s_nop 0
	global_load_lds_dwordx4 v[234:235], off
	s_add_u32 s86, s58, 0x40000
	s_addc_u32 s87, s59, 0
	s_add_i32 s6, s6, s71
	v_lshl_add_u64 v[250:251], s[86:87], 0, v[140:141]
	s_mov_b32 m0, s6
	s_nop 0
	global_load_lds_dwordx4 v[250:251], off
	v_lshl_add_u64 v[250:251], s[86:87], 0, v[150:151]
	s_add_i32 m0, s6, 0x2000
	s_nop 0
	global_load_lds_dwordx4 v[250:251], off
	s_waitcnt vmcnt(40)
	s_cmp_lg_u32 s100, 0
	s_cbranch_scc1 .Lm4bp_103
	s_waitcnt vmcnt(8)
.Lm4bp_103:
	s_waitcnt lgkmcnt(0)
	s_mov_b32 s100, 0
	s_barrier
	s_setprio 1
	v_mfma_f32_16x16x32_bf16 v[60:63], v[128:131], v[162:165], 0
	v_mfma_f32_16x16x32_bf16 v[56:59], v[136:139], v[162:165], 0
	v_mfma_f32_16x16x32_bf16 v[48:51], v[128:131], v[170:173], 0
	v_mfma_f32_16x16x32_bf16 v[40:43], v[136:139], v[170:173], 0
	v_mfma_f32_16x16x32_bf16 v[32:35], v[128:131], v[178:181], 0
	v_mfma_f32_16x16x32_bf16 v[24:27], v[136:139], v[178:181], 0
	v_mfma_f32_16x16x32_bf16 v[16:19], v[128:131], v[194:197], 0
	v_mfma_f32_16x16x32_bf16 v[8:11], v[136:139], v[194:197], 0
	v_mfma_f32_16x16x32_bf16 v[60:63], v[132:135], v[166:169], v[60:63]
	v_mfma_f32_16x16x32_bf16 v[56:59], v[146:149], v[166:169], v[56:59]
	v_mfma_f32_16x16x32_bf16 v[48:51], v[132:135], v[174:177], v[48:51]
	v_mfma_f32_16x16x32_bf16 v[40:43], v[146:149], v[174:177], v[40:43]
	v_mfma_f32_16x16x32_bf16 v[32:35], v[132:135], v[182:185], v[32:35]
	v_mfma_f32_16x16x32_bf16 v[24:27], v[146:149], v[182:185], v[24:27]
	v_mfma_f32_16x16x32_bf16 v[16:19], v[132:135], v[210:213], v[16:19]
	v_mfma_f32_16x16x32_bf16 v[8:11], v[146:149], v[210:213], v[8:11]
	v_mfma_f32_16x16x32_bf16 v[52:55], v[214:217], v[162:165], 0
	v_mfma_f32_16x16x32_bf16 v[44:47], v[222:225], v[162:165], 0
	v_mfma_f32_16x16x32_bf16 v[36:39], v[214:217], v[170:173], 0
	v_mfma_f32_16x16x32_bf16 v[28:31], v[222:225], v[170:173], 0
	v_mfma_f32_16x16x32_bf16 v[20:23], v[214:217], v[178:181], 0
	v_mfma_f32_16x16x32_bf16 v[12:15], v[222:225], v[178:181], 0
	v_mfma_f32_16x16x32_bf16 v[4:7], v[214:217], v[194:197], 0
	v_mfma_f32_16x16x32_bf16 v[0:3], v[222:225], v[194:197], 0
	v_mfma_f32_16x16x32_bf16 v[52:55], v[218:221], v[166:169], v[52:55]
	v_mfma_f32_16x16x32_bf16 v[44:47], v[226:229], v[166:169], v[44:47]
	v_mfma_f32_16x16x32_bf16 v[36:39], v[218:221], v[174:177], v[36:39]
	v_mfma_f32_16x16x32_bf16 v[28:31], v[226:229], v[174:177], v[28:31]
	v_mfma_f32_16x16x32_bf16 v[20:23], v[218:221], v[182:185], v[20:23]
	v_mfma_f32_16x16x32_bf16 v[12:15], v[226:229], v[182:185], v[12:15]
	v_mfma_f32_16x16x32_bf16 v[4:7], v[218:221], v[210:213], v[4:7]
	v_mfma_f32_16x16x32_bf16 v[0:3], v[226:229], v[210:213], v[0:3]
	s_setprio 0
	s_barrier
	s_add_i32 s6, 0, 0x18000
	v_add_u32_e32 v146, s6, v206
	ds_read_b128 v[128:131], v146
	ds_read_b128 v[132:135], v146 offset:1024
	ds_read_b128 v[136:139], v146 offset:2048
	ds_read_b128 v[146:149], v146 offset:3072
	s_add_u32 s68, s68, 0x40000
	s_addc_u32 s69, s69, 0
	s_mov_b32 m0, s74
	v_lshl_add_u64 v[214:215], s[68:69], 0, v[154:155]
	ds_read_b128 v[162:165], v208 offset:32768
	ds_read_b128 v[166:169], v208 offset:33792
	ds_read_b128 v[170:173], v208 offset:34816
	ds_read_b128 v[174:177], v208 offset:35840
	ds_read_b128 v[178:181], v208 offset:36864
	ds_read_b128 v[182:185], v208 offset:37888
	ds_read_b128 v[194:197], v208 offset:38912
	ds_read_b128 v[210:213], v208 offset:39936
	global_load_lds_dwordx4 v[214:215], off
	v_lshl_add_u64 v[214:215], s[68:69], 0, v[152:153]
	s_mov_b32 m0, s75
	s_nop 0
	global_load_lds_dwordx4 v[214:215], off
	s_add_i32 s19, 0, 0x1c000
	v_add_u32_e32 v209, s19, v206
	ds_read_b128 v[214:217], v209
	ds_read_b128 v[218:221], v209 offset:1024
	ds_read_b128 v[222:225], v209 offset:2048
	ds_read_b128 v[226:229], v209 offset:3072
	s_waitcnt vmcnt(8)
	s_waitcnt lgkmcnt(0)
	s_barrier
	s_setprio 1
	v_mfma_f32_16x16x32_bf16 v[124:127], v[128:131], v[162:165], v[124:127]
	v_mfma_f32_16x16x32_bf16 v[120:123], v[136:139], v[162:165], v[120:123]
	v_mfma_f32_16x16x32_bf16 v[108:111], v[128:131], v[170:173], v[108:111]
	v_mfma_f32_16x16x32_bf16 v[104:107], v[136:139], v[170:173], v[104:107]
	v_mfma_f32_16x16x32_bf16 v[96:99], v[128:131], v[178:181], v[96:99]
	v_mfma_f32_16x16x32_bf16 v[88:91], v[136:139], v[178:181], v[88:91]
	v_mfma_f32_16x16x32_bf16 v[84:87], v[128:131], v[194:197], v[84:87]
	v_mfma_f32_16x16x32_bf16 v[80:83], v[136:139], v[194:197], v[80:83]
	v_mfma_f32_16x16x32_bf16 v[124:127], v[132:135], v[166:169], v[124:127]
	v_mfma_f32_16x16x32_bf16 v[120:123], v[146:149], v[166:169], v[120:123]
	v_mfma_f32_16x16x32_bf16 v[108:111], v[132:135], v[174:177], v[108:111]
	v_mfma_f32_16x16x32_bf16 v[104:107], v[146:149], v[174:177], v[104:107]
	v_mfma_f32_16x16x32_bf16 v[96:99], v[132:135], v[182:185], v[96:99]
	v_mfma_f32_16x16x32_bf16 v[88:91], v[146:149], v[182:185], v[88:91]
	v_mfma_f32_16x16x32_bf16 v[84:87], v[132:135], v[210:213], v[84:87]
	v_mfma_f32_16x16x32_bf16 v[80:83], v[146:149], v[210:213], v[80:83]
	v_mfma_f32_16x16x32_bf16 v[116:119], v[214:217], v[162:165], v[116:119]
	v_mfma_f32_16x16x32_bf16 v[112:115], v[222:225], v[162:165], v[112:115]
	v_mfma_f32_16x16x32_bf16 v[100:103], v[214:217], v[170:173], v[100:103]
	v_mfma_f32_16x16x32_bf16 v[92:95], v[222:225], v[170:173], v[92:95]
	v_mfma_f32_16x16x32_bf16 v[76:79], v[214:217], v[178:181], v[76:79]
	v_mfma_f32_16x16x32_bf16 v[72:75], v[222:225], v[178:181], v[72:75]
	v_mfma_f32_16x16x32_bf16 v[68:71], v[214:217], v[194:197], v[68:71]
	v_mfma_f32_16x16x32_bf16 v[64:67], v[222:225], v[194:197], v[64:67]
	v_mfma_f32_16x16x32_bf16 v[116:119], v[218:221], v[166:169], v[116:119]
	v_mfma_f32_16x16x32_bf16 v[112:115], v[226:229], v[166:169], v[112:115]
	v_mfma_f32_16x16x32_bf16 v[100:103], v[218:221], v[174:177], v[100:103]
	v_mfma_f32_16x16x32_bf16 v[92:95], v[226:229], v[174:177], v[92:95]
	v_mfma_f32_16x16x32_bf16 v[76:79], v[218:221], v[182:185], v[76:79]
	v_mfma_f32_16x16x32_bf16 v[72:75], v[226:229], v[182:185], v[72:75]
	v_mfma_f32_16x16x32_bf16 v[68:71], v[218:221], v[210:213], v[68:71]
	v_mfma_f32_16x16x32_bf16 v[64:67], v[226:229], v[210:213], v[64:67]
	s_setprio 0
	s_barrier
	s_add_i32 s6, s6, s71
	v_lshl_add_u64 v[192:193], v[192:193], 0, s[36:37]
	s_mov_b32 m0, s6
	s_nop 0
	global_load_lds_dwordx4 v[192:193], off
	v_lshl_add_u64 v[192:193], v[230:231], 0, s[36:37]
	s_add_i32 m0, s6, 0x2000
	s_nop 0
	global_load_lds_dwordx4 v[192:193], off
	s_mov_b32 m0, s80
	v_lshl_add_u64 v[192:193], v[232:233], 0, s[36:37]
	ds_read_b128 v[162:165], v208 offset:49152
	ds_read_b128 v[166:169], v208 offset:50176
	ds_read_b128 v[170:173], v208 offset:51200
	ds_read_b128 v[174:177], v208 offset:52224
	ds_read_b128 v[178:181], v208 offset:53248
	ds_read_b128 v[182:185], v208 offset:54272
	ds_read_b128 v[194:197], v208 offset:55296
	ds_read_b128 v[210:213], v208 offset:56320
	global_load_lds_dwordx4 v[192:193], off
	v_lshl_add_u64 v[192:193], v[234:235], 0, s[36:37]
	s_mov_b32 m0, s81
	s_nop 0
	global_load_lds_dwordx4 v[192:193], off
	s_add_u32 s58, s58, 0x40080
	s_addc_u32 s59, s59, 0
	s_add_i32 s6, s19, s71
	v_lshl_add_u64 v[250:251], s[58:59], 0, v[140:141]
	s_mov_b32 m0, s6
	s_nop 0
	global_load_lds_dwordx4 v[250:251], off
	v_lshl_add_u64 v[250:251], s[58:59], 0, v[150:151]
	s_add_i32 m0, s6, 0x2000
	s_nop 0
	global_load_lds_dwordx4 v[250:251], off
	s_waitcnt vmcnt(8)
	s_waitcnt lgkmcnt(0)
	s_barrier
	s_setprio 1
	v_mfma_f32_16x16x32_bf16 v[60:63], v[128:131], v[162:165], v[60:63]
	v_mfma_f32_16x16x32_bf16 v[56:59], v[136:139], v[162:165], v[56:59]
	v_mfma_f32_16x16x32_bf16 v[48:51], v[128:131], v[170:173], v[48:51]
	v_mfma_f32_16x16x32_bf16 v[40:43], v[136:139], v[170:173], v[40:43]
	v_mfma_f32_16x16x32_bf16 v[32:35], v[128:131], v[178:181], v[32:35]
	v_mfma_f32_16x16x32_bf16 v[24:27], v[136:139], v[178:181], v[24:27]
	v_mfma_f32_16x16x32_bf16 v[16:19], v[128:131], v[194:197], v[16:19]
	v_mfma_f32_16x16x32_bf16 v[8:11], v[136:139], v[194:197], v[8:11]
	v_mfma_f32_16x16x32_bf16 v[60:63], v[132:135], v[166:169], v[60:63]
	v_mfma_f32_16x16x32_bf16 v[56:59], v[146:149], v[166:169], v[56:59]
	v_mfma_f32_16x16x32_bf16 v[48:51], v[132:135], v[174:177], v[48:51]
	v_mfma_f32_16x16x32_bf16 v[40:43], v[146:149], v[174:177], v[40:43]
	v_mfma_f32_16x16x32_bf16 v[32:35], v[132:135], v[182:185], v[32:35]
	v_mfma_f32_16x16x32_bf16 v[24:27], v[146:149], v[182:185], v[24:27]
	v_mfma_f32_16x16x32_bf16 v[16:19], v[132:135], v[210:213], v[16:19]
	v_mfma_f32_16x16x32_bf16 v[8:11], v[146:149], v[210:213], v[8:11]
	v_mfma_f32_16x16x32_bf16 v[52:55], v[214:217], v[162:165], v[52:55]
	v_mfma_f32_16x16x32_bf16 v[44:47], v[222:225], v[162:165], v[44:47]
	v_mfma_f32_16x16x32_bf16 v[36:39], v[214:217], v[170:173], v[36:39]
	v_mfma_f32_16x16x32_bf16 v[28:31], v[222:225], v[170:173], v[28:31]
	v_mfma_f32_16x16x32_bf16 v[20:23], v[214:217], v[178:181], v[20:23]
	v_mfma_f32_16x16x32_bf16 v[12:15], v[222:225], v[178:181], v[12:15]
	v_mfma_f32_16x16x32_bf16 v[4:7], v[214:217], v[194:197], v[4:7]
	v_mfma_f32_16x16x32_bf16 v[0:3], v[222:225], v[194:197], v[0:3]
	v_mfma_f32_16x16x32_bf16 v[52:55], v[218:221], v[166:169], v[52:55]
	v_mfma_f32_16x16x32_bf16 v[44:47], v[226:229], v[166:169], v[44:47]
	v_mfma_f32_16x16x32_bf16 v[36:39], v[218:221], v[174:177], v[36:39]
	v_mfma_f32_16x16x32_bf16 v[28:31], v[226:229], v[174:177], v[28:31]
	v_mfma_f32_16x16x32_bf16 v[20:23], v[218:221], v[182:185], v[20:23]
	v_mfma_f32_16x16x32_bf16 v[12:15], v[226:229], v[182:185], v[12:15]
	v_mfma_f32_16x16x32_bf16 v[4:7], v[218:221], v[210:213], v[4:7]
	v_mfma_f32_16x16x32_bf16 v[0:3], v[226:229], v[210:213], v[0:3]
	s_setprio 0
	s_add_i32 s12, s12, 2
	s_add_u32 s54, s54, 0x100
	s_addc_u32 s55, s55, 0
	s_add_u32 s10, s10, 0x100
	s_addc_u32 s11, s11, 0
	s_cmp_gt_u32 s12, 13
	s_barrier
.LBB0_103:
	s_add_u32 s6, s54, 0xfffc0080
	s_addc_u32 s19, s55, -1
	s_add_i32 s23, 0, 0x10000
	v_add_u32_e32 v146, s23, v206
	ds_read_b128 v[128:131], v146
	ds_read_b128 v[132:135], v146 offset:1024
	ds_read_b128 v[136:139], v146 offset:2048
	ds_read_b128 v[146:149], v146 offset:3072
	s_cmp_eq_u32 s12, 12
	s_cselect_b32 s69, s47, s19
	s_cselect_b32 s68, s46, s6
	s_cselect_b32 s59, s49, s11
	s_cselect_b32 s58, s48, s10
	v_lshl_add_u64 v[192:193], s[54:55], 0, v[158:159]
	s_add_i32 m0, s72, 0xc000
	ds_read_b128 v[162:165], v208
	ds_read_b128 v[166:169], v208 offset:1024
	ds_read_b128 v[170:173], v208 offset:2048
	ds_read_b128 v[174:177], v208 offset:3072
	ds_read_b128 v[178:181], v208 offset:4096
	ds_read_b128 v[182:185], v208 offset:5120
	ds_read_b128 v[194:197], v208 offset:6144
	ds_read_b128 v[210:213], v208 offset:7168
	global_load_lds_dwordx4 v[192:193], off
	v_lshl_add_u64 v[192:193], s[54:55], 0, v[160:161]
	s_add_i32 m0, s72, 0xe000
	s_nop 0
	global_load_lds_dwordx4 v[192:193], off
	s_add_i32 s6, 0, 0x14000
	v_add_u32_e32 v192, s6, v206
	ds_read_b128 v[214:217], v192
	ds_read_b128 v[218:221], v192 offset:1024
	ds_read_b128 v[222:225], v192 offset:2048
	ds_read_b128 v[226:229], v192 offset:3072
	s_waitcnt vmcnt(8)
	s_waitcnt lgkmcnt(0)
	s_barrier
	s_setprio 1
	v_mfma_f32_16x16x32_bf16 v[124:127], v[128:131], v[162:165], v[124:127]
	v_mfma_f32_16x16x32_bf16 v[120:123], v[136:139], v[162:165], v[120:123]
	v_mfma_f32_16x16x32_bf16 v[108:111], v[128:131], v[170:173], v[108:111]
	v_mfma_f32_16x16x32_bf16 v[104:107], v[136:139], v[170:173], v[104:107]
	v_mfma_f32_16x16x32_bf16 v[96:99], v[128:131], v[178:181], v[96:99]
	v_mfma_f32_16x16x32_bf16 v[88:91], v[136:139], v[178:181], v[88:91]
	v_mfma_f32_16x16x32_bf16 v[84:87], v[128:131], v[194:197], v[84:87]
	v_mfma_f32_16x16x32_bf16 v[80:83], v[136:139], v[194:197], v[80:83]
	v_mfma_f32_16x16x32_bf16 v[124:127], v[132:135], v[166:169], v[124:127]
	v_mfma_f32_16x16x32_bf16 v[120:123], v[146:149], v[166:169], v[120:123]
	v_mfma_f32_16x16x32_bf16 v[108:111], v[132:135], v[174:177], v[108:111]
	v_mfma_f32_16x16x32_bf16 v[104:107], v[146:149], v[174:177], v[104:107]
	v_mfma_f32_16x16x32_bf16 v[96:99], v[132:135], v[182:185], v[96:99]
	v_mfma_f32_16x16x32_bf16 v[88:91], v[146:149], v[182:185], v[88:91]
	v_mfma_f32_16x16x32_bf16 v[84:87], v[132:135], v[210:213], v[84:87]
	v_mfma_f32_16x16x32_bf16 v[80:83], v[146:149], v[210:213], v[80:83]
	v_mfma_f32_16x16x32_bf16 v[116:119], v[214:217], v[162:165], v[116:119]
	v_mfma_f32_16x16x32_bf16 v[112:115], v[222:225], v[162:165], v[112:115]
	v_mfma_f32_16x16x32_bf16 v[100:103], v[214:217], v[170:173], v[100:103]
	v_mfma_f32_16x16x32_bf16 v[92:95], v[222:225], v[170:173], v[92:95]
	v_mfma_f32_16x16x32_bf16 v[76:79], v[214:217], v[178:181], v[76:79]
	v_mfma_f32_16x16x32_bf16 v[72:75], v[222:225], v[178:181], v[72:75]
	v_mfma_f32_16x16x32_bf16 v[68:71], v[214:217], v[194:197], v[68:71]
	v_mfma_f32_16x16x32_bf16 v[64:67], v[222:225], v[194:197], v[64:67]
	v_mfma_f32_16x16x32_bf16 v[116:119], v[218:221], v[166:169], v[116:119]
	v_mfma_f32_16x16x32_bf16 v[112:115], v[226:229], v[166:169], v[112:115]
	v_mfma_f32_16x16x32_bf16 v[100:103], v[218:221], v[174:177], v[100:103]
	v_mfma_f32_16x16x32_bf16 v[92:95], v[226:229], v[174:177], v[92:95]
	v_mfma_f32_16x16x32_bf16 v[76:79], v[218:221], v[182:185], v[76:79]
	v_mfma_f32_16x16x32_bf16 v[72:75], v[226:229], v[182:185], v[72:75]
	v_mfma_f32_16x16x32_bf16 v[68:71], v[218:221], v[210:213], v[68:71]
	v_mfma_f32_16x16x32_bf16 v[64:67], v[226:229], v[210:213], v[64:67]
	s_setprio 0
	s_barrier
	s_add_i32 s19, s23, s71
	v_lshl_add_u64 v[192:193], s[58:59], 0, v[140:141]
	s_mov_b32 m0, s19
	v_lshl_add_u64 v[230:231], s[58:59], 0, v[150:151]
	global_load_lds_dwordx4 v[192:193], off
	s_add_i32 m0, s19, 0x2000
	s_nop 0
	global_load_lds_dwordx4 v[230:231], off
	s_mov_b32 m0, s72
	v_lshl_add_u64 v[232:233], s[68:69], 0, v[154:155]
	ds_read_b128 v[162:165], v208 offset:16384
	ds_read_b128 v[166:169], v208 offset:17408
	ds_read_b128 v[170:173], v208 offset:18432
	ds_read_b128 v[174:177], v208 offset:19456
	ds_read_b128 v[178:181], v208 offset:20480
	ds_read_b128 v[182:185], v208 offset:21504
	ds_read_b128 v[194:197], v208 offset:22528
	ds_read_b128 v[210:213], v208 offset:23552
	global_load_lds_dwordx4 v[232:233], off
	v_lshl_add_u64 v[234:235], s[68:69], 0, v[152:153]
	s_mov_b32 m0, s73
	s_nop 0
	global_load_lds_dwordx4 v[234:235], off
	s_add_u32 s86, s58, 0x40000
	s_addc_u32 s87, s59, 0
	s_add_i32 s6, s6, s71
	v_lshl_add_u64 v[250:251], s[86:87], 0, v[140:141]
	s_mov_b32 m0, s6
	s_nop 0
	global_load_lds_dwordx4 v[250:251], off
	v_lshl_add_u64 v[250:251], s[86:87], 0, v[150:151]
	s_add_i32 m0, s6, 0x2000
	s_nop 0
	global_load_lds_dwordx4 v[250:251], off
	s_waitcnt vmcnt(8)
	s_waitcnt lgkmcnt(0)
	s_barrier
	s_setprio 1
	v_mfma_f32_16x16x32_bf16 v[60:63], v[128:131], v[162:165], v[60:63]
	v_mfma_f32_16x16x32_bf16 v[56:59], v[136:139], v[162:165], v[56:59]
	v_mfma_f32_16x16x32_bf16 v[48:51], v[128:131], v[170:173], v[48:51]
	v_mfma_f32_16x16x32_bf16 v[40:43], v[136:139], v[170:173], v[40:43]
	v_mfma_f32_16x16x32_bf16 v[32:35], v[128:131], v[178:181], v[32:35]
	v_mfma_f32_16x16x32_bf16 v[24:27], v[136:139], v[178:181], v[24:27]
	v_mfma_f32_16x16x32_bf16 v[16:19], v[128:131], v[194:197], v[16:19]
	v_mfma_f32_16x16x32_bf16 v[8:11], v[136:139], v[194:197], v[8:11]
	v_mfma_f32_16x16x32_bf16 v[60:63], v[132:135], v[166:169], v[60:63]
	v_mfma_f32_16x16x32_bf16 v[56:59], v[146:149], v[166:169], v[56:59]
	v_mfma_f32_16x16x32_bf16 v[48:51], v[132:135], v[174:177], v[48:51]
	v_mfma_f32_16x16x32_bf16 v[40:43], v[146:149], v[174:177], v[40:43]
	v_mfma_f32_16x16x32_bf16 v[32:35], v[132:135], v[182:185], v[32:35]
	v_mfma_f32_16x16x32_bf16 v[24:27], v[146:149], v[182:185], v[24:27]
	v_mfma_f32_16x16x32_bf16 v[16:19], v[132:135], v[210:213], v[16:19]
	v_mfma_f32_16x16x32_bf16 v[8:11], v[146:149], v[210:213], v[8:11]
	v_mfma_f32_16x16x32_bf16 v[52:55], v[214:217], v[162:165], v[52:55]
	v_mfma_f32_16x16x32_bf16 v[44:47], v[222:225], v[162:165], v[44:47]
	v_mfma_f32_16x16x32_bf16 v[36:39], v[214:217], v[170:173], v[36:39]
	v_mfma_f32_16x16x32_bf16 v[28:31], v[222:225], v[170:173], v[28:31]
	v_mfma_f32_16x16x32_bf16 v[20:23], v[214:217], v[178:181], v[20:23]
	v_mfma_f32_16x16x32_bf16 v[12:15], v[222:225], v[178:181], v[12:15]
	v_mfma_f32_16x16x32_bf16 v[4:7], v[214:217], v[194:197], v[4:7]
	v_mfma_f32_16x16x32_bf16 v[0:3], v[222:225], v[194:197], v[0:3]
	v_mfma_f32_16x16x32_bf16 v[52:55], v[218:221], v[166:169], v[52:55]
	v_mfma_f32_16x16x32_bf16 v[44:47], v[226:229], v[166:169], v[44:47]
	v_mfma_f32_16x16x32_bf16 v[36:39], v[218:221], v[174:177], v[36:39]
	v_mfma_f32_16x16x32_bf16 v[28:31], v[226:229], v[174:177], v[28:31]
	v_mfma_f32_16x16x32_bf16 v[20:23], v[218:221], v[182:185], v[20:23]
	v_mfma_f32_16x16x32_bf16 v[12:15], v[226:229], v[182:185], v[12:15]
	v_mfma_f32_16x16x32_bf16 v[4:7], v[218:221], v[210:213], v[4:7]
	v_mfma_f32_16x16x32_bf16 v[0:3], v[226:229], v[210:213], v[0:3]
	s_setprio 0
	s_barrier
	s_add_i32 s6, 0, 0x18000
	v_add_u32_e32 v146, s6, v206
	ds_read_b128 v[128:131], v146
	ds_read_b128 v[132:135], v146 offset:1024
	ds_read_b128 v[136:139], v146 offset:2048
	ds_read_b128 v[146:149], v146 offset:3072
	s_add_u32 s68, s68, 0x40000
	s_addc_u32 s69, s69, 0
	s_mov_b32 m0, s74
	v_lshl_add_u64 v[214:215], s[68:69], 0, v[154:155]
	ds_read_b128 v[162:165], v208 offset:32768
	ds_read_b128 v[166:169], v208 offset:33792
	ds_read_b128 v[170:173], v208 offset:34816
	ds_read_b128 v[174:177], v208 offset:35840
	ds_read_b128 v[178:181], v208 offset:36864
	ds_read_b128 v[182:185], v208 offset:37888
	ds_read_b128 v[194:197], v208 offset:38912
	ds_read_b128 v[210:213], v208 offset:39936
	global_load_lds_dwordx4 v[214:215], off
	v_lshl_add_u64 v[214:215], s[68:69], 0, v[152:153]
	s_mov_b32 m0, s75
	s_nop 0
	global_load_lds_dwordx4 v[214:215], off
	s_add_i32 s19, 0, 0x1c000
	v_add_u32_e32 v209, s19, v206
	ds_read_b128 v[214:217], v209
	ds_read_b128 v[218:221], v209 offset:1024
	ds_read_b128 v[222:225], v209 offset:2048
	ds_read_b128 v[226:229], v209 offset:3072
	s_waitcnt vmcnt(8)
	s_waitcnt lgkmcnt(0)
	s_barrier
	s_setprio 1
	v_mfma_f32_16x16x32_bf16 v[124:127], v[128:131], v[162:165], v[124:127]
	v_mfma_f32_16x16x32_bf16 v[120:123], v[136:139], v[162:165], v[120:123]
	v_mfma_f32_16x16x32_bf16 v[108:111], v[128:131], v[170:173], v[108:111]
	v_mfma_f32_16x16x32_bf16 v[104:107], v[136:139], v[170:173], v[104:107]
	v_mfma_f32_16x16x32_bf16 v[96:99], v[128:131], v[178:181], v[96:99]
	v_mfma_f32_16x16x32_bf16 v[88:91], v[136:139], v[178:181], v[88:91]
	v_mfma_f32_16x16x32_bf16 v[84:87], v[128:131], v[194:197], v[84:87]
	v_mfma_f32_16x16x32_bf16 v[80:83], v[136:139], v[194:197], v[80:83]
	v_mfma_f32_16x16x32_bf16 v[124:127], v[132:135], v[166:169], v[124:127]
	v_mfma_f32_16x16x32_bf16 v[120:123], v[146:149], v[166:169], v[120:123]
	v_mfma_f32_16x16x32_bf16 v[108:111], v[132:135], v[174:177], v[108:111]
	v_mfma_f32_16x16x32_bf16 v[104:107], v[146:149], v[174:177], v[104:107]
	v_mfma_f32_16x16x32_bf16 v[96:99], v[132:135], v[182:185], v[96:99]
	v_mfma_f32_16x16x32_bf16 v[88:91], v[146:149], v[182:185], v[88:91]
	v_mfma_f32_16x16x32_bf16 v[84:87], v[132:135], v[210:213], v[84:87]
	v_mfma_f32_16x16x32_bf16 v[80:83], v[146:149], v[210:213], v[80:83]
	v_mfma_f32_16x16x32_bf16 v[116:119], v[214:217], v[162:165], v[116:119]
	v_mfma_f32_16x16x32_bf16 v[112:115], v[222:225], v[162:165], v[112:115]
	v_mfma_f32_16x16x32_bf16 v[100:103], v[214:217], v[170:173], v[100:103]
	v_mfma_f32_16x16x32_bf16 v[92:95], v[222:225], v[170:173], v[92:95]
	v_mfma_f32_16x16x32_bf16 v[76:79], v[214:217], v[178:181], v[76:79]
	v_mfma_f32_16x16x32_bf16 v[72:75], v[222:225], v[178:181], v[72:75]
	v_mfma_f32_16x16x32_bf16 v[68:71], v[214:217], v[194:197], v[68:71]
	v_mfma_f32_16x16x32_bf16 v[64:67], v[222:225], v[194:197], v[64:67]
	v_mfma_f32_16x16x32_bf16 v[116:119], v[218:221], v[166:169], v[116:119]
	v_mfma_f32_16x16x32_bf16 v[112:115], v[226:229], v[166:169], v[112:115]
	v_mfma_f32_16x16x32_bf16 v[100:103], v[218:221], v[174:177], v[100:103]
	v_mfma_f32_16x16x32_bf16 v[92:95], v[226:229], v[174:177], v[92:95]
	v_mfma_f32_16x16x32_bf16 v[76:79], v[218:221], v[182:185], v[76:79]
	v_mfma_f32_16x16x32_bf16 v[72:75], v[226:229], v[182:185], v[72:75]
	v_mfma_f32_16x16x32_bf16 v[68:71], v[218:221], v[210:213], v[68:71]
	v_mfma_f32_16x16x32_bf16 v[64:67], v[226:229], v[210:213], v[64:67]
	s_setprio 0
	s_barrier
	s_add_i32 s6, s6, s71
	v_lshl_add_u64 v[192:193], v[192:193], 0, s[36:37]
	s_mov_b32 m0, s6
	s_nop 0
	global_load_lds_dwordx4 v[192:193], off
	v_lshl_add_u64 v[192:193], v[230:231], 0, s[36:37]
	s_add_i32 m0, s6, 0x2000
	s_nop 0
	global_load_lds_dwordx4 v[192:193], off
	s_mov_b32 m0, s80
	v_lshl_add_u64 v[192:193], v[232:233], 0, s[36:37]
	ds_read_b128 v[162:165], v208 offset:49152
	ds_read_b128 v[166:169], v208 offset:50176
	ds_read_b128 v[170:173], v208 offset:51200
	ds_read_b128 v[174:177], v208 offset:52224
	ds_read_b128 v[178:181], v208 offset:53248
	ds_read_b128 v[182:185], v208 offset:54272
	ds_read_b128 v[194:197], v208 offset:55296
	ds_read_b128 v[210:213], v208 offset:56320
	global_load_lds_dwordx4 v[192:193], off
	v_lshl_add_u64 v[192:193], v[234:235], 0, s[36:37]
	s_mov_b32 m0, s81
	s_nop 0
	global_load_lds_dwordx4 v[192:193], off
	s_add_u32 s58, s58, 0x40080
	s_addc_u32 s59, s59, 0
	s_add_i32 s6, s19, s71
	v_lshl_add_u64 v[250:251], s[58:59], 0, v[140:141]
	s_mov_b32 m0, s6
	s_nop 0
	global_load_lds_dwordx4 v[250:251], off
	v_lshl_add_u64 v[250:251], s[58:59], 0, v[150:151]
	s_add_i32 m0, s6, 0x2000
	s_nop 0
	global_load_lds_dwordx4 v[250:251], off
	s_waitcnt vmcnt(8)
	s_waitcnt lgkmcnt(0)
	s_barrier
	s_setprio 1
	v_mfma_f32_16x16x32_bf16 v[60:63], v[128:131], v[162:165], v[60:63]
	v_mfma_f32_16x16x32_bf16 v[56:59], v[136:139], v[162:165], v[56:59]
	v_mfma_f32_16x16x32_bf16 v[48:51], v[128:131], v[170:173], v[48:51]
	v_mfma_f32_16x16x32_bf16 v[40:43], v[136:139], v[170:173], v[40:43]
	v_mfma_f32_16x16x32_bf16 v[32:35], v[128:131], v[178:181], v[32:35]
	v_mfma_f32_16x16x32_bf16 v[24:27], v[136:139], v[178:181], v[24:27]
	v_mfma_f32_16x16x32_bf16 v[16:19], v[128:131], v[194:197], v[16:19]
	v_mfma_f32_16x16x32_bf16 v[8:11], v[136:139], v[194:197], v[8:11]
	v_mfma_f32_16x16x32_bf16 v[60:63], v[132:135], v[166:169], v[60:63]
	v_mfma_f32_16x16x32_bf16 v[56:59], v[146:149], v[166:169], v[56:59]
	v_mfma_f32_16x16x32_bf16 v[48:51], v[132:135], v[174:177], v[48:51]
	v_mfma_f32_16x16x32_bf16 v[40:43], v[146:149], v[174:177], v[40:43]
	v_mfma_f32_16x16x32_bf16 v[32:35], v[132:135], v[182:185], v[32:35]
	v_mfma_f32_16x16x32_bf16 v[24:27], v[146:149], v[182:185], v[24:27]
	v_mfma_f32_16x16x32_bf16 v[16:19], v[132:135], v[210:213], v[16:19]
	v_mfma_f32_16x16x32_bf16 v[8:11], v[146:149], v[210:213], v[8:11]
	v_mfma_f32_16x16x32_bf16 v[52:55], v[214:217], v[162:165], v[52:55]
	v_mfma_f32_16x16x32_bf16 v[44:47], v[222:225], v[162:165], v[44:47]
	v_mfma_f32_16x16x32_bf16 v[36:39], v[214:217], v[170:173], v[36:39]
	v_mfma_f32_16x16x32_bf16 v[28:31], v[222:225], v[170:173], v[28:31]
	v_mfma_f32_16x16x32_bf16 v[20:23], v[214:217], v[178:181], v[20:23]
	v_mfma_f32_16x16x32_bf16 v[12:15], v[222:225], v[178:181], v[12:15]
	v_mfma_f32_16x16x32_bf16 v[4:7], v[214:217], v[194:197], v[4:7]
	v_mfma_f32_16x16x32_bf16 v[0:3], v[222:225], v[194:197], v[0:3]
	v_mfma_f32_16x16x32_bf16 v[52:55], v[218:221], v[166:169], v[52:55]
	v_mfma_f32_16x16x32_bf16 v[44:47], v[226:229], v[166:169], v[44:47]
	v_mfma_f32_16x16x32_bf16 v[36:39], v[218:221], v[174:177], v[36:39]
	v_mfma_f32_16x16x32_bf16 v[28:31], v[226:229], v[174:177], v[28:31]
	v_mfma_f32_16x16x32_bf16 v[20:23], v[218:221], v[182:185], v[20:23]
	v_mfma_f32_16x16x32_bf16 v[12:15], v[226:229], v[182:185], v[12:15]
	v_mfma_f32_16x16x32_bf16 v[4:7], v[218:221], v[210:213], v[4:7]
	v_mfma_f32_16x16x32_bf16 v[0:3], v[226:229], v[210:213], v[0:3]
	s_setprio 0
	s_add_i32 s12, s12, 2
	s_add_u32 s54, s54, 0x100
	s_addc_u32 s55, s55, 0
	s_add_u32 s10, s10, 0x100
	s_addc_u32 s11, s11, 0
	s_cmp_gt_u32 s12, 13
	s_barrier
	s_cbranch_scc0 .LBB0_103
	s_mov_b32 s100, 1
	s_ashr_i32 s51, s50, 31
	s_ashr_i32 s53, s52, 31
	s_lshl_b64 s[10:11], s[50:51], 13
	s_lshl_b64 s[50:51], s[52:53], 8
	s_add_u32 s10, s50, s10
	v_lshl_or_b32 v128, s85, 8, v207
	s_addc_u32 s11, s51, s11
	v_ashrrev_i32_e32 v129, 31, v128
	v_lshl_add_u64 v[168:169], s[10:11], 0, v[156:157]
	v_lshlrev_b64 v[170:171], 1, v[128:129]
	v_lshl_add_u64 v[174:175], s[26:27], 0, v[170:171]
	v_lshlrev_b64 v[172:173], 11, v[168:169]
	v_or_b32_e32 v166, 16, v168
	v_mov_b32_e32 v167, v169
	v_lshl_add_u64 v[128:129], v[174:175], 0, v[172:173]
	v_lshlrev_b64 v[176:177], 11, v[166:167]
	global_load_dwordx4 v[146:149], v[128:129], off
	global_load_dwordx4 v[182:185], v[128:129], off offset:256
	v_lshl_add_u64 v[128:129], v[174:175], 0, v[176:177]
	global_load_dwordx4 v[194:197], v[128:129], off
	global_load_dwordx4 v[210:213], v[128:129], off offset:256
	v_or_b32_e32 v164, 32, v168
	v_mov_b32_e32 v165, v169
	v_or_b32_e32 v162, 48, v168
	v_mov_b32_e32 v163, v169
	v_lshlrev_b64 v[180:181], 11, v[164:165]
	v_lshlrev_b64 v[178:179], 11, v[162:163]
	v_lshl_add_u64 v[128:129], v[174:175], 0, v[180:181]
	v_lshl_add_u64 v[130:131], v[174:175], 0, v[178:179]
	global_load_dwordx4 v[214:217], v[128:129], off
	global_load_dwordx4 v[136:139], v[128:129], off offset:256
	global_load_dwordx4 v[132:135], v[130:131], off
	s_nop 0
	global_load_dwordx4 v[128:131], v[130:131], off offset:256
	s_mov_b64 s[10:11], 0x90
	v_lshl_add_u64 v[172:173], s[28:29], 0, v[172:173]
	v_lshl_add_u64 v[172:173], v[172:173], 0, v[170:171]
	s_waitcnt vmcnt(0)
	v_lshlrev_b32_e32 v192, 16, v146
	v_and_b32_e32 v193, 0xffff0000, v146
	v_lshlrev_b32_e32 v218, 16, v148
	v_and_b32_e32 v219, 0xffff0000, v148
	v_lshlrev_b32_e32 v146, 16, v147
	v_and_b32_e32 v147, 0xffff0000, v147
	v_lshlrev_b32_e32 v148, 16, v149
	v_and_b32_e32 v149, 0xffff0000, v149
	v_lshlrev_b32_e32 v220, 16, v182
	v_and_b32_e32 v221, 0xffff0000, v182
	v_lshlrev_b32_e32 v222, 16, v184
	v_and_b32_e32 v223, 0xffff0000, v184
	v_lshlrev_b32_e32 v182, 16, v183
	v_and_b32_e32 v183, 0xffff0000, v183
	v_lshlrev_b32_e32 v184, 16, v185
	v_and_b32_e32 v185, 0xffff0000, v185
	v_pk_add_f32 v[124:125], v[124:125], v[192:193]
	v_pk_add_f32 v[126:127], v[126:127], v[146:147]
	v_pk_add_f32 v[122:123], v[122:123], v[148:149]
	v_pk_add_f32 v[116:117], v[116:117], v[220:221]
	v_pk_add_f32 v[146:147], v[112:113], v[222:223]
	v_pk_add_f32 v[118:119], v[118:119], v[182:183]
	v_pk_add_f32 v[148:149], v[114:115], v[184:185]
	v_lshlrev_b32_e32 v182, 16, v194
	v_and_b32_e32 v183, 0xffff0000, v194
	v_lshlrev_b32_e32 v184, 16, v196
	v_and_b32_e32 v185, 0xffff0000, v196
	v_lshlrev_b32_e32 v192, 16, v195
	v_and_b32_e32 v193, 0xffff0000, v195
	v_lshlrev_b32_e32 v194, 16, v197
	v_and_b32_e32 v195, 0xffff0000, v197
	v_pk_mul_f32 v[196:197], v[124:125], v[124:125]
	v_pk_add_f32 v[120:121], v[120:121], v[218:219]
	v_pk_mul_f32 v[218:219], v[126:127], v[126:127]
	v_cvt_pk_bf16_f32 v112, v124, v125
	v_cvt_pk_bf16_f32 v113, v126, v127
	v_pk_mul_f32 v[124:125], v[116:117], v[116:117]
	v_pk_mul_f32 v[126:127], v[118:119], v[118:119]
	v_pk_mul_f32 v[224:225], v[146:147], v[146:147]
	v_cvt_pk_bf16_f32 v116, v116, v117
	v_cvt_pk_bf16_f32 v117, v118, v119
	v_cvt_pk_bf16_f32 v118, v146, v147
	v_add_f32_e32 v146, v196, v197
	v_add_f32_e32 v146, v218, v146
	v_pk_mul_f32 v[220:221], v[120:121], v[120:121]
	v_add_f32_e32 v146, v219, v146
	v_add_f32_e32 v146, v220, v146
	v_pk_mul_f32 v[222:223], v[122:123], v[122:123]
	v_add_f32_e32 v146, v221, v146
	v_add_f32_e32 v146, v222, v146
	v_add_f32_e32 v146, v223, v146
	v_add_f32_e32 v124, v124, v146
	v_add_f32_e32 v124, v125, v124
	v_add_f32_e32 v124, v126, v124
	v_add_f32_e32 v124, v127, v124
	v_add_f32_e32 v124, v224, v124
	v_pk_mul_f32 v[226:227], v[148:149], v[148:149]
	v_add_f32_e32 v124, v225, v124
	v_add_f32_e32 v124, v226, v124
	v_add_f32_e32 v209, v227, v124
	v_lshlrev_b32_e32 v124, 16, v210
	v_and_b32_e32 v125, 0xffff0000, v210
	v_pk_add_f32 v[100:101], v[100:101], v[124:125]
	v_lshlrev_b32_e32 v124, 16, v212
	v_and_b32_e32 v125, 0xffff0000, v212
	v_pk_add_f32 v[124:125], v[92:93], v[124:125]
	v_lshlrev_b32_e32 v92, 16, v211
	v_and_b32_e32 v93, 0xffff0000, v211
	v_pk_add_f32 v[102:103], v[102:103], v[92:93]
	v_lshlrev_b32_e32 v92, 16, v213
	v_and_b32_e32 v93, 0xffff0000, v213
	v_pk_add_f32 v[126:127], v[94:95], v[92:93]
	v_lshlrev_b32_e32 v92, 16, v214
	v_and_b32_e32 v93, 0xffff0000, v214
	v_pk_add_f32 v[92:93], v[96:97], v[92:93]
	v_lshlrev_b32_e32 v96, 16, v217
	v_and_b32_e32 v97, 0xffff0000, v217
	v_lshlrev_b32_e32 v94, 16, v216
	v_and_b32_e32 v95, 0xffff0000, v216
	v_pk_add_f32 v[90:91], v[90:91], v[96:97]
	v_lshlrev_b32_e32 v96, 16, v136
	v_and_b32_e32 v97, 0xffff0000, v136
	v_pk_add_f32 v[88:89], v[88:89], v[94:95]
	v_lshlrev_b32_e32 v94, 16, v215
	v_and_b32_e32 v95, 0xffff0000, v215
	v_pk_add_f32 v[96:97], v[76:77], v[96:97]
	v_lshl_add_u64 v[76:77], v[168:169], 0, s[36:37]
	v_cvt_pk_bf16_f32 v114, v120, v121
	v_pk_add_f32 v[120:121], v[108:109], v[182:183]
	v_pk_add_f32 v[94:95], v[98:99], v[94:95]
	v_lshlrev_b64 v[182:183], 11, v[76:77]
	v_lshlrev_b32_e32 v98, 16, v138
	v_and_b32_e32 v99, 0xffff0000, v138
	v_pk_add_f32 v[108:109], v[104:105], v[184:185]
	v_lshl_add_u64 v[184:185], v[174:175], 0, v[182:183]
	v_pk_add_f32 v[98:99], v[72:73], v[98:99]
	v_lshlrev_b32_e32 v72, 16, v137
	v_and_b32_e32 v73, 0xffff0000, v137
	global_load_dwordx4 v[210:213], v[184:185], off
	global_load_dwordx4 v[218:221], v[184:185], off offset:256
	v_pk_add_f32 v[136:137], v[78:79], v[72:73]
	v_lshlrev_b32_e32 v72, 16, v139
	v_and_b32_e32 v73, 0xffff0000, v139
	v_pk_add_f32 v[138:139], v[74:75], v[72:73]
	v_lshlrev_b32_e32 v72, 16, v132
	v_and_b32_e32 v73, 0xffff0000, v132
	v_pk_add_f32 v[74:75], v[84:85], v[72:73]
	v_lshlrev_b32_e32 v72, 16, v134
	v_and_b32_e32 v73, 0xffff0000, v134
	v_pk_add_f32 v[78:79], v[80:81], v[72:73]
	v_lshlrev_b32_e32 v72, 16, v133
	v_and_b32_e32 v73, 0xffff0000, v133
	v_pk_add_f32 v[80:81], v[86:87], v[72:73]
	v_lshlrev_b32_e32 v72, 16, v135
	v_and_b32_e32 v73, 0xffff0000, v135
	v_pk_add_f32 v[82:83], v[82:83], v[72:73]
	v_lshl_add_u64 v[72:73], v[168:169], 0, s[10:11]
	v_lshlrev_b64 v[132:133], 11, v[72:73]
	v_lshl_add_u64 v[134:135], v[174:175], 0, v[132:133]
	v_lshlrev_b32_e32 v84, 16, v128
	v_and_b32_e32 v85, 0xffff0000, v128
	global_load_dwordx4 v[226:229], v[134:135], off
	global_load_dwordx4 v[234:237], v[134:135], off offset:256
	v_pk_add_f32 v[84:85], v[68:69], v[84:85]
	v_lshlrev_b32_e32 v68, 16, v130
	v_and_b32_e32 v69, 0xffff0000, v130
	v_pk_add_f32 v[86:87], v[64:65], v[68:69]
	v_lshlrev_b32_e32 v64, 16, v129
	v_and_b32_e32 v65, 0xffff0000, v129
	s_mov_b64 s[10:11], 0xa0
	v_pk_add_f32 v[128:129], v[70:71], v[64:65]
	v_lshl_add_u64 v[70:71], v[168:169], 0, s[10:11]
	s_mov_b64 s[10:11], 0xb0
	v_lshlrev_b32_e32 v64, 16, v131
	v_and_b32_e32 v65, 0xffff0000, v131
	v_lshlrev_b64 v[134:135], 11, v[70:71]
	v_lshl_add_u64 v[68:69], v[168:169], 0, s[10:11]
	v_pk_add_f32 v[130:131], v[66:67], v[64:65]
	v_lshl_add_u64 v[64:65], v[174:175], 0, v[134:135]
	v_lshlrev_b64 v[184:185], 11, v[68:69]
	global_load_dwordx4 v[238:241], v[64:65], off
	global_load_dwordx4 v[242:245], v[64:65], off offset:256
	v_lshl_add_u64 v[64:65], v[174:175], 0, v[184:185]
	global_load_dwordx4 v[246:249], v[64:65], off
	s_nop 0
	global_load_dwordx4 v[64:67], v[64:65], off offset:256
	v_cvt_pk_bf16_f32 v115, v122, v123
	v_cvt_pk_bf16_f32 v119, v148, v149
	v_pk_add_f32 v[110:111], v[110:111], v[192:193]
	v_pk_add_f32 v[122:123], v[106:107], v[194:195]
	global_store_dwordx4 v[172:173], v[112:115], off
	global_store_dwordx4 v[172:173], v[116:119], off offset:256
	v_cvt_pk_bf16_f32 v104, v120, v121
	v_lshl_add_u64 v[112:113], s[28:29], 0, v[176:177]
	v_cvt_pk_bf16_f32 v105, v110, v111
	v_cvt_pk_bf16_f32 v106, v108, v109
	v_cvt_pk_bf16_f32 v107, v122, v123
	v_lshl_add_u64 v[112:113], v[112:113], 0, v[170:171]
	v_cvt_pk_bf16_f32 v146, v100, v101
	v_cvt_pk_bf16_f32 v147, v102, v103
	v_cvt_pk_bf16_f32 v148, v124, v125
	v_cvt_pk_bf16_f32 v149, v126, v127
	global_store_dwordx4 v[112:113], v[104:107], off
	global_store_dwordx4 v[112:113], v[146:149], off offset:256
	v_cvt_pk_bf16_f32 v194, v92, v93
	v_lshl_add_u64 v[104:105], s[28:29], 0, v[180:181]
	v_cvt_pk_bf16_f32 v195, v94, v95
	v_cvt_pk_bf16_f32 v196, v88, v89
	v_cvt_pk_bf16_f32 v197, v90, v91
	v_lshl_add_u64 v[104:105], v[104:105], 0, v[170:171]
	v_cvt_pk_bf16_f32 v214, v96, v97
	v_cvt_pk_bf16_f32 v215, v136, v137
	v_cvt_pk_bf16_f32 v216, v98, v99
	v_cvt_pk_bf16_f32 v217, v138, v139
	global_store_dwordx4 v[104:105], v[194:197], off
	global_store_dwordx4 v[104:105], v[214:217], off offset:256
	v_lshl_add_u64 v[104:105], s[28:29], 0, v[178:179]
	v_cvt_pk_bf16_f32 v222, v74, v75
	v_cvt_pk_bf16_f32 v223, v80, v81
	v_cvt_pk_bf16_f32 v224, v78, v79
	v_cvt_pk_bf16_f32 v225, v82, v83
	v_lshl_add_u64 v[104:105], v[104:105], 0, v[170:171]
	v_cvt_pk_bf16_f32 v230, v84, v85
	v_cvt_pk_bf16_f32 v231, v128, v129
	v_cvt_pk_bf16_f32 v232, v86, v87
	v_cvt_pk_bf16_f32 v233, v130, v131
	global_store_dwordx4 v[104:105], v[222:225], off
	global_store_dwordx4 v[104:105], v[230:233], off offset:256
	s_waitcnt vmcnt(0)
	v_lshlrev_b32_e32 v104, 16, v210
	v_and_b32_e32 v105, 0xffff0000, v210
	v_pk_add_f32 v[60:61], v[60:61], v[104:105]
	v_lshlrev_b32_e32 v104, 16, v212
	v_and_b32_e32 v105, 0xffff0000, v212
	v_pk_add_f32 v[56:57], v[56:57], v[104:105]
	v_lshlrev_b32_e32 v104, 16, v211
	v_and_b32_e32 v105, 0xffff0000, v211
	v_pk_add_f32 v[62:63], v[62:63], v[104:105]
	v_lshlrev_b32_e32 v104, 16, v213
	v_and_b32_e32 v105, 0xffff0000, v213
	v_pk_add_f32 v[58:59], v[58:59], v[104:105]
	v_lshlrev_b32_e32 v104, 16, v218
	v_and_b32_e32 v105, 0xffff0000, v218
	v_pk_add_f32 v[52:53], v[52:53], v[104:105]
	v_lshlrev_b32_e32 v104, 16, v220
	v_and_b32_e32 v105, 0xffff0000, v220
	v_pk_add_f32 v[104:105], v[44:45], v[104:105]
	v_lshlrev_b32_e32 v44, 16, v219
	v_and_b32_e32 v45, 0xffff0000, v219
	v_pk_add_f32 v[54:55], v[54:55], v[44:45]
	v_lshlrev_b32_e32 v44, 16, v221
	v_and_b32_e32 v45, 0xffff0000, v221
	v_pk_add_f32 v[106:107], v[46:47], v[44:45]
	v_lshlrev_b32_e32 v44, 16, v226
	v_and_b32_e32 v45, 0xffff0000, v226
	v_pk_add_f32 v[44:45], v[48:49], v[44:45]
	v_lshlrev_b32_e32 v48, 16, v229
	v_and_b32_e32 v49, 0xffff0000, v229
	v_pk_add_f32 v[42:43], v[42:43], v[48:49]
	v_lshlrev_b32_e32 v48, 16, v234
	v_and_b32_e32 v49, 0xffff0000, v234
	v_pk_add_f32 v[36:37], v[36:37], v[48:49]
	v_lshlrev_b32_e32 v48, 16, v236
	v_and_b32_e32 v49, 0xffff0000, v236
	v_lshlrev_b32_e32 v46, 16, v228
	v_and_b32_e32 v47, 0xffff0000, v228
	v_pk_add_f32 v[48:49], v[28:29], v[48:49]
	v_lshlrev_b32_e32 v28, 16, v235
	v_and_b32_e32 v29, 0xffff0000, v235
	v_pk_add_f32 v[40:41], v[40:41], v[46:47]
	v_lshlrev_b32_e32 v46, 16, v227
	v_and_b32_e32 v47, 0xffff0000, v227
	v_pk_add_f32 v[38:39], v[38:39], v[28:29]
	v_lshlrev_b32_e32 v28, 16, v237
	v_and_b32_e32 v29, 0xffff0000, v237
	v_pk_add_f32 v[46:47], v[50:51], v[46:47]
	v_pk_add_f32 v[50:51], v[30:31], v[28:29]
	v_lshlrev_b32_e32 v28, 16, v238
	v_and_b32_e32 v29, 0xffff0000, v238
	v_lshlrev_b32_e32 v180, 16, v64
	v_and_b32_e32 v181, 0xffff0000, v64
	v_pk_add_f32 v[28:29], v[32:33], v[28:29]
	v_lshlrev_b32_e32 v32, 16, v241
	v_and_b32_e32 v33, 0xffff0000, v241
	v_pk_add_f32 v[4:5], v[4:5], v[180:181]
	v_lshlrev_b32_e32 v180, 16, v66
	v_and_b32_e32 v181, 0xffff0000, v66
	v_pk_add_f32 v[26:27], v[26:27], v[32:33]
	v_lshlrev_b32_e32 v32, 16, v242
	v_and_b32_e32 v33, 0xffff0000, v242
	v_pk_add_f32 v[0:1], v[0:1], v[180:181]
	v_lshl_add_u64 v[180:181], s[28:29], 0, v[182:183]
	v_cvt_pk_bf16_f32 v112, v60, v61
	v_cvt_pk_bf16_f32 v113, v62, v63
	v_cvt_pk_bf16_f32 v114, v56, v57
	v_cvt_pk_bf16_f32 v115, v58, v59
	v_pk_add_f32 v[20:21], v[20:21], v[32:33]
	v_lshlrev_b32_e32 v32, 16, v244
	v_and_b32_e32 v33, 0xffff0000, v244
	v_lshl_add_u64 v[180:181], v[180:181], 0, v[170:171]
	v_cvt_pk_bf16_f32 v116, v52, v53
	v_cvt_pk_bf16_f32 v117, v54, v55
	v_cvt_pk_bf16_f32 v118, v104, v105
	v_cvt_pk_bf16_f32 v119, v106, v107
	v_lshlrev_b32_e32 v30, 16, v240
	v_and_b32_e32 v31, 0xffff0000, v240
	v_pk_add_f32 v[32:33], v[12:13], v[32:33]
	v_lshlrev_b32_e32 v12, 16, v243
	v_and_b32_e32 v13, 0xffff0000, v243
	global_store_dwordx4 v[180:181], v[112:115], off
	global_store_dwordx4 v[180:181], v[116:119], off offset:256
	v_cvt_pk_bf16_f32 v146, v44, v45
	v_lshl_add_u64 v[112:113], s[28:29], 0, v[132:133]
	v_cvt_pk_bf16_f32 v147, v46, v47
	v_cvt_pk_bf16_f32 v148, v40, v41
	v_cvt_pk_bf16_f32 v149, v42, v43
	v_pk_add_f32 v[24:25], v[24:25], v[30:31]
	v_lshlrev_b32_e32 v30, 16, v239
	v_and_b32_e32 v31, 0xffff0000, v239
	v_pk_add_f32 v[22:23], v[22:23], v[12:13]
	v_lshlrev_b32_e32 v12, 16, v245
	v_and_b32_e32 v13, 0xffff0000, v245
	v_lshl_add_u64 v[112:113], v[112:113], 0, v[170:171]
	v_cvt_pk_bf16_f32 v172, v36, v37
	v_cvt_pk_bf16_f32 v173, v38, v39
	v_cvt_pk_bf16_f32 v174, v48, v49
	v_cvt_pk_bf16_f32 v175, v50, v51
	v_pk_add_f32 v[30:31], v[34:35], v[30:31]
	v_pk_add_f32 v[34:35], v[14:15], v[12:13]
	v_lshlrev_b32_e32 v12, 16, v246
	v_and_b32_e32 v13, 0xffff0000, v246
	v_lshlrev_b32_e32 v14, 16, v248
	v_and_b32_e32 v15, 0xffff0000, v248
	global_store_dwordx4 v[112:113], v[146:149], off
	global_store_dwordx4 v[112:113], v[172:175], off offset:256
	v_lshl_add_u64 v[112:113], s[28:29], 0, v[134:135]
	v_cvt_pk_bf16_f32 v176, v28, v29
	v_cvt_pk_bf16_f32 v177, v30, v31
	v_cvt_pk_bf16_f32 v178, v24, v25
	v_cvt_pk_bf16_f32 v179, v26, v27
	v_pk_add_f32 v[12:13], v[16:17], v[12:13]
	v_pk_add_f32 v[8:9], v[8:9], v[14:15]
	v_lshlrev_b32_e32 v14, 16, v247
	v_and_b32_e32 v15, 0xffff0000, v247
	v_lshlrev_b32_e32 v16, 16, v249
	v_and_b32_e32 v17, 0xffff0000, v249
	v_lshlrev_b32_e32 v64, 16, v65
	v_and_b32_e32 v65, 0xffff0000, v65
	v_lshl_add_u64 v[112:113], v[112:113], 0, v[170:171]
	v_cvt_pk_bf16_f32 v194, v20, v21
	v_cvt_pk_bf16_f32 v195, v22, v23
	v_cvt_pk_bf16_f32 v196, v32, v33
	v_cvt_pk_bf16_f32 v197, v34, v35
	v_pk_add_f32 v[14:15], v[18:19], v[14:15]
	v_pk_add_f32 v[10:11], v[10:11], v[16:17]
	v_pk_add_f32 v[6:7], v[6:7], v[64:65]
	v_lshlrev_b32_e32 v64, 16, v67
	v_and_b32_e32 v65, 0xffff0000, v67
	global_store_dwordx4 v[112:113], v[176:179], off
	global_store_dwordx4 v[112:113], v[194:197], off offset:256
	v_lshl_add_u64 v[112:113], s[28:29], 0, v[184:185]
	v_cvt_pk_bf16_f32 v16, v12, v13
	v_cvt_pk_bf16_f32 v17, v14, v15
	v_cvt_pk_bf16_f32 v18, v8, v9
	v_cvt_pk_bf16_f32 v19, v10, v11
	v_pk_add_f32 v[2:3], v[2:3], v[64:65]
	v_lshl_add_u64 v[112:113], v[112:113], 0, v[170:171]
	v_cvt_pk_bf16_f32 v64, v4, v5
	v_cvt_pk_bf16_f32 v65, v6, v7
	v_cvt_pk_bf16_f32 v66, v0, v1
	v_cvt_pk_bf16_f32 v67, v2, v3
	global_store_dwordx4 v[112:113], v[16:19], off
	global_store_dwordx4 v[112:113], v[64:67], off offset:256
	s_lshl_b32 s10, s85, 2
	v_and_b32_e32 v17, 64, v188
	v_xor_b32_e32 v16, 16, v188
	v_add_u32_e32 v17, 64, v17
	v_cmp_lt_i32_e32 vcc, v16, v17
	v_xor_b32_e32 v18, 32, v188
	s_ashr_i32 s11, s10, 31
	v_cndmask_b32_e32 v16, v188, v16, vcc
	v_lshlrev_b32_e32 v16, 2, v16
	ds_bpermute_b32 v19, v16, v209
	v_cmp_lt_i32_e32 vcc, v18, v17
	s_lshl_b64 s[10:11], s[10:11], 2
	s_add_u32 s50, s83, s10
	v_cndmask_b32_e32 v17, v188, v18, vcc
	v_lshlrev_b32_e32 v17, 2, v17
	s_waitcnt lgkmcnt(0)
	v_add_f32_e32 v18, v209, v19
	ds_bpermute_b32 v19, v17, v18
	s_addc_u32 s51, s84, s11
	s_and_saveexec_b64 s[52:53], s[42:43]
	s_cbranch_execz .LBB0_106
	s_waitcnt lgkmcnt(0)
	v_add_f32_e32 v64, v18, v19
	v_lshlrev_b64 v[18:19], 6, v[168:169]
	v_lshl_add_u64 v[18:19], s[50:51], 0, v[18:19]
	global_store_dword v[18:19], v64, off

.LBB0_247:
	s_ashr_i32 s35, s34, 31
	s_lshl_b64 s[10:11], s[34:35], 19
	v_cmp_lt_i64_e32 vcc, s[46:47], v[142:143]
	s_add_u32 s46, s26, s10
	s_addc_u32 s47, s27, s11
	s_and_b64 s[10:11], vcc, exec
	s_cselect_b32 s10, s47, s53
	s_cselect_b32 s11, s46, s52
	s_ashr_i32 s39, s38, 31
	s_lshl_b64 s[48:49], s[38:39], 19
	s_add_u32 s48, s33, s48
	s_addc_u32 s49, s41, s49
	s_and_b64 s[58:59], vcc, exec
	s_cselect_b32 s12, s49, s55
	s_cselect_b32 s35, s48, s54
	s_add_u32 s52, s52, 0x40080
	s_addc_u32 s53, s53, 0
	s_add_u32 s39, s54, 0x100
	s_addc_u32 s51, s55, 0
	s_mov_b32 s82, -2
	s_waitcnt lgkmcnt(0)
	s_add_u32 s6, s52, 0xfffc0080
	s_addc_u32 s19, s53, -1
	s_add_i32 s23, 0, 0x10000
	v_add_u32_e32 v146, s23, v206
	ds_read_b128 v[128:131], v146
	ds_read_b128 v[132:135], v146 offset:1024
	ds_read_b128 v[136:139], v146 offset:2048
	ds_read_b128 v[146:149], v146 offset:3072
	s_cmp_eq_u32 s82, 12
	s_cselect_b32 s59, s10, s19
	s_cselect_b32 s58, s11, s6
	s_cselect_b32 s55, s12, s51
	s_cselect_b32 s54, s35, s39
	v_lshl_add_u64 v[214:215], s[52:53], 0, v[158:159]
	s_add_i32 m0, s68, 0xc000
	ds_read_b128 v[162:165], v208
	ds_read_b128 v[166:169], v208 offset:1024
	ds_read_b128 v[170:173], v208 offset:2048
	ds_read_b128 v[174:177], v208 offset:3072
	ds_read_b128 v[178:181], v208 offset:4096
	ds_read_b128 v[182:185], v208 offset:5120
	ds_read_b128 v[194:197], v208 offset:6144
	ds_read_b128 v[210:213], v208 offset:7168
	global_load_lds_dwordx4 v[214:215], off
	v_lshl_add_u64 v[214:215], s[52:53], 0, v[160:161]
	s_add_i32 m0, s68, 0xe000
	s_nop 0
	global_load_lds_dwordx4 v[214:215], off
	s_add_i32 s6, 0, 0x14000
	v_add_u32_e32 v192, s6, v206
	ds_read_b128 v[214:217], v192
	ds_read_b128 v[218:221], v192 offset:1024
	ds_read_b128 v[222:225], v192 offset:2048
	ds_read_b128 v[226:229], v192 offset:3072
	s_waitcnt vmcnt(40)
	s_cmp_lg_u32 s100, 0
	s_cbranch_scc1 .Lm4ap_248
	s_waitcnt vmcnt(8)
.Lm4ap_248:
	s_waitcnt lgkmcnt(0)
	s_barrier
	s_setprio 1
	v_mfma_f32_16x16x32_bf16 v[124:127], v[128:131], v[162:165], 0
	v_mfma_f32_16x16x32_bf16 v[120:123], v[136:139], v[162:165], 0
	v_mfma_f32_16x16x32_bf16 v[108:111], v[128:131], v[170:173], 0
	v_mfma_f32_16x16x32_bf16 v[104:107], v[136:139], v[170:173], 0
	v_mfma_f32_16x16x32_bf16 v[96:99], v[128:131], v[178:181], 0
	v_mfma_f32_16x16x32_bf16 v[88:91], v[136:139], v[178:181], 0
	v_mfma_f32_16x16x32_bf16 v[84:87], v[128:131], v[194:197], 0
	v_mfma_f32_16x16x32_bf16 v[80:83], v[136:139], v[194:197], 0
	v_mfma_f32_16x16x32_bf16 v[124:127], v[132:135], v[166:169], v[124:127]
	v_mfma_f32_16x16x32_bf16 v[120:123], v[146:149], v[166:169], v[120:123]
	v_mfma_f32_16x16x32_bf16 v[108:111], v[132:135], v[174:177], v[108:111]
	v_mfma_f32_16x16x32_bf16 v[104:107], v[146:149], v[174:177], v[104:107]
	v_mfma_f32_16x16x32_bf16 v[96:99], v[132:135], v[182:185], v[96:99]
	v_mfma_f32_16x16x32_bf16 v[88:91], v[146:149], v[182:185], v[88:91]
	v_mfma_f32_16x16x32_bf16 v[84:87], v[132:135], v[210:213], v[84:87]
	v_mfma_f32_16x16x32_bf16 v[80:83], v[146:149], v[210:213], v[80:83]
	v_mfma_f32_16x16x32_bf16 v[116:119], v[214:217], v[162:165], 0
	v_mfma_f32_16x16x32_bf16 v[112:115], v[222:225], v[162:165], 0
	v_mfma_f32_16x16x32_bf16 v[100:103], v[214:217], v[170:173], 0
	v_mfma_f32_16x16x32_bf16 v[92:95], v[222:225], v[170:173], 0
	v_mfma_f32_16x16x32_bf16 v[76:79], v[214:217], v[178:181], 0
	v_mfma_f32_16x16x32_bf16 v[72:75], v[222:225], v[178:181], 0
	v_mfma_f32_16x16x32_bf16 v[68:71], v[214:217], v[194:197], 0
	v_mfma_f32_16x16x32_bf16 v[64:67], v[222:225], v[194:197], 0
	v_mfma_f32_16x16x32_bf16 v[116:119], v[218:221], v[166:169], v[116:119]
	v_mfma_f32_16x16x32_bf16 v[112:115], v[226:229], v[166:169], v[112:115]
	v_mfma_f32_16x16x32_bf16 v[100:103], v[218:221], v[174:177], v[100:103]
	v_mfma_f32_16x16x32_bf16 v[92:95], v[226:229], v[174:177], v[92:95]
	v_mfma_f32_16x16x32_bf16 v[76:79], v[218:221], v[182:185], v[76:79]
	v_mfma_f32_16x16x32_bf16 v[72:75], v[226:229], v[182:185], v[72:75]
	v_mfma_f32_16x16x32_bf16 v[68:71], v[218:221], v[210:213], v[68:71]
	v_mfma_f32_16x16x32_bf16 v[64:67], v[226:229], v[210:213], v[64:67]
	s_setprio 0
	s_barrier
	s_add_i32 s19, s23, s57
	v_lshl_add_u64 v[230:231], s[54:55], 0, v[140:141]
	s_mov_b32 m0, s19
	s_nop 0
	global_load_lds_dwordx4 v[230:231], off
	v_lshl_add_u64 v[232:233], s[54:55], 0, v[150:151]
	s_add_i32 m0, s19, 0x2000
	s_nop 0
	global_load_lds_dwordx4 v[232:233], off
	s_mov_b32 m0, s68
	v_lshl_add_u64 v[234:235], s[58:59], 0, v[154:155]
	ds_read_b128 v[162:165], v208 offset:16384
	ds_read_b128 v[166:169], v208 offset:17408
	ds_read_b128 v[170:173], v208 offset:18432
	ds_read_b128 v[174:177], v208 offset:19456
	ds_read_b128 v[178:181], v208 offset:20480
	ds_read_b128 v[182:185], v208 offset:21504
	ds_read_b128 v[194:197], v208 offset:22528
	ds_read_b128 v[210:213], v208 offset:23552
	global_load_lds_dwordx4 v[234:235], off
	v_lshl_add_u64 v[236:237], s[58:59], 0, v[152:153]
	s_mov_b32 m0, s69
	s_nop 0
	global_load_lds_dwordx4 v[236:237], off
	s_add_u32 s84, s54, 0x40000
	s_addc_u32 s85, s55, 0
	s_add_i32 s6, s6, s57
	v_lshl_add_u64 v[250:251], s[84:85], 0, v[140:141]
	s_mov_b32 m0, s6
	s_nop 0
	global_load_lds_dwordx4 v[250:251], off
	v_lshl_add_u64 v[250:251], s[84:85], 0, v[150:151]
	s_add_i32 m0, s6, 0x2000
	s_nop 0
	global_load_lds_dwordx4 v[250:251], off
	s_waitcnt vmcnt(40)
	s_cmp_lg_u32 s100, 0
	s_cbranch_scc1 .Lm4bp_248
	s_waitcnt vmcnt(8)
.Lm4bp_248:
	s_waitcnt lgkmcnt(0)
	s_mov_b32 s100, 0
	s_barrier
	s_setprio 1
	v_mfma_f32_16x16x32_bf16 v[60:63], v[128:131], v[162:165], 0
	v_mfma_f32_16x16x32_bf16 v[56:59], v[136:139], v[162:165], 0
	v_mfma_f32_16x16x32_bf16 v[48:51], v[128:131], v[170:173], 0
	v_mfma_f32_16x16x32_bf16 v[40:43], v[136:139], v[170:173], 0
	v_mfma_f32_16x16x32_bf16 v[32:35], v[128:131], v[178:181], 0
	v_mfma_f32_16x16x32_bf16 v[24:27], v[136:139], v[178:181], 0
	v_mfma_f32_16x16x32_bf16 v[16:19], v[128:131], v[194:197], 0
	v_mfma_f32_16x16x32_bf16 v[8:11], v[136:139], v[194:197], 0
	v_mfma_f32_16x16x32_bf16 v[60:63], v[132:135], v[166:169], v[60:63]
	v_mfma_f32_16x16x32_bf16 v[56:59], v[146:149], v[166:169], v[56:59]
	v_mfma_f32_16x16x32_bf16 v[48:51], v[132:135], v[174:177], v[48:51]
	v_mfma_f32_16x16x32_bf16 v[40:43], v[146:149], v[174:177], v[40:43]
	v_mfma_f32_16x16x32_bf16 v[32:35], v[132:135], v[182:185], v[32:35]
	v_mfma_f32_16x16x32_bf16 v[24:27], v[146:149], v[182:185], v[24:27]
	v_mfma_f32_16x16x32_bf16 v[16:19], v[132:135], v[210:213], v[16:19]
	v_mfma_f32_16x16x32_bf16 v[8:11], v[146:149], v[210:213], v[8:11]
	v_mfma_f32_16x16x32_bf16 v[52:55], v[214:217], v[162:165], 0
	v_mfma_f32_16x16x32_bf16 v[44:47], v[222:225], v[162:165], 0
	v_mfma_f32_16x16x32_bf16 v[36:39], v[214:217], v[170:173], 0
	v_mfma_f32_16x16x32_bf16 v[28:31], v[222:225], v[170:173], 0
	v_mfma_f32_16x16x32_bf16 v[20:23], v[214:217], v[178:181], 0
	v_mfma_f32_16x16x32_bf16 v[12:15], v[222:225], v[178:181], 0
	v_mfma_f32_16x16x32_bf16 v[4:7], v[214:217], v[194:197], 0
	v_mfma_f32_16x16x32_bf16 v[0:3], v[222:225], v[194:197], 0
	v_mfma_f32_16x16x32_bf16 v[52:55], v[218:221], v[166:169], v[52:55]
	v_mfma_f32_16x16x32_bf16 v[44:47], v[226:229], v[166:169], v[44:47]
	v_mfma_f32_16x16x32_bf16 v[36:39], v[218:221], v[174:177], v[36:39]
	v_mfma_f32_16x16x32_bf16 v[28:31], v[226:229], v[174:177], v[28:31]
	v_mfma_f32_16x16x32_bf16 v[20:23], v[218:221], v[182:185], v[20:23]
	v_mfma_f32_16x16x32_bf16 v[12:15], v[226:229], v[182:185], v[12:15]
	v_mfma_f32_16x16x32_bf16 v[4:7], v[218:221], v[210:213], v[4:7]
	v_mfma_f32_16x16x32_bf16 v[0:3], v[226:229], v[210:213], v[0:3]
	s_setprio 0
	s_barrier
	s_add_i32 s6, 0, 0x18000
	v_add_u32_e32 v146, s6, v206
	ds_read_b128 v[128:131], v146
	ds_read_b128 v[132:135], v146 offset:1024
	ds_read_b128 v[136:139], v146 offset:2048
	ds_read_b128 v[146:149], v146 offset:3072
	s_add_u32 s58, s58, 0x40000
	s_addc_u32 s59, s59, 0
	s_mov_b32 m0, s70
	v_lshl_add_u64 v[214:215], s[58:59], 0, v[154:155]
	ds_read_b128 v[162:165], v208 offset:32768
	ds_read_b128 v[166:169], v208 offset:33792
	ds_read_b128 v[170:173], v208 offset:34816
	ds_read_b128 v[174:177], v208 offset:35840
	ds_read_b128 v[178:181], v208 offset:36864
	ds_read_b128 v[182:185], v208 offset:37888
	ds_read_b128 v[194:197], v208 offset:38912
	ds_read_b128 v[210:213], v208 offset:39936
	global_load_lds_dwordx4 v[214:215], off
	v_lshl_add_u64 v[214:215], s[58:59], 0, v[152:153]
	s_mov_b32 m0, s71
	s_nop 0
	global_load_lds_dwordx4 v[214:215], off
	s_add_i32 s19, 0, 0x1c000
	v_add_u32_e32 v192, s19, v206
	ds_read_b128 v[214:217], v192
	ds_read_b128 v[218:221], v192 offset:1024
	ds_read_b128 v[222:225], v192 offset:2048
	ds_read_b128 v[226:229], v192 offset:3072
	s_waitcnt vmcnt(8)
	s_waitcnt lgkmcnt(0)
	s_barrier
	s_setprio 1
	v_mfma_f32_16x16x32_bf16 v[124:127], v[128:131], v[162:165], v[124:127]
	v_mfma_f32_16x16x32_bf16 v[120:123], v[136:139], v[162:165], v[120:123]
	v_mfma_f32_16x16x32_bf16 v[108:111], v[128:131], v[170:173], v[108:111]
	v_mfma_f32_16x16x32_bf16 v[104:107], v[136:139], v[170:173], v[104:107]
	v_mfma_f32_16x16x32_bf16 v[96:99], v[128:131], v[178:181], v[96:99]
	v_mfma_f32_16x16x32_bf16 v[88:91], v[136:139], v[178:181], v[88:91]
	v_mfma_f32_16x16x32_bf16 v[84:87], v[128:131], v[194:197], v[84:87]
	v_mfma_f32_16x16x32_bf16 v[80:83], v[136:139], v[194:197], v[80:83]
	v_mfma_f32_16x16x32_bf16 v[124:127], v[132:135], v[166:169], v[124:127]
	v_mfma_f32_16x16x32_bf16 v[120:123], v[146:149], v[166:169], v[120:123]
	v_mfma_f32_16x16x32_bf16 v[108:111], v[132:135], v[174:177], v[108:111]
	v_mfma_f32_16x16x32_bf16 v[104:107], v[146:149], v[174:177], v[104:107]
	v_mfma_f32_16x16x32_bf16 v[96:99], v[132:135], v[182:185], v[96:99]
	v_mfma_f32_16x16x32_bf16 v[88:91], v[146:149], v[182:185], v[88:91]
	v_mfma_f32_16x16x32_bf16 v[84:87], v[132:135], v[210:213], v[84:87]
	v_mfma_f32_16x16x32_bf16 v[80:83], v[146:149], v[210:213], v[80:83]
	v_mfma_f32_16x16x32_bf16 v[116:119], v[214:217], v[162:165], v[116:119]
	v_mfma_f32_16x16x32_bf16 v[112:115], v[222:225], v[162:165], v[112:115]
	v_mfma_f32_16x16x32_bf16 v[100:103], v[214:217], v[170:173], v[100:103]
	v_mfma_f32_16x16x32_bf16 v[92:95], v[222:225], v[170:173], v[92:95]
	v_mfma_f32_16x16x32_bf16 v[76:79], v[214:217], v[178:181], v[76:79]
	v_mfma_f32_16x16x32_bf16 v[72:75], v[222:225], v[178:181], v[72:75]
	v_mfma_f32_16x16x32_bf16 v[68:71], v[214:217], v[194:197], v[68:71]
	v_mfma_f32_16x16x32_bf16 v[64:67], v[222:225], v[194:197], v[64:67]
	v_mfma_f32_16x16x32_bf16 v[116:119], v[218:221], v[166:169], v[116:119]
	v_mfma_f32_16x16x32_bf16 v[112:115], v[226:229], v[166:169], v[112:115]
	v_mfma_f32_16x16x32_bf16 v[100:103], v[218:221], v[174:177], v[100:103]
	v_mfma_f32_16x16x32_bf16 v[92:95], v[226:229], v[174:177], v[92:95]
	v_mfma_f32_16x16x32_bf16 v[76:79], v[218:221], v[182:185], v[76:79]
	v_mfma_f32_16x16x32_bf16 v[72:75], v[226:229], v[182:185], v[72:75]
	v_mfma_f32_16x16x32_bf16 v[68:71], v[218:221], v[210:213], v[68:71]
	v_mfma_f32_16x16x32_bf16 v[64:67], v[226:229], v[210:213], v[64:67]
	s_setprio 0
	s_barrier
	s_add_i32 s6, s6, s57
	v_lshl_add_u64 v[230:231], v[230:231], 0, s[36:37]
	s_mov_b32 m0, s6
	s_nop 0
	global_load_lds_dwordx4 v[230:231], off
	v_lshl_add_u64 v[230:231], v[232:233], 0, s[36:37]
	s_add_i32 m0, s6, 0x2000
	s_nop 0
	global_load_lds_dwordx4 v[230:231], off
	s_mov_b32 m0, s72
	v_lshl_add_u64 v[230:231], v[234:235], 0, s[36:37]
	ds_read_b128 v[162:165], v208 offset:49152
	ds_read_b128 v[166:169], v208 offset:50176
	ds_read_b128 v[170:173], v208 offset:51200
	ds_read_b128 v[174:177], v208 offset:52224
	ds_read_b128 v[178:181], v208 offset:53248
	ds_read_b128 v[182:185], v208 offset:54272
	ds_read_b128 v[194:197], v208 offset:55296
	ds_read_b128 v[210:213], v208 offset:56320
	global_load_lds_dwordx4 v[230:231], off
	v_lshl_add_u64 v[230:231], v[236:237], 0, s[36:37]
	s_mov_b32 m0, s73
	s_nop 0
	global_load_lds_dwordx4 v[230:231], off
	s_add_u32 s54, s54, 0x40080
	s_addc_u32 s55, s55, 0
	s_add_i32 s6, s19, s57
	v_lshl_add_u64 v[250:251], s[54:55], 0, v[140:141]
	s_mov_b32 m0, s6
	s_nop 0
	global_load_lds_dwordx4 v[250:251], off
	v_lshl_add_u64 v[250:251], s[54:55], 0, v[150:151]
	s_add_i32 m0, s6, 0x2000
	s_nop 0
	global_load_lds_dwordx4 v[250:251], off
	s_waitcnt vmcnt(8)
	s_waitcnt lgkmcnt(0)
	s_barrier
	s_setprio 1
	v_mfma_f32_16x16x32_bf16 v[60:63], v[128:131], v[162:165], v[60:63]
	v_mfma_f32_16x16x32_bf16 v[56:59], v[136:139], v[162:165], v[56:59]
	v_mfma_f32_16x16x32_bf16 v[48:51], v[128:131], v[170:173], v[48:51]
	v_mfma_f32_16x16x32_bf16 v[40:43], v[136:139], v[170:173], v[40:43]
	v_mfma_f32_16x16x32_bf16 v[32:35], v[128:131], v[178:181], v[32:35]
	v_mfma_f32_16x16x32_bf16 v[24:27], v[136:139], v[178:181], v[24:27]
	v_mfma_f32_16x16x32_bf16 v[16:19], v[128:131], v[194:197], v[16:19]
	v_mfma_f32_16x16x32_bf16 v[8:11], v[136:139], v[194:197], v[8:11]
	v_mfma_f32_16x16x32_bf16 v[60:63], v[132:135], v[166:169], v[60:63]
	v_mfma_f32_16x16x32_bf16 v[56:59], v[146:149], v[166:169], v[56:59]
	v_mfma_f32_16x16x32_bf16 v[48:51], v[132:135], v[174:177], v[48:51]
	v_mfma_f32_16x16x32_bf16 v[40:43], v[146:149], v[174:177], v[40:43]
	v_mfma_f32_16x16x32_bf16 v[32:35], v[132:135], v[182:185], v[32:35]
	v_mfma_f32_16x16x32_bf16 v[24:27], v[146:149], v[182:185], v[24:27]
	v_mfma_f32_16x16x32_bf16 v[16:19], v[132:135], v[210:213], v[16:19]
	v_mfma_f32_16x16x32_bf16 v[8:11], v[146:149], v[210:213], v[8:11]
	v_mfma_f32_16x16x32_bf16 v[52:55], v[214:217], v[162:165], v[52:55]
	v_mfma_f32_16x16x32_bf16 v[44:47], v[222:225], v[162:165], v[44:47]
	v_mfma_f32_16x16x32_bf16 v[36:39], v[214:217], v[170:173], v[36:39]
	v_mfma_f32_16x16x32_bf16 v[28:31], v[222:225], v[170:173], v[28:31]
	v_mfma_f32_16x16x32_bf16 v[20:23], v[214:217], v[178:181], v[20:23]
	v_mfma_f32_16x16x32_bf16 v[12:15], v[222:225], v[178:181], v[12:15]
	v_mfma_f32_16x16x32_bf16 v[4:7], v[214:217], v[194:197], v[4:7]
	v_mfma_f32_16x16x32_bf16 v[0:3], v[222:225], v[194:197], v[0:3]
	v_mfma_f32_16x16x32_bf16 v[52:55], v[218:221], v[166:169], v[52:55]
	v_mfma_f32_16x16x32_bf16 v[44:47], v[226:229], v[166:169], v[44:47]
	v_mfma_f32_16x16x32_bf16 v[36:39], v[218:221], v[174:177], v[36:39]
	v_mfma_f32_16x16x32_bf16 v[28:31], v[226:229], v[174:177], v[28:31]
	v_mfma_f32_16x16x32_bf16 v[20:23], v[218:221], v[182:185], v[20:23]
	v_mfma_f32_16x16x32_bf16 v[12:15], v[226:229], v[182:185], v[12:15]
	v_mfma_f32_16x16x32_bf16 v[4:7], v[218:221], v[210:213], v[4:7]
	v_mfma_f32_16x16x32_bf16 v[0:3], v[226:229], v[210:213], v[0:3]
	s_setprio 0
	s_add_i32 s82, s82, 2
	s_add_u32 s52, s52, 0x100
	s_addc_u32 s53, s53, 0
	s_add_u32 s39, s39, 0x100
	s_addc_u32 s51, s51, 0
	s_cmp_gt_u32 s82, 13
	s_barrier
.LBB0_248:
	s_add_u32 s6, s52, 0xfffc0080
	s_addc_u32 s19, s53, -1
	s_add_i32 s23, 0, 0x10000
	v_add_u32_e32 v146, s23, v206
	ds_read_b128 v[128:131], v146
	ds_read_b128 v[132:135], v146 offset:1024
	ds_read_b128 v[136:139], v146 offset:2048
	ds_read_b128 v[146:149], v146 offset:3072
	s_cmp_eq_u32 s82, 12
	s_cselect_b32 s59, s10, s19
	s_cselect_b32 s58, s11, s6
	s_cselect_b32 s55, s12, s51
	s_cselect_b32 s54, s35, s39
	v_lshl_add_u64 v[214:215], s[52:53], 0, v[158:159]
	s_add_i32 m0, s68, 0xc000
	ds_read_b128 v[162:165], v208
	ds_read_b128 v[166:169], v208 offset:1024
	ds_read_b128 v[170:173], v208 offset:2048
	ds_read_b128 v[174:177], v208 offset:3072
	ds_read_b128 v[178:181], v208 offset:4096
	ds_read_b128 v[182:185], v208 offset:5120
	ds_read_b128 v[194:197], v208 offset:6144
	ds_read_b128 v[210:213], v208 offset:7168
	global_load_lds_dwordx4 v[214:215], off
	v_lshl_add_u64 v[214:215], s[52:53], 0, v[160:161]
	s_add_i32 m0, s68, 0xe000
	s_nop 0
	global_load_lds_dwordx4 v[214:215], off
	s_add_i32 s6, 0, 0x14000
	v_add_u32_e32 v192, s6, v206
	ds_read_b128 v[214:217], v192
	ds_read_b128 v[218:221], v192 offset:1024
	ds_read_b128 v[222:225], v192 offset:2048
	ds_read_b128 v[226:229], v192 offset:3072
	s_waitcnt vmcnt(8)
	s_waitcnt lgkmcnt(0)
	s_barrier
	s_setprio 1
	v_mfma_f32_16x16x32_bf16 v[124:127], v[128:131], v[162:165], v[124:127]
	v_mfma_f32_16x16x32_bf16 v[120:123], v[136:139], v[162:165], v[120:123]
	v_mfma_f32_16x16x32_bf16 v[108:111], v[128:131], v[170:173], v[108:111]
	v_mfma_f32_16x16x32_bf16 v[104:107], v[136:139], v[170:173], v[104:107]
	v_mfma_f32_16x16x32_bf16 v[96:99], v[128:131], v[178:181], v[96:99]
	v_mfma_f32_16x16x32_bf16 v[88:91], v[136:139], v[178:181], v[88:91]
	v_mfma_f32_16x16x32_bf16 v[84:87], v[128:131], v[194:197], v[84:87]
	v_mfma_f32_16x16x32_bf16 v[80:83], v[136:139], v[194:197], v[80:83]
	v_mfma_f32_16x16x32_bf16 v[124:127], v[132:135], v[166:169], v[124:127]
	v_mfma_f32_16x16x32_bf16 v[120:123], v[146:149], v[166:169], v[120:123]
	v_mfma_f32_16x16x32_bf16 v[108:111], v[132:135], v[174:177], v[108:111]
	v_mfma_f32_16x16x32_bf16 v[104:107], v[146:149], v[174:177], v[104:107]
	v_mfma_f32_16x16x32_bf16 v[96:99], v[132:135], v[182:185], v[96:99]
	v_mfma_f32_16x16x32_bf16 v[88:91], v[146:149], v[182:185], v[88:91]
	v_mfma_f32_16x16x32_bf16 v[84:87], v[132:135], v[210:213], v[84:87]
	v_mfma_f32_16x16x32_bf16 v[80:83], v[146:149], v[210:213], v[80:83]
	v_mfma_f32_16x16x32_bf16 v[116:119], v[214:217], v[162:165], v[116:119]
	v_mfma_f32_16x16x32_bf16 v[112:115], v[222:225], v[162:165], v[112:115]
	v_mfma_f32_16x16x32_bf16 v[100:103], v[214:217], v[170:173], v[100:103]
	v_mfma_f32_16x16x32_bf16 v[92:95], v[222:225], v[170:173], v[92:95]
	v_mfma_f32_16x16x32_bf16 v[76:79], v[214:217], v[178:181], v[76:79]
	v_mfma_f32_16x16x32_bf16 v[72:75], v[222:225], v[178:181], v[72:75]
	v_mfma_f32_16x16x32_bf16 v[68:71], v[214:217], v[194:197], v[68:71]
	v_mfma_f32_16x16x32_bf16 v[64:67], v[222:225], v[194:197], v[64:67]
	v_mfma_f32_16x16x32_bf16 v[116:119], v[218:221], v[166:169], v[116:119]
	v_mfma_f32_16x16x32_bf16 v[112:115], v[226:229], v[166:169], v[112:115]
	v_mfma_f32_16x16x32_bf16 v[100:103], v[218:221], v[174:177], v[100:103]
	v_mfma_f32_16x16x32_bf16 v[92:95], v[226:229], v[174:177], v[92:95]
	v_mfma_f32_16x16x32_bf16 v[76:79], v[218:221], v[182:185], v[76:79]
	v_mfma_f32_16x16x32_bf16 v[72:75], v[226:229], v[182:185], v[72:75]
	v_mfma_f32_16x16x32_bf16 v[68:71], v[218:221], v[210:213], v[68:71]
	v_mfma_f32_16x16x32_bf16 v[64:67], v[226:229], v[210:213], v[64:67]
	s_setprio 0
	s_barrier
	s_add_i32 s19, s23, s57
	v_lshl_add_u64 v[230:231], s[54:55], 0, v[140:141]
	s_mov_b32 m0, s19
	s_nop 0
	global_load_lds_dwordx4 v[230:231], off
	v_lshl_add_u64 v[232:233], s[54:55], 0, v[150:151]
	s_add_i32 m0, s19, 0x2000
	s_nop 0
	global_load_lds_dwordx4 v[232:233], off
	s_mov_b32 m0, s68
	v_lshl_add_u64 v[234:235], s[58:59], 0, v[154:155]
	ds_read_b128 v[162:165], v208 offset:16384
	ds_read_b128 v[166:169], v208 offset:17408
	ds_read_b128 v[170:173], v208 offset:18432
	ds_read_b128 v[174:177], v208 offset:19456
	ds_read_b128 v[178:181], v208 offset:20480
	ds_read_b128 v[182:185], v208 offset:21504
	ds_read_b128 v[194:197], v208 offset:22528
	ds_read_b128 v[210:213], v208 offset:23552
	global_load_lds_dwordx4 v[234:235], off
	v_lshl_add_u64 v[236:237], s[58:59], 0, v[152:153]
	s_mov_b32 m0, s69
	s_nop 0
	global_load_lds_dwordx4 v[236:237], off
	s_add_u32 s84, s54, 0x40000
	s_addc_u32 s85, s55, 0
	s_add_i32 s6, s6, s57
	v_lshl_add_u64 v[250:251], s[84:85], 0, v[140:141]
	s_mov_b32 m0, s6
	s_nop 0
	global_load_lds_dwordx4 v[250:251], off
	v_lshl_add_u64 v[250:251], s[84:85], 0, v[150:151]
	s_add_i32 m0, s6, 0x2000
	s_nop 0
	global_load_lds_dwordx4 v[250:251], off
	s_waitcnt vmcnt(8)
	s_waitcnt lgkmcnt(0)
	s_barrier
	s_setprio 1
	v_mfma_f32_16x16x32_bf16 v[60:63], v[128:131], v[162:165], v[60:63]
	v_mfma_f32_16x16x32_bf16 v[56:59], v[136:139], v[162:165], v[56:59]
	v_mfma_f32_16x16x32_bf16 v[48:51], v[128:131], v[170:173], v[48:51]
	v_mfma_f32_16x16x32_bf16 v[40:43], v[136:139], v[170:173], v[40:43]
	v_mfma_f32_16x16x32_bf16 v[32:35], v[128:131], v[178:181], v[32:35]
	v_mfma_f32_16x16x32_bf16 v[24:27], v[136:139], v[178:181], v[24:27]
	v_mfma_f32_16x16x32_bf16 v[16:19], v[128:131], v[194:197], v[16:19]
	v_mfma_f32_16x16x32_bf16 v[8:11], v[136:139], v[194:197], v[8:11]
	v_mfma_f32_16x16x32_bf16 v[60:63], v[132:135], v[166:169], v[60:63]
	v_mfma_f32_16x16x32_bf16 v[56:59], v[146:149], v[166:169], v[56:59]
	v_mfma_f32_16x16x32_bf16 v[48:51], v[132:135], v[174:177], v[48:51]
	v_mfma_f32_16x16x32_bf16 v[40:43], v[146:149], v[174:177], v[40:43]
	v_mfma_f32_16x16x32_bf16 v[32:35], v[132:135], v[182:185], v[32:35]
	v_mfma_f32_16x16x32_bf16 v[24:27], v[146:149], v[182:185], v[24:27]
	v_mfma_f32_16x16x32_bf16 v[16:19], v[132:135], v[210:213], v[16:19]
	v_mfma_f32_16x16x32_bf16 v[8:11], v[146:149], v[210:213], v[8:11]
	v_mfma_f32_16x16x32_bf16 v[52:55], v[214:217], v[162:165], v[52:55]
	v_mfma_f32_16x16x32_bf16 v[44:47], v[222:225], v[162:165], v[44:47]
	v_mfma_f32_16x16x32_bf16 v[36:39], v[214:217], v[170:173], v[36:39]
	v_mfma_f32_16x16x32_bf16 v[28:31], v[222:225], v[170:173], v[28:31]
	v_mfma_f32_16x16x32_bf16 v[20:23], v[214:217], v[178:181], v[20:23]
	v_mfma_f32_16x16x32_bf16 v[12:15], v[222:225], v[178:181], v[12:15]
	v_mfma_f32_16x16x32_bf16 v[4:7], v[214:217], v[194:197], v[4:7]
	v_mfma_f32_16x16x32_bf16 v[0:3], v[222:225], v[194:197], v[0:3]
	v_mfma_f32_16x16x32_bf16 v[52:55], v[218:221], v[166:169], v[52:55]
	v_mfma_f32_16x16x32_bf16 v[44:47], v[226:229], v[166:169], v[44:47]
	v_mfma_f32_16x16x32_bf16 v[36:39], v[218:221], v[174:177], v[36:39]
	v_mfma_f32_16x16x32_bf16 v[28:31], v[226:229], v[174:177], v[28:31]
	v_mfma_f32_16x16x32_bf16 v[20:23], v[218:221], v[182:185], v[20:23]
	v_mfma_f32_16x16x32_bf16 v[12:15], v[226:229], v[182:185], v[12:15]
	v_mfma_f32_16x16x32_bf16 v[4:7], v[218:221], v[210:213], v[4:7]
	v_mfma_f32_16x16x32_bf16 v[0:3], v[226:229], v[210:213], v[0:3]
	s_setprio 0
	s_barrier
	s_add_i32 s6, 0, 0x18000
	v_add_u32_e32 v146, s6, v206
	ds_read_b128 v[128:131], v146
	ds_read_b128 v[132:135], v146 offset:1024
	ds_read_b128 v[136:139], v146 offset:2048
	ds_read_b128 v[146:149], v146 offset:3072
	s_add_u32 s58, s58, 0x40000
	s_addc_u32 s59, s59, 0
	s_mov_b32 m0, s70
	v_lshl_add_u64 v[214:215], s[58:59], 0, v[154:155]
	ds_read_b128 v[162:165], v208 offset:32768
	ds_read_b128 v[166:169], v208 offset:33792
	ds_read_b128 v[170:173], v208 offset:34816
	ds_read_b128 v[174:177], v208 offset:35840
	ds_read_b128 v[178:181], v208 offset:36864
	ds_read_b128 v[182:185], v208 offset:37888
	ds_read_b128 v[194:197], v208 offset:38912
	ds_read_b128 v[210:213], v208 offset:39936
	global_load_lds_dwordx4 v[214:215], off
	v_lshl_add_u64 v[214:215], s[58:59], 0, v[152:153]
	s_mov_b32 m0, s71
	s_nop 0
	global_load_lds_dwordx4 v[214:215], off
	s_add_i32 s19, 0, 0x1c000
	v_add_u32_e32 v192, s19, v206
	ds_read_b128 v[214:217], v192
	ds_read_b128 v[218:221], v192 offset:1024
	ds_read_b128 v[222:225], v192 offset:2048
	ds_read_b128 v[226:229], v192 offset:3072
	s_waitcnt vmcnt(8)
	s_waitcnt lgkmcnt(0)
	s_barrier
	s_setprio 1
	v_mfma_f32_16x16x32_bf16 v[124:127], v[128:131], v[162:165], v[124:127]
	v_mfma_f32_16x16x32_bf16 v[120:123], v[136:139], v[162:165], v[120:123]
	v_mfma_f32_16x16x32_bf16 v[108:111], v[128:131], v[170:173], v[108:111]
	v_mfma_f32_16x16x32_bf16 v[104:107], v[136:139], v[170:173], v[104:107]
	v_mfma_f32_16x16x32_bf16 v[96:99], v[128:131], v[178:181], v[96:99]
	v_mfma_f32_16x16x32_bf16 v[88:91], v[136:139], v[178:181], v[88:91]
	v_mfma_f32_16x16x32_bf16 v[84:87], v[128:131], v[194:197], v[84:87]
	v_mfma_f32_16x16x32_bf16 v[80:83], v[136:139], v[194:197], v[80:83]
	v_mfma_f32_16x16x32_bf16 v[124:127], v[132:135], v[166:169], v[124:127]
	v_mfma_f32_16x16x32_bf16 v[120:123], v[146:149], v[166:169], v[120:123]
	v_mfma_f32_16x16x32_bf16 v[108:111], v[132:135], v[174:177], v[108:111]
	v_mfma_f32_16x16x32_bf16 v[104:107], v[146:149], v[174:177], v[104:107]
	v_mfma_f32_16x16x32_bf16 v[96:99], v[132:135], v[182:185], v[96:99]
	v_mfma_f32_16x16x32_bf16 v[88:91], v[146:149], v[182:185], v[88:91]
	v_mfma_f32_16x16x32_bf16 v[84:87], v[132:135], v[210:213], v[84:87]
	v_mfma_f32_16x16x32_bf16 v[80:83], v[146:149], v[210:213], v[80:83]
	v_mfma_f32_16x16x32_bf16 v[116:119], v[214:217], v[162:165], v[116:119]
	v_mfma_f32_16x16x32_bf16 v[112:115], v[222:225], v[162:165], v[112:115]
	v_mfma_f32_16x16x32_bf16 v[100:103], v[214:217], v[170:173], v[100:103]
	v_mfma_f32_16x16x32_bf16 v[92:95], v[222:225], v[170:173], v[92:95]
	v_mfma_f32_16x16x32_bf16 v[76:79], v[214:217], v[178:181], v[76:79]
	v_mfma_f32_16x16x32_bf16 v[72:75], v[222:225], v[178:181], v[72:75]
	v_mfma_f32_16x16x32_bf16 v[68:71], v[214:217], v[194:197], v[68:71]
	v_mfma_f32_16x16x32_bf16 v[64:67], v[222:225], v[194:197], v[64:67]
	v_mfma_f32_16x16x32_bf16 v[116:119], v[218:221], v[166:169], v[116:119]
	v_mfma_f32_16x16x32_bf16 v[112:115], v[226:229], v[166:169], v[112:115]
	v_mfma_f32_16x16x32_bf16 v[100:103], v[218:221], v[174:177], v[100:103]
	v_mfma_f32_16x16x32_bf16 v[92:95], v[226:229], v[174:177], v[92:95]
	v_mfma_f32_16x16x32_bf16 v[76:79], v[218:221], v[182:185], v[76:79]
	v_mfma_f32_16x16x32_bf16 v[72:75], v[226:229], v[182:185], v[72:75]
	v_mfma_f32_16x16x32_bf16 v[68:71], v[218:221], v[210:213], v[68:71]
	v_mfma_f32_16x16x32_bf16 v[64:67], v[226:229], v[210:213], v[64:67]
	s_setprio 0
	s_barrier
	s_add_i32 s6, s6, s57
	v_lshl_add_u64 v[230:231], v[230:231], 0, s[36:37]
	s_mov_b32 m0, s6
	s_nop 0
	global_load_lds_dwordx4 v[230:231], off
	v_lshl_add_u64 v[230:231], v[232:233], 0, s[36:37]
	s_add_i32 m0, s6, 0x2000
	s_nop 0
	global_load_lds_dwordx4 v[230:231], off
	s_mov_b32 m0, s72
	v_lshl_add_u64 v[230:231], v[234:235], 0, s[36:37]
	ds_read_b128 v[162:165], v208 offset:49152
	ds_read_b128 v[166:169], v208 offset:50176
	ds_read_b128 v[170:173], v208 offset:51200
	ds_read_b128 v[174:177], v208 offset:52224
	ds_read_b128 v[178:181], v208 offset:53248
	ds_read_b128 v[182:185], v208 offset:54272
	ds_read_b128 v[194:197], v208 offset:55296
	ds_read_b128 v[210:213], v208 offset:56320
	global_load_lds_dwordx4 v[230:231], off
	v_lshl_add_u64 v[230:231], v[236:237], 0, s[36:37]
	s_mov_b32 m0, s73
	s_nop 0
	global_load_lds_dwordx4 v[230:231], off
	s_add_u32 s54, s54, 0x40080
	s_addc_u32 s55, s55, 0
	s_add_i32 s6, s19, s57
	v_lshl_add_u64 v[250:251], s[54:55], 0, v[140:141]
	s_mov_b32 m0, s6
	s_nop 0
	global_load_lds_dwordx4 v[250:251], off
	v_lshl_add_u64 v[250:251], s[54:55], 0, v[150:151]
	s_add_i32 m0, s6, 0x2000
	s_nop 0
	global_load_lds_dwordx4 v[250:251], off
	s_waitcnt vmcnt(8)
	s_waitcnt lgkmcnt(0)
	s_barrier
	s_setprio 1
	v_mfma_f32_16x16x32_bf16 v[60:63], v[128:131], v[162:165], v[60:63]
	v_mfma_f32_16x16x32_bf16 v[56:59], v[136:139], v[162:165], v[56:59]
	v_mfma_f32_16x16x32_bf16 v[48:51], v[128:131], v[170:173], v[48:51]
	v_mfma_f32_16x16x32_bf16 v[40:43], v[136:139], v[170:173], v[40:43]
	v_mfma_f32_16x16x32_bf16 v[32:35], v[128:131], v[178:181], v[32:35]
	v_mfma_f32_16x16x32_bf16 v[24:27], v[136:139], v[178:181], v[24:27]
	v_mfma_f32_16x16x32_bf16 v[16:19], v[128:131], v[194:197], v[16:19]
	v_mfma_f32_16x16x32_bf16 v[8:11], v[136:139], v[194:197], v[8:11]
	v_mfma_f32_16x16x32_bf16 v[60:63], v[132:135], v[166:169], v[60:63]
	v_mfma_f32_16x16x32_bf16 v[56:59], v[146:149], v[166:169], v[56:59]
	v_mfma_f32_16x16x32_bf16 v[48:51], v[132:135], v[174:177], v[48:51]
	v_mfma_f32_16x16x32_bf16 v[40:43], v[146:149], v[174:177], v[40:43]
	v_mfma_f32_16x16x32_bf16 v[32:35], v[132:135], v[182:185], v[32:35]
	v_mfma_f32_16x16x32_bf16 v[24:27], v[146:149], v[182:185], v[24:27]
	v_mfma_f32_16x16x32_bf16 v[16:19], v[132:135], v[210:213], v[16:19]
	v_mfma_f32_16x16x32_bf16 v[8:11], v[146:149], v[210:213], v[8:11]
	v_mfma_f32_16x16x32_bf16 v[52:55], v[214:217], v[162:165], v[52:55]
	v_mfma_f32_16x16x32_bf16 v[44:47], v[222:225], v[162:165], v[44:47]
	v_mfma_f32_16x16x32_bf16 v[36:39], v[214:217], v[170:173], v[36:39]
	v_mfma_f32_16x16x32_bf16 v[28:31], v[222:225], v[170:173], v[28:31]
	v_mfma_f32_16x16x32_bf16 v[20:23], v[214:217], v[178:181], v[20:23]
	v_mfma_f32_16x16x32_bf16 v[12:15], v[222:225], v[178:181], v[12:15]
	v_mfma_f32_16x16x32_bf16 v[4:7], v[214:217], v[194:197], v[4:7]
	v_mfma_f32_16x16x32_bf16 v[0:3], v[222:225], v[194:197], v[0:3]
	v_mfma_f32_16x16x32_bf16 v[52:55], v[218:221], v[166:169], v[52:55]
	v_mfma_f32_16x16x32_bf16 v[44:47], v[226:229], v[166:169], v[44:47]
	v_mfma_f32_16x16x32_bf16 v[36:39], v[218:221], v[174:177], v[36:39]
	v_mfma_f32_16x16x32_bf16 v[28:31], v[226:229], v[174:177], v[28:31]
	v_mfma_f32_16x16x32_bf16 v[20:23], v[218:221], v[182:185], v[20:23]
	v_mfma_f32_16x16x32_bf16 v[12:15], v[226:229], v[182:185], v[12:15]
	v_mfma_f32_16x16x32_bf16 v[4:7], v[218:221], v[210:213], v[4:7]
	v_mfma_f32_16x16x32_bf16 v[0:3], v[226:229], v[210:213], v[0:3]
	s_setprio 0
	s_add_i32 s82, s82, 2
	s_add_u32 s52, s52, 0x100
	s_addc_u32 s53, s53, 0
	s_add_u32 s39, s39, 0x100
	s_addc_u32 s51, s51, 0
	s_cmp_gt_u32 s82, 13
	s_barrier
	s_cbranch_scc0 .LBB0_248
	s_mov_b32 s100, 1
	s_ashr_i32 s51, s50, 31
	v_lshl_or_b32 v128, s81, 8, v207
	s_lshl_b64 s[10:11], s[50:51], 8
	v_ashrrev_i32_e32 v129, 31, v128
	v_lshl_add_u64 v[168:169], s[10:11], 0, v[156:157]
	v_lshlrev_b64 v[170:171], 1, v[128:129]
	v_lshl_add_u64 v[174:175], s[28:29], 0, v[170:171]
	v_lshlrev_b64 v[172:173], 11, v[168:169]
	v_lshl_add_u64 v[128:129], v[174:175], 0, v[172:173]
	global_load_dwordx4 v[146:149], v[128:129], off
	global_load_dwordx4 v[182:185], v[128:129], off offset:256
	v_or_b32_e32 v166, 16, v168
	v_mov_b32_e32 v167, v169
	v_lshlrev_b64 v[176:177], 11, v[166:167]
	v_lshl_add_u64 v[128:129], v[174:175], 0, v[176:177]
	global_load_dwordx4 v[194:197], v[128:129], off
	global_load_dwordx4 v[210:213], v[128:129], off offset:256
	v_or_b32_e32 v164, 32, v168
	v_mov_b32_e32 v165, v169
	v_or_b32_e32 v162, 48, v168
	v_mov_b32_e32 v163, v169
	v_lshlrev_b64 v[180:181], 11, v[164:165]
	v_lshlrev_b64 v[178:179], 11, v[162:163]
	v_lshl_add_u64 v[128:129], v[174:175], 0, v[180:181]
	v_lshl_add_u64 v[130:131], v[174:175], 0, v[178:179]
	global_load_dwordx4 v[214:217], v[128:129], off
	global_load_dwordx4 v[136:139], v[128:129], off offset:256
	global_load_dwordx4 v[132:135], v[130:131], off
	s_nop 0
	global_load_dwordx4 v[128:131], v[130:131], off offset:256
	s_mov_b64 s[10:11], 0x90
	v_lshl_add_u64 v[172:173], s[30:31], 0, v[172:173]
	v_lshl_add_u64 v[172:173], v[172:173], 0, v[170:171]
	s_waitcnt vmcnt(0)
	v_lshlrev_b32_e32 v218, 16, v146
	v_and_b32_e32 v219, 0xffff0000, v146
	v_lshlrev_b32_e32 v220, 16, v148
	v_and_b32_e32 v221, 0xffff0000, v148
	v_lshlrev_b32_e32 v146, 16, v147
	v_and_b32_e32 v147, 0xffff0000, v147
	v_lshlrev_b32_e32 v222, 16, v182
	v_and_b32_e32 v223, 0xffff0000, v182
	v_lshlrev_b32_e32 v224, 16, v184
	v_and_b32_e32 v225, 0xffff0000, v184
	v_lshlrev_b32_e32 v182, 16, v183
	v_and_b32_e32 v183, 0xffff0000, v183
	v_pk_add_f32 v[124:125], v[124:125], v[218:219]
	v_pk_add_f32 v[120:121], v[120:121], v[220:221]
	v_pk_add_f32 v[126:127], v[126:127], v[146:147]
	v_pk_add_f32 v[116:117], v[116:117], v[222:223]
	v_pk_add_f32 v[146:147], v[112:113], v[224:225]
	v_pk_add_f32 v[118:119], v[118:119], v[182:183]
	v_pk_mul_f32 v[220:221], v[124:125], v[124:125]
	v_pk_mul_f32 v[222:223], v[126:127], v[126:127]
	v_cvt_pk_bf16_f32 v112, v124, v125
	v_cvt_pk_bf16_f32 v113, v126, v127
	v_pk_mul_f32 v[124:125], v[116:117], v[116:117]
	v_pk_mul_f32 v[126:127], v[118:119], v[118:119]
	v_pk_mul_f32 v[228:229], v[146:147], v[146:147]
	v_cvt_pk_bf16_f32 v116, v116, v117
	v_cvt_pk_bf16_f32 v117, v118, v119
	v_cvt_pk_bf16_f32 v118, v146, v147
	v_add_f32_e32 v146, v220, v221
	v_add_f32_e32 v146, v222, v146
	v_lshlrev_b32_e32 v148, 16, v149
	v_and_b32_e32 v149, 0xffff0000, v149
	v_pk_mul_f32 v[224:225], v[120:121], v[120:121]
	v_add_f32_e32 v146, v223, v146
	v_pk_add_f32 v[122:123], v[122:123], v[148:149]
	v_add_f32_e32 v146, v224, v146
	v_pk_mul_f32 v[226:227], v[122:123], v[122:123]
	v_add_f32_e32 v146, v225, v146
	v_add_f32_e32 v146, v226, v146
	v_add_f32_e32 v146, v227, v146
	v_add_f32_e32 v124, v124, v146
	v_add_f32_e32 v124, v125, v124
	v_add_f32_e32 v124, v126, v124
	v_lshlrev_b32_e32 v184, 16, v185
	v_and_b32_e32 v185, 0xffff0000, v185
	v_add_f32_e32 v124, v127, v124
	v_pk_add_f32 v[148:149], v[114:115], v[184:185]
	v_add_f32_e32 v124, v228, v124
	v_pk_mul_f32 v[230:231], v[148:149], v[148:149]
	v_add_f32_e32 v124, v229, v124
	v_add_f32_e32 v124, v230, v124
	v_add_f32_e32 v209, v231, v124
	v_lshlrev_b32_e32 v124, 16, v212
	v_and_b32_e32 v125, 0xffff0000, v212
	v_pk_add_f32 v[124:125], v[92:93], v[124:125]
	v_lshlrev_b32_e32 v92, 16, v211
	v_and_b32_e32 v93, 0xffff0000, v211
	v_pk_add_f32 v[102:103], v[102:103], v[92:93]
	v_lshlrev_b32_e32 v92, 16, v213
	v_and_b32_e32 v93, 0xffff0000, v213
	v_pk_add_f32 v[126:127], v[94:95], v[92:93]
	v_lshlrev_b32_e32 v92, 16, v214
	v_and_b32_e32 v93, 0xffff0000, v214
	v_pk_add_f32 v[92:93], v[96:97], v[92:93]
	v_lshlrev_b32_e32 v96, 16, v217
	v_and_b32_e32 v97, 0xffff0000, v217
	v_lshlrev_b32_e32 v94, 16, v216
	v_and_b32_e32 v95, 0xffff0000, v216
	v_pk_add_f32 v[90:91], v[90:91], v[96:97]
	v_lshlrev_b32_e32 v96, 16, v136
	v_and_b32_e32 v97, 0xffff0000, v136
	v_lshlrev_b32_e32 v182, 16, v194
	v_and_b32_e32 v183, 0xffff0000, v194
	v_pk_add_f32 v[88:89], v[88:89], v[94:95]
	v_lshlrev_b32_e32 v94, 16, v215
	v_and_b32_e32 v95, 0xffff0000, v215
	v_pk_add_f32 v[96:97], v[76:77], v[96:97]
	v_lshl_add_u64 v[76:77], v[168:169], 0, s[36:37]
	v_lshlrev_b32_e32 v184, 16, v196
	v_and_b32_e32 v185, 0xffff0000, v196
	v_cvt_pk_bf16_f32 v114, v120, v121
	v_pk_add_f32 v[120:121], v[108:109], v[182:183]
	v_pk_add_f32 v[94:95], v[98:99], v[94:95]
	v_lshlrev_b64 v[182:183], 11, v[76:77]
	v_lshlrev_b32_e32 v98, 16, v138
	v_and_b32_e32 v99, 0xffff0000, v138
	v_pk_add_f32 v[108:109], v[104:105], v[184:185]
	v_lshl_add_u64 v[184:185], v[174:175], 0, v[182:183]
	v_pk_add_f32 v[98:99], v[72:73], v[98:99]
	v_lshlrev_b32_e32 v72, 16, v137
	v_and_b32_e32 v73, 0xffff0000, v137
	v_lshlrev_b32_e32 v218, 16, v210
	v_and_b32_e32 v219, 0xffff0000, v210
	global_load_dwordx4 v[210:213], v[184:185], off
	v_pk_add_f32 v[136:137], v[78:79], v[72:73]
	v_lshlrev_b32_e32 v72, 16, v139
	v_and_b32_e32 v73, 0xffff0000, v139
	v_pk_add_f32 v[138:139], v[74:75], v[72:73]
	v_lshlrev_b32_e32 v72, 16, v132
	v_and_b32_e32 v73, 0xffff0000, v132
	v_pk_add_f32 v[74:75], v[84:85], v[72:73]
	v_lshlrev_b32_e32 v72, 16, v134
	v_and_b32_e32 v73, 0xffff0000, v134
	v_pk_add_f32 v[78:79], v[80:81], v[72:73]
	v_lshlrev_b32_e32 v72, 16, v133
	v_and_b32_e32 v73, 0xffff0000, v133
	v_pk_add_f32 v[100:101], v[100:101], v[218:219]
	global_load_dwordx4 v[218:221], v[184:185], off offset:256
	v_pk_add_f32 v[80:81], v[86:87], v[72:73]
	v_lshlrev_b32_e32 v72, 16, v135
	v_and_b32_e32 v73, 0xffff0000, v135
	v_pk_add_f32 v[82:83], v[82:83], v[72:73]
	v_lshl_add_u64 v[72:73], v[168:169], 0, s[10:11]
	v_lshlrev_b64 v[132:133], 11, v[72:73]
	v_lshl_add_u64 v[134:135], v[174:175], 0, v[132:133]
	v_lshlrev_b32_e32 v84, 16, v128
	v_and_b32_e32 v85, 0xffff0000, v128
	global_load_dwordx4 v[226:229], v[134:135], off
	global_load_dwordx4 v[234:237], v[134:135], off offset:256
	v_pk_add_f32 v[84:85], v[68:69], v[84:85]
	v_lshlrev_b32_e32 v68, 16, v130
	v_and_b32_e32 v69, 0xffff0000, v130
	v_pk_add_f32 v[86:87], v[64:65], v[68:69]
	v_lshlrev_b32_e32 v64, 16, v129
	v_and_b32_e32 v65, 0xffff0000, v129
	s_mov_b64 s[10:11], 0xa0
	v_pk_add_f32 v[128:129], v[70:71], v[64:65]
	v_lshl_add_u64 v[70:71], v[168:169], 0, s[10:11]
	s_mov_b64 s[10:11], 0xb0
	v_lshlrev_b32_e32 v64, 16, v131
	v_and_b32_e32 v65, 0xffff0000, v131
	v_lshlrev_b64 v[134:135], 11, v[70:71]
	v_lshl_add_u64 v[68:69], v[168:169], 0, s[10:11]
	v_pk_add_f32 v[130:131], v[66:67], v[64:65]
	v_lshl_add_u64 v[64:65], v[174:175], 0, v[134:135]
	v_lshlrev_b64 v[184:185], 11, v[68:69]
	global_load_dwordx4 v[238:241], v[64:65], off
	global_load_dwordx4 v[242:245], v[64:65], off offset:256
	v_lshl_add_u64 v[64:65], v[174:175], 0, v[184:185]
	global_load_dwordx4 v[246:249], v[64:65], off
	s_nop 0
	global_load_dwordx4 v[64:67], v[64:65], off offset:256
	v_lshlrev_b32_e32 v194, 16, v195
	v_and_b32_e32 v195, 0xffff0000, v195
	v_lshlrev_b32_e32 v196, 16, v197
	v_and_b32_e32 v197, 0xffff0000, v197
	v_cvt_pk_bf16_f32 v115, v122, v123
	v_cvt_pk_bf16_f32 v119, v148, v149
	v_pk_add_f32 v[122:123], v[110:111], v[194:195]
	v_pk_add_f32 v[110:111], v[106:107], v[196:197]
	global_store_dwordx4 v[172:173], v[112:115], off
	global_store_dwordx4 v[172:173], v[116:119], off offset:256
	v_cvt_pk_bf16_f32 v104, v120, v121
	v_lshl_add_u64 v[112:113], s[30:31], 0, v[176:177]
	v_cvt_pk_bf16_f32 v105, v122, v123
	v_cvt_pk_bf16_f32 v106, v108, v109
	v_cvt_pk_bf16_f32 v107, v110, v111
	v_lshl_add_u64 v[112:113], v[112:113], 0, v[170:171]
	v_cvt_pk_bf16_f32 v146, v100, v101
	v_cvt_pk_bf16_f32 v147, v102, v103
	v_cvt_pk_bf16_f32 v148, v124, v125
	v_cvt_pk_bf16_f32 v149, v126, v127
	global_store_dwordx4 v[112:113], v[104:107], off
	global_store_dwordx4 v[112:113], v[146:149], off offset:256
	v_cvt_pk_bf16_f32 v194, v92, v93
	v_lshl_add_u64 v[104:105], s[30:31], 0, v[180:181]
	v_cvt_pk_bf16_f32 v195, v94, v95
	v_cvt_pk_bf16_f32 v196, v88, v89
	v_cvt_pk_bf16_f32 v197, v90, v91
	v_lshl_add_u64 v[104:105], v[104:105], 0, v[170:171]
	v_cvt_pk_bf16_f32 v214, v96, v97
	v_cvt_pk_bf16_f32 v215, v136, v137
	v_cvt_pk_bf16_f32 v216, v98, v99
	v_cvt_pk_bf16_f32 v217, v138, v139
	global_store_dwordx4 v[104:105], v[194:197], off
	global_store_dwordx4 v[104:105], v[214:217], off offset:256
	v_lshl_add_u64 v[104:105], s[30:31], 0, v[178:179]
	v_cvt_pk_bf16_f32 v222, v74, v75
	v_cvt_pk_bf16_f32 v223, v80, v81
	v_cvt_pk_bf16_f32 v224, v78, v79
	v_cvt_pk_bf16_f32 v225, v82, v83
	v_lshl_add_u64 v[104:105], v[104:105], 0, v[170:171]
	v_cvt_pk_bf16_f32 v230, v84, v85
	v_cvt_pk_bf16_f32 v231, v128, v129
	v_cvt_pk_bf16_f32 v232, v86, v87
	v_cvt_pk_bf16_f32 v233, v130, v131
	global_store_dwordx4 v[104:105], v[222:225], off
	global_store_dwordx4 v[104:105], v[230:233], off offset:256
	s_waitcnt vmcnt(0)
	v_lshlrev_b32_e32 v104, 16, v210
	v_and_b32_e32 v105, 0xffff0000, v210
	v_pk_add_f32 v[60:61], v[60:61], v[104:105]
	v_lshlrev_b32_e32 v104, 16, v212
	v_and_b32_e32 v105, 0xffff0000, v212
	v_pk_add_f32 v[56:57], v[56:57], v[104:105]
	v_lshlrev_b32_e32 v104, 16, v211
	v_and_b32_e32 v105, 0xffff0000, v211
	v_pk_add_f32 v[62:63], v[62:63], v[104:105]
	v_lshlrev_b32_e32 v104, 16, v213
	v_and_b32_e32 v105, 0xffff0000, v213
	v_pk_add_f32 v[58:59], v[58:59], v[104:105]
	v_lshlrev_b32_e32 v104, 16, v218
	v_and_b32_e32 v105, 0xffff0000, v218
	v_pk_add_f32 v[52:53], v[52:53], v[104:105]
	v_lshlrev_b32_e32 v104, 16, v220
	v_and_b32_e32 v105, 0xffff0000, v220
	v_pk_add_f32 v[104:105], v[44:45], v[104:105]
	v_lshlrev_b32_e32 v44, 16, v219
	v_and_b32_e32 v45, 0xffff0000, v219
	v_pk_add_f32 v[54:55], v[54:55], v[44:45]
	v_lshlrev_b32_e32 v44, 16, v221
	v_and_b32_e32 v45, 0xffff0000, v221
	v_pk_add_f32 v[106:107], v[46:47], v[44:45]
	v_lshlrev_b32_e32 v44, 16, v226
	v_and_b32_e32 v45, 0xffff0000, v226
	v_pk_add_f32 v[44:45], v[48:49], v[44:45]
	v_lshlrev_b32_e32 v48, 16, v229
	v_and_b32_e32 v49, 0xffff0000, v229
	v_pk_add_f32 v[42:43], v[42:43], v[48:49]
	v_lshlrev_b32_e32 v48, 16, v234
	v_and_b32_e32 v49, 0xffff0000, v234
	v_pk_add_f32 v[36:37], v[36:37], v[48:49]
	v_lshlrev_b32_e32 v48, 16, v236
	v_and_b32_e32 v49, 0xffff0000, v236
	v_lshlrev_b32_e32 v46, 16, v228
	v_and_b32_e32 v47, 0xffff0000, v228
	v_pk_add_f32 v[48:49], v[28:29], v[48:49]
	v_lshlrev_b32_e32 v28, 16, v235
	v_and_b32_e32 v29, 0xffff0000, v235
	v_pk_add_f32 v[40:41], v[40:41], v[46:47]
	v_lshlrev_b32_e32 v46, 16, v227
	v_and_b32_e32 v47, 0xffff0000, v227
	v_pk_add_f32 v[38:39], v[38:39], v[28:29]
	v_lshlrev_b32_e32 v28, 16, v237
	v_and_b32_e32 v29, 0xffff0000, v237
	v_pk_add_f32 v[46:47], v[50:51], v[46:47]
	v_pk_add_f32 v[50:51], v[30:31], v[28:29]
	v_lshlrev_b32_e32 v28, 16, v238
	v_and_b32_e32 v29, 0xffff0000, v238
	v_lshlrev_b32_e32 v180, 16, v64
	v_and_b32_e32 v181, 0xffff0000, v64
	v_pk_add_f32 v[28:29], v[32:33], v[28:29]
	v_lshlrev_b32_e32 v32, 16, v241
	v_and_b32_e32 v33, 0xffff0000, v241
	v_pk_add_f32 v[4:5], v[4:5], v[180:181]
	v_lshlrev_b32_e32 v180, 16, v66
	v_and_b32_e32 v181, 0xffff0000, v66
	v_pk_add_f32 v[26:27], v[26:27], v[32:33]
	v_lshlrev_b32_e32 v32, 16, v242
	v_and_b32_e32 v33, 0xffff0000, v242
	v_pk_add_f32 v[0:1], v[0:1], v[180:181]
	v_lshl_add_u64 v[180:181], s[30:31], 0, v[182:183]
	v_cvt_pk_bf16_f32 v112, v60, v61
	v_cvt_pk_bf16_f32 v113, v62, v63
	v_cvt_pk_bf16_f32 v114, v56, v57
	v_cvt_pk_bf16_f32 v115, v58, v59
	v_pk_add_f32 v[20:21], v[20:21], v[32:33]
	v_lshlrev_b32_e32 v32, 16, v244
	v_and_b32_e32 v33, 0xffff0000, v244
	v_lshl_add_u64 v[180:181], v[180:181], 0, v[170:171]
	v_cvt_pk_bf16_f32 v116, v52, v53
	v_cvt_pk_bf16_f32 v117, v54, v55
	v_cvt_pk_bf16_f32 v118, v104, v105
	v_cvt_pk_bf16_f32 v119, v106, v107
	v_lshlrev_b32_e32 v30, 16, v240
	v_and_b32_e32 v31, 0xffff0000, v240
	v_pk_add_f32 v[32:33], v[12:13], v[32:33]
	v_lshlrev_b32_e32 v12, 16, v243
	v_and_b32_e32 v13, 0xffff0000, v243
	global_store_dwordx4 v[180:181], v[112:115], off
	global_store_dwordx4 v[180:181], v[116:119], off offset:256
	v_cvt_pk_bf16_f32 v146, v44, v45
	v_lshl_add_u64 v[112:113], s[30:31], 0, v[132:133]
	v_cvt_pk_bf16_f32 v147, v46, v47
	v_cvt_pk_bf16_f32 v148, v40, v41
	v_cvt_pk_bf16_f32 v149, v42, v43
	v_pk_add_f32 v[24:25], v[24:25], v[30:31]
	v_lshlrev_b32_e32 v30, 16, v239
	v_and_b32_e32 v31, 0xffff0000, v239
	v_pk_add_f32 v[22:23], v[22:23], v[12:13]
	v_lshlrev_b32_e32 v12, 16, v245
	v_and_b32_e32 v13, 0xffff0000, v245
	v_lshl_add_u64 v[112:113], v[112:113], 0, v[170:171]
	v_cvt_pk_bf16_f32 v172, v36, v37
	v_cvt_pk_bf16_f32 v173, v38, v39
	v_cvt_pk_bf16_f32 v174, v48, v49
	v_cvt_pk_bf16_f32 v175, v50, v51
	v_pk_add_f32 v[30:31], v[34:35], v[30:31]
	v_pk_add_f32 v[34:35], v[14:15], v[12:13]
	v_lshlrev_b32_e32 v12, 16, v246
	v_and_b32_e32 v13, 0xffff0000, v246
	v_lshlrev_b32_e32 v14, 16, v248
	v_and_b32_e32 v15, 0xffff0000, v248
	global_store_dwordx4 v[112:113], v[146:149], off
	global_store_dwordx4 v[112:113], v[172:175], off offset:256
	v_lshl_add_u64 v[112:113], s[30:31], 0, v[134:135]
	v_cvt_pk_bf16_f32 v176, v28, v29
	v_cvt_pk_bf16_f32 v177, v30, v31
	v_cvt_pk_bf16_f32 v178, v24, v25
	v_cvt_pk_bf16_f32 v179, v26, v27
	v_pk_add_f32 v[12:13], v[16:17], v[12:13]
	v_pk_add_f32 v[8:9], v[8:9], v[14:15]
	v_lshlrev_b32_e32 v14, 16, v247
	v_and_b32_e32 v15, 0xffff0000, v247
	v_lshlrev_b32_e32 v16, 16, v249
	v_and_b32_e32 v17, 0xffff0000, v249
	v_lshlrev_b32_e32 v64, 16, v65
	v_and_b32_e32 v65, 0xffff0000, v65
	v_lshl_add_u64 v[112:113], v[112:113], 0, v[170:171]
	v_cvt_pk_bf16_f32 v194, v20, v21
	v_cvt_pk_bf16_f32 v195, v22, v23
	v_cvt_pk_bf16_f32 v196, v32, v33
	v_cvt_pk_bf16_f32 v197, v34, v35
	v_pk_add_f32 v[14:15], v[18:19], v[14:15]
	v_pk_add_f32 v[10:11], v[10:11], v[16:17]
	v_pk_add_f32 v[6:7], v[6:7], v[64:65]
	v_lshlrev_b32_e32 v64, 16, v67
	v_and_b32_e32 v65, 0xffff0000, v67
	global_store_dwordx4 v[112:113], v[176:179], off
	global_store_dwordx4 v[112:113], v[194:197], off offset:256
	v_lshl_add_u64 v[112:113], s[30:31], 0, v[184:185]
	v_cvt_pk_bf16_f32 v16, v12, v13
	v_cvt_pk_bf16_f32 v17, v14, v15
	v_cvt_pk_bf16_f32 v18, v8, v9
	v_cvt_pk_bf16_f32 v19, v10, v11
	v_pk_add_f32 v[2:3], v[2:3], v[64:65]
	v_lshl_add_u64 v[112:113], v[112:113], 0, v[170:171]
	v_cvt_pk_bf16_f32 v64, v4, v5
	v_cvt_pk_bf16_f32 v65, v6, v7
	v_cvt_pk_bf16_f32 v66, v0, v1
	v_cvt_pk_bf16_f32 v67, v2, v3
	global_store_dwordx4 v[112:113], v[16:19], off
	global_store_dwordx4 v[112:113], v[64:67], off offset:256
	s_lshl_b32 s10, s81, 2
	v_and_b32_e32 v17, 64, v188
	v_xor_b32_e32 v16, 16, v188
	v_add_u32_e32 v17, 64, v17
	v_cmp_lt_i32_e32 vcc, v16, v17
	v_xor_b32_e32 v18, 32, v188
	s_ashr_i32 s11, s10, 31
	v_cndmask_b32_e32 v16, v188, v16, vcc
	v_lshlrev_b32_e32 v16, 2, v16
	ds_bpermute_b32 v19, v16, v209
	v_cmp_lt_i32_e32 vcc, v18, v17
	s_lshl_b64 s[10:11], s[10:11], 2
	s_add_u32 s50, s75, s10
	v_cndmask_b32_e32 v17, v188, v18, vcc
	v_lshlrev_b32_e32 v17, 2, v17
	s_waitcnt lgkmcnt(0)
	v_add_f32_e32 v18, v209, v19
	ds_bpermute_b32 v19, v17, v18
	s_addc_u32 s51, s80, s11
	s_and_saveexec_b64 s[52:53], s[42:43]
	s_cbranch_execz .LBB0_251
	s_waitcnt lgkmcnt(0)
	v_add_f32_e32 v64, v18, v19
	v_lshlrev_b64 v[18:19], 6, v[168:169]
	v_lshl_add_u64 v[18:19], s[50:51], 0, v[18:19]
	global_store_dword v[18:19], v64, off

.LBB0_290:
	s_add_u32 s26, s26, 0x3290000
	v_and_b32_e32 v15, 15, v8
	v_lshrrev_b32_e32 v8, 1, v8
	s_addc_u32 s27, s27, 0
	v_and_b32_e32 v8, 24, v8
	s_lshl_b32 s10, s10, 5
	v_lshlrev_b32_e32 v16, 1, v8
	v_lshlrev_b32_e32 v17, 2, v15
	s_and_b32 s19, s10, 0x60
	s_add_i32 m0, s58, 0x18000
	v_lshl_add_u64 v[6:7], v[6:7], 0, s[36:37]
	s_lshl_b32 s12, s6, 6
	v_lshl_or_b32 v16, v15, 6, v16
	s_lshl_b32 s11, s6, 13
	v_and_b32_e32 v18, 32, v17
	s_lshl_b32 s10, s19, 7
	s_waitcnt vmcnt(0)
	s_barrier
	global_load_lds_dwordx4 v[6:7], off
	v_lshl_add_u64 v[4:5], v[4:5], 0, s[36:37]
	s_add_i32 m0, s58, 0x1a000
	s_add_i32 s70, s58, 0x8000
	s_add_i32 s71, s58, 0xa000
	v_bitop3_b32 v154, v16, s10, v18 bitop3:0xde
	global_load_lds_dwordx4 v[4:5], off
	v_lshl_add_u64 v[2:3], v[2:3], 0, s[36:37]
	s_mov_b32 m0, s70
	s_add_u32 s10, s48, 0x40080
	v_bitop3_b32 v19, v16, s11, v18 bitop3:0xde
	global_load_lds_dwordx4 v[2:3], off
	v_lshl_add_u64 v[0:1], v[0:1], 0, s[36:37]
	s_mov_b32 m0, s71
	s_addc_u32 s11, s49, 0
	global_load_lds_dwordx4 v[0:1], off
	s_add_i32 m0, s58, 0x1c000
	v_lshl_add_u64 v[0:1], s[10:11], 0, v[140:141]
	global_load_lds_dwordx4 v[0:1], off
	v_lshl_add_u64 v[0:1], s[10:11], 0, v[132:133]
	s_add_i32 m0, s58, 0x1e000
	s_lshl_b32 s6, s6, 8
	global_load_lds_dwordx4 v[0:1], off
	v_lshlrev_b32_e32 v0, 14, v9
	v_and_b32_e32 v0, 0xffff8000, v0
	v_lshl_add_u32 v0, v10, 11, v0
	v_and_b32_e32 v1, 1, v9
	v_lshl_or_b32 v0, v1, 6, v0
	v_lshl_add_u32 v136, v11, 1, v0
	v_lshlrev_b32_e32 v0, 14, v12
	v_and_b32_e32 v0, 0xffff8000, v0
	s_add_i32 s6, s6, 0
	v_lshl_add_u32 v0, v13, 11, v0
	v_and_b32_e32 v1, 1, v12
	s_waitcnt vmcnt(6)
	s_add_i32 s6, s6, 0x22000
	v_lshl_or_b32 v0, v1, 6, v0
	v_add_u32_e32 v155, s6, v17
	s_ashr_i32 s6, s12, 31
	v_lshl_add_u32 v138, v14, 1, v0
	v_or_b32_e32 v134, s12, v15
	v_mov_b32_e32 v135, s6
	v_or_b32_e32 v156, s19, v8
	v_mov_b32_e32 v137, v141
	v_mov_b32_e32 v139, v141
	s_mov_b32 s73, 0
	v_add_u32_e32 v157, 0, v19
	v_readlane_b32 s72, v253, 46
	v_readlane_b32 s28, v253, 60
	s_barrier
	v_readlane_b32 s29, v253, 61
	s_mov_b32 s100, 0
	s_branch .LBB0_292
.LBB0_291:
	s_mov_b32 s72, s34
	s_mov_b32 s28, s30
	s_mov_b64 s[4:5], s[46:47]
	s_mov_b32 s73, s74
	s_andn2_b64 vcc, exec, s[42:43]
	s_mov_b64 s[48:49], s[38:39]
	s_cbranch_vccz .LBB0_298

.LBB0_294:
	s_add_u32 s10, s48, 0x100
	s_addc_u32 s11, s49, 0
	s_ashr_i32 s31, s30, 31
	s_lshl_b64 s[38:39], s[30:31], 19
	s_add_u32 s46, s33, s38
	s_addc_u32 s47, s41, s39
	s_and_b64 s[38:39], s[44:45], exec
	s_cselect_b32 s12, s47, s5
	s_cselect_b32 s29, s46, s4
	s_ashr_i32 s35, s34, 31
	s_lshl_b64 s[38:39], s[34:35], 19
	s_add_u32 s38, s54, s38
	s_addc_u32 s39, s55, s39
	s_and_b64 s[50:51], s[44:45], exec
	s_cselect_b32 s31, s39, s49
	s_cselect_b32 s35, s38, s48
	s_add_u32 s48, s4, 0x40080
	s_addc_u32 s49, s5, 0
	v_lshl_add_u64 v[150:151], s[48:49], 0, v[136:137]
	v_lshl_add_u64 v[152:153], s[48:49], 0, v[138:139]
	s_mov_b32 s75, -2
	s_mov_b64 s[48:49], 0
	s_add_u32 s6, s4, s48
	s_addc_u32 s19, s5, s49
	s_add_u32 s6, s6, 0x100
	s_addc_u32 s19, s19, 0
	s_add_u32 s23, s10, s48
	s_addc_u32 s50, s11, s49
	s_add_i32 s80, 0, 0x10000
	v_add_u32_e32 v166, s80, v154
	ds_read_b128 v[146:149], v166
	ds_read_b128 v[158:161], v166 offset:1024
	ds_read_b128 v[162:165], v166 offset:2048
	ds_read_b128 v[166:169], v166 offset:3072
	s_cmpk_eq_i32 s48, 0x700
	s_cselect_b32 s53, s12, s19
	s_cselect_b32 s52, s29, s6
	s_cselect_b32 s51, s31, s50
	s_cselect_b32 s50, s35, s23
	v_lshl_add_u64 v[218:219], v[150:151], 0, s[48:49]
	s_add_i32 m0, s58, 0xc000
	ds_read_b128 v[170:173], v157
	ds_read_b128 v[174:177], v157 offset:1024
	ds_read_b128 v[178:181], v157 offset:2048
	ds_read_b128 v[182:185], v157 offset:3072
	ds_read_b128 v[194:197], v157 offset:4096
	ds_read_b128 v[206:209], v157 offset:5120
	ds_read_b128 v[210:213], v157 offset:6144
	ds_read_b128 v[214:217], v157 offset:7168
	global_load_lds_dwordx4 v[218:219], off
	v_lshl_add_u64 v[218:219], v[152:153], 0, s[48:49]
	s_add_i32 m0, s58, 0xe000
	s_nop 0
	global_load_lds_dwordx4 v[218:219], off
	s_add_i32 s6, 0, 0x14000
	v_add_u32_e32 v192, s6, v154
	ds_read_b128 v[218:221], v192
	ds_read_b128 v[222:225], v192 offset:1024
	ds_read_b128 v[226:229], v192 offset:2048
	ds_read_b128 v[230:233], v192 offset:3072
	s_waitcnt vmcnt(24)
	s_cmp_lg_u32 s100, 0
	s_cbranch_scc1 .Lm4ap_295
	s_waitcnt vmcnt(8)
.Lm4ap_295:
	s_waitcnt lgkmcnt(0)
	s_barrier
	s_setprio 1
	v_mfma_f32_16x16x32_bf16 v[124:127], v[146:149], v[170:173], 0
	v_mfma_f32_16x16x32_bf16 v[120:123], v[162:165], v[170:173], 0
	v_mfma_f32_16x16x32_bf16 v[116:119], v[146:149], v[178:181], 0
	v_mfma_f32_16x16x32_bf16 v[112:115], v[162:165], v[178:181], 0
	v_mfma_f32_16x16x32_bf16 v[108:111], v[146:149], v[194:197], 0
	v_mfma_f32_16x16x32_bf16 v[104:107], v[162:165], v[194:197], 0
	v_mfma_f32_16x16x32_bf16 v[100:103], v[146:149], v[210:213], 0
	v_mfma_f32_16x16x32_bf16 v[96:99], v[162:165], v[210:213], 0
	v_mfma_f32_16x16x32_bf16 v[124:127], v[158:161], v[174:177], v[124:127]
	v_mfma_f32_16x16x32_bf16 v[120:123], v[166:169], v[174:177], v[120:123]
	v_mfma_f32_16x16x32_bf16 v[116:119], v[158:161], v[182:185], v[116:119]
	v_mfma_f32_16x16x32_bf16 v[112:115], v[166:169], v[182:185], v[112:115]
	v_mfma_f32_16x16x32_bf16 v[108:111], v[158:161], v[206:209], v[108:111]
	v_mfma_f32_16x16x32_bf16 v[104:107], v[166:169], v[206:209], v[104:107]
	v_mfma_f32_16x16x32_bf16 v[100:103], v[158:161], v[214:217], v[100:103]
	v_mfma_f32_16x16x32_bf16 v[96:99], v[166:169], v[214:217], v[96:99]
	v_mfma_f32_16x16x32_bf16 v[92:95], v[218:221], v[170:173], 0
	v_mfma_f32_16x16x32_bf16 v[88:91], v[226:229], v[170:173], 0
	v_mfma_f32_16x16x32_bf16 v[84:87], v[218:221], v[178:181], 0
	v_mfma_f32_16x16x32_bf16 v[80:83], v[226:229], v[178:181], 0
	v_mfma_f32_16x16x32_bf16 v[76:79], v[218:221], v[194:197], 0
	v_mfma_f32_16x16x32_bf16 v[72:75], v[226:229], v[194:197], 0
	v_mfma_f32_16x16x32_bf16 v[68:71], v[218:221], v[210:213], 0
	v_mfma_f32_16x16x32_bf16 v[64:67], v[226:229], v[210:213], 0
	v_mfma_f32_16x16x32_bf16 v[92:95], v[222:225], v[174:177], v[92:95]
	v_mfma_f32_16x16x32_bf16 v[88:91], v[230:233], v[174:177], v[88:91]
	v_mfma_f32_16x16x32_bf16 v[84:87], v[222:225], v[182:185], v[84:87]
	v_mfma_f32_16x16x32_bf16 v[80:83], v[230:233], v[182:185], v[80:83]
	v_mfma_f32_16x16x32_bf16 v[76:79], v[222:225], v[206:209], v[76:79]
	v_mfma_f32_16x16x32_bf16 v[72:75], v[230:233], v[206:209], v[72:75]
	v_mfma_f32_16x16x32_bf16 v[68:71], v[222:225], v[214:217], v[68:71]
	v_mfma_f32_16x16x32_bf16 v[64:67], v[230:233], v[214:217], v[64:67]
	s_setprio 0
	s_barrier
	s_add_i32 s19, s80, s57
	v_lshl_add_u64 v[234:235], s[50:51], 0, v[140:141]
	s_mov_b32 m0, s19
	s_nop 0
	global_load_lds_dwordx4 v[234:235], off
	v_lshl_add_u64 v[236:237], s[50:51], 0, v[132:133]
	s_add_i32 m0, s19, 0x2000
	s_nop 0
	global_load_lds_dwordx4 v[236:237], off
	s_mov_b32 m0, s58
	v_lshl_add_u64 v[238:239], s[52:53], 0, v[128:129]
	ds_read_b128 v[170:173], v157 offset:16384
	ds_read_b128 v[174:177], v157 offset:17408
	ds_read_b128 v[178:181], v157 offset:18432
	ds_read_b128 v[182:185], v157 offset:19456
	ds_read_b128 v[194:197], v157 offset:20480
	ds_read_b128 v[206:209], v157 offset:21504
	ds_read_b128 v[210:213], v157 offset:22528
	ds_read_b128 v[214:217], v157 offset:23552
	global_load_lds_dwordx4 v[238:239], off
	v_lshl_add_u64 v[240:241], s[52:53], 0, v[130:131]
	s_mov_b32 m0, s59
	s_nop 0
	global_load_lds_dwordx4 v[240:241], off
	s_add_u32 s80, s50, 0x40000
	s_addc_u32 s81, s51, 0
	s_add_i32 s6, s6, s57
	v_lshl_add_u64 v[250:251], s[80:81], 0, v[140:141]
	s_mov_b32 m0, s6
	s_nop 0
	global_load_lds_dwordx4 v[250:251], off
	v_lshl_add_u64 v[250:251], s[80:81], 0, v[132:133]
	s_add_i32 m0, s6, 0x2000
	s_nop 0
	global_load_lds_dwordx4 v[250:251], off
	s_waitcnt vmcnt(24)
	s_cmp_lg_u32 s100, 0
	s_cbranch_scc1 .Lm4bp_295
	s_waitcnt vmcnt(8)
.Lm4bp_295:
	s_waitcnt lgkmcnt(0)
	s_mov_b32 s100, 0
	s_barrier
	s_setprio 1
	v_mfma_f32_16x16x32_bf16 v[60:63], v[146:149], v[170:173], 0
	v_mfma_f32_16x16x32_bf16 v[56:59], v[162:165], v[170:173], 0
	v_mfma_f32_16x16x32_bf16 v[52:55], v[146:149], v[178:181], 0
	v_mfma_f32_16x16x32_bf16 v[48:51], v[162:165], v[178:181], 0
	v_mfma_f32_16x16x32_bf16 v[44:47], v[146:149], v[194:197], 0
	v_mfma_f32_16x16x32_bf16 v[40:43], v[162:165], v[194:197], 0
	v_mfma_f32_16x16x32_bf16 v[36:39], v[146:149], v[210:213], 0
	v_mfma_f32_16x16x32_bf16 v[32:35], v[162:165], v[210:213], 0
	v_mfma_f32_16x16x32_bf16 v[60:63], v[158:161], v[174:177], v[60:63]
	v_mfma_f32_16x16x32_bf16 v[56:59], v[166:169], v[174:177], v[56:59]
	v_mfma_f32_16x16x32_bf16 v[52:55], v[158:161], v[182:185], v[52:55]
	v_mfma_f32_16x16x32_bf16 v[48:51], v[166:169], v[182:185], v[48:51]
	v_mfma_f32_16x16x32_bf16 v[44:47], v[158:161], v[206:209], v[44:47]
	v_mfma_f32_16x16x32_bf16 v[40:43], v[166:169], v[206:209], v[40:43]
	v_mfma_f32_16x16x32_bf16 v[36:39], v[158:161], v[214:217], v[36:39]
	v_mfma_f32_16x16x32_bf16 v[32:35], v[166:169], v[214:217], v[32:35]
	v_mfma_f32_16x16x32_bf16 v[28:31], v[218:221], v[170:173], 0
	v_mfma_f32_16x16x32_bf16 v[24:27], v[226:229], v[170:173], 0
	v_mfma_f32_16x16x32_bf16 v[20:23], v[218:221], v[178:181], 0
	v_mfma_f32_16x16x32_bf16 v[16:19], v[226:229], v[178:181], 0
	v_mfma_f32_16x16x32_bf16 v[12:15], v[218:221], v[194:197], 0
	v_mfma_f32_16x16x32_bf16 v[8:11], v[226:229], v[194:197], 0
	v_mfma_f32_16x16x32_bf16 v[4:7], v[218:221], v[210:213], 0
	v_mfma_f32_16x16x32_bf16 v[0:3], v[226:229], v[210:213], 0
	v_mfma_f32_16x16x32_bf16 v[28:31], v[222:225], v[174:177], v[28:31]
	v_mfma_f32_16x16x32_bf16 v[24:27], v[230:233], v[174:177], v[24:27]
	v_mfma_f32_16x16x32_bf16 v[20:23], v[222:225], v[182:185], v[20:23]
	v_mfma_f32_16x16x32_bf16 v[16:19], v[230:233], v[182:185], v[16:19]
	v_mfma_f32_16x16x32_bf16 v[12:15], v[222:225], v[206:209], v[12:15]
	v_mfma_f32_16x16x32_bf16 v[8:11], v[230:233], v[206:209], v[8:11]
	v_mfma_f32_16x16x32_bf16 v[4:7], v[222:225], v[214:217], v[4:7]
	v_mfma_f32_16x16x32_bf16 v[0:3], v[230:233], v[214:217], v[0:3]
	s_setprio 0
	s_barrier
	s_add_i32 s6, 0, 0x18000
	v_add_u32_e32 v166, s6, v154
	ds_read_b128 v[146:149], v166
	ds_read_b128 v[158:161], v166 offset:1024
	ds_read_b128 v[162:165], v166 offset:2048
	ds_read_b128 v[166:169], v166 offset:3072
	s_add_u32 s52, s52, 0x40000
	s_addc_u32 s53, s53, 0
	s_mov_b32 m0, s68
	v_lshl_add_u64 v[218:219], s[52:53], 0, v[128:129]
	ds_read_b128 v[170:173], v157 offset:32768
	ds_read_b128 v[174:177], v157 offset:33792
	ds_read_b128 v[178:181], v157 offset:34816
	ds_read_b128 v[182:185], v157 offset:35840
	ds_read_b128 v[194:197], v157 offset:36864
	ds_read_b128 v[206:209], v157 offset:37888
	ds_read_b128 v[210:213], v157 offset:38912
	ds_read_b128 v[214:217], v157 offset:39936
	global_load_lds_dwordx4 v[218:219], off
	v_lshl_add_u64 v[218:219], s[52:53], 0, v[130:131]
	s_mov_b32 m0, s69
	s_nop 0
	global_load_lds_dwordx4 v[218:219], off
	s_add_i32 s19, 0, 0x1c000
	v_add_u32_e32 v192, s19, v154
	ds_read_b128 v[218:221], v192
	ds_read_b128 v[222:225], v192 offset:1024
	ds_read_b128 v[226:229], v192 offset:2048
	ds_read_b128 v[230:233], v192 offset:3072
	s_waitcnt vmcnt(8)
	s_waitcnt lgkmcnt(0)
	s_barrier
	s_setprio 1
	v_mfma_f32_16x16x32_bf16 v[124:127], v[146:149], v[170:173], v[124:127]
	v_mfma_f32_16x16x32_bf16 v[120:123], v[162:165], v[170:173], v[120:123]
	v_mfma_f32_16x16x32_bf16 v[116:119], v[146:149], v[178:181], v[116:119]
	v_mfma_f32_16x16x32_bf16 v[112:115], v[162:165], v[178:181], v[112:115]
	v_mfma_f32_16x16x32_bf16 v[108:111], v[146:149], v[194:197], v[108:111]
	v_mfma_f32_16x16x32_bf16 v[104:107], v[162:165], v[194:197], v[104:107]
	v_mfma_f32_16x16x32_bf16 v[100:103], v[146:149], v[210:213], v[100:103]
	v_mfma_f32_16x16x32_bf16 v[96:99], v[162:165], v[210:213], v[96:99]
	v_mfma_f32_16x16x32_bf16 v[124:127], v[158:161], v[174:177], v[124:127]
	v_mfma_f32_16x16x32_bf16 v[120:123], v[166:169], v[174:177], v[120:123]
	v_mfma_f32_16x16x32_bf16 v[116:119], v[158:161], v[182:185], v[116:119]
	v_mfma_f32_16x16x32_bf16 v[112:115], v[166:169], v[182:185], v[112:115]
	v_mfma_f32_16x16x32_bf16 v[108:111], v[158:161], v[206:209], v[108:111]
	v_mfma_f32_16x16x32_bf16 v[104:107], v[166:169], v[206:209], v[104:107]
	v_mfma_f32_16x16x32_bf16 v[100:103], v[158:161], v[214:217], v[100:103]
	v_mfma_f32_16x16x32_bf16 v[96:99], v[166:169], v[214:217], v[96:99]
	v_mfma_f32_16x16x32_bf16 v[92:95], v[218:221], v[170:173], v[92:95]
	v_mfma_f32_16x16x32_bf16 v[88:91], v[226:229], v[170:173], v[88:91]
	v_mfma_f32_16x16x32_bf16 v[84:87], v[218:221], v[178:181], v[84:87]
	v_mfma_f32_16x16x32_bf16 v[80:83], v[226:229], v[178:181], v[80:83]
	v_mfma_f32_16x16x32_bf16 v[76:79], v[218:221], v[194:197], v[76:79]
	v_mfma_f32_16x16x32_bf16 v[72:75], v[226:229], v[194:197], v[72:75]
	v_mfma_f32_16x16x32_bf16 v[68:71], v[218:221], v[210:213], v[68:71]
	v_mfma_f32_16x16x32_bf16 v[64:67], v[226:229], v[210:213], v[64:67]
	v_mfma_f32_16x16x32_bf16 v[92:95], v[222:225], v[174:177], v[92:95]
	v_mfma_f32_16x16x32_bf16 v[88:91], v[230:233], v[174:177], v[88:91]
	v_mfma_f32_16x16x32_bf16 v[84:87], v[222:225], v[182:185], v[84:87]
	v_mfma_f32_16x16x32_bf16 v[80:83], v[230:233], v[182:185], v[80:83]
	v_mfma_f32_16x16x32_bf16 v[76:79], v[222:225], v[206:209], v[76:79]
	v_mfma_f32_16x16x32_bf16 v[72:75], v[230:233], v[206:209], v[72:75]
	v_mfma_f32_16x16x32_bf16 v[68:71], v[222:225], v[214:217], v[68:71]
	v_mfma_f32_16x16x32_bf16 v[64:67], v[230:233], v[214:217], v[64:67]
	s_setprio 0
	s_barrier
	s_add_i32 s6, s6, s57
	v_lshl_add_u64 v[234:235], v[234:235], 0, s[36:37]
	s_mov_b32 m0, s6
	s_nop 0
	global_load_lds_dwordx4 v[234:235], off
	v_lshl_add_u64 v[234:235], v[236:237], 0, s[36:37]
	s_add_i32 m0, s6, 0x2000
	s_nop 0
	global_load_lds_dwordx4 v[234:235], off
	s_mov_b32 m0, s70
	v_lshl_add_u64 v[234:235], v[238:239], 0, s[36:37]
	ds_read_b128 v[170:173], v157 offset:49152
	ds_read_b128 v[174:177], v157 offset:50176
	ds_read_b128 v[178:181], v157 offset:51200
	ds_read_b128 v[182:185], v157 offset:52224
	ds_read_b128 v[194:197], v157 offset:53248
	ds_read_b128 v[206:209], v157 offset:54272
	ds_read_b128 v[210:213], v157 offset:55296
	ds_read_b128 v[214:217], v157 offset:56320
	global_load_lds_dwordx4 v[234:235], off
	v_lshl_add_u64 v[234:235], v[240:241], 0, s[36:37]
	s_mov_b32 m0, s71
	s_nop 0
	global_load_lds_dwordx4 v[234:235], off
	s_add_u32 s50, s50, 0x40080
	s_addc_u32 s51, s51, 0
	s_add_i32 s6, s19, s57
	v_lshl_add_u64 v[250:251], s[50:51], 0, v[140:141]
	s_mov_b32 m0, s6
	s_nop 0
	global_load_lds_dwordx4 v[250:251], off
	v_lshl_add_u64 v[250:251], s[50:51], 0, v[132:133]
	s_add_i32 m0, s6, 0x2000
	s_nop 0
	global_load_lds_dwordx4 v[250:251], off
	s_waitcnt vmcnt(8)
	s_waitcnt lgkmcnt(0)
	s_barrier
	s_setprio 1
	v_mfma_f32_16x16x32_bf16 v[60:63], v[146:149], v[170:173], v[60:63]
	v_mfma_f32_16x16x32_bf16 v[56:59], v[162:165], v[170:173], v[56:59]
	v_mfma_f32_16x16x32_bf16 v[52:55], v[146:149], v[178:181], v[52:55]
	v_mfma_f32_16x16x32_bf16 v[48:51], v[162:165], v[178:181], v[48:51]
	v_mfma_f32_16x16x32_bf16 v[44:47], v[146:149], v[194:197], v[44:47]
	v_mfma_f32_16x16x32_bf16 v[40:43], v[162:165], v[194:197], v[40:43]
	v_mfma_f32_16x16x32_bf16 v[36:39], v[146:149], v[210:213], v[36:39]
	v_mfma_f32_16x16x32_bf16 v[32:35], v[162:165], v[210:213], v[32:35]
	v_mfma_f32_16x16x32_bf16 v[60:63], v[158:161], v[174:177], v[60:63]
	v_mfma_f32_16x16x32_bf16 v[56:59], v[166:169], v[174:177], v[56:59]
	v_mfma_f32_16x16x32_bf16 v[52:55], v[158:161], v[182:185], v[52:55]
	v_mfma_f32_16x16x32_bf16 v[48:51], v[166:169], v[182:185], v[48:51]
	v_mfma_f32_16x16x32_bf16 v[44:47], v[158:161], v[206:209], v[44:47]
	v_mfma_f32_16x16x32_bf16 v[40:43], v[166:169], v[206:209], v[40:43]
	v_mfma_f32_16x16x32_bf16 v[36:39], v[158:161], v[214:217], v[36:39]
	v_mfma_f32_16x16x32_bf16 v[32:35], v[166:169], v[214:217], v[32:35]
	v_mfma_f32_16x16x32_bf16 v[28:31], v[218:221], v[170:173], v[28:31]
	v_mfma_f32_16x16x32_bf16 v[24:27], v[226:229], v[170:173], v[24:27]
	v_mfma_f32_16x16x32_bf16 v[20:23], v[218:221], v[178:181], v[20:23]
	v_mfma_f32_16x16x32_bf16 v[16:19], v[226:229], v[178:181], v[16:19]
	v_mfma_f32_16x16x32_bf16 v[12:15], v[218:221], v[194:197], v[12:15]
	v_mfma_f32_16x16x32_bf16 v[8:11], v[226:229], v[194:197], v[8:11]
	v_mfma_f32_16x16x32_bf16 v[4:7], v[218:221], v[210:213], v[4:7]
	v_mfma_f32_16x16x32_bf16 v[0:3], v[226:229], v[210:213], v[0:3]
	v_mfma_f32_16x16x32_bf16 v[28:31], v[222:225], v[174:177], v[28:31]
	v_mfma_f32_16x16x32_bf16 v[24:27], v[230:233], v[174:177], v[24:27]
	v_mfma_f32_16x16x32_bf16 v[20:23], v[222:225], v[182:185], v[20:23]
	v_mfma_f32_16x16x32_bf16 v[16:19], v[230:233], v[182:185], v[16:19]
	v_mfma_f32_16x16x32_bf16 v[12:15], v[222:225], v[206:209], v[12:15]
	v_mfma_f32_16x16x32_bf16 v[8:11], v[230:233], v[206:209], v[8:11]
	v_mfma_f32_16x16x32_bf16 v[4:7], v[222:225], v[214:217], v[4:7]
	v_mfma_f32_16x16x32_bf16 v[0:3], v[230:233], v[214:217], v[0:3]
	s_setprio 0
	s_add_i32 s75, s75, 2
	s_add_u32 s48, s48, 0x100
	s_addc_u32 s49, s49, 0
	s_cmp_gt_u32 s75, 13
	s_barrier
.LBB0_295:
	s_add_u32 s6, s4, s48
	s_addc_u32 s19, s5, s49
	s_add_u32 s6, s6, 0x100
	s_addc_u32 s19, s19, 0
	s_add_u32 s23, s10, s48
	s_addc_u32 s50, s11, s49
	s_add_i32 s80, 0, 0x10000
	v_add_u32_e32 v166, s80, v154
	ds_read_b128 v[146:149], v166
	ds_read_b128 v[158:161], v166 offset:1024
	ds_read_b128 v[162:165], v166 offset:2048
	ds_read_b128 v[166:169], v166 offset:3072
	s_cmpk_eq_i32 s48, 0x700
	s_cselect_b32 s53, s12, s19
	s_cselect_b32 s52, s29, s6
	s_cselect_b32 s51, s31, s50
	s_cselect_b32 s50, s35, s23
	v_lshl_add_u64 v[218:219], v[150:151], 0, s[48:49]
	s_add_i32 m0, s58, 0xc000
	ds_read_b128 v[170:173], v157
	ds_read_b128 v[174:177], v157 offset:1024
	ds_read_b128 v[178:181], v157 offset:2048
	ds_read_b128 v[182:185], v157 offset:3072
	ds_read_b128 v[194:197], v157 offset:4096
	ds_read_b128 v[206:209], v157 offset:5120
	ds_read_b128 v[210:213], v157 offset:6144
	ds_read_b128 v[214:217], v157 offset:7168
	global_load_lds_dwordx4 v[218:219], off
	v_lshl_add_u64 v[218:219], v[152:153], 0, s[48:49]
	s_add_i32 m0, s58, 0xe000
	s_nop 0
	global_load_lds_dwordx4 v[218:219], off
	s_add_i32 s6, 0, 0x14000
	v_add_u32_e32 v192, s6, v154
	ds_read_b128 v[218:221], v192
	ds_read_b128 v[222:225], v192 offset:1024
	ds_read_b128 v[226:229], v192 offset:2048
	ds_read_b128 v[230:233], v192 offset:3072
	s_waitcnt vmcnt(8)
	s_waitcnt lgkmcnt(0)
	s_barrier
	s_setprio 1
	v_mfma_f32_16x16x32_bf16 v[124:127], v[146:149], v[170:173], v[124:127]
	v_mfma_f32_16x16x32_bf16 v[120:123], v[162:165], v[170:173], v[120:123]
	v_mfma_f32_16x16x32_bf16 v[116:119], v[146:149], v[178:181], v[116:119]
	v_mfma_f32_16x16x32_bf16 v[112:115], v[162:165], v[178:181], v[112:115]
	v_mfma_f32_16x16x32_bf16 v[108:111], v[146:149], v[194:197], v[108:111]
	v_mfma_f32_16x16x32_bf16 v[104:107], v[162:165], v[194:197], v[104:107]
	v_mfma_f32_16x16x32_bf16 v[100:103], v[146:149], v[210:213], v[100:103]
	v_mfma_f32_16x16x32_bf16 v[96:99], v[162:165], v[210:213], v[96:99]
	v_mfma_f32_16x16x32_bf16 v[124:127], v[158:161], v[174:177], v[124:127]
	v_mfma_f32_16x16x32_bf16 v[120:123], v[166:169], v[174:177], v[120:123]
	v_mfma_f32_16x16x32_bf16 v[116:119], v[158:161], v[182:185], v[116:119]
	v_mfma_f32_16x16x32_bf16 v[112:115], v[166:169], v[182:185], v[112:115]
	v_mfma_f32_16x16x32_bf16 v[108:111], v[158:161], v[206:209], v[108:111]
	v_mfma_f32_16x16x32_bf16 v[104:107], v[166:169], v[206:209], v[104:107]
	v_mfma_f32_16x16x32_bf16 v[100:103], v[158:161], v[214:217], v[100:103]
	v_mfma_f32_16x16x32_bf16 v[96:99], v[166:169], v[214:217], v[96:99]
	v_mfma_f32_16x16x32_bf16 v[92:95], v[218:221], v[170:173], v[92:95]
	v_mfma_f32_16x16x32_bf16 v[88:91], v[226:229], v[170:173], v[88:91]
	v_mfma_f32_16x16x32_bf16 v[84:87], v[218:221], v[178:181], v[84:87]
	v_mfma_f32_16x16x32_bf16 v[80:83], v[226:229], v[178:181], v[80:83]
	v_mfma_f32_16x16x32_bf16 v[76:79], v[218:221], v[194:197], v[76:79]
	v_mfma_f32_16x16x32_bf16 v[72:75], v[226:229], v[194:197], v[72:75]
	v_mfma_f32_16x16x32_bf16 v[68:71], v[218:221], v[210:213], v[68:71]
	v_mfma_f32_16x16x32_bf16 v[64:67], v[226:229], v[210:213], v[64:67]
	v_mfma_f32_16x16x32_bf16 v[92:95], v[222:225], v[174:177], v[92:95]
	v_mfma_f32_16x16x32_bf16 v[88:91], v[230:233], v[174:177], v[88:91]
	v_mfma_f32_16x16x32_bf16 v[84:87], v[222:225], v[182:185], v[84:87]
	v_mfma_f32_16x16x32_bf16 v[80:83], v[230:233], v[182:185], v[80:83]
	v_mfma_f32_16x16x32_bf16 v[76:79], v[222:225], v[206:209], v[76:79]
	v_mfma_f32_16x16x32_bf16 v[72:75], v[230:233], v[206:209], v[72:75]
	v_mfma_f32_16x16x32_bf16 v[68:71], v[222:225], v[214:217], v[68:71]
	v_mfma_f32_16x16x32_bf16 v[64:67], v[230:233], v[214:217], v[64:67]
	s_setprio 0
	s_barrier
	s_add_i32 s19, s80, s57
	v_lshl_add_u64 v[234:235], s[50:51], 0, v[140:141]
	s_mov_b32 m0, s19
	s_nop 0
	global_load_lds_dwordx4 v[234:235], off
	v_lshl_add_u64 v[236:237], s[50:51], 0, v[132:133]
	s_add_i32 m0, s19, 0x2000
	s_nop 0
	global_load_lds_dwordx4 v[236:237], off
	s_mov_b32 m0, s58
	v_lshl_add_u64 v[238:239], s[52:53], 0, v[128:129]
	ds_read_b128 v[170:173], v157 offset:16384
	ds_read_b128 v[174:177], v157 offset:17408
	ds_read_b128 v[178:181], v157 offset:18432
	ds_read_b128 v[182:185], v157 offset:19456
	ds_read_b128 v[194:197], v157 offset:20480
	ds_read_b128 v[206:209], v157 offset:21504
	ds_read_b128 v[210:213], v157 offset:22528
	ds_read_b128 v[214:217], v157 offset:23552
	global_load_lds_dwordx4 v[238:239], off
	v_lshl_add_u64 v[240:241], s[52:53], 0, v[130:131]
	s_mov_b32 m0, s59
	s_nop 0
	global_load_lds_dwordx4 v[240:241], off
	s_add_u32 s80, s50, 0x40000
	s_addc_u32 s81, s51, 0
	s_add_i32 s6, s6, s57
	v_lshl_add_u64 v[250:251], s[80:81], 0, v[140:141]
	s_mov_b32 m0, s6
	s_nop 0
	global_load_lds_dwordx4 v[250:251], off
	v_lshl_add_u64 v[250:251], s[80:81], 0, v[132:133]
	s_add_i32 m0, s6, 0x2000
	s_nop 0
	global_load_lds_dwordx4 v[250:251], off
	s_waitcnt vmcnt(8)
	s_waitcnt lgkmcnt(0)
	s_barrier
	s_setprio 1
	v_mfma_f32_16x16x32_bf16 v[60:63], v[146:149], v[170:173], v[60:63]
	v_mfma_f32_16x16x32_bf16 v[56:59], v[162:165], v[170:173], v[56:59]
	v_mfma_f32_16x16x32_bf16 v[52:55], v[146:149], v[178:181], v[52:55]
	v_mfma_f32_16x16x32_bf16 v[48:51], v[162:165], v[178:181], v[48:51]
	v_mfma_f32_16x16x32_bf16 v[44:47], v[146:149], v[194:197], v[44:47]
	v_mfma_f32_16x16x32_bf16 v[40:43], v[162:165], v[194:197], v[40:43]
	v_mfma_f32_16x16x32_bf16 v[36:39], v[146:149], v[210:213], v[36:39]
	v_mfma_f32_16x16x32_bf16 v[32:35], v[162:165], v[210:213], v[32:35]
	v_mfma_f32_16x16x32_bf16 v[60:63], v[158:161], v[174:177], v[60:63]
	v_mfma_f32_16x16x32_bf16 v[56:59], v[166:169], v[174:177], v[56:59]
	v_mfma_f32_16x16x32_bf16 v[52:55], v[158:161], v[182:185], v[52:55]
	v_mfma_f32_16x16x32_bf16 v[48:51], v[166:169], v[182:185], v[48:51]
	v_mfma_f32_16x16x32_bf16 v[44:47], v[158:161], v[206:209], v[44:47]
	v_mfma_f32_16x16x32_bf16 v[40:43], v[166:169], v[206:209], v[40:43]
	v_mfma_f32_16x16x32_bf16 v[36:39], v[158:161], v[214:217], v[36:39]
	v_mfma_f32_16x16x32_bf16 v[32:35], v[166:169], v[214:217], v[32:35]
	v_mfma_f32_16x16x32_bf16 v[28:31], v[218:221], v[170:173], v[28:31]
	v_mfma_f32_16x16x32_bf16 v[24:27], v[226:229], v[170:173], v[24:27]
	v_mfma_f32_16x16x32_bf16 v[20:23], v[218:221], v[178:181], v[20:23]
	v_mfma_f32_16x16x32_bf16 v[16:19], v[226:229], v[178:181], v[16:19]
	v_mfma_f32_16x16x32_bf16 v[12:15], v[218:221], v[194:197], v[12:15]
	v_mfma_f32_16x16x32_bf16 v[8:11], v[226:229], v[194:197], v[8:11]
	v_mfma_f32_16x16x32_bf16 v[4:7], v[218:221], v[210:213], v[4:7]
	v_mfma_f32_16x16x32_bf16 v[0:3], v[226:229], v[210:213], v[0:3]
	v_mfma_f32_16x16x32_bf16 v[28:31], v[222:225], v[174:177], v[28:31]
	v_mfma_f32_16x16x32_bf16 v[24:27], v[230:233], v[174:177], v[24:27]
	v_mfma_f32_16x16x32_bf16 v[20:23], v[222:225], v[182:185], v[20:23]
	v_mfma_f32_16x16x32_bf16 v[16:19], v[230:233], v[182:185], v[16:19]
	v_mfma_f32_16x16x32_bf16 v[12:15], v[222:225], v[206:209], v[12:15]
	v_mfma_f32_16x16x32_bf16 v[8:11], v[230:233], v[206:209], v[8:11]
	v_mfma_f32_16x16x32_bf16 v[4:7], v[222:225], v[214:217], v[4:7]
	v_mfma_f32_16x16x32_bf16 v[0:3], v[230:233], v[214:217], v[0:3]
	s_setprio 0
	s_barrier
	s_add_i32 s6, 0, 0x18000
	v_add_u32_e32 v166, s6, v154
	ds_read_b128 v[146:149], v166
	ds_read_b128 v[158:161], v166 offset:1024
	ds_read_b128 v[162:165], v166 offset:2048
	ds_read_b128 v[166:169], v166 offset:3072
	s_add_u32 s52, s52, 0x40000
	s_addc_u32 s53, s53, 0
	s_mov_b32 m0, s68
	v_lshl_add_u64 v[218:219], s[52:53], 0, v[128:129]
	ds_read_b128 v[170:173], v157 offset:32768
	ds_read_b128 v[174:177], v157 offset:33792
	ds_read_b128 v[178:181], v157 offset:34816
	ds_read_b128 v[182:185], v157 offset:35840
	ds_read_b128 v[194:197], v157 offset:36864
	ds_read_b128 v[206:209], v157 offset:37888
	ds_read_b128 v[210:213], v157 offset:38912
	ds_read_b128 v[214:217], v157 offset:39936
	global_load_lds_dwordx4 v[218:219], off
	v_lshl_add_u64 v[218:219], s[52:53], 0, v[130:131]
	s_mov_b32 m0, s69
	s_nop 0
	global_load_lds_dwordx4 v[218:219], off
	s_add_i32 s19, 0, 0x1c000
	v_add_u32_e32 v192, s19, v154
	ds_read_b128 v[218:221], v192
	ds_read_b128 v[222:225], v192 offset:1024
	ds_read_b128 v[226:229], v192 offset:2048
	ds_read_b128 v[230:233], v192 offset:3072
	s_waitcnt vmcnt(8)
	s_waitcnt lgkmcnt(0)
	s_barrier
	s_setprio 1
	v_mfma_f32_16x16x32_bf16 v[124:127], v[146:149], v[170:173], v[124:127]
	v_mfma_f32_16x16x32_bf16 v[120:123], v[162:165], v[170:173], v[120:123]
	v_mfma_f32_16x16x32_bf16 v[116:119], v[146:149], v[178:181], v[116:119]
	v_mfma_f32_16x16x32_bf16 v[112:115], v[162:165], v[178:181], v[112:115]
	v_mfma_f32_16x16x32_bf16 v[108:111], v[146:149], v[194:197], v[108:111]
	v_mfma_f32_16x16x32_bf16 v[104:107], v[162:165], v[194:197], v[104:107]
	v_mfma_f32_16x16x32_bf16 v[100:103], v[146:149], v[210:213], v[100:103]
	v_mfma_f32_16x16x32_bf16 v[96:99], v[162:165], v[210:213], v[96:99]
	v_mfma_f32_16x16x32_bf16 v[124:127], v[158:161], v[174:177], v[124:127]
	v_mfma_f32_16x16x32_bf16 v[120:123], v[166:169], v[174:177], v[120:123]
	v_mfma_f32_16x16x32_bf16 v[116:119], v[158:161], v[182:185], v[116:119]
	v_mfma_f32_16x16x32_bf16 v[112:115], v[166:169], v[182:185], v[112:115]
	v_mfma_f32_16x16x32_bf16 v[108:111], v[158:161], v[206:209], v[108:111]
	v_mfma_f32_16x16x32_bf16 v[104:107], v[166:169], v[206:209], v[104:107]
	v_mfma_f32_16x16x32_bf16 v[100:103], v[158:161], v[214:217], v[100:103]
	v_mfma_f32_16x16x32_bf16 v[96:99], v[166:169], v[214:217], v[96:99]
	v_mfma_f32_16x16x32_bf16 v[92:95], v[218:221], v[170:173], v[92:95]
	v_mfma_f32_16x16x32_bf16 v[88:91], v[226:229], v[170:173], v[88:91]
	v_mfma_f32_16x16x32_bf16 v[84:87], v[218:221], v[178:181], v[84:87]
	v_mfma_f32_16x16x32_bf16 v[80:83], v[226:229], v[178:181], v[80:83]
	v_mfma_f32_16x16x32_bf16 v[76:79], v[218:221], v[194:197], v[76:79]
	v_mfma_f32_16x16x32_bf16 v[72:75], v[226:229], v[194:197], v[72:75]
	v_mfma_f32_16x16x32_bf16 v[68:71], v[218:221], v[210:213], v[68:71]
	v_mfma_f32_16x16x32_bf16 v[64:67], v[226:229], v[210:213], v[64:67]
	v_mfma_f32_16x16x32_bf16 v[92:95], v[222:225], v[174:177], v[92:95]
	v_mfma_f32_16x16x32_bf16 v[88:91], v[230:233], v[174:177], v[88:91]
	v_mfma_f32_16x16x32_bf16 v[84:87], v[222:225], v[182:185], v[84:87]
	v_mfma_f32_16x16x32_bf16 v[80:83], v[230:233], v[182:185], v[80:83]
	v_mfma_f32_16x16x32_bf16 v[76:79], v[222:225], v[206:209], v[76:79]
	v_mfma_f32_16x16x32_bf16 v[72:75], v[230:233], v[206:209], v[72:75]
	v_mfma_f32_16x16x32_bf16 v[68:71], v[222:225], v[214:217], v[68:71]
	v_mfma_f32_16x16x32_bf16 v[64:67], v[230:233], v[214:217], v[64:67]
	s_setprio 0
	s_barrier
	s_add_i32 s6, s6, s57
	v_lshl_add_u64 v[234:235], v[234:235], 0, s[36:37]
	s_mov_b32 m0, s6
	s_nop 0
	global_load_lds_dwordx4 v[234:235], off
	v_lshl_add_u64 v[234:235], v[236:237], 0, s[36:37]
	s_add_i32 m0, s6, 0x2000
	s_nop 0
	global_load_lds_dwordx4 v[234:235], off
	s_mov_b32 m0, s70
	v_lshl_add_u64 v[234:235], v[238:239], 0, s[36:37]
	ds_read_b128 v[170:173], v157 offset:49152
	ds_read_b128 v[174:177], v157 offset:50176
	ds_read_b128 v[178:181], v157 offset:51200
	ds_read_b128 v[182:185], v157 offset:52224
	ds_read_b128 v[194:197], v157 offset:53248
	ds_read_b128 v[206:209], v157 offset:54272
	ds_read_b128 v[210:213], v157 offset:55296
	ds_read_b128 v[214:217], v157 offset:56320
	global_load_lds_dwordx4 v[234:235], off
	v_lshl_add_u64 v[234:235], v[240:241], 0, s[36:37]
	s_mov_b32 m0, s71
	s_nop 0
	global_load_lds_dwordx4 v[234:235], off
	s_add_u32 s50, s50, 0x40080
	s_addc_u32 s51, s51, 0
	s_add_i32 s6, s19, s57
	v_lshl_add_u64 v[250:251], s[50:51], 0, v[140:141]
	s_mov_b32 m0, s6
	s_nop 0
	global_load_lds_dwordx4 v[250:251], off
	v_lshl_add_u64 v[250:251], s[50:51], 0, v[132:133]
	s_add_i32 m0, s6, 0x2000
	s_nop 0
	global_load_lds_dwordx4 v[250:251], off
	s_waitcnt vmcnt(8)
	s_waitcnt lgkmcnt(0)
	s_barrier
	s_setprio 1
	v_mfma_f32_16x16x32_bf16 v[60:63], v[146:149], v[170:173], v[60:63]
	v_mfma_f32_16x16x32_bf16 v[56:59], v[162:165], v[170:173], v[56:59]
	v_mfma_f32_16x16x32_bf16 v[52:55], v[146:149], v[178:181], v[52:55]
	v_mfma_f32_16x16x32_bf16 v[48:51], v[162:165], v[178:181], v[48:51]
	v_mfma_f32_16x16x32_bf16 v[44:47], v[146:149], v[194:197], v[44:47]
	v_mfma_f32_16x16x32_bf16 v[40:43], v[162:165], v[194:197], v[40:43]
	v_mfma_f32_16x16x32_bf16 v[36:39], v[146:149], v[210:213], v[36:39]
	v_mfma_f32_16x16x32_bf16 v[32:35], v[162:165], v[210:213], v[32:35]
	v_mfma_f32_16x16x32_bf16 v[60:63], v[158:161], v[174:177], v[60:63]
	v_mfma_f32_16x16x32_bf16 v[56:59], v[166:169], v[174:177], v[56:59]
	v_mfma_f32_16x16x32_bf16 v[52:55], v[158:161], v[182:185], v[52:55]
	v_mfma_f32_16x16x32_bf16 v[48:51], v[166:169], v[182:185], v[48:51]
	v_mfma_f32_16x16x32_bf16 v[44:47], v[158:161], v[206:209], v[44:47]
	v_mfma_f32_16x16x32_bf16 v[40:43], v[166:169], v[206:209], v[40:43]
	v_mfma_f32_16x16x32_bf16 v[36:39], v[158:161], v[214:217], v[36:39]
	v_mfma_f32_16x16x32_bf16 v[32:35], v[166:169], v[214:217], v[32:35]
	v_mfma_f32_16x16x32_bf16 v[28:31], v[218:221], v[170:173], v[28:31]
	v_mfma_f32_16x16x32_bf16 v[24:27], v[226:229], v[170:173], v[24:27]
	v_mfma_f32_16x16x32_bf16 v[20:23], v[218:221], v[178:181], v[20:23]
	v_mfma_f32_16x16x32_bf16 v[16:19], v[226:229], v[178:181], v[16:19]
	v_mfma_f32_16x16x32_bf16 v[12:15], v[218:221], v[194:197], v[12:15]
	v_mfma_f32_16x16x32_bf16 v[8:11], v[226:229], v[194:197], v[8:11]
	v_mfma_f32_16x16x32_bf16 v[4:7], v[218:221], v[210:213], v[4:7]
	v_mfma_f32_16x16x32_bf16 v[0:3], v[226:229], v[210:213], v[0:3]
	v_mfma_f32_16x16x32_bf16 v[28:31], v[222:225], v[174:177], v[28:31]
	v_mfma_f32_16x16x32_bf16 v[24:27], v[230:233], v[174:177], v[24:27]
	v_mfma_f32_16x16x32_bf16 v[20:23], v[222:225], v[182:185], v[20:23]
	v_mfma_f32_16x16x32_bf16 v[16:19], v[230:233], v[182:185], v[16:19]
	v_mfma_f32_16x16x32_bf16 v[12:15], v[222:225], v[206:209], v[12:15]
	v_mfma_f32_16x16x32_bf16 v[8:11], v[230:233], v[206:209], v[8:11]
	v_mfma_f32_16x16x32_bf16 v[4:7], v[222:225], v[214:217], v[4:7]
	v_mfma_f32_16x16x32_bf16 v[0:3], v[230:233], v[214:217], v[0:3]
	s_setprio 0
	s_add_i32 s75, s75, 2
	s_add_u32 s48, s48, 0x100
	s_addc_u32 s49, s49, 0
	s_cmp_gt_u32 s75, 13
	s_barrier
	s_cbranch_scc0 .LBB0_295
	s_mov_b32 s100, 1
	s_add_u32 s48, s10, 0xffffff00
	v_lshl_add_u32 v166, s73, 10, v155
	s_addc_u32 s49, s11, -1
	s_ashr_i32 s29, s28, 31
	v_lshl_or_b32 v146, s72, 8, v156
	ds_read2_b32 v[158:159], v166 offset1:16
	s_lshl_b64 s[10:11], s[28:29], 8
	v_ashrrev_i32_e32 v147, 31, v146
	v_lshl_add_u64 v[148:149], s[10:11], 0, v[134:135]
	v_lshl_add_u64 v[146:147], v[146:147], 1, s[26:27]
	v_mad_u64_u32 v[150:151], s[10:11], v148, s13, v[146:147]
	v_mov_b32_e32 v146, v151
	v_mad_u64_u32 v[152:153], s[10:11], v149, s13, v[146:147]
	s_waitcnt lgkmcnt(0)
	v_pk_mul_f32 v[148:149], v[126:127], v[158:159] op_sel_hi:[1,0]
	v_pk_mul_f32 v[146:147], v[124:125], v[158:159] op_sel_hi:[1,0]
	v_pk_mul_f32 v[160:161], v[122:123], v[158:159] op_sel_hi:[1,0]
	v_pk_mul_f32 v[162:163], v[120:121], v[158:159] op_sel_hi:[1,0]
	v_mov_b32_e32 v151, v152
	v_cvt_pk_bf16_f32 v146, v146, v147
	v_cvt_pk_bf16_f32 v147, v148, v149
	v_cvt_pk_bf16_f32 v148, v162, v163
	v_cvt_pk_bf16_f32 v149, v160, v161
	global_store_dwordx4 v[150:151], v[146:149], off
	v_pk_mul_f32 v[160:161], v[90:91], v[158:159] op_sel_hi:[1,0]
	v_pk_mul_f32 v[162:163], v[88:89], v[158:159] op_sel_hi:[1,0]
	v_pk_mul_f32 v[148:149], v[94:95], v[158:159] op_sel_hi:[1,0]
	v_pk_mul_f32 v[146:147], v[92:93], v[158:159] op_sel_hi:[1,0]
	v_mov_b32_e32 v158, v159
	v_cvt_pk_bf16_f32 v146, v146, v147
	v_cvt_pk_bf16_f32 v147, v148, v149
	v_cvt_pk_bf16_f32 v148, v162, v163
	v_cvt_pk_bf16_f32 v149, v160, v161
	global_store_dwordx4 v[150:151], v[146:149], off offset:256
	v_pk_mul_f32 v[160:161], v[114:115], v[158:159] op_sel_hi:[1,0]
	s_mov_b32 s6, 0x1e000
	v_pk_mul_f32 v[148:149], v[118:119], v[158:159] op_sel_hi:[1,0]
	v_pk_mul_f32 v[146:147], v[116:117], v[158:159] op_sel_hi:[1,0]
	ds_read2_b32 v[164:165], v166 offset0:32 offset1:48
	v_pk_mul_f32 v[162:163], v[112:113], v[158:159] op_sel_hi:[1,0]
	v_cvt_pk_bf16_f32 v146, v146, v147
	v_cvt_pk_bf16_f32 v147, v148, v149
	v_cvt_pk_bf16_f32 v149, v160, v161
	v_add_co_u32_e32 v160, vcc, s6, v150
	v_cvt_pk_bf16_f32 v148, v162, v163
	s_nop 0
	v_addc_co_u32_e32 v161, vcc, 0, v152, vcc
	global_store_dwordx4 v[160:161], v[146:149], off
	v_pk_mul_f32 v[162:163], v[82:83], v[158:159] op_sel_hi:[1,0]
	s_mov_b32 s6, 0x3c000
	v_pk_mul_f32 v[148:149], v[86:87], v[158:159] op_sel_hi:[1,0]
	v_pk_mul_f32 v[146:147], v[84:85], v[158:159] op_sel_hi:[1,0]
	v_pk_mul_f32 v[158:159], v[80:81], v[158:159] op_sel_hi:[1,0]
	v_cvt_pk_bf16_f32 v146, v146, v147
	v_cvt_pk_bf16_f32 v147, v148, v149
	v_cvt_pk_bf16_f32 v148, v158, v159
	v_cvt_pk_bf16_f32 v149, v162, v163
	global_store_dwordx4 v[160:161], v[146:149], off offset:256
	s_waitcnt lgkmcnt(0)
	v_pk_mul_f32 v[158:159], v[106:107], v[164:165] op_sel_hi:[1,0]
	v_pk_mul_f32 v[160:161], v[104:105], v[164:165] op_sel_hi:[1,0]
	v_pk_mul_f32 v[148:149], v[110:111], v[164:165] op_sel_hi:[1,0]
	v_pk_mul_f32 v[146:147], v[108:109], v[164:165] op_sel_hi:[1,0]
	v_pk_mul_f32 v[162:163], v[72:73], v[164:165] op_sel_hi:[1,0]
	v_cvt_pk_bf16_f32 v146, v146, v147
	v_cvt_pk_bf16_f32 v147, v148, v149
	v_cvt_pk_bf16_f32 v149, v158, v159
	v_add_co_u32_e32 v158, vcc, s6, v150
	v_cvt_pk_bf16_f32 v148, v160, v161
	s_nop 0
	v_addc_co_u32_e32 v159, vcc, 0, v152, vcc
	global_store_dwordx4 v[158:159], v[146:149], off
	v_pk_mul_f32 v[160:161], v[74:75], v[164:165] op_sel_hi:[1,0]
	s_mov_b32 s6, 0x5a000
	v_pk_mul_f32 v[148:149], v[78:79], v[164:165] op_sel_hi:[1,0]
	v_pk_mul_f32 v[146:147], v[76:77], v[164:165] op_sel_hi:[1,0]
	s_nop 0
	v_cvt_pk_bf16_f32 v146, v146, v147
	v_cvt_pk_bf16_f32 v147, v148, v149
	v_cvt_pk_bf16_f32 v148, v162, v163
	v_cvt_pk_bf16_f32 v149, v160, v161
	global_store_dwordx4 v[158:159], v[146:149], off offset:256
	v_mov_b32_e32 v158, v165
	v_pk_mul_f32 v[160:161], v[98:99], v[158:159] op_sel_hi:[1,0]
	v_pk_mul_f32 v[148:149], v[102:103], v[158:159] op_sel_hi:[1,0]
	v_pk_mul_f32 v[146:147], v[100:101], v[158:159] op_sel_hi:[1,0]
	ds_read2_b32 v[164:165], v166 offset0:128 offset1:144
	v_pk_mul_f32 v[162:163], v[96:97], v[158:159] op_sel_hi:[1,0]
	v_cvt_pk_bf16_f32 v146, v146, v147
	v_cvt_pk_bf16_f32 v147, v148, v149
	v_cvt_pk_bf16_f32 v149, v160, v161
	v_add_co_u32_e32 v160, vcc, s6, v150
	v_cvt_pk_bf16_f32 v148, v162, v163
	s_nop 0
	v_addc_co_u32_e32 v161, vcc, 0, v152, vcc
	global_store_dwordx4 v[160:161], v[146:149], off
	v_pk_mul_f32 v[162:163], v[66:67], v[158:159] op_sel_hi:[1,0]
	s_mov_b32 s6, 0xf0000
	v_pk_mul_f32 v[148:149], v[70:71], v[158:159] op_sel_hi:[1,0]
	v_pk_mul_f32 v[146:147], v[68:69], v[158:159] op_sel_hi:[1,0]
	v_pk_mul_f32 v[158:159], v[64:65], v[158:159] op_sel_hi:[1,0]
	v_cvt_pk_bf16_f32 v146, v146, v147
	v_cvt_pk_bf16_f32 v147, v148, v149
	v_cvt_pk_bf16_f32 v148, v158, v159
	v_cvt_pk_bf16_f32 v149, v162, v163
	global_store_dwordx4 v[160:161], v[146:149], off offset:256
	s_waitcnt lgkmcnt(0)
	v_pk_mul_f32 v[158:159], v[58:59], v[164:165] op_sel_hi:[1,0]
	v_pk_mul_f32 v[160:161], v[56:57], v[164:165] op_sel_hi:[1,0]
	v_pk_mul_f32 v[148:149], v[62:63], v[164:165] op_sel_hi:[1,0]
	v_pk_mul_f32 v[146:147], v[60:61], v[164:165] op_sel_hi:[1,0]
	v_pk_mul_f32 v[162:163], v[24:25], v[164:165] op_sel_hi:[1,0]
	v_cvt_pk_bf16_f32 v146, v146, v147
	v_cvt_pk_bf16_f32 v147, v148, v149
	v_cvt_pk_bf16_f32 v149, v158, v159
	v_add_co_u32_e32 v158, vcc, s6, v150
	v_cvt_pk_bf16_f32 v148, v160, v161
	s_nop 0
	v_addc_co_u32_e32 v159, vcc, 0, v152, vcc
	global_store_dwordx4 v[158:159], v[146:149], off
	v_pk_mul_f32 v[160:161], v[26:27], v[164:165] op_sel_hi:[1,0]
	s_mov_b32 s6, 0x10e000
	v_pk_mul_f32 v[148:149], v[30:31], v[164:165] op_sel_hi:[1,0]
	v_pk_mul_f32 v[146:147], v[28:29], v[164:165] op_sel_hi:[1,0]
	s_nop 0
	v_cvt_pk_bf16_f32 v146, v146, v147
	v_cvt_pk_bf16_f32 v147, v148, v149
	v_cvt_pk_bf16_f32 v148, v162, v163
	v_cvt_pk_bf16_f32 v149, v160, v161
	global_store_dwordx4 v[158:159], v[146:149], off offset:256
	v_mov_b32_e32 v158, v165
	v_pk_mul_f32 v[160:161], v[50:51], v[158:159] op_sel_hi:[1,0]
	v_pk_mul_f32 v[148:149], v[54:55], v[158:159] op_sel_hi:[1,0]
	v_pk_mul_f32 v[146:147], v[52:53], v[158:159] op_sel_hi:[1,0]
	ds_read2_b32 v[164:165], v166 offset0:160 offset1:176
	v_pk_mul_f32 v[162:163], v[48:49], v[158:159] op_sel_hi:[1,0]
	v_cvt_pk_bf16_f32 v146, v146, v147
	v_cvt_pk_bf16_f32 v147, v148, v149
	v_cvt_pk_bf16_f32 v149, v160, v161
	v_add_co_u32_e32 v160, vcc, s6, v150
	v_cvt_pk_bf16_f32 v148, v162, v163
	s_nop 0
	v_addc_co_u32_e32 v161, vcc, 0, v152, vcc
	global_store_dwordx4 v[160:161], v[146:149], off
	v_pk_mul_f32 v[162:163], v[18:19], v[158:159] op_sel_hi:[1,0]
	s_mov_b32 s6, 0x12c000
	v_pk_mul_f32 v[148:149], v[22:23], v[158:159] op_sel_hi:[1,0]
	v_pk_mul_f32 v[146:147], v[20:21], v[158:159] op_sel_hi:[1,0]
	v_pk_mul_f32 v[158:159], v[16:17], v[158:159] op_sel_hi:[1,0]
	v_cvt_pk_bf16_f32 v146, v146, v147
	v_cvt_pk_bf16_f32 v147, v148, v149
	v_cvt_pk_bf16_f32 v148, v158, v159
	v_cvt_pk_bf16_f32 v149, v162, v163
	global_store_dwordx4 v[160:161], v[146:149], off offset:256
	s_waitcnt lgkmcnt(0)
	v_pk_mul_f32 v[158:159], v[42:43], v[164:165] op_sel_hi:[1,0]
	v_pk_mul_f32 v[160:161], v[40:41], v[164:165] op_sel_hi:[1,0]
	v_pk_mul_f32 v[148:149], v[46:47], v[164:165] op_sel_hi:[1,0]
	v_pk_mul_f32 v[146:147], v[44:45], v[164:165] op_sel_hi:[1,0]
	v_pk_mul_f32 v[162:163], v[8:9], v[164:165] op_sel_hi:[1,0]
	v_cvt_pk_bf16_f32 v146, v146, v147
	v_cvt_pk_bf16_f32 v147, v148, v149
	v_cvt_pk_bf16_f32 v149, v158, v159
	v_add_co_u32_e32 v158, vcc, s6, v150
	v_cvt_pk_bf16_f32 v148, v160, v161
	s_nop 0
	v_addc_co_u32_e32 v159, vcc, 0, v152, vcc
	global_store_dwordx4 v[158:159], v[146:149], off
	v_pk_mul_f32 v[160:161], v[10:11], v[164:165] op_sel_hi:[1,0]
	s_mov_b32 s6, 0x14a000
	v_pk_mul_f32 v[148:149], v[14:15], v[164:165] op_sel_hi:[1,0]
	v_pk_mul_f32 v[146:147], v[12:13], v[164:165] op_sel_hi:[1,0]
	v_add_co_u32_e32 v150, vcc, s6, v150
	v_cvt_pk_bf16_f32 v146, v146, v147
	v_cvt_pk_bf16_f32 v147, v148, v149
	v_cvt_pk_bf16_f32 v148, v162, v163
	v_cvt_pk_bf16_f32 v149, v160, v161
	global_store_dwordx4 v[158:159], v[146:149], off offset:256
	v_mov_b32_e32 v158, v165
	v_pk_mul_f32 v[160:161], v[34:35], v[158:159] op_sel_hi:[1,0]
	v_pk_mul_f32 v[148:149], v[38:39], v[158:159] op_sel_hi:[1,0]
	v_pk_mul_f32 v[146:147], v[36:37], v[158:159] op_sel_hi:[1,0]
	v_pk_mul_f32 v[162:163], v[32:33], v[158:159] op_sel_hi:[1,0]
	v_cvt_pk_bf16_f32 v146, v146, v147
	v_cvt_pk_bf16_f32 v147, v148, v149
	v_cvt_pk_bf16_f32 v148, v162, v163
	v_cvt_pk_bf16_f32 v149, v160, v161
	v_addc_co_u32_e32 v151, vcc, 0, v152, vcc
	global_store_dwordx4 v[150:151], v[146:149], off
	v_pk_mul_f32 v[152:153], v[2:3], v[158:159] op_sel_hi:[1,0]
	s_andn2_b64 vcc, exec, s[44:45]
	v_pk_mul_f32 v[148:149], v[6:7], v[158:159] op_sel_hi:[1,0]
	v_pk_mul_f32 v[146:147], v[4:5], v[158:159] op_sel_hi:[1,0]
	v_pk_mul_f32 v[158:159], v[0:1], v[158:159] op_sel_hi:[1,0]
	v_cvt_pk_bf16_f32 v146, v146, v147
	v_cvt_pk_bf16_f32 v147, v148, v149
	v_cvt_pk_bf16_f32 v148, v158, v159
	v_cvt_pk_bf16_f32 v149, v152, v153
	global_store_dwordx4 v[150:151], v[146:149], off offset:256
	s_cbranch_vccz .LBB0_291
	s_mov_b64 s[38:39], s[48:49]
	s_andn2_b64 vcc, exec, s[42:43]
	s_mov_b64 s[48:49], s[38:39]
	s_cbranch_vccnz .LBB0_292

.LBB0_306:
	v_lshrrev_b32_e32 v16, 1, v10
	v_and_b32_e32 v16, 24, v16
	s_add_u32 s26, s26, 0x1db10000
	v_and_b32_e32 v15, 15, v10
	v_lshlrev_b32_e32 v17, 1, v16
	v_lshlrev_b32_e32 v10, 2, v10
	s_addc_u32 s27, s27, 0
	s_lshl_b32 s12, s6, 6
	v_lshl_or_b32 v17, v15, 6, v17
	s_lshl_b32 s6, s6, 13
	v_and_b32_e32 v10, 32, v10
	v_bitop3_b32 v18, v17, s6, v10 bitop3:0xde
	s_lshl_b32 s6, s10, 5
	s_and_b32 s6, s6, 0x60
	s_add_i32 m0, s58, 0x18000
	v_lshl_add_u64 v[6:7], v[6:7], 0, s[36:37]
	s_lshl_b32 s10, s6, 7
	s_waitcnt vmcnt(0)
	s_barrier
	global_load_lds_dwordx4 v[6:7], off
	v_lshl_add_u64 v[4:5], v[4:5], 0, s[36:37]
	s_add_i32 m0, s58, 0x1a000
	s_add_i32 s71, s58, 0x8000
	s_add_i32 s72, s58, 0xa000
	v_bitop3_b32 v154, v17, s10, v10 bitop3:0xde
	global_load_lds_dwordx4 v[4:5], off
	v_lshl_add_u64 v[2:3], v[2:3], 0, s[36:37]
	s_mov_b32 m0, s71
	s_add_u32 s10, s48, 0x40080
	global_load_lds_dwordx4 v[2:3], off
	v_lshl_add_u64 v[0:1], v[0:1], 0, s[36:37]
	s_mov_b32 m0, s72
	s_addc_u32 s11, s49, 0
	global_load_lds_dwordx4 v[0:1], off
	s_add_i32 m0, s58, 0x1c000
	v_lshl_add_u64 v[0:1], s[10:11], 0, v[140:141]
	global_load_lds_dwordx4 v[0:1], off
	v_lshl_add_u64 v[0:1], s[10:11], 0, v[132:133]
	s_add_i32 m0, s58, 0x1e000
	s_ashr_i32 s10, s12, 31
	global_load_lds_dwordx4 v[0:1], off
	v_or_b32_e32 v0, s12, v15
	v_mov_b32_e32 v1, s10
	v_lshlrev_b64 v[134:135], 12, v[0:1]
	v_lshlrev_b32_e32 v0, 14, v8
	v_and_b32_e32 v0, 0xffff8000, v0
	v_lshl_add_u32 v0, v9, 11, v0
	v_and_b32_e32 v1, 1, v8
	v_lshl_or_b32 v0, v1, 6, v0
	v_lshl_add_u32 v136, v11, 1, v0
	v_lshlrev_b32_e32 v0, 14, v12
	v_and_b32_e32 v0, 0xffff8000, v0
	v_lshl_add_u32 v0, v13, 11, v0
	v_and_b32_e32 v1, 1, v12
	s_waitcnt vmcnt(6)
	v_lshl_or_b32 v0, v1, 6, v0
	v_lshl_add_u32 v138, v14, 1, v0
	s_sext_i32_i8 s28, s28
	s_sext_i32_i8 s70, s30
	v_or_b32_e32 v155, s6, v16
	v_mov_b32_e32 v137, v141
	v_mov_b32_e32 v139, v141
	s_mov_b32 s73, 0
	v_add_u32_e32 v156, 0, v18
	s_barrier
	s_mov_b32 s100, 0
	s_branch .LBB0_308
.LBB0_307:
	s_mov_b32 s70, s34
	s_mov_b32 s28, s30
	s_mov_b64 s[4:5], s[46:47]
	s_mov_b32 s73, s10
	s_andn2_b64 vcc, exec, s[38:39]
	s_mov_b64 s[48:49], s[42:43]
	s_cbranch_vccz .LBB0_318

.LBB0_314:
	s_add_u32 s11, s48, 0x100
	s_addc_u32 s12, s49, 0
	s_ashr_i32 s31, s30, 31
	s_lshl_b64 s[42:43], s[30:31], 19
	s_add_u32 s46, s33, s42
	s_addc_u32 s47, s41, s43
	s_and_b64 s[42:43], s[44:45], exec
	s_cselect_b32 s29, s47, s5
	s_cselect_b32 s31, s46, s4
	s_ashr_i32 s35, s34, 31
	s_lshl_b64 s[42:43], s[34:35], 19
	s_add_u32 s42, s54, s42
	s_addc_u32 s43, s55, s43
	s_and_b64 s[50:51], s[44:45], exec
	s_cselect_b32 s35, s43, s49
	s_cselect_b32 s74, s42, s48
	s_add_u32 s48, s4, 0x40080
	s_addc_u32 s49, s5, 0
	v_lshl_add_u64 v[150:151], s[48:49], 0, v[136:137]
	v_lshl_add_u64 v[152:153], s[48:49], 0, v[138:139]
	s_mov_b32 s75, -2
	s_mov_b64 s[48:49], 0
	s_add_u32 s6, s4, s48
	s_addc_u32 s19, s5, s49
	s_add_u32 s6, s6, 0x100
	s_addc_u32 s19, s19, 0
	s_add_u32 s23, s11, s48
	s_addc_u32 s50, s12, s49
	s_add_i32 s80, 0, 0x10000
	v_add_u32_e32 v157, s80, v154
	ds_read_b128 v[146:149], v157
	ds_read_b128 v[158:161], v157 offset:1024
	ds_read_b128 v[162:165], v157 offset:2048
	ds_read_b128 v[166:169], v157 offset:3072
	s_cmpk_eq_i32 s48, 0x700
	s_cselect_b32 s53, s29, s19
	s_cselect_b32 s52, s31, s6
	s_cselect_b32 s51, s35, s50
	s_cselect_b32 s50, s74, s23
	v_lshl_add_u64 v[218:219], v[150:151], 0, s[48:49]
	s_add_i32 m0, s58, 0xc000
	ds_read_b128 v[170:173], v156
	ds_read_b128 v[174:177], v156 offset:1024
	ds_read_b128 v[178:181], v156 offset:2048
	ds_read_b128 v[182:185], v156 offset:3072
	ds_read_b128 v[194:197], v156 offset:4096
	ds_read_b128 v[206:209], v156 offset:5120
	ds_read_b128 v[210:213], v156 offset:6144
	ds_read_b128 v[214:217], v156 offset:7168
	global_load_lds_dwordx4 v[218:219], off
	v_lshl_add_u64 v[218:219], v[152:153], 0, s[48:49]
	s_add_i32 m0, s58, 0xe000
	s_nop 0
	global_load_lds_dwordx4 v[218:219], off
	s_add_i32 s6, 0, 0x14000
	v_add_u32_e32 v157, s6, v154
	ds_read_b128 v[218:221], v157
	ds_read_b128 v[222:225], v157 offset:1024
	ds_read_b128 v[226:229], v157 offset:2048
	ds_read_b128 v[230:233], v157 offset:3072
	s_waitcnt vmcnt(24)
	s_cmp_lg_u32 s100, 0
	s_cbranch_scc1 .Lm4ap_315
	s_waitcnt vmcnt(8)
.Lm4ap_315:
	s_waitcnt lgkmcnt(0)
	s_barrier
	s_setprio 1
	v_mfma_f32_16x16x32_bf16 v[124:127], v[146:149], v[170:173], 0
	v_mfma_f32_16x16x32_bf16 v[120:123], v[162:165], v[170:173], 0
	v_mfma_f32_16x16x32_bf16 v[116:119], v[146:149], v[178:181], 0
	v_mfma_f32_16x16x32_bf16 v[112:115], v[162:165], v[178:181], 0
	v_mfma_f32_16x16x32_bf16 v[108:111], v[146:149], v[194:197], 0
	v_mfma_f32_16x16x32_bf16 v[104:107], v[162:165], v[194:197], 0
	v_mfma_f32_16x16x32_bf16 v[100:103], v[146:149], v[210:213], 0
	v_mfma_f32_16x16x32_bf16 v[96:99], v[162:165], v[210:213], 0
	v_mfma_f32_16x16x32_bf16 v[124:127], v[158:161], v[174:177], v[124:127]
	v_mfma_f32_16x16x32_bf16 v[120:123], v[166:169], v[174:177], v[120:123]
	v_mfma_f32_16x16x32_bf16 v[116:119], v[158:161], v[182:185], v[116:119]
	v_mfma_f32_16x16x32_bf16 v[112:115], v[166:169], v[182:185], v[112:115]
	v_mfma_f32_16x16x32_bf16 v[108:111], v[158:161], v[206:209], v[108:111]
	v_mfma_f32_16x16x32_bf16 v[104:107], v[166:169], v[206:209], v[104:107]
	v_mfma_f32_16x16x32_bf16 v[100:103], v[158:161], v[214:217], v[100:103]
	v_mfma_f32_16x16x32_bf16 v[96:99], v[166:169], v[214:217], v[96:99]
	v_mfma_f32_16x16x32_bf16 v[92:95], v[218:221], v[170:173], 0
	v_mfma_f32_16x16x32_bf16 v[88:91], v[226:229], v[170:173], 0
	v_mfma_f32_16x16x32_bf16 v[84:87], v[218:221], v[178:181], 0
	v_mfma_f32_16x16x32_bf16 v[80:83], v[226:229], v[178:181], 0
	v_mfma_f32_16x16x32_bf16 v[76:79], v[218:221], v[194:197], 0
	v_mfma_f32_16x16x32_bf16 v[72:75], v[226:229], v[194:197], 0
	v_mfma_f32_16x16x32_bf16 v[68:71], v[218:221], v[210:213], 0
	v_mfma_f32_16x16x32_bf16 v[64:67], v[226:229], v[210:213], 0
	v_mfma_f32_16x16x32_bf16 v[92:95], v[222:225], v[174:177], v[92:95]
	v_mfma_f32_16x16x32_bf16 v[88:91], v[230:233], v[174:177], v[88:91]
	v_mfma_f32_16x16x32_bf16 v[84:87], v[222:225], v[182:185], v[84:87]
	v_mfma_f32_16x16x32_bf16 v[80:83], v[230:233], v[182:185], v[80:83]
	v_mfma_f32_16x16x32_bf16 v[76:79], v[222:225], v[206:209], v[76:79]
	v_mfma_f32_16x16x32_bf16 v[72:75], v[230:233], v[206:209], v[72:75]
	v_mfma_f32_16x16x32_bf16 v[68:71], v[222:225], v[214:217], v[68:71]
	v_mfma_f32_16x16x32_bf16 v[64:67], v[230:233], v[214:217], v[64:67]
	s_setprio 0
	s_barrier
	s_add_i32 s19, s80, s57
	v_lshl_add_u64 v[234:235], s[50:51], 0, v[140:141]
	s_mov_b32 m0, s19
	s_nop 0
	global_load_lds_dwordx4 v[234:235], off
	v_lshl_add_u64 v[236:237], s[50:51], 0, v[132:133]
	s_add_i32 m0, s19, 0x2000
	s_nop 0
	global_load_lds_dwordx4 v[236:237], off
	s_mov_b32 m0, s58
	v_lshl_add_u64 v[238:239], s[52:53], 0, v[128:129]
	ds_read_b128 v[170:173], v156 offset:16384
	ds_read_b128 v[174:177], v156 offset:17408
	ds_read_b128 v[178:181], v156 offset:18432
	ds_read_b128 v[182:185], v156 offset:19456
	ds_read_b128 v[194:197], v156 offset:20480
	ds_read_b128 v[206:209], v156 offset:21504
	ds_read_b128 v[210:213], v156 offset:22528
	ds_read_b128 v[214:217], v156 offset:23552
	global_load_lds_dwordx4 v[238:239], off
	v_lshl_add_u64 v[240:241], s[52:53], 0, v[130:131]
	s_mov_b32 m0, s59
	s_nop 0
	global_load_lds_dwordx4 v[240:241], off
	s_add_u32 s80, s50, 0x40000
	s_addc_u32 s81, s51, 0
	s_add_i32 s6, s6, s57
	v_lshl_add_u64 v[250:251], s[80:81], 0, v[140:141]
	s_mov_b32 m0, s6
	s_nop 0
	global_load_lds_dwordx4 v[250:251], off
	v_lshl_add_u64 v[250:251], s[80:81], 0, v[132:133]
	s_add_i32 m0, s6, 0x2000
	s_nop 0
	global_load_lds_dwordx4 v[250:251], off
	s_waitcnt vmcnt(24)
	s_cmp_lg_u32 s100, 0
	s_cbranch_scc1 .Lm4bp_315
	s_waitcnt vmcnt(8)
.Lm4bp_315:
	s_waitcnt lgkmcnt(0)
	s_mov_b32 s100, 0
	s_barrier
	s_setprio 1
	v_mfma_f32_16x16x32_bf16 v[60:63], v[146:149], v[170:173], 0
	v_mfma_f32_16x16x32_bf16 v[56:59], v[162:165], v[170:173], 0
	v_mfma_f32_16x16x32_bf16 v[52:55], v[146:149], v[178:181], 0
	v_mfma_f32_16x16x32_bf16 v[48:51], v[162:165], v[178:181], 0
	v_mfma_f32_16x16x32_bf16 v[44:47], v[146:149], v[194:197], 0
	v_mfma_f32_16x16x32_bf16 v[40:43], v[162:165], v[194:197], 0
	v_mfma_f32_16x16x32_bf16 v[36:39], v[146:149], v[210:213], 0
	v_mfma_f32_16x16x32_bf16 v[32:35], v[162:165], v[210:213], 0
	v_mfma_f32_16x16x32_bf16 v[60:63], v[158:161], v[174:177], v[60:63]
	v_mfma_f32_16x16x32_bf16 v[56:59], v[166:169], v[174:177], v[56:59]
	v_mfma_f32_16x16x32_bf16 v[52:55], v[158:161], v[182:185], v[52:55]
	v_mfma_f32_16x16x32_bf16 v[48:51], v[166:169], v[182:185], v[48:51]
	v_mfma_f32_16x16x32_bf16 v[44:47], v[158:161], v[206:209], v[44:47]
	v_mfma_f32_16x16x32_bf16 v[40:43], v[166:169], v[206:209], v[40:43]
	v_mfma_f32_16x16x32_bf16 v[36:39], v[158:161], v[214:217], v[36:39]
	v_mfma_f32_16x16x32_bf16 v[32:35], v[166:169], v[214:217], v[32:35]
	v_mfma_f32_16x16x32_bf16 v[28:31], v[218:221], v[170:173], 0
	v_mfma_f32_16x16x32_bf16 v[24:27], v[226:229], v[170:173], 0
	v_mfma_f32_16x16x32_bf16 v[20:23], v[218:221], v[178:181], 0
	v_mfma_f32_16x16x32_bf16 v[16:19], v[226:229], v[178:181], 0
	v_mfma_f32_16x16x32_bf16 v[12:15], v[218:221], v[194:197], 0
	v_mfma_f32_16x16x32_bf16 v[8:11], v[226:229], v[194:197], 0
	v_mfma_f32_16x16x32_bf16 v[4:7], v[218:221], v[210:213], 0
	v_mfma_f32_16x16x32_bf16 v[0:3], v[226:229], v[210:213], 0
	v_mfma_f32_16x16x32_bf16 v[28:31], v[222:225], v[174:177], v[28:31]
	v_mfma_f32_16x16x32_bf16 v[24:27], v[230:233], v[174:177], v[24:27]
	v_mfma_f32_16x16x32_bf16 v[20:23], v[222:225], v[182:185], v[20:23]
	v_mfma_f32_16x16x32_bf16 v[16:19], v[230:233], v[182:185], v[16:19]
	v_mfma_f32_16x16x32_bf16 v[12:15], v[222:225], v[206:209], v[12:15]
	v_mfma_f32_16x16x32_bf16 v[8:11], v[230:233], v[206:209], v[8:11]
	v_mfma_f32_16x16x32_bf16 v[4:7], v[222:225], v[214:217], v[4:7]
	v_mfma_f32_16x16x32_bf16 v[0:3], v[230:233], v[214:217], v[0:3]
	s_setprio 0
	s_barrier
	s_add_i32 s6, 0, 0x18000
	v_add_u32_e32 v157, s6, v154
	ds_read_b128 v[146:149], v157
	ds_read_b128 v[158:161], v157 offset:1024
	ds_read_b128 v[162:165], v157 offset:2048
	ds_read_b128 v[166:169], v157 offset:3072
	s_add_u32 s52, s52, 0x40000
	s_addc_u32 s53, s53, 0
	s_mov_b32 m0, s68
	v_lshl_add_u64 v[218:219], s[52:53], 0, v[128:129]
	ds_read_b128 v[170:173], v156 offset:32768
	ds_read_b128 v[174:177], v156 offset:33792
	ds_read_b128 v[178:181], v156 offset:34816
	ds_read_b128 v[182:185], v156 offset:35840
	ds_read_b128 v[194:197], v156 offset:36864
	ds_read_b128 v[206:209], v156 offset:37888
	ds_read_b128 v[210:213], v156 offset:38912
	ds_read_b128 v[214:217], v156 offset:39936
	global_load_lds_dwordx4 v[218:219], off
	v_lshl_add_u64 v[218:219], s[52:53], 0, v[130:131]
	s_mov_b32 m0, s69
	s_nop 0
	global_load_lds_dwordx4 v[218:219], off
	s_add_i32 s19, 0, 0x1c000
	v_add_u32_e32 v157, s19, v154
	ds_read_b128 v[218:221], v157
	ds_read_b128 v[222:225], v157 offset:1024
	ds_read_b128 v[226:229], v157 offset:2048
	ds_read_b128 v[230:233], v157 offset:3072
	s_waitcnt vmcnt(8)
	s_waitcnt lgkmcnt(0)
	s_barrier
	s_setprio 1
	v_mfma_f32_16x16x32_bf16 v[124:127], v[146:149], v[170:173], v[124:127]
	v_mfma_f32_16x16x32_bf16 v[120:123], v[162:165], v[170:173], v[120:123]
	v_mfma_f32_16x16x32_bf16 v[116:119], v[146:149], v[178:181], v[116:119]
	v_mfma_f32_16x16x32_bf16 v[112:115], v[162:165], v[178:181], v[112:115]
	v_mfma_f32_16x16x32_bf16 v[108:111], v[146:149], v[194:197], v[108:111]
	v_mfma_f32_16x16x32_bf16 v[104:107], v[162:165], v[194:197], v[104:107]
	v_mfma_f32_16x16x32_bf16 v[100:103], v[146:149], v[210:213], v[100:103]
	v_mfma_f32_16x16x32_bf16 v[96:99], v[162:165], v[210:213], v[96:99]
	v_mfma_f32_16x16x32_bf16 v[124:127], v[158:161], v[174:177], v[124:127]
	v_mfma_f32_16x16x32_bf16 v[120:123], v[166:169], v[174:177], v[120:123]
	v_mfma_f32_16x16x32_bf16 v[116:119], v[158:161], v[182:185], v[116:119]
	v_mfma_f32_16x16x32_bf16 v[112:115], v[166:169], v[182:185], v[112:115]
	v_mfma_f32_16x16x32_bf16 v[108:111], v[158:161], v[206:209], v[108:111]
	v_mfma_f32_16x16x32_bf16 v[104:107], v[166:169], v[206:209], v[104:107]
	v_mfma_f32_16x16x32_bf16 v[100:103], v[158:161], v[214:217], v[100:103]
	v_mfma_f32_16x16x32_bf16 v[96:99], v[166:169], v[214:217], v[96:99]
	v_mfma_f32_16x16x32_bf16 v[92:95], v[218:221], v[170:173], v[92:95]
	v_mfma_f32_16x16x32_bf16 v[88:91], v[226:229], v[170:173], v[88:91]
	v_mfma_f32_16x16x32_bf16 v[84:87], v[218:221], v[178:181], v[84:87]
	v_mfma_f32_16x16x32_bf16 v[80:83], v[226:229], v[178:181], v[80:83]
	v_mfma_f32_16x16x32_bf16 v[76:79], v[218:221], v[194:197], v[76:79]
	v_mfma_f32_16x16x32_bf16 v[72:75], v[226:229], v[194:197], v[72:75]
	v_mfma_f32_16x16x32_bf16 v[68:71], v[218:221], v[210:213], v[68:71]
	v_mfma_f32_16x16x32_bf16 v[64:67], v[226:229], v[210:213], v[64:67]
	v_mfma_f32_16x16x32_bf16 v[92:95], v[222:225], v[174:177], v[92:95]
	v_mfma_f32_16x16x32_bf16 v[88:91], v[230:233], v[174:177], v[88:91]
	v_mfma_f32_16x16x32_bf16 v[84:87], v[222:225], v[182:185], v[84:87]
	v_mfma_f32_16x16x32_bf16 v[80:83], v[230:233], v[182:185], v[80:83]
	v_mfma_f32_16x16x32_bf16 v[76:79], v[222:225], v[206:209], v[76:79]
	v_mfma_f32_16x16x32_bf16 v[72:75], v[230:233], v[206:209], v[72:75]
	v_mfma_f32_16x16x32_bf16 v[68:71], v[222:225], v[214:217], v[68:71]
	v_mfma_f32_16x16x32_bf16 v[64:67], v[230:233], v[214:217], v[64:67]
	s_setprio 0
	s_barrier
	s_add_i32 s6, s6, s57
	v_lshl_add_u64 v[234:235], v[234:235], 0, s[36:37]
	s_mov_b32 m0, s6
	s_nop 0
	global_load_lds_dwordx4 v[234:235], off
	v_lshl_add_u64 v[234:235], v[236:237], 0, s[36:37]
	s_add_i32 m0, s6, 0x2000
	s_nop 0
	global_load_lds_dwordx4 v[234:235], off
	s_mov_b32 m0, s71
	v_lshl_add_u64 v[234:235], v[238:239], 0, s[36:37]
	ds_read_b128 v[170:173], v156 offset:49152
	ds_read_b128 v[174:177], v156 offset:50176
	ds_read_b128 v[178:181], v156 offset:51200
	ds_read_b128 v[182:185], v156 offset:52224
	ds_read_b128 v[194:197], v156 offset:53248
	ds_read_b128 v[206:209], v156 offset:54272
	ds_read_b128 v[210:213], v156 offset:55296
	ds_read_b128 v[214:217], v156 offset:56320
	global_load_lds_dwordx4 v[234:235], off
	v_lshl_add_u64 v[234:235], v[240:241], 0, s[36:37]
	s_mov_b32 m0, s72
	s_nop 0
	global_load_lds_dwordx4 v[234:235], off
	s_add_u32 s50, s50, 0x40080
	s_addc_u32 s51, s51, 0
	s_add_i32 s6, s19, s57
	v_lshl_add_u64 v[250:251], s[50:51], 0, v[140:141]
	s_mov_b32 m0, s6
	s_nop 0
	global_load_lds_dwordx4 v[250:251], off
	v_lshl_add_u64 v[250:251], s[50:51], 0, v[132:133]
	s_add_i32 m0, s6, 0x2000
	s_nop 0
	global_load_lds_dwordx4 v[250:251], off
	s_waitcnt vmcnt(8)
	s_waitcnt lgkmcnt(0)
	s_barrier
	s_setprio 1
	v_mfma_f32_16x16x32_bf16 v[60:63], v[146:149], v[170:173], v[60:63]
	v_mfma_f32_16x16x32_bf16 v[56:59], v[162:165], v[170:173], v[56:59]
	v_mfma_f32_16x16x32_bf16 v[52:55], v[146:149], v[178:181], v[52:55]
	v_mfma_f32_16x16x32_bf16 v[48:51], v[162:165], v[178:181], v[48:51]
	v_mfma_f32_16x16x32_bf16 v[44:47], v[146:149], v[194:197], v[44:47]
	v_mfma_f32_16x16x32_bf16 v[40:43], v[162:165], v[194:197], v[40:43]
	v_mfma_f32_16x16x32_bf16 v[36:39], v[146:149], v[210:213], v[36:39]
	v_mfma_f32_16x16x32_bf16 v[32:35], v[162:165], v[210:213], v[32:35]
	v_mfma_f32_16x16x32_bf16 v[60:63], v[158:161], v[174:177], v[60:63]
	v_mfma_f32_16x16x32_bf16 v[56:59], v[166:169], v[174:177], v[56:59]
	v_mfma_f32_16x16x32_bf16 v[52:55], v[158:161], v[182:185], v[52:55]
	v_mfma_f32_16x16x32_bf16 v[48:51], v[166:169], v[182:185], v[48:51]
	v_mfma_f32_16x16x32_bf16 v[44:47], v[158:161], v[206:209], v[44:47]
	v_mfma_f32_16x16x32_bf16 v[40:43], v[166:169], v[206:209], v[40:43]
	v_mfma_f32_16x16x32_bf16 v[36:39], v[158:161], v[214:217], v[36:39]
	v_mfma_f32_16x16x32_bf16 v[32:35], v[166:169], v[214:217], v[32:35]
	v_mfma_f32_16x16x32_bf16 v[28:31], v[218:221], v[170:173], v[28:31]
	v_mfma_f32_16x16x32_bf16 v[24:27], v[226:229], v[170:173], v[24:27]
	v_mfma_f32_16x16x32_bf16 v[20:23], v[218:221], v[178:181], v[20:23]
	v_mfma_f32_16x16x32_bf16 v[16:19], v[226:229], v[178:181], v[16:19]
	v_mfma_f32_16x16x32_bf16 v[12:15], v[218:221], v[194:197], v[12:15]
	v_mfma_f32_16x16x32_bf16 v[8:11], v[226:229], v[194:197], v[8:11]
	v_mfma_f32_16x16x32_bf16 v[4:7], v[218:221], v[210:213], v[4:7]
	v_mfma_f32_16x16x32_bf16 v[0:3], v[226:229], v[210:213], v[0:3]
	v_mfma_f32_16x16x32_bf16 v[28:31], v[222:225], v[174:177], v[28:31]
	v_mfma_f32_16x16x32_bf16 v[24:27], v[230:233], v[174:177], v[24:27]
	v_mfma_f32_16x16x32_bf16 v[20:23], v[222:225], v[182:185], v[20:23]
	v_mfma_f32_16x16x32_bf16 v[16:19], v[230:233], v[182:185], v[16:19]
	v_mfma_f32_16x16x32_bf16 v[12:15], v[222:225], v[206:209], v[12:15]
	v_mfma_f32_16x16x32_bf16 v[8:11], v[230:233], v[206:209], v[8:11]
	v_mfma_f32_16x16x32_bf16 v[4:7], v[222:225], v[214:217], v[4:7]
	v_mfma_f32_16x16x32_bf16 v[0:3], v[230:233], v[214:217], v[0:3]
	s_setprio 0
	s_add_i32 s75, s75, 2
	s_add_u32 s48, s48, 0x100
	s_addc_u32 s49, s49, 0
	s_cmp_gt_u32 s75, 13
	s_barrier
.LBB0_315:
	s_add_u32 s6, s4, s48
	s_addc_u32 s19, s5, s49
	s_add_u32 s6, s6, 0x100
	s_addc_u32 s19, s19, 0
	s_add_u32 s23, s11, s48
	s_addc_u32 s50, s12, s49
	s_add_i32 s80, 0, 0x10000
	v_add_u32_e32 v157, s80, v154
	ds_read_b128 v[146:149], v157
	ds_read_b128 v[158:161], v157 offset:1024
	ds_read_b128 v[162:165], v157 offset:2048
	ds_read_b128 v[166:169], v157 offset:3072
	s_cmpk_eq_i32 s48, 0x700
	s_cselect_b32 s53, s29, s19
	s_cselect_b32 s52, s31, s6
	s_cselect_b32 s51, s35, s50
	s_cselect_b32 s50, s74, s23
	v_lshl_add_u64 v[218:219], v[150:151], 0, s[48:49]
	s_add_i32 m0, s58, 0xc000
	ds_read_b128 v[170:173], v156
	ds_read_b128 v[174:177], v156 offset:1024
	ds_read_b128 v[178:181], v156 offset:2048
	ds_read_b128 v[182:185], v156 offset:3072
	ds_read_b128 v[194:197], v156 offset:4096
	ds_read_b128 v[206:209], v156 offset:5120
	ds_read_b128 v[210:213], v156 offset:6144
	ds_read_b128 v[214:217], v156 offset:7168
	global_load_lds_dwordx4 v[218:219], off
	v_lshl_add_u64 v[218:219], v[152:153], 0, s[48:49]
	s_add_i32 m0, s58, 0xe000
	s_nop 0
	global_load_lds_dwordx4 v[218:219], off
	s_add_i32 s6, 0, 0x14000
	v_add_u32_e32 v157, s6, v154
	ds_read_b128 v[218:221], v157
	ds_read_b128 v[222:225], v157 offset:1024
	ds_read_b128 v[226:229], v157 offset:2048
	ds_read_b128 v[230:233], v157 offset:3072
	s_waitcnt vmcnt(8)
	s_waitcnt lgkmcnt(0)
	s_barrier
	s_setprio 1
	v_mfma_f32_16x16x32_bf16 v[124:127], v[146:149], v[170:173], v[124:127]
	v_mfma_f32_16x16x32_bf16 v[120:123], v[162:165], v[170:173], v[120:123]
	v_mfma_f32_16x16x32_bf16 v[116:119], v[146:149], v[178:181], v[116:119]
	v_mfma_f32_16x16x32_bf16 v[112:115], v[162:165], v[178:181], v[112:115]
	v_mfma_f32_16x16x32_bf16 v[108:111], v[146:149], v[194:197], v[108:111]
	v_mfma_f32_16x16x32_bf16 v[104:107], v[162:165], v[194:197], v[104:107]
	v_mfma_f32_16x16x32_bf16 v[100:103], v[146:149], v[210:213], v[100:103]
	v_mfma_f32_16x16x32_bf16 v[96:99], v[162:165], v[210:213], v[96:99]
	v_mfma_f32_16x16x32_bf16 v[124:127], v[158:161], v[174:177], v[124:127]
	v_mfma_f32_16x16x32_bf16 v[120:123], v[166:169], v[174:177], v[120:123]
	v_mfma_f32_16x16x32_bf16 v[116:119], v[158:161], v[182:185], v[116:119]
	v_mfma_f32_16x16x32_bf16 v[112:115], v[166:169], v[182:185], v[112:115]
	v_mfma_f32_16x16x32_bf16 v[108:111], v[158:161], v[206:209], v[108:111]
	v_mfma_f32_16x16x32_bf16 v[104:107], v[166:169], v[206:209], v[104:107]
	v_mfma_f32_16x16x32_bf16 v[100:103], v[158:161], v[214:217], v[100:103]
	v_mfma_f32_16x16x32_bf16 v[96:99], v[166:169], v[214:217], v[96:99]
	v_mfma_f32_16x16x32_bf16 v[92:95], v[218:221], v[170:173], v[92:95]
	v_mfma_f32_16x16x32_bf16 v[88:91], v[226:229], v[170:173], v[88:91]
	v_mfma_f32_16x16x32_bf16 v[84:87], v[218:221], v[178:181], v[84:87]
	v_mfma_f32_16x16x32_bf16 v[80:83], v[226:229], v[178:181], v[80:83]
	v_mfma_f32_16x16x32_bf16 v[76:79], v[218:221], v[194:197], v[76:79]
	v_mfma_f32_16x16x32_bf16 v[72:75], v[226:229], v[194:197], v[72:75]
	v_mfma_f32_16x16x32_bf16 v[68:71], v[218:221], v[210:213], v[68:71]
	v_mfma_f32_16x16x32_bf16 v[64:67], v[226:229], v[210:213], v[64:67]
	v_mfma_f32_16x16x32_bf16 v[92:95], v[222:225], v[174:177], v[92:95]
	v_mfma_f32_16x16x32_bf16 v[88:91], v[230:233], v[174:177], v[88:91]
	v_mfma_f32_16x16x32_bf16 v[84:87], v[222:225], v[182:185], v[84:87]
	v_mfma_f32_16x16x32_bf16 v[80:83], v[230:233], v[182:185], v[80:83]
	v_mfma_f32_16x16x32_bf16 v[76:79], v[222:225], v[206:209], v[76:79]
	v_mfma_f32_16x16x32_bf16 v[72:75], v[230:233], v[206:209], v[72:75]
	v_mfma_f32_16x16x32_bf16 v[68:71], v[222:225], v[214:217], v[68:71]
	v_mfma_f32_16x16x32_bf16 v[64:67], v[230:233], v[214:217], v[64:67]
	s_setprio 0
	s_barrier
	s_add_i32 s19, s80, s57
	v_lshl_add_u64 v[234:235], s[50:51], 0, v[140:141]
	s_mov_b32 m0, s19
	s_nop 0
	global_load_lds_dwordx4 v[234:235], off
	v_lshl_add_u64 v[236:237], s[50:51], 0, v[132:133]
	s_add_i32 m0, s19, 0x2000
	s_nop 0
	global_load_lds_dwordx4 v[236:237], off
	s_mov_b32 m0, s58
	v_lshl_add_u64 v[238:239], s[52:53], 0, v[128:129]
	ds_read_b128 v[170:173], v156 offset:16384
	ds_read_b128 v[174:177], v156 offset:17408
	ds_read_b128 v[178:181], v156 offset:18432
	ds_read_b128 v[182:185], v156 offset:19456
	ds_read_b128 v[194:197], v156 offset:20480
	ds_read_b128 v[206:209], v156 offset:21504
	ds_read_b128 v[210:213], v156 offset:22528
	ds_read_b128 v[214:217], v156 offset:23552
	global_load_lds_dwordx4 v[238:239], off
	v_lshl_add_u64 v[240:241], s[52:53], 0, v[130:131]
	s_mov_b32 m0, s59
	s_nop 0
	global_load_lds_dwordx4 v[240:241], off
	s_add_u32 s80, s50, 0x40000
	s_addc_u32 s81, s51, 0
	s_add_i32 s6, s6, s57
	v_lshl_add_u64 v[250:251], s[80:81], 0, v[140:141]
	s_mov_b32 m0, s6
	s_nop 0
	global_load_lds_dwordx4 v[250:251], off
	v_lshl_add_u64 v[250:251], s[80:81], 0, v[132:133]
	s_add_i32 m0, s6, 0x2000
	s_nop 0
	global_load_lds_dwordx4 v[250:251], off
	s_waitcnt vmcnt(8)
	s_waitcnt lgkmcnt(0)
	s_barrier
	s_setprio 1
	v_mfma_f32_16x16x32_bf16 v[60:63], v[146:149], v[170:173], v[60:63]
	v_mfma_f32_16x16x32_bf16 v[56:59], v[162:165], v[170:173], v[56:59]
	v_mfma_f32_16x16x32_bf16 v[52:55], v[146:149], v[178:181], v[52:55]
	v_mfma_f32_16x16x32_bf16 v[48:51], v[162:165], v[178:181], v[48:51]
	v_mfma_f32_16x16x32_bf16 v[44:47], v[146:149], v[194:197], v[44:47]
	v_mfma_f32_16x16x32_bf16 v[40:43], v[162:165], v[194:197], v[40:43]
	v_mfma_f32_16x16x32_bf16 v[36:39], v[146:149], v[210:213], v[36:39]
	v_mfma_f32_16x16x32_bf16 v[32:35], v[162:165], v[210:213], v[32:35]
	v_mfma_f32_16x16x32_bf16 v[60:63], v[158:161], v[174:177], v[60:63]
	v_mfma_f32_16x16x32_bf16 v[56:59], v[166:169], v[174:177], v[56:59]
	v_mfma_f32_16x16x32_bf16 v[52:55], v[158:161], v[182:185], v[52:55]
	v_mfma_f32_16x16x32_bf16 v[48:51], v[166:169], v[182:185], v[48:51]
	v_mfma_f32_16x16x32_bf16 v[44:47], v[158:161], v[206:209], v[44:47]
	v_mfma_f32_16x16x32_bf16 v[40:43], v[166:169], v[206:209], v[40:43]
	v_mfma_f32_16x16x32_bf16 v[36:39], v[158:161], v[214:217], v[36:39]
	v_mfma_f32_16x16x32_bf16 v[32:35], v[166:169], v[214:217], v[32:35]
	v_mfma_f32_16x16x32_bf16 v[28:31], v[218:221], v[170:173], v[28:31]
	v_mfma_f32_16x16x32_bf16 v[24:27], v[226:229], v[170:173], v[24:27]
	v_mfma_f32_16x16x32_bf16 v[20:23], v[218:221], v[178:181], v[20:23]
	v_mfma_f32_16x16x32_bf16 v[16:19], v[226:229], v[178:181], v[16:19]
	v_mfma_f32_16x16x32_bf16 v[12:15], v[218:221], v[194:197], v[12:15]
	v_mfma_f32_16x16x32_bf16 v[8:11], v[226:229], v[194:197], v[8:11]
	v_mfma_f32_16x16x32_bf16 v[4:7], v[218:221], v[210:213], v[4:7]
	v_mfma_f32_16x16x32_bf16 v[0:3], v[226:229], v[210:213], v[0:3]
	v_mfma_f32_16x16x32_bf16 v[28:31], v[222:225], v[174:177], v[28:31]
	v_mfma_f32_16x16x32_bf16 v[24:27], v[230:233], v[174:177], v[24:27]
	v_mfma_f32_16x16x32_bf16 v[20:23], v[222:225], v[182:185], v[20:23]
	v_mfma_f32_16x16x32_bf16 v[16:19], v[230:233], v[182:185], v[16:19]
	v_mfma_f32_16x16x32_bf16 v[12:15], v[222:225], v[206:209], v[12:15]
	v_mfma_f32_16x16x32_bf16 v[8:11], v[230:233], v[206:209], v[8:11]
	v_mfma_f32_16x16x32_bf16 v[4:7], v[222:225], v[214:217], v[4:7]
	v_mfma_f32_16x16x32_bf16 v[0:3], v[230:233], v[214:217], v[0:3]
	s_setprio 0
	s_barrier
	s_add_i32 s6, 0, 0x18000
	v_add_u32_e32 v157, s6, v154
	ds_read_b128 v[146:149], v157
	ds_read_b128 v[158:161], v157 offset:1024
	ds_read_b128 v[162:165], v157 offset:2048
	ds_read_b128 v[166:169], v157 offset:3072
	s_add_u32 s52, s52, 0x40000
	s_addc_u32 s53, s53, 0
	s_mov_b32 m0, s68
	v_lshl_add_u64 v[218:219], s[52:53], 0, v[128:129]
	ds_read_b128 v[170:173], v156 offset:32768
	ds_read_b128 v[174:177], v156 offset:33792
	ds_read_b128 v[178:181], v156 offset:34816
	ds_read_b128 v[182:185], v156 offset:35840
	ds_read_b128 v[194:197], v156 offset:36864
	ds_read_b128 v[206:209], v156 offset:37888
	ds_read_b128 v[210:213], v156 offset:38912
	ds_read_b128 v[214:217], v156 offset:39936
	global_load_lds_dwordx4 v[218:219], off
	v_lshl_add_u64 v[218:219], s[52:53], 0, v[130:131]
	s_mov_b32 m0, s69
	s_nop 0
	global_load_lds_dwordx4 v[218:219], off
	s_add_i32 s19, 0, 0x1c000
	v_add_u32_e32 v157, s19, v154
	ds_read_b128 v[218:221], v157
	ds_read_b128 v[222:225], v157 offset:1024
	ds_read_b128 v[226:229], v157 offset:2048
	ds_read_b128 v[230:233], v157 offset:3072
	s_waitcnt vmcnt(8)
	s_waitcnt lgkmcnt(0)
	s_barrier
	s_setprio 1
	v_mfma_f32_16x16x32_bf16 v[124:127], v[146:149], v[170:173], v[124:127]
	v_mfma_f32_16x16x32_bf16 v[120:123], v[162:165], v[170:173], v[120:123]
	v_mfma_f32_16x16x32_bf16 v[116:119], v[146:149], v[178:181], v[116:119]
	v_mfma_f32_16x16x32_bf16 v[112:115], v[162:165], v[178:181], v[112:115]
	v_mfma_f32_16x16x32_bf16 v[108:111], v[146:149], v[194:197], v[108:111]
	v_mfma_f32_16x16x32_bf16 v[104:107], v[162:165], v[194:197], v[104:107]
	v_mfma_f32_16x16x32_bf16 v[100:103], v[146:149], v[210:213], v[100:103]
	v_mfma_f32_16x16x32_bf16 v[96:99], v[162:165], v[210:213], v[96:99]
	v_mfma_f32_16x16x32_bf16 v[124:127], v[158:161], v[174:177], v[124:127]
	v_mfma_f32_16x16x32_bf16 v[120:123], v[166:169], v[174:177], v[120:123]
	v_mfma_f32_16x16x32_bf16 v[116:119], v[158:161], v[182:185], v[116:119]
	v_mfma_f32_16x16x32_bf16 v[112:115], v[166:169], v[182:185], v[112:115]
	v_mfma_f32_16x16x32_bf16 v[108:111], v[158:161], v[206:209], v[108:111]
	v_mfma_f32_16x16x32_bf16 v[104:107], v[166:169], v[206:209], v[104:107]
	v_mfma_f32_16x16x32_bf16 v[100:103], v[158:161], v[214:217], v[100:103]
	v_mfma_f32_16x16x32_bf16 v[96:99], v[166:169], v[214:217], v[96:99]
	v_mfma_f32_16x16x32_bf16 v[92:95], v[218:221], v[170:173], v[92:95]
	v_mfma_f32_16x16x32_bf16 v[88:91], v[226:229], v[170:173], v[88:91]
	v_mfma_f32_16x16x32_bf16 v[84:87], v[218:221], v[178:181], v[84:87]
	v_mfma_f32_16x16x32_bf16 v[80:83], v[226:229], v[178:181], v[80:83]
	v_mfma_f32_16x16x32_bf16 v[76:79], v[218:221], v[194:197], v[76:79]
	v_mfma_f32_16x16x32_bf16 v[72:75], v[226:229], v[194:197], v[72:75]
	v_mfma_f32_16x16x32_bf16 v[68:71], v[218:221], v[210:213], v[68:71]
	v_mfma_f32_16x16x32_bf16 v[64:67], v[226:229], v[210:213], v[64:67]
	v_mfma_f32_16x16x32_bf16 v[92:95], v[222:225], v[174:177], v[92:95]
	v_mfma_f32_16x16x32_bf16 v[88:91], v[230:233], v[174:177], v[88:91]
	v_mfma_f32_16x16x32_bf16 v[84:87], v[222:225], v[182:185], v[84:87]
	v_mfma_f32_16x16x32_bf16 v[80:83], v[230:233], v[182:185], v[80:83]
	v_mfma_f32_16x16x32_bf16 v[76:79], v[222:225], v[206:209], v[76:79]
	v_mfma_f32_16x16x32_bf16 v[72:75], v[230:233], v[206:209], v[72:75]
	v_mfma_f32_16x16x32_bf16 v[68:71], v[222:225], v[214:217], v[68:71]
	v_mfma_f32_16x16x32_bf16 v[64:67], v[230:233], v[214:217], v[64:67]
	s_setprio 0
	s_barrier
	s_add_i32 s6, s6, s57
	v_lshl_add_u64 v[234:235], v[234:235], 0, s[36:37]
	s_mov_b32 m0, s6
	s_nop 0
	global_load_lds_dwordx4 v[234:235], off
	v_lshl_add_u64 v[234:235], v[236:237], 0, s[36:37]
	s_add_i32 m0, s6, 0x2000
	s_nop 0
	global_load_lds_dwordx4 v[234:235], off
	s_mov_b32 m0, s71
	v_lshl_add_u64 v[234:235], v[238:239], 0, s[36:37]
	ds_read_b128 v[170:173], v156 offset:49152
	ds_read_b128 v[174:177], v156 offset:50176
	ds_read_b128 v[178:181], v156 offset:51200
	ds_read_b128 v[182:185], v156 offset:52224
	ds_read_b128 v[194:197], v156 offset:53248
	ds_read_b128 v[206:209], v156 offset:54272
	ds_read_b128 v[210:213], v156 offset:55296
	ds_read_b128 v[214:217], v156 offset:56320
	global_load_lds_dwordx4 v[234:235], off
	v_lshl_add_u64 v[234:235], v[240:241], 0, s[36:37]
	s_mov_b32 m0, s72
	s_nop 0
	global_load_lds_dwordx4 v[234:235], off
	s_add_u32 s50, s50, 0x40080
	s_addc_u32 s51, s51, 0
	s_add_i32 s6, s19, s57
	v_lshl_add_u64 v[250:251], s[50:51], 0, v[140:141]
	s_mov_b32 m0, s6
	s_nop 0
	global_load_lds_dwordx4 v[250:251], off
	v_lshl_add_u64 v[250:251], s[50:51], 0, v[132:133]
	s_add_i32 m0, s6, 0x2000
	s_nop 0
	global_load_lds_dwordx4 v[250:251], off
	s_waitcnt vmcnt(8)
	s_waitcnt lgkmcnt(0)
	s_barrier
	s_setprio 1
	v_mfma_f32_16x16x32_bf16 v[60:63], v[146:149], v[170:173], v[60:63]
	v_mfma_f32_16x16x32_bf16 v[56:59], v[162:165], v[170:173], v[56:59]
	v_mfma_f32_16x16x32_bf16 v[52:55], v[146:149], v[178:181], v[52:55]
	v_mfma_f32_16x16x32_bf16 v[48:51], v[162:165], v[178:181], v[48:51]
	v_mfma_f32_16x16x32_bf16 v[44:47], v[146:149], v[194:197], v[44:47]
	v_mfma_f32_16x16x32_bf16 v[40:43], v[162:165], v[194:197], v[40:43]
	v_mfma_f32_16x16x32_bf16 v[36:39], v[146:149], v[210:213], v[36:39]
	v_mfma_f32_16x16x32_bf16 v[32:35], v[162:165], v[210:213], v[32:35]
	v_mfma_f32_16x16x32_bf16 v[60:63], v[158:161], v[174:177], v[60:63]
	v_mfma_f32_16x16x32_bf16 v[56:59], v[166:169], v[174:177], v[56:59]
	v_mfma_f32_16x16x32_bf16 v[52:55], v[158:161], v[182:185], v[52:55]
	v_mfma_f32_16x16x32_bf16 v[48:51], v[166:169], v[182:185], v[48:51]
	v_mfma_f32_16x16x32_bf16 v[44:47], v[158:161], v[206:209], v[44:47]
	v_mfma_f32_16x16x32_bf16 v[40:43], v[166:169], v[206:209], v[40:43]
	v_mfma_f32_16x16x32_bf16 v[36:39], v[158:161], v[214:217], v[36:39]
	v_mfma_f32_16x16x32_bf16 v[32:35], v[166:169], v[214:217], v[32:35]
	v_mfma_f32_16x16x32_bf16 v[28:31], v[218:221], v[170:173], v[28:31]
	v_mfma_f32_16x16x32_bf16 v[24:27], v[226:229], v[170:173], v[24:27]
	v_mfma_f32_16x16x32_bf16 v[20:23], v[218:221], v[178:181], v[20:23]
	v_mfma_f32_16x16x32_bf16 v[16:19], v[226:229], v[178:181], v[16:19]
	v_mfma_f32_16x16x32_bf16 v[12:15], v[218:221], v[194:197], v[12:15]
	v_mfma_f32_16x16x32_bf16 v[8:11], v[226:229], v[194:197], v[8:11]
	v_mfma_f32_16x16x32_bf16 v[4:7], v[218:221], v[210:213], v[4:7]
	v_mfma_f32_16x16x32_bf16 v[0:3], v[226:229], v[210:213], v[0:3]
	v_mfma_f32_16x16x32_bf16 v[28:31], v[222:225], v[174:177], v[28:31]
	v_mfma_f32_16x16x32_bf16 v[24:27], v[230:233], v[174:177], v[24:27]
	v_mfma_f32_16x16x32_bf16 v[20:23], v[222:225], v[182:185], v[20:23]
	v_mfma_f32_16x16x32_bf16 v[16:19], v[230:233], v[182:185], v[16:19]
	v_mfma_f32_16x16x32_bf16 v[12:15], v[222:225], v[206:209], v[12:15]
	v_mfma_f32_16x16x32_bf16 v[8:11], v[230:233], v[206:209], v[8:11]
	v_mfma_f32_16x16x32_bf16 v[4:7], v[222:225], v[214:217], v[4:7]
	v_mfma_f32_16x16x32_bf16 v[0:3], v[230:233], v[214:217], v[0:3]
	s_setprio 0
	s_add_i32 s75, s75, 2
	s_add_u32 s48, s48, 0x100
	s_addc_u32 s49, s49, 0
	s_cmp_gt_u32 s75, 13
	s_barrier
	s_cbranch_scc0 .LBB0_315
	s_mov_b32 s100, 1
	s_add_u32 s48, s11, 0xffffff00
	v_lshl_or_b32 v146, s70, 8, v155
	s_addc_u32 s49, s12, -1
	s_ashr_i32 s29, s28, 31
	v_ashrrev_i32_e32 v147, 31, v146
	v_lshl_add_u64 v[146:147], v[146:147], 1, s[26:27]
	s_lshl_b64 s[50:51], s[28:29], 20
	v_lshl_add_u64 v[146:147], v[146:147], 0, s[50:51]
	v_lshl_add_u64 v[150:151], v[146:147], 0, v[134:135]
	v_cvt_pk_bf16_f32 v146, v124, v125
	v_cvt_pk_bf16_f32 v147, v126, v127
	v_cvt_pk_bf16_f32 v148, v120, v121
	v_cvt_pk_bf16_f32 v149, v122, v123
	global_store_dwordx4 v[150:151], v[146:149], off
	v_add_co_u32_e32 v152, vcc, s66, v150
	s_nop 0
	v_cvt_pk_bf16_f32 v146, v92, v93
	v_cvt_pk_bf16_f32 v147, v94, v95
	v_cvt_pk_bf16_f32 v148, v88, v89
	v_cvt_pk_bf16_f32 v149, v90, v91
	global_store_dwordx4 v[150:151], v[146:149], off offset:256
	v_addc_co_u32_e32 v153, vcc, 0, v151, vcc
	s_nop 0
	v_cvt_pk_bf16_f32 v146, v116, v117
	v_cvt_pk_bf16_f32 v147, v118, v119
	v_cvt_pk_bf16_f32 v148, v112, v113
	v_cvt_pk_bf16_f32 v149, v114, v115
	global_store_dwordx4 v[152:153], v[146:149], off
	s_mov_b32 s6, 0x20000
	s_nop 0
	v_cvt_pk_bf16_f32 v146, v84, v85
	v_cvt_pk_bf16_f32 v147, v86, v87
	v_cvt_pk_bf16_f32 v148, v80, v81
	v_cvt_pk_bf16_f32 v149, v82, v83
	global_store_dwordx4 v[152:153], v[146:149], off offset:256
	v_add_co_u32_e32 v152, vcc, s6, v150
	s_nop 0
	v_cvt_pk_bf16_f32 v146, v108, v109
	v_cvt_pk_bf16_f32 v147, v110, v111
	v_cvt_pk_bf16_f32 v148, v104, v105
	v_cvt_pk_bf16_f32 v149, v106, v107
	v_addc_co_u32_e32 v153, vcc, 0, v151, vcc
	global_store_dwordx4 v[152:153], v[146:149], off
	s_mov_b32 s6, 0x30000
	s_nop 0
	v_cvt_pk_bf16_f32 v146, v76, v77
	v_cvt_pk_bf16_f32 v147, v78, v79
	v_cvt_pk_bf16_f32 v148, v72, v73
	v_cvt_pk_bf16_f32 v149, v74, v75
	global_store_dwordx4 v[152:153], v[146:149], off offset:256
	v_add_co_u32_e32 v152, vcc, s6, v150
	s_nop 0
	v_cvt_pk_bf16_f32 v146, v100, v101
	v_cvt_pk_bf16_f32 v147, v102, v103
	v_cvt_pk_bf16_f32 v148, v96, v97
	v_cvt_pk_bf16_f32 v149, v98, v99
	v_addc_co_u32_e32 v153, vcc, 0, v151, vcc
	global_store_dwordx4 v[152:153], v[146:149], off
	s_mov_b32 s6, 0x80000
	s_nop 0
	v_cvt_pk_bf16_f32 v146, v68, v69
	v_cvt_pk_bf16_f32 v147, v70, v71
	v_cvt_pk_bf16_f32 v148, v64, v65
	v_cvt_pk_bf16_f32 v149, v66, v67
	global_store_dwordx4 v[152:153], v[146:149], off offset:256
	v_add_co_u32_e32 v152, vcc, s6, v150
	s_nop 0
	v_cvt_pk_bf16_f32 v146, v60, v61
	v_cvt_pk_bf16_f32 v147, v62, v63
	v_cvt_pk_bf16_f32 v148, v56, v57
	v_cvt_pk_bf16_f32 v149, v58, v59
	v_addc_co_u32_e32 v153, vcc, 0, v151, vcc
	global_store_dwordx4 v[152:153], v[146:149], off
	s_mov_b32 s6, 0x90000
	s_nop 0
	v_cvt_pk_bf16_f32 v146, v28, v29
	v_cvt_pk_bf16_f32 v147, v30, v31
	v_cvt_pk_bf16_f32 v148, v24, v25
	v_cvt_pk_bf16_f32 v149, v26, v27
	global_store_dwordx4 v[152:153], v[146:149], off offset:256
	v_add_co_u32_e32 v152, vcc, s6, v150
	s_nop 0
	v_cvt_pk_bf16_f32 v146, v52, v53
	v_cvt_pk_bf16_f32 v147, v54, v55
	v_cvt_pk_bf16_f32 v148, v48, v49
	v_cvt_pk_bf16_f32 v149, v50, v51
	v_addc_co_u32_e32 v153, vcc, 0, v151, vcc
	global_store_dwordx4 v[152:153], v[146:149], off
	s_mov_b32 s6, 0xa0000
	s_nop 0
	v_cvt_pk_bf16_f32 v146, v20, v21
	v_cvt_pk_bf16_f32 v147, v22, v23
	v_cvt_pk_bf16_f32 v148, v16, v17
	v_cvt_pk_bf16_f32 v149, v18, v19
	global_store_dwordx4 v[152:153], v[146:149], off offset:256
	v_add_co_u32_e32 v152, vcc, s6, v150
	s_nop 0
	v_cvt_pk_bf16_f32 v146, v44, v45
	v_cvt_pk_bf16_f32 v147, v46, v47
	v_cvt_pk_bf16_f32 v148, v40, v41
	v_cvt_pk_bf16_f32 v149, v42, v43
	v_addc_co_u32_e32 v153, vcc, 0, v151, vcc
	s_mov_b32 s6, 0xb0000
	global_store_dwordx4 v[152:153], v[146:149], off
	v_add_co_u32_e32 v150, vcc, s6, v150
	s_nop 0
	v_cvt_pk_bf16_f32 v146, v12, v13
	v_cvt_pk_bf16_f32 v147, v14, v15
	v_cvt_pk_bf16_f32 v148, v8, v9
	v_cvt_pk_bf16_f32 v149, v10, v11
	global_store_dwordx4 v[152:153], v[146:149], off offset:256
	v_addc_co_u32_e32 v151, vcc, 0, v151, vcc
	s_nop 0
	v_cvt_pk_bf16_f32 v146, v36, v37
	v_cvt_pk_bf16_f32 v147, v38, v39
	v_cvt_pk_bf16_f32 v148, v32, v33
	v_cvt_pk_bf16_f32 v149, v34, v35
	global_store_dwordx4 v[150:151], v[146:149], off
	s_andn2_b64 vcc, exec, s[44:45]
	s_nop 0
	v_cvt_pk_bf16_f32 v146, v4, v5
	v_cvt_pk_bf16_f32 v147, v6, v7
	v_cvt_pk_bf16_f32 v148, v0, v1
	v_cvt_pk_bf16_f32 v149, v2, v3
	global_store_dwordx4 v[150:151], v[146:149], off offset:256
	s_cbranch_vccz .LBB0_307
	s_mov_b64 s[42:43], s[48:49]
	s_andn2_b64 vcc, exec, s[38:39]
	s_mov_b64 s[48:49], s[42:43]
	s_cbranch_vccnz .LBB0_308

.LBB0_341:
	s_add_u32 s46, s50, 0x100
	s_addc_u32 s47, s51, 0
	s_add_i32 s6, 0, 0x10000
	v_add_u32_e32 v146, s6, v206
	ds_read_b128 v[128:131], v146
	ds_read_b128 v[132:135], v146 offset:1024
	ds_read_b128 v[136:139], v146 offset:2048
	ds_read_b128 v[146:149], v146 offset:3072
	s_cmp_eq_u32 s12, 40
	s_cselect_b32 s53, s31, s47
	s_cselect_b32 s52, s30, s46
	s_cselect_b32 s49, s35, s11
	s_cselect_b32 s48, s34, s10
	v_lshl_add_u64 v[214:215], s[50:51], 0, v[158:159]
	s_add_i32 m0, s58, 0xc000
	ds_read_b128 v[162:165], v208
	ds_read_b128 v[166:169], v208 offset:1024
	ds_read_b128 v[170:173], v208 offset:2048
	ds_read_b128 v[174:177], v208 offset:3072
	ds_read_b128 v[178:181], v208 offset:4096
	ds_read_b128 v[182:185], v208 offset:5120
	ds_read_b128 v[194:197], v208 offset:6144
	ds_read_b128 v[210:213], v208 offset:7168
	global_load_lds_dwordx4 v[214:215], off
	v_lshl_add_u64 v[214:215], s[50:51], 0, v[160:161]
	s_add_i32 m0, s58, 0xe000
	s_nop 0
	global_load_lds_dwordx4 v[214:215], off
	s_add_i32 s19, 0, 0x14000
	v_add_u32_e32 v192, s19, v206
	ds_read_b128 v[214:217], v192
	ds_read_b128 v[218:221], v192 offset:1024
	ds_read_b128 v[222:225], v192 offset:2048
	ds_read_b128 v[226:229], v192 offset:3072
	s_waitcnt vmcnt(8)
	s_waitcnt lgkmcnt(0)
	s_barrier
	s_setprio 1
	v_mfma_f32_16x16x32_bf16 v[124:127], v[128:131], v[162:165], v[124:127]
	v_mfma_f32_16x16x32_bf16 v[120:123], v[136:139], v[162:165], v[120:123]
	v_mfma_f32_16x16x32_bf16 v[108:111], v[128:131], v[170:173], v[108:111]
	v_mfma_f32_16x16x32_bf16 v[104:107], v[136:139], v[170:173], v[104:107]
	v_mfma_f32_16x16x32_bf16 v[96:99], v[128:131], v[178:181], v[96:99]
	v_mfma_f32_16x16x32_bf16 v[88:91], v[136:139], v[178:181], v[88:91]
	v_mfma_f32_16x16x32_bf16 v[84:87], v[128:131], v[194:197], v[84:87]
	v_mfma_f32_16x16x32_bf16 v[80:83], v[136:139], v[194:197], v[80:83]
	v_mfma_f32_16x16x32_bf16 v[124:127], v[132:135], v[166:169], v[124:127]
	v_mfma_f32_16x16x32_bf16 v[120:123], v[146:149], v[166:169], v[120:123]
	v_mfma_f32_16x16x32_bf16 v[108:111], v[132:135], v[174:177], v[108:111]
	v_mfma_f32_16x16x32_bf16 v[104:107], v[146:149], v[174:177], v[104:107]
	v_mfma_f32_16x16x32_bf16 v[96:99], v[132:135], v[182:185], v[96:99]
	v_mfma_f32_16x16x32_bf16 v[88:91], v[146:149], v[182:185], v[88:91]
	v_mfma_f32_16x16x32_bf16 v[84:87], v[132:135], v[210:213], v[84:87]
	v_mfma_f32_16x16x32_bf16 v[80:83], v[146:149], v[210:213], v[80:83]
	v_mfma_f32_16x16x32_bf16 v[116:119], v[214:217], v[162:165], v[116:119]
	v_mfma_f32_16x16x32_bf16 v[112:115], v[222:225], v[162:165], v[112:115]
	v_mfma_f32_16x16x32_bf16 v[100:103], v[214:217], v[170:173], v[100:103]
	v_mfma_f32_16x16x32_bf16 v[92:95], v[222:225], v[170:173], v[92:95]
	v_mfma_f32_16x16x32_bf16 v[76:79], v[214:217], v[178:181], v[76:79]
	v_mfma_f32_16x16x32_bf16 v[72:75], v[222:225], v[178:181], v[72:75]
	v_mfma_f32_16x16x32_bf16 v[68:71], v[214:217], v[194:197], v[68:71]
	v_mfma_f32_16x16x32_bf16 v[64:67], v[222:225], v[194:197], v[64:67]
	v_mfma_f32_16x16x32_bf16 v[116:119], v[218:221], v[166:169], v[116:119]
	v_mfma_f32_16x16x32_bf16 v[112:115], v[226:229], v[166:169], v[112:115]
	v_mfma_f32_16x16x32_bf16 v[100:103], v[218:221], v[174:177], v[100:103]
	v_mfma_f32_16x16x32_bf16 v[92:95], v[226:229], v[174:177], v[92:95]
	v_mfma_f32_16x16x32_bf16 v[76:79], v[218:221], v[182:185], v[76:79]
	v_mfma_f32_16x16x32_bf16 v[72:75], v[226:229], v[182:185], v[72:75]
	v_mfma_f32_16x16x32_bf16 v[68:71], v[218:221], v[210:213], v[68:71]
	v_mfma_f32_16x16x32_bf16 v[64:67], v[226:229], v[210:213], v[64:67]
	s_setprio 0
	s_barrier
	s_add_i32 s6, s6, s57
	v_lshl_add_u64 v[230:231], s[48:49], 0, v[140:141]
	s_mov_b32 m0, s6
	s_nop 0
	global_load_lds_dwordx4 v[230:231], off
	v_lshl_add_u64 v[232:233], s[48:49], 0, v[150:151]
	s_add_i32 m0, s6, 0x2000
	s_nop 0
	global_load_lds_dwordx4 v[232:233], off
	s_mov_b32 m0, s58
	v_lshl_add_u64 v[234:235], s[52:53], 0, v[154:155]
	ds_read_b128 v[162:165], v208 offset:16384
	ds_read_b128 v[166:169], v208 offset:17408
	ds_read_b128 v[170:173], v208 offset:18432
	ds_read_b128 v[174:177], v208 offset:19456
	ds_read_b128 v[178:181], v208 offset:20480
	ds_read_b128 v[182:185], v208 offset:21504
	ds_read_b128 v[194:197], v208 offset:22528
	ds_read_b128 v[210:213], v208 offset:23552
	global_load_lds_dwordx4 v[234:235], off
	v_lshl_add_u64 v[236:237], s[52:53], 0, v[152:153]
	s_mov_b32 m0, s59
	s_nop 0
	global_load_lds_dwordx4 v[236:237], off
	s_add_u32 s50, s48, 0xb0000
	s_addc_u32 s51, s49, 0
	s_add_i32 s6, s19, s57
	v_lshl_add_u64 v[250:251], s[50:51], 0, v[140:141]
	s_mov_b32 m0, s6
	s_nop 0
	global_load_lds_dwordx4 v[250:251], off
	v_lshl_add_u64 v[250:251], s[50:51], 0, v[150:151]
	s_add_i32 m0, s6, 0x2000
	s_nop 0
	global_load_lds_dwordx4 v[250:251], off
	s_waitcnt vmcnt(8)
	s_waitcnt lgkmcnt(0)
	s_barrier
	s_setprio 1
	v_mfma_f32_16x16x32_bf16 v[60:63], v[128:131], v[162:165], v[60:63]
	v_mfma_f32_16x16x32_bf16 v[56:59], v[136:139], v[162:165], v[56:59]
	v_mfma_f32_16x16x32_bf16 v[48:51], v[128:131], v[170:173], v[48:51]
	v_mfma_f32_16x16x32_bf16 v[40:43], v[136:139], v[170:173], v[40:43]
	v_mfma_f32_16x16x32_bf16 v[32:35], v[128:131], v[178:181], v[32:35]
	v_mfma_f32_16x16x32_bf16 v[24:27], v[136:139], v[178:181], v[24:27]
	v_mfma_f32_16x16x32_bf16 v[16:19], v[128:131], v[194:197], v[16:19]
	v_mfma_f32_16x16x32_bf16 v[8:11], v[136:139], v[194:197], v[8:11]
	v_mfma_f32_16x16x32_bf16 v[60:63], v[132:135], v[166:169], v[60:63]
	v_mfma_f32_16x16x32_bf16 v[56:59], v[146:149], v[166:169], v[56:59]
	v_mfma_f32_16x16x32_bf16 v[48:51], v[132:135], v[174:177], v[48:51]
	v_mfma_f32_16x16x32_bf16 v[40:43], v[146:149], v[174:177], v[40:43]
	v_mfma_f32_16x16x32_bf16 v[32:35], v[132:135], v[182:185], v[32:35]
	v_mfma_f32_16x16x32_bf16 v[24:27], v[146:149], v[182:185], v[24:27]
	v_mfma_f32_16x16x32_bf16 v[16:19], v[132:135], v[210:213], v[16:19]
	v_mfma_f32_16x16x32_bf16 v[8:11], v[146:149], v[210:213], v[8:11]
	v_mfma_f32_16x16x32_bf16 v[52:55], v[214:217], v[162:165], v[52:55]
	v_mfma_f32_16x16x32_bf16 v[44:47], v[222:225], v[162:165], v[44:47]
	v_mfma_f32_16x16x32_bf16 v[36:39], v[214:217], v[170:173], v[36:39]
	v_mfma_f32_16x16x32_bf16 v[28:31], v[222:225], v[170:173], v[28:31]
	v_mfma_f32_16x16x32_bf16 v[20:23], v[214:217], v[178:181], v[20:23]
	v_mfma_f32_16x16x32_bf16 v[12:15], v[222:225], v[178:181], v[12:15]
	v_mfma_f32_16x16x32_bf16 v[4:7], v[214:217], v[194:197], v[4:7]
	v_mfma_f32_16x16x32_bf16 v[0:3], v[222:225], v[194:197], v[0:3]
	v_mfma_f32_16x16x32_bf16 v[52:55], v[218:221], v[166:169], v[52:55]
	v_mfma_f32_16x16x32_bf16 v[44:47], v[226:229], v[166:169], v[44:47]
	v_mfma_f32_16x16x32_bf16 v[36:39], v[218:221], v[174:177], v[36:39]
	v_mfma_f32_16x16x32_bf16 v[28:31], v[226:229], v[174:177], v[28:31]
	v_mfma_f32_16x16x32_bf16 v[20:23], v[218:221], v[182:185], v[20:23]
	v_mfma_f32_16x16x32_bf16 v[12:15], v[226:229], v[182:185], v[12:15]
	v_mfma_f32_16x16x32_bf16 v[4:7], v[218:221], v[210:213], v[4:7]
	v_mfma_f32_16x16x32_bf16 v[0:3], v[226:229], v[210:213], v[0:3]
	s_setprio 0
	s_barrier
	s_add_i32 s6, 0, 0x18000
	v_add_u32_e32 v146, s6, v206
	ds_read_b128 v[128:131], v146
	ds_read_b128 v[132:135], v146 offset:1024
	ds_read_b128 v[136:139], v146 offset:2048
	ds_read_b128 v[146:149], v146 offset:3072
	s_add_u32 s50, s52, 0xb0000
	s_addc_u32 s51, s53, 0
	s_mov_b32 m0, s68
	v_lshl_add_u64 v[214:215], s[50:51], 0, v[154:155]
	ds_read_b128 v[162:165], v208 offset:32768
	ds_read_b128 v[166:169], v208 offset:33792
	ds_read_b128 v[170:173], v208 offset:34816
	ds_read_b128 v[174:177], v208 offset:35840
	ds_read_b128 v[178:181], v208 offset:36864
	ds_read_b128 v[182:185], v208 offset:37888
	ds_read_b128 v[194:197], v208 offset:38912
	ds_read_b128 v[210:213], v208 offset:39936
	global_load_lds_dwordx4 v[214:215], off
	v_lshl_add_u64 v[214:215], s[50:51], 0, v[152:153]
	s_mov_b32 m0, s69
	s_nop 0
	global_load_lds_dwordx4 v[214:215], off
	s_add_i32 s19, 0, 0x1c000
	v_add_u32_e32 v192, s19, v206
	ds_read_b128 v[214:217], v192
	ds_read_b128 v[218:221], v192 offset:1024
	ds_read_b128 v[222:225], v192 offset:2048
	ds_read_b128 v[226:229], v192 offset:3072
	s_waitcnt vmcnt(8)
	s_waitcnt lgkmcnt(0)
	s_barrier
	s_setprio 1
	v_mfma_f32_16x16x32_bf16 v[124:127], v[128:131], v[162:165], v[124:127]
	v_mfma_f32_16x16x32_bf16 v[120:123], v[136:139], v[162:165], v[120:123]
	v_mfma_f32_16x16x32_bf16 v[108:111], v[128:131], v[170:173], v[108:111]
	v_mfma_f32_16x16x32_bf16 v[104:107], v[136:139], v[170:173], v[104:107]
	v_mfma_f32_16x16x32_bf16 v[96:99], v[128:131], v[178:181], v[96:99]
	v_mfma_f32_16x16x32_bf16 v[88:91], v[136:139], v[178:181], v[88:91]
	v_mfma_f32_16x16x32_bf16 v[84:87], v[128:131], v[194:197], v[84:87]
	v_mfma_f32_16x16x32_bf16 v[80:83], v[136:139], v[194:197], v[80:83]
	v_mfma_f32_16x16x32_bf16 v[124:127], v[132:135], v[166:169], v[124:127]
	v_mfma_f32_16x16x32_bf16 v[120:123], v[146:149], v[166:169], v[120:123]
	v_mfma_f32_16x16x32_bf16 v[108:111], v[132:135], v[174:177], v[108:111]
	v_mfma_f32_16x16x32_bf16 v[104:107], v[146:149], v[174:177], v[104:107]
	v_mfma_f32_16x16x32_bf16 v[96:99], v[132:135], v[182:185], v[96:99]
	v_mfma_f32_16x16x32_bf16 v[88:91], v[146:149], v[182:185], v[88:91]
	v_mfma_f32_16x16x32_bf16 v[84:87], v[132:135], v[210:213], v[84:87]
	v_mfma_f32_16x16x32_bf16 v[80:83], v[146:149], v[210:213], v[80:83]
	v_mfma_f32_16x16x32_bf16 v[116:119], v[214:217], v[162:165], v[116:119]
	v_mfma_f32_16x16x32_bf16 v[112:115], v[222:225], v[162:165], v[112:115]
	v_mfma_f32_16x16x32_bf16 v[100:103], v[214:217], v[170:173], v[100:103]
	v_mfma_f32_16x16x32_bf16 v[92:95], v[222:225], v[170:173], v[92:95]
	v_mfma_f32_16x16x32_bf16 v[76:79], v[214:217], v[178:181], v[76:79]
	v_mfma_f32_16x16x32_bf16 v[72:75], v[222:225], v[178:181], v[72:75]
	v_mfma_f32_16x16x32_bf16 v[68:71], v[214:217], v[194:197], v[68:71]
	v_mfma_f32_16x16x32_bf16 v[64:67], v[222:225], v[194:197], v[64:67]
	v_mfma_f32_16x16x32_bf16 v[116:119], v[218:221], v[166:169], v[116:119]
	v_mfma_f32_16x16x32_bf16 v[112:115], v[226:229], v[166:169], v[112:115]
	v_mfma_f32_16x16x32_bf16 v[100:103], v[218:221], v[174:177], v[100:103]
	v_mfma_f32_16x16x32_bf16 v[92:95], v[226:229], v[174:177], v[92:95]
	v_mfma_f32_16x16x32_bf16 v[76:79], v[218:221], v[182:185], v[76:79]
	v_mfma_f32_16x16x32_bf16 v[72:75], v[226:229], v[182:185], v[72:75]
	v_mfma_f32_16x16x32_bf16 v[68:71], v[218:221], v[210:213], v[68:71]
	v_mfma_f32_16x16x32_bf16 v[64:67], v[226:229], v[210:213], v[64:67]
	s_setprio 0
	s_barrier
	s_add_i32 s6, s6, s57
	v_lshl_add_u64 v[230:231], v[230:231], 0, s[36:37]
	s_mov_b32 m0, s6
	s_nop 0
	global_load_lds_dwordx4 v[230:231], off
	v_lshl_add_u64 v[230:231], v[232:233], 0, s[36:37]
	s_add_i32 m0, s6, 0x2000
	s_nop 0
	global_load_lds_dwordx4 v[230:231], off
	s_mov_b32 m0, s70
	v_lshl_add_u64 v[230:231], v[234:235], 0, s[36:37]
	ds_read_b128 v[162:165], v208 offset:49152
	ds_read_b128 v[166:169], v208 offset:50176
	ds_read_b128 v[170:173], v208 offset:51200
	ds_read_b128 v[174:177], v208 offset:52224
	ds_read_b128 v[178:181], v208 offset:53248
	ds_read_b128 v[182:185], v208 offset:54272
	ds_read_b128 v[194:197], v208 offset:55296
	ds_read_b128 v[210:213], v208 offset:56320
	global_load_lds_dwordx4 v[230:231], off
	v_lshl_add_u64 v[230:231], v[236:237], 0, s[36:37]
	s_mov_b32 m0, s71
	s_nop 0
	global_load_lds_dwordx4 v[230:231], off
	s_add_u32 s48, s48, 0xb0080
	s_addc_u32 s49, s49, 0
	s_add_i32 s6, s19, s57
	v_lshl_add_u64 v[250:251], s[48:49], 0, v[140:141]
	s_mov_b32 m0, s6
	s_nop 0
	global_load_lds_dwordx4 v[250:251], off
	v_lshl_add_u64 v[250:251], s[48:49], 0, v[150:151]
	s_add_i32 m0, s6, 0x2000
	s_nop 0
	global_load_lds_dwordx4 v[250:251], off
	s_waitcnt vmcnt(8)
	s_waitcnt lgkmcnt(0)
	s_barrier
	s_setprio 1
	v_mfma_f32_16x16x32_bf16 v[60:63], v[128:131], v[162:165], v[60:63]
	v_mfma_f32_16x16x32_bf16 v[56:59], v[136:139], v[162:165], v[56:59]
	v_mfma_f32_16x16x32_bf16 v[48:51], v[128:131], v[170:173], v[48:51]
	v_mfma_f32_16x16x32_bf16 v[40:43], v[136:139], v[170:173], v[40:43]
	v_mfma_f32_16x16x32_bf16 v[32:35], v[128:131], v[178:181], v[32:35]
	v_mfma_f32_16x16x32_bf16 v[24:27], v[136:139], v[178:181], v[24:27]
	v_mfma_f32_16x16x32_bf16 v[16:19], v[128:131], v[194:197], v[16:19]
	v_mfma_f32_16x16x32_bf16 v[8:11], v[136:139], v[194:197], v[8:11]
	v_mfma_f32_16x16x32_bf16 v[60:63], v[132:135], v[166:169], v[60:63]
	v_mfma_f32_16x16x32_bf16 v[56:59], v[146:149], v[166:169], v[56:59]
	v_mfma_f32_16x16x32_bf16 v[48:51], v[132:135], v[174:177], v[48:51]
	v_mfma_f32_16x16x32_bf16 v[40:43], v[146:149], v[174:177], v[40:43]
	v_mfma_f32_16x16x32_bf16 v[32:35], v[132:135], v[182:185], v[32:35]
	v_mfma_f32_16x16x32_bf16 v[24:27], v[146:149], v[182:185], v[24:27]
	v_mfma_f32_16x16x32_bf16 v[16:19], v[132:135], v[210:213], v[16:19]
	v_mfma_f32_16x16x32_bf16 v[8:11], v[146:149], v[210:213], v[8:11]
	v_mfma_f32_16x16x32_bf16 v[52:55], v[214:217], v[162:165], v[52:55]
	v_mfma_f32_16x16x32_bf16 v[44:47], v[222:225], v[162:165], v[44:47]
	v_mfma_f32_16x16x32_bf16 v[36:39], v[214:217], v[170:173], v[36:39]
	v_mfma_f32_16x16x32_bf16 v[28:31], v[222:225], v[170:173], v[28:31]
	v_mfma_f32_16x16x32_bf16 v[20:23], v[214:217], v[178:181], v[20:23]
	v_mfma_f32_16x16x32_bf16 v[12:15], v[222:225], v[178:181], v[12:15]
	v_mfma_f32_16x16x32_bf16 v[4:7], v[214:217], v[194:197], v[4:7]
	v_mfma_f32_16x16x32_bf16 v[0:3], v[222:225], v[194:197], v[0:3]
	v_mfma_f32_16x16x32_bf16 v[52:55], v[218:221], v[166:169], v[52:55]
	v_mfma_f32_16x16x32_bf16 v[44:47], v[226:229], v[166:169], v[44:47]
	v_mfma_f32_16x16x32_bf16 v[36:39], v[218:221], v[174:177], v[36:39]
	v_mfma_f32_16x16x32_bf16 v[28:31], v[226:229], v[174:177], v[28:31]
	v_mfma_f32_16x16x32_bf16 v[20:23], v[218:221], v[182:185], v[20:23]
	v_mfma_f32_16x16x32_bf16 v[12:15], v[226:229], v[182:185], v[12:15]
	v_mfma_f32_16x16x32_bf16 v[4:7], v[218:221], v[210:213], v[4:7]
	v_mfma_f32_16x16x32_bf16 v[0:3], v[226:229], v[210:213], v[0:3]
	s_setprio 0
	s_add_i32 s12, s12, 2
	s_add_u32 s10, s10, 0x100
	s_addc_u32 s11, s11, 0
	s_cmp_gt_u32 s12, 41
	s_mov_b64 s[50:51], s[46:47]
	s_barrier
	s_cbranch_scc0 .LBB0_341
	s_mov_b32 s100, 1
	s_ashr_i32 s39, s38, 31
	v_lshl_or_b32 v128, s81, 8, v207
	s_lshl_b64 s[10:11], s[38:39], 8
	v_ashrrev_i32_e32 v129, 31, v128
	v_lshl_add_u64 v[168:169], s[10:11], 0, v[156:157]
	v_lshlrev_b64 v[170:171], 1, v[128:129]
	v_lshl_add_u64 v[174:175], s[26:27], 0, v[170:171]
	v_lshlrev_b64 v[172:173], 11, v[168:169]
	v_lshl_add_u64 v[128:129], v[174:175], 0, v[172:173]
	global_load_dwordx4 v[182:185], v[128:129], off
	global_load_dwordx4 v[210:213], v[128:129], off offset:256
	v_or_b32_e32 v166, 16, v168
	v_mov_b32_e32 v167, v169
	v_lshlrev_b64 v[176:177], 11, v[166:167]
	v_lshl_add_u64 v[128:129], v[174:175], 0, v[176:177]
	global_load_dwordx4 v[214:217], v[128:129], off
	global_load_dwordx4 v[218:221], v[128:129], off offset:256
	v_or_b32_e32 v164, 32, v168
	v_mov_b32_e32 v165, v169
	v_or_b32_e32 v162, 48, v168
	v_mov_b32_e32 v163, v169
	v_lshlrev_b64 v[180:181], 11, v[164:165]
	v_lshlrev_b64 v[178:179], 11, v[162:163]
	v_lshl_add_u64 v[128:129], v[174:175], 0, v[180:181]
	v_lshl_add_u64 v[130:131], v[174:175], 0, v[178:179]
	global_load_dwordx4 v[222:225], v[128:129], off
	global_load_dwordx4 v[136:139], v[128:129], off offset:256
	global_load_dwordx4 v[132:135], v[130:131], off
	s_nop 0
	global_load_dwordx4 v[128:131], v[130:131], off offset:256
	s_mov_b64 s[10:11], 0x90
	v_lshl_add_u64 v[172:173], s[28:29], 0, v[172:173]
	v_lshl_add_u64 v[172:173], v[172:173], 0, v[170:171]
	s_waitcnt vmcnt(0)
	v_lshlrev_b32_e32 v146, 16, v182
	v_and_b32_e32 v147, 0xffff0000, v182
	v_lshlrev_b32_e32 v148, 16, v184
	v_and_b32_e32 v149, 0xffff0000, v184
	v_lshlrev_b32_e32 v182, 16, v183
	v_and_b32_e32 v183, 0xffff0000, v183
	v_lshlrev_b32_e32 v194, 16, v210
	v_and_b32_e32 v195, 0xffff0000, v210
	v_lshlrev_b32_e32 v196, 16, v212
	v_and_b32_e32 v197, 0xffff0000, v212
	v_lshlrev_b32_e32 v210, 16, v211
	v_and_b32_e32 v211, 0xffff0000, v211
	v_lshlrev_b32_e32 v212, 16, v213
	v_and_b32_e32 v213, 0xffff0000, v213
	v_pk_fma_f32 v[124:125], v[124:125], 0.5, v[146:147] op_sel_hi:[1,0,1]
	v_pk_fma_f32 v[120:121], v[120:121], 0.5, v[148:149] op_sel_hi:[1,0,1]
	v_pk_fma_f32 v[126:127], v[126:127], 0.5, v[182:183] op_sel_hi:[1,0,1]
	v_pk_fma_f32 v[116:117], v[116:117], 0.5, v[194:195] op_sel_hi:[1,0,1]
	v_pk_fma_f32 v[146:147], v[112:113], 0.5, v[196:197] op_sel_hi:[1,0,1]
	v_pk_fma_f32 v[118:119], v[118:119], 0.5, v[210:211] op_sel_hi:[1,0,1]
	v_pk_fma_f32 v[148:149], v[114:115], 0.5, v[212:213] op_sel_hi:[1,0,1]
	v_pk_mul_f32 v[212:213], v[124:125], v[124:125]
	v_lshlrev_b32_e32 v182, 16, v214
	v_and_b32_e32 v183, 0xffff0000, v214
	v_lshlrev_b32_e32 v194, 16, v215
	v_and_b32_e32 v195, 0xffff0000, v215
	v_pk_mul_f32 v[214:215], v[126:127], v[126:127]
	v_cvt_pk_bf16_f32 v112, v124, v125
	v_cvt_pk_bf16_f32 v113, v126, v127
	v_pk_mul_f32 v[124:125], v[116:117], v[116:117]
	v_pk_mul_f32 v[126:127], v[118:119], v[118:119]
	v_pk_mul_f32 v[228:229], v[146:147], v[146:147]
	v_cvt_pk_bf16_f32 v116, v116, v117
	v_cvt_pk_bf16_f32 v117, v118, v119
	v_cvt_pk_bf16_f32 v118, v146, v147
	v_add_f32_e32 v146, v212, v213
	v_lshlrev_b32_e32 v184, 16, v185
	v_and_b32_e32 v185, 0xffff0000, v185
	v_add_f32_e32 v146, v214, v146
	v_pk_fma_f32 v[122:123], v[122:123], 0.5, v[184:185] op_sel_hi:[1,0,1]
	v_lshlrev_b32_e32 v184, 16, v216
	v_and_b32_e32 v185, 0xffff0000, v216
	v_lshlrev_b32_e32 v196, 16, v217
	v_and_b32_e32 v197, 0xffff0000, v217
	v_pk_mul_f32 v[216:217], v[120:121], v[120:121]
	v_add_f32_e32 v146, v215, v146
	v_add_f32_e32 v146, v216, v146
	v_pk_mul_f32 v[226:227], v[122:123], v[122:123]
	v_add_f32_e32 v146, v217, v146
	v_add_f32_e32 v146, v226, v146
	v_add_f32_e32 v146, v227, v146
	v_add_f32_e32 v124, v124, v146
	v_add_f32_e32 v124, v125, v124
	v_add_f32_e32 v124, v126, v124
	v_add_f32_e32 v124, v127, v124
	v_add_f32_e32 v124, v228, v124
	v_pk_mul_f32 v[230:231], v[148:149], v[148:149]
	v_add_f32_e32 v124, v229, v124
	v_add_f32_e32 v124, v230, v124
	v_add_f32_e32 v209, v231, v124
	v_lshlrev_b32_e32 v124, 16, v220
	v_and_b32_e32 v125, 0xffff0000, v220
	v_pk_fma_f32 v[124:125], v[92:93], 0.5, v[124:125] op_sel_hi:[1,0,1]
	v_lshlrev_b32_e32 v92, 16, v219
	v_and_b32_e32 v93, 0xffff0000, v219
	v_pk_fma_f32 v[102:103], v[102:103], 0.5, v[92:93] op_sel_hi:[1,0,1]
	v_lshlrev_b32_e32 v92, 16, v221
	v_and_b32_e32 v93, 0xffff0000, v221
	v_pk_fma_f32 v[126:127], v[94:95], 0.5, v[92:93] op_sel_hi:[1,0,1]
	v_lshlrev_b32_e32 v92, 16, v222
	v_and_b32_e32 v93, 0xffff0000, v222
	v_pk_fma_f32 v[92:93], v[96:97], 0.5, v[92:93] op_sel_hi:[1,0,1]
	v_lshlrev_b32_e32 v96, 16, v225
	v_and_b32_e32 v97, 0xffff0000, v225
	v_lshlrev_b32_e32 v94, 16, v224
	v_and_b32_e32 v95, 0xffff0000, v224
	v_pk_fma_f32 v[90:91], v[90:91], 0.5, v[96:97] op_sel_hi:[1,0,1]
	v_lshlrev_b32_e32 v96, 16, v136
	v_and_b32_e32 v97, 0xffff0000, v136
	v_pk_fma_f32 v[88:89], v[88:89], 0.5, v[94:95] op_sel_hi:[1,0,1]
	v_lshlrev_b32_e32 v94, 16, v223
	v_and_b32_e32 v95, 0xffff0000, v223
	v_pk_fma_f32 v[96:97], v[76:77], 0.5, v[96:97] op_sel_hi:[1,0,1]
	v_lshl_add_u64 v[76:77], v[168:169], 0, s[36:37]
	v_cvt_pk_bf16_f32 v114, v120, v121
	v_pk_fma_f32 v[120:121], v[108:109], 0.5, v[182:183] op_sel_hi:[1,0,1]
	v_pk_fma_f32 v[94:95], v[98:99], 0.5, v[94:95] op_sel_hi:[1,0,1]
	v_lshlrev_b64 v[182:183], 11, v[76:77]
	v_lshlrev_b32_e32 v98, 16, v138
	v_and_b32_e32 v99, 0xffff0000, v138
	v_lshl_add_u64 v[146:147], v[174:175], 0, v[182:183]
	v_pk_fma_f32 v[98:99], v[72:73], 0.5, v[98:99] op_sel_hi:[1,0,1]
	v_lshlrev_b32_e32 v72, 16, v137
	v_and_b32_e32 v73, 0xffff0000, v137
	v_lshlrev_b32_e32 v210, 16, v218
	v_and_b32_e32 v211, 0xffff0000, v218
	global_load_dwordx4 v[218:221], v[146:147], off
	global_load_dwordx4 v[226:229], v[146:147], off offset:256
	v_pk_fma_f32 v[136:137], v[78:79], 0.5, v[72:73] op_sel_hi:[1,0,1]
	v_lshlrev_b32_e32 v72, 16, v139
	v_and_b32_e32 v73, 0xffff0000, v139
	v_pk_fma_f32 v[138:139], v[74:75], 0.5, v[72:73] op_sel_hi:[1,0,1]
	v_lshlrev_b32_e32 v72, 16, v132
	v_and_b32_e32 v73, 0xffff0000, v132
	v_pk_fma_f32 v[74:75], v[84:85], 0.5, v[72:73] op_sel_hi:[1,0,1]
	v_lshlrev_b32_e32 v72, 16, v134
	v_and_b32_e32 v73, 0xffff0000, v134
	v_pk_fma_f32 v[78:79], v[80:81], 0.5, v[72:73] op_sel_hi:[1,0,1]
	v_lshlrev_b32_e32 v72, 16, v133
	v_and_b32_e32 v73, 0xffff0000, v133
	v_pk_fma_f32 v[80:81], v[86:87], 0.5, v[72:73] op_sel_hi:[1,0,1]
	v_lshlrev_b32_e32 v72, 16, v135
	v_and_b32_e32 v73, 0xffff0000, v135
	v_pk_fma_f32 v[82:83], v[82:83], 0.5, v[72:73] op_sel_hi:[1,0,1]
	v_lshl_add_u64 v[72:73], v[168:169], 0, s[10:11]
	v_lshlrev_b64 v[132:133], 11, v[72:73]
	v_lshl_add_u64 v[134:135], v[174:175], 0, v[132:133]
	global_load_dwordx4 v[234:237], v[134:135], off
	global_load_dwordx4 v[242:245], v[134:135], off offset:256
	v_lshlrev_b32_e32 v84, 16, v128
	v_and_b32_e32 v85, 0xffff0000, v128
	v_pk_fma_f32 v[84:85], v[68:69], 0.5, v[84:85] op_sel_hi:[1,0,1]
	v_lshlrev_b32_e32 v68, 16, v130
	v_and_b32_e32 v69, 0xffff0000, v130
	v_pk_fma_f32 v[86:87], v[64:65], 0.5, v[68:69] op_sel_hi:[1,0,1]
	v_lshlrev_b32_e32 v64, 16, v129
	v_and_b32_e32 v65, 0xffff0000, v129
	s_mov_b64 s[10:11], 0xa0
	v_pk_fma_f32 v[128:129], v[70:71], 0.5, v[64:65] op_sel_hi:[1,0,1]
	v_lshl_add_u64 v[70:71], v[168:169], 0, s[10:11]
	v_lshlrev_b32_e32 v64, 16, v131
	v_and_b32_e32 v65, 0xffff0000, v131
	v_lshlrev_b64 v[134:135], 11, v[70:71]
	v_pk_fma_f32 v[130:131], v[66:67], 0.5, v[64:65] op_sel_hi:[1,0,1]
	v_lshl_add_u64 v[64:65], v[174:175], 0, v[134:135]
	v_cvt_pk_bf16_f32 v115, v122, v123
	v_pk_fma_f32 v[122:123], v[110:111], 0.5, v[194:195] op_sel_hi:[1,0,1]
	v_pk_fma_f32 v[110:111], v[106:107], 0.5, v[196:197] op_sel_hi:[1,0,1]
	global_load_dwordx4 v[246:249], v[64:65], off
	global_load_dwordx4 v[194:197], v[64:65], off offset:256
	s_mov_b64 s[10:11], 0xb0
	v_lshl_add_u64 v[68:69], v[168:169], 0, s[10:11]
	v_pk_fma_f32 v[108:109], v[104:105], 0.5, v[184:185] op_sel_hi:[1,0,1]
	v_lshlrev_b64 v[184:185], 11, v[68:69]
	v_lshl_add_u64 v[64:65], v[174:175], 0, v[184:185]
	v_cvt_pk_bf16_f32 v119, v148, v149
	global_load_dwordx4 v[146:149], v[64:65], off
	s_nop 0
	global_load_dwordx4 v[64:67], v[64:65], off offset:256
	global_store_dwordx4 v[172:173], v[112:115], off
	global_store_dwordx4 v[172:173], v[116:119], off offset:256
	v_cvt_pk_bf16_f32 v104, v120, v121
	v_lshl_add_u64 v[112:113], s[28:29], 0, v[176:177]
	v_cvt_pk_bf16_f32 v105, v122, v123
	v_cvt_pk_bf16_f32 v106, v108, v109
	v_cvt_pk_bf16_f32 v107, v110, v111
	v_pk_fma_f32 v[100:101], v[100:101], 0.5, v[210:211] op_sel_hi:[1,0,1]
	v_lshl_add_u64 v[112:113], v[112:113], 0, v[170:171]
	v_cvt_pk_bf16_f32 v210, v100, v101
	v_cvt_pk_bf16_f32 v211, v102, v103
	v_cvt_pk_bf16_f32 v212, v124, v125
	v_cvt_pk_bf16_f32 v213, v126, v127
	global_store_dwordx4 v[112:113], v[104:107], off
	global_store_dwordx4 v[112:113], v[210:213], off offset:256
	v_cvt_pk_bf16_f32 v214, v92, v93
	v_lshl_add_u64 v[104:105], s[28:29], 0, v[180:181]
	v_cvt_pk_bf16_f32 v215, v94, v95
	v_cvt_pk_bf16_f32 v216, v88, v89
	v_cvt_pk_bf16_f32 v217, v90, v91
	v_lshl_add_u64 v[104:105], v[104:105], 0, v[170:171]
	v_cvt_pk_bf16_f32 v222, v96, v97
	v_cvt_pk_bf16_f32 v223, v136, v137
	v_cvt_pk_bf16_f32 v224, v98, v99
	v_cvt_pk_bf16_f32 v225, v138, v139
	global_store_dwordx4 v[104:105], v[214:217], off
	global_store_dwordx4 v[104:105], v[222:225], off offset:256
	v_lshl_add_u64 v[104:105], s[28:29], 0, v[178:179]
	v_cvt_pk_bf16_f32 v230, v74, v75
	v_cvt_pk_bf16_f32 v231, v80, v81
	v_cvt_pk_bf16_f32 v232, v78, v79
	v_cvt_pk_bf16_f32 v233, v82, v83
	v_lshl_add_u64 v[104:105], v[104:105], 0, v[170:171]
	v_cvt_pk_bf16_f32 v238, v84, v85
	v_cvt_pk_bf16_f32 v239, v128, v129
	v_cvt_pk_bf16_f32 v240, v86, v87
	v_cvt_pk_bf16_f32 v241, v130, v131
	global_store_dwordx4 v[104:105], v[230:233], off
	global_store_dwordx4 v[104:105], v[238:241], off offset:256
	s_waitcnt vmcnt(0)
	v_lshlrev_b32_e32 v104, 16, v218
	v_and_b32_e32 v105, 0xffff0000, v218
	v_pk_fma_f32 v[60:61], v[60:61], 0.5, v[104:105] op_sel_hi:[1,0,1]
	v_lshlrev_b32_e32 v104, 16, v220
	v_and_b32_e32 v105, 0xffff0000, v220
	v_pk_fma_f32 v[56:57], v[56:57], 0.5, v[104:105] op_sel_hi:[1,0,1]
	v_lshlrev_b32_e32 v104, 16, v219
	v_and_b32_e32 v105, 0xffff0000, v219
	v_pk_fma_f32 v[62:63], v[62:63], 0.5, v[104:105] op_sel_hi:[1,0,1]
	v_lshlrev_b32_e32 v104, 16, v221
	v_and_b32_e32 v105, 0xffff0000, v221
	v_pk_fma_f32 v[58:59], v[58:59], 0.5, v[104:105] op_sel_hi:[1,0,1]
	v_lshlrev_b32_e32 v104, 16, v226
	v_and_b32_e32 v105, 0xffff0000, v226
	v_pk_fma_f32 v[52:53], v[52:53], 0.5, v[104:105] op_sel_hi:[1,0,1]
	v_lshlrev_b32_e32 v104, 16, v228
	v_and_b32_e32 v105, 0xffff0000, v228
	v_pk_fma_f32 v[104:105], v[44:45], 0.5, v[104:105] op_sel_hi:[1,0,1]
	v_lshlrev_b32_e32 v44, 16, v227
	v_and_b32_e32 v45, 0xffff0000, v227
	v_pk_fma_f32 v[54:55], v[54:55], 0.5, v[44:45] op_sel_hi:[1,0,1]
	v_lshlrev_b32_e32 v44, 16, v229
	v_and_b32_e32 v45, 0xffff0000, v229
	v_pk_fma_f32 v[106:107], v[46:47], 0.5, v[44:45] op_sel_hi:[1,0,1]
	v_lshlrev_b32_e32 v44, 16, v234
	v_and_b32_e32 v45, 0xffff0000, v234
	v_pk_fma_f32 v[44:45], v[48:49], 0.5, v[44:45] op_sel_hi:[1,0,1]
	v_lshlrev_b32_e32 v48, 16, v237
	v_and_b32_e32 v49, 0xffff0000, v237
	v_pk_fma_f32 v[42:43], v[42:43], 0.5, v[48:49] op_sel_hi:[1,0,1]
	v_lshlrev_b32_e32 v48, 16, v242
	v_and_b32_e32 v49, 0xffff0000, v242
	v_pk_fma_f32 v[36:37], v[36:37], 0.5, v[48:49] op_sel_hi:[1,0,1]
	v_lshlrev_b32_e32 v48, 16, v244
	v_and_b32_e32 v49, 0xffff0000, v244
	v_lshlrev_b32_e32 v46, 16, v236
	v_and_b32_e32 v47, 0xffff0000, v236
	v_pk_fma_f32 v[48:49], v[28:29], 0.5, v[48:49] op_sel_hi:[1,0,1]
	v_lshlrev_b32_e32 v28, 16, v243
	v_and_b32_e32 v29, 0xffff0000, v243
	v_pk_fma_f32 v[40:41], v[40:41], 0.5, v[46:47] op_sel_hi:[1,0,1]
	v_lshlrev_b32_e32 v46, 16, v235
	v_and_b32_e32 v47, 0xffff0000, v235
	v_pk_fma_f32 v[38:39], v[38:39], 0.5, v[28:29] op_sel_hi:[1,0,1]
	v_lshlrev_b32_e32 v28, 16, v245
	v_and_b32_e32 v29, 0xffff0000, v245
	v_pk_fma_f32 v[46:47], v[50:51], 0.5, v[46:47] op_sel_hi:[1,0,1]
	v_pk_fma_f32 v[50:51], v[30:31], 0.5, v[28:29] op_sel_hi:[1,0,1]
	v_lshlrev_b32_e32 v28, 16, v246
	v_and_b32_e32 v29, 0xffff0000, v246
	v_pk_fma_f32 v[28:29], v[32:33], 0.5, v[28:29] op_sel_hi:[1,0,1]
	v_lshlrev_b32_e32 v32, 16, v249
	v_and_b32_e32 v33, 0xffff0000, v249
	v_pk_fma_f32 v[26:27], v[26:27], 0.5, v[32:33] op_sel_hi:[1,0,1]
	v_lshlrev_b32_e32 v32, 16, v194
	v_and_b32_e32 v33, 0xffff0000, v194
	v_pk_fma_f32 v[20:21], v[20:21], 0.5, v[32:33] op_sel_hi:[1,0,1]
	v_lshlrev_b32_e32 v32, 16, v196
	v_and_b32_e32 v33, 0xffff0000, v196
	v_lshlrev_b32_e32 v30, 16, v248
	v_and_b32_e32 v31, 0xffff0000, v248
	v_pk_fma_f32 v[32:33], v[12:13], 0.5, v[32:33] op_sel_hi:[1,0,1]
	v_lshlrev_b32_e32 v12, 16, v195
	v_and_b32_e32 v13, 0xffff0000, v195
	v_pk_fma_f32 v[24:25], v[24:25], 0.5, v[30:31] op_sel_hi:[1,0,1]
	v_lshlrev_b32_e32 v30, 16, v247
	v_and_b32_e32 v31, 0xffff0000, v247
	v_pk_fma_f32 v[22:23], v[22:23], 0.5, v[12:13] op_sel_hi:[1,0,1]
	v_lshlrev_b32_e32 v12, 16, v197
	v_and_b32_e32 v13, 0xffff0000, v197
	v_pk_fma_f32 v[30:31], v[34:35], 0.5, v[30:31] op_sel_hi:[1,0,1]
	v_pk_fma_f32 v[34:35], v[14:15], 0.5, v[12:13] op_sel_hi:[1,0,1]
	v_lshlrev_b32_e32 v14, 16, v148
	v_and_b32_e32 v15, 0xffff0000, v148
	v_lshlrev_b32_e32 v12, 16, v146
	v_and_b32_e32 v13, 0xffff0000, v146
	v_pk_fma_f32 v[8:9], v[8:9], 0.5, v[14:15] op_sel_hi:[1,0,1]
	v_lshlrev_b32_e32 v14, 16, v147
	v_and_b32_e32 v15, 0xffff0000, v147
	v_lshlrev_b32_e32 v146, 16, v64
	v_and_b32_e32 v147, 0xffff0000, v64
	v_pk_fma_f32 v[4:5], v[4:5], 0.5, v[146:147] op_sel_hi:[1,0,1]
	v_lshlrev_b32_e32 v146, 16, v66
	v_and_b32_e32 v147, 0xffff0000, v66
	v_pk_fma_f32 v[0:1], v[0:1], 0.5, v[146:147] op_sel_hi:[1,0,1]
	v_lshl_add_u64 v[146:147], s[28:29], 0, v[182:183]
	v_cvt_pk_bf16_f32 v112, v60, v61
	v_cvt_pk_bf16_f32 v113, v62, v63
	v_cvt_pk_bf16_f32 v114, v56, v57
	v_cvt_pk_bf16_f32 v115, v58, v59
	v_lshl_add_u64 v[146:147], v[146:147], 0, v[170:171]
	v_cvt_pk_bf16_f32 v116, v52, v53
	v_cvt_pk_bf16_f32 v117, v54, v55
	v_cvt_pk_bf16_f32 v118, v104, v105
	v_cvt_pk_bf16_f32 v119, v106, v107
	global_store_dwordx4 v[146:147], v[112:115], off
	global_store_dwordx4 v[146:147], v[116:119], off offset:256
	v_cvt_pk_bf16_f32 v172, v44, v45
	v_lshl_add_u64 v[112:113], s[28:29], 0, v[132:133]
	v_cvt_pk_bf16_f32 v173, v46, v47
	v_cvt_pk_bf16_f32 v174, v40, v41
	v_cvt_pk_bf16_f32 v175, v42, v43
	v_lshl_add_u64 v[112:113], v[112:113], 0, v[170:171]
	v_cvt_pk_bf16_f32 v176, v36, v37
	v_cvt_pk_bf16_f32 v177, v38, v39
	v_cvt_pk_bf16_f32 v178, v48, v49
	v_cvt_pk_bf16_f32 v179, v50, v51
	global_store_dwordx4 v[112:113], v[172:175], off
	global_store_dwordx4 v[112:113], v[176:179], off offset:256
	v_lshl_add_u64 v[112:113], s[28:29], 0, v[134:135]
	v_cvt_pk_bf16_f32 v210, v28, v29
	v_cvt_pk_bf16_f32 v211, v30, v31
	v_cvt_pk_bf16_f32 v212, v24, v25
	v_cvt_pk_bf16_f32 v213, v26, v27
	v_pk_fma_f32 v[12:13], v[16:17], 0.5, v[12:13] op_sel_hi:[1,0,1]
	v_lshlrev_b32_e32 v16, 16, v149
	v_and_b32_e32 v17, 0xffff0000, v149
	v_lshlrev_b32_e32 v64, 16, v65
	v_and_b32_e32 v65, 0xffff0000, v65
	v_lshl_add_u64 v[112:113], v[112:113], 0, v[170:171]
	v_cvt_pk_bf16_f32 v194, v20, v21
	v_cvt_pk_bf16_f32 v195, v22, v23
	v_cvt_pk_bf16_f32 v196, v32, v33
	v_cvt_pk_bf16_f32 v197, v34, v35
	v_pk_fma_f32 v[14:15], v[18:19], 0.5, v[14:15] op_sel_hi:[1,0,1]
	v_pk_fma_f32 v[10:11], v[10:11], 0.5, v[16:17] op_sel_hi:[1,0,1]
	v_pk_fma_f32 v[6:7], v[6:7], 0.5, v[64:65] op_sel_hi:[1,0,1]
	v_lshlrev_b32_e32 v64, 16, v67
	v_and_b32_e32 v65, 0xffff0000, v67
	global_store_dwordx4 v[112:113], v[210:213], off
	global_store_dwordx4 v[112:113], v[194:197], off offset:256
	v_lshl_add_u64 v[112:113], s[28:29], 0, v[184:185]
	v_cvt_pk_bf16_f32 v16, v12, v13
	v_cvt_pk_bf16_f32 v17, v14, v15
	v_cvt_pk_bf16_f32 v18, v8, v9
	v_cvt_pk_bf16_f32 v19, v10, v11
	v_pk_fma_f32 v[2:3], v[2:3], 0.5, v[64:65] op_sel_hi:[1,0,1]
	v_lshl_add_u64 v[112:113], v[112:113], 0, v[170:171]
	v_cvt_pk_bf16_f32 v64, v4, v5
	v_cvt_pk_bf16_f32 v65, v6, v7
	v_cvt_pk_bf16_f32 v66, v0, v1
	v_cvt_pk_bf16_f32 v67, v2, v3
	global_store_dwordx4 v[112:113], v[16:19], off
	global_store_dwordx4 v[112:113], v[64:67], off offset:256
	s_lshl_b32 s10, s81, 2
	v_and_b32_e32 v17, 64, v188
	v_xor_b32_e32 v16, 16, v188
	v_add_u32_e32 v17, 64, v17
	v_cmp_lt_i32_e32 vcc, v16, v17
	v_xor_b32_e32 v18, 32, v188
	s_ashr_i32 s11, s10, 31
	v_cndmask_b32_e32 v16, v188, v16, vcc
	v_lshlrev_b32_e32 v16, 2, v16
	ds_bpermute_b32 v19, v16, v209
	v_cmp_lt_i32_e32 vcc, v18, v17
	s_lshl_b64 s[10:11], s[10:11], 2
	s_add_u32 s38, s73, s10
	v_cndmask_b32_e32 v17, v188, v18, vcc
	v_lshlrev_b32_e32 v17, 2, v17
	s_waitcnt lgkmcnt(0)
	v_add_f32_e32 v18, v209, v19
	ds_bpermute_b32 v19, v17, v18
	s_addc_u32 s39, s74, s11
	s_and_saveexec_b64 s[46:47], s[42:43]
	s_cbranch_execz .LBB0_344
	s_waitcnt lgkmcnt(0)
	v_add_f32_e32 v64, v18, v19
	v_lshlrev_b64 v[18:19], 6, v[168:169]
	v_lshl_add_u64 v[18:19], s[38:39], 0, v[18:19]
	global_store_dword v[18:19], v64, off

.LBB0_381:
	s_add_u32 s30, s30, 0x3290000
	v_and_b32_e32 v15, 15, v8
	v_lshrrev_b32_e32 v8, 1, v8
	s_addc_u32 s31, s31, 0
	v_and_b32_e32 v8, 24, v8
	s_lshl_b32 s10, s10, 5
	v_lshlrev_b32_e32 v16, 1, v8
	v_lshlrev_b32_e32 v17, 2, v15
	s_and_b32 s19, s10, 0x60
	s_add_i32 m0, s68, 0x18000
	v_lshl_add_u64 v[6:7], v[6:7], 0, s[36:37]
	s_lshl_b32 s12, s6, 6
	v_lshl_or_b32 v16, v15, 6, v16
	s_lshl_b32 s11, s6, 13
	v_and_b32_e32 v18, 32, v17
	s_lshl_b32 s10, s19, 7
	s_waitcnt vmcnt(0)
	s_barrier
	global_load_lds_dwordx4 v[6:7], off
	v_lshl_add_u64 v[4:5], v[4:5], 0, s[36:37]
	s_add_i32 m0, s68, 0x1a000
	s_add_i32 s72, s68, 0x8000
	s_add_i32 s73, s68, 0xa000
	v_bitop3_b32 v154, v16, s10, v18 bitop3:0xde
	global_load_lds_dwordx4 v[4:5], off
	v_lshl_add_u64 v[2:3], v[2:3], 0, s[36:37]
	s_mov_b32 m0, s72
	s_add_u32 s10, s52, 0x40080
	v_bitop3_b32 v19, v16, s11, v18 bitop3:0xde
	global_load_lds_dwordx4 v[2:3], off
	v_lshl_add_u64 v[0:1], v[0:1], 0, s[36:37]
	s_mov_b32 m0, s73
	s_addc_u32 s11, s53, 0
	global_load_lds_dwordx4 v[0:1], off
	s_add_i32 m0, s68, 0x1c000
	v_lshl_add_u64 v[0:1], s[10:11], 0, v[140:141]
	global_load_lds_dwordx4 v[0:1], off
	v_lshl_add_u64 v[0:1], s[10:11], 0, v[132:133]
	s_add_i32 m0, s68, 0x1e000
	s_lshl_b32 s6, s6, 8
	global_load_lds_dwordx4 v[0:1], off
	v_lshlrev_b32_e32 v0, 14, v9
	v_and_b32_e32 v0, 0xffff8000, v0
	v_lshl_add_u32 v0, v10, 11, v0
	v_and_b32_e32 v1, 1, v9
	v_lshl_or_b32 v0, v1, 6, v0
	v_lshl_add_u32 v136, v11, 1, v0
	v_lshlrev_b32_e32 v0, 14, v12
	v_and_b32_e32 v0, 0xffff8000, v0
	s_add_i32 s6, s6, 0
	v_lshl_add_u32 v0, v13, 11, v0
	v_and_b32_e32 v1, 1, v12
	s_waitcnt vmcnt(6)
	s_add_i32 s6, s6, 0x22000
	v_lshl_or_b32 v0, v1, 6, v0
	v_add_u32_e32 v155, s6, v17
	s_ashr_i32 s6, s12, 31
	v_lshl_add_u32 v138, v14, 1, v0
	v_or_b32_e32 v134, s12, v15
	v_mov_b32_e32 v135, s6
	v_or_b32_e32 v156, s19, v8
	v_mov_b32_e32 v137, v141
	v_mov_b32_e32 v139, v141
	s_mov_b32 s75, 0
	v_add_u32_e32 v157, 0, v19
	v_readlane_b32 s74, v253, 49
	v_readlane_b32 s34, v254, 0
	s_barrier
	v_readlane_b32 s35, v254, 1
	s_mov_b32 s100, 0
	s_branch .LBB0_383
.LBB0_382:
	s_mov_b32 s74, s46
	s_mov_b32 s34, s38
	s_mov_b64 s[28:29], s[50:51]
	s_mov_b32 s75, s80
	s_andn2_b64 vcc, exec, s[42:43]
	s_mov_b64 s[52:53], s[48:49]
	s_cbranch_vccz .LBB0_389

.LBB0_385:
	s_add_u32 s10, s52, 0x100
	s_addc_u32 s11, s53, 0
	s_ashr_i32 s39, s38, 31
	s_lshl_b64 s[48:49], s[38:39], 19
	s_add_u32 s50, s33, s48
	s_addc_u32 s51, s41, s49
	s_and_b64 s[48:49], s[44:45], exec
	s_cselect_b32 s12, s51, s29
	s_cselect_b32 s35, s50, s28
	s_ashr_i32 s47, s46, 31
	s_lshl_b64 s[48:49], s[46:47], 19
	s_add_u32 s48, s26, s48
	s_addc_u32 s49, s27, s49
	s_and_b64 s[54:55], s[44:45], exec
	s_cselect_b32 s39, s49, s53
	s_cselect_b32 s47, s48, s52
	s_add_u32 s52, s28, 0x40080
	s_addc_u32 s53, s29, 0
	v_lshl_add_u64 v[150:151], s[52:53], 0, v[136:137]
	v_lshl_add_u64 v[152:153], s[52:53], 0, v[138:139]
	s_mov_b32 s81, -2
	s_mov_b64 s[52:53], 0
	s_add_u32 s6, s28, s52
	s_addc_u32 s19, s29, s53
	s_add_u32 s6, s6, 0x100
	s_addc_u32 s19, s19, 0
	s_add_u32 s23, s10, s52
	s_addc_u32 s54, s11, s53
	s_add_i32 s82, 0, 0x10000
	v_add_u32_e32 v146, s82, v154
	ds_read_b128 v[158:161], v146
	ds_read_b128 v[162:165], v146 offset:1024
	ds_read_b128 v[166:169], v146 offset:2048
	ds_read_b128 v[170:173], v146 offset:3072
	s_cmpk_eq_i32 s52, 0x700
	s_cselect_b32 s59, s12, s19
	s_cselect_b32 s58, s35, s6
	s_cselect_b32 s55, s39, s54
	s_cselect_b32 s54, s47, s23
	v_lshl_add_u64 v[146:147], v[150:151], 0, s[52:53]
	s_add_i32 m0, s68, 0xc000
	ds_read_b128 v[174:177], v157
	ds_read_b128 v[178:181], v157 offset:1024
	ds_read_b128 v[182:185], v157 offset:2048
	ds_read_b128 v[206:209], v157 offset:3072
	ds_read_b128 v[210:213], v157 offset:4096
	ds_read_b128 v[214:217], v157 offset:5120
	ds_read_b128 v[218:221], v157 offset:6144
	ds_read_b128 v[222:225], v157 offset:7168
	global_load_lds_dwordx4 v[146:147], off
	v_lshl_add_u64 v[146:147], v[152:153], 0, s[52:53]
	s_add_i32 m0, s68, 0xe000
	s_nop 0
	global_load_lds_dwordx4 v[146:147], off
	s_add_i32 s6, 0, 0x14000
	v_add_u32_e32 v146, s6, v154
	ds_read_b128 v[226:229], v146
	ds_read_b128 v[230:233], v146 offset:1024
	ds_read_b128 v[234:237], v146 offset:2048
	ds_read_b128 v[238:241], v146 offset:3072
	s_waitcnt vmcnt(16)
	s_cmp_lg_u32 s100, 0
	s_cbranch_scc1 .Lm4ap_386
	s_waitcnt vmcnt(8)
.Lm4ap_386:
	s_waitcnt lgkmcnt(0)
	s_barrier
	s_setprio 1
	v_mfma_f32_16x16x32_bf16 v[124:127], v[158:161], v[174:177], 0
	v_mfma_f32_16x16x32_bf16 v[120:123], v[166:169], v[174:177], 0
	v_mfma_f32_16x16x32_bf16 v[116:119], v[158:161], v[182:185], 0
	v_mfma_f32_16x16x32_bf16 v[112:115], v[166:169], v[182:185], 0
	v_mfma_f32_16x16x32_bf16 v[108:111], v[158:161], v[210:213], 0
	v_mfma_f32_16x16x32_bf16 v[104:107], v[166:169], v[210:213], 0
	v_mfma_f32_16x16x32_bf16 v[100:103], v[158:161], v[218:221], 0
	v_mfma_f32_16x16x32_bf16 v[96:99], v[166:169], v[218:221], 0
	v_mfma_f32_16x16x32_bf16 v[124:127], v[162:165], v[178:181], v[124:127]
	v_mfma_f32_16x16x32_bf16 v[120:123], v[170:173], v[178:181], v[120:123]
	v_mfma_f32_16x16x32_bf16 v[116:119], v[162:165], v[206:209], v[116:119]
	v_mfma_f32_16x16x32_bf16 v[112:115], v[170:173], v[206:209], v[112:115]
	v_mfma_f32_16x16x32_bf16 v[108:111], v[162:165], v[214:217], v[108:111]
	v_mfma_f32_16x16x32_bf16 v[104:107], v[170:173], v[214:217], v[104:107]
	v_mfma_f32_16x16x32_bf16 v[100:103], v[162:165], v[222:225], v[100:103]
	v_mfma_f32_16x16x32_bf16 v[96:99], v[170:173], v[222:225], v[96:99]
	v_mfma_f32_16x16x32_bf16 v[92:95], v[226:229], v[174:177], 0
	v_mfma_f32_16x16x32_bf16 v[88:91], v[234:237], v[174:177], 0
	v_mfma_f32_16x16x32_bf16 v[84:87], v[226:229], v[182:185], 0
	v_mfma_f32_16x16x32_bf16 v[80:83], v[234:237], v[182:185], 0
	v_mfma_f32_16x16x32_bf16 v[76:79], v[226:229], v[210:213], 0
	v_mfma_f32_16x16x32_bf16 v[72:75], v[234:237], v[210:213], 0
	v_mfma_f32_16x16x32_bf16 v[68:71], v[226:229], v[218:221], 0
	v_mfma_f32_16x16x32_bf16 v[64:67], v[234:237], v[218:221], 0
	v_mfma_f32_16x16x32_bf16 v[92:95], v[230:233], v[178:181], v[92:95]
	v_mfma_f32_16x16x32_bf16 v[88:91], v[238:241], v[178:181], v[88:91]
	v_mfma_f32_16x16x32_bf16 v[84:87], v[230:233], v[206:209], v[84:87]
	v_mfma_f32_16x16x32_bf16 v[80:83], v[238:241], v[206:209], v[80:83]
	v_mfma_f32_16x16x32_bf16 v[76:79], v[230:233], v[214:217], v[76:79]
	v_mfma_f32_16x16x32_bf16 v[72:75], v[238:241], v[214:217], v[72:75]
	v_mfma_f32_16x16x32_bf16 v[68:71], v[230:233], v[222:225], v[68:71]
	v_mfma_f32_16x16x32_bf16 v[64:67], v[238:241], v[222:225], v[64:67]
	s_setprio 0
	s_barrier
	s_add_i32 s19, s82, s57
	v_lshl_add_u64 v[146:147], s[54:55], 0, v[140:141]
	s_mov_b32 m0, s19
	v_lshl_add_u64 v[148:149], s[54:55], 0, v[132:133]
	global_load_lds_dwordx4 v[146:147], off
	s_add_i32 m0, s19, 0x2000
	s_nop 0
	global_load_lds_dwordx4 v[148:149], off
	s_mov_b32 m0, s68
	v_lshl_add_u64 v[194:195], s[58:59], 0, v[128:129]
	ds_read_b128 v[174:177], v157 offset:16384
	ds_read_b128 v[178:181], v157 offset:17408
	ds_read_b128 v[182:185], v157 offset:18432
	ds_read_b128 v[206:209], v157 offset:19456
	ds_read_b128 v[210:213], v157 offset:20480
	ds_read_b128 v[214:217], v157 offset:21504
	ds_read_b128 v[218:221], v157 offset:22528
	ds_read_b128 v[222:225], v157 offset:23552
	global_load_lds_dwordx4 v[194:195], off
	v_lshl_add_u64 v[196:197], s[58:59], 0, v[130:131]
	s_mov_b32 m0, s69
	s_nop 0
	global_load_lds_dwordx4 v[196:197], off
	s_add_u32 s82, s54, 0x40000
	s_addc_u32 s83, s55, 0
	s_add_i32 s6, s6, s57
	v_lshl_add_u64 v[250:251], s[82:83], 0, v[140:141]
	s_mov_b32 m0, s6
	s_nop 0
	global_load_lds_dwordx4 v[250:251], off
	v_lshl_add_u64 v[250:251], s[82:83], 0, v[132:133]
	s_add_i32 m0, s6, 0x2000
	s_nop 0
	global_load_lds_dwordx4 v[250:251], off
	s_waitcnt vmcnt(16)
	s_cmp_lg_u32 s100, 0
	s_cbranch_scc1 .Lm4bp_386
	s_waitcnt vmcnt(8)
.Lm4bp_386:
	s_waitcnt lgkmcnt(0)
	s_mov_b32 s100, 0
	s_barrier
	s_setprio 1
	v_mfma_f32_16x16x32_bf16 v[60:63], v[158:161], v[174:177], 0
	v_mfma_f32_16x16x32_bf16 v[56:59], v[166:169], v[174:177], 0
	v_mfma_f32_16x16x32_bf16 v[52:55], v[158:161], v[182:185], 0
	v_mfma_f32_16x16x32_bf16 v[48:51], v[166:169], v[182:185], 0
	v_mfma_f32_16x16x32_bf16 v[44:47], v[158:161], v[210:213], 0
	v_mfma_f32_16x16x32_bf16 v[40:43], v[166:169], v[210:213], 0
	v_mfma_f32_16x16x32_bf16 v[36:39], v[158:161], v[218:221], 0
	v_mfma_f32_16x16x32_bf16 v[32:35], v[166:169], v[218:221], 0
	v_mfma_f32_16x16x32_bf16 v[60:63], v[162:165], v[178:181], v[60:63]
	v_mfma_f32_16x16x32_bf16 v[56:59], v[170:173], v[178:181], v[56:59]
	v_mfma_f32_16x16x32_bf16 v[52:55], v[162:165], v[206:209], v[52:55]
	v_mfma_f32_16x16x32_bf16 v[48:51], v[170:173], v[206:209], v[48:51]
	v_mfma_f32_16x16x32_bf16 v[44:47], v[162:165], v[214:217], v[44:47]
	v_mfma_f32_16x16x32_bf16 v[40:43], v[170:173], v[214:217], v[40:43]
	v_mfma_f32_16x16x32_bf16 v[36:39], v[162:165], v[222:225], v[36:39]
	v_mfma_f32_16x16x32_bf16 v[32:35], v[170:173], v[222:225], v[32:35]
	v_mfma_f32_16x16x32_bf16 v[28:31], v[226:229], v[174:177], 0
	v_mfma_f32_16x16x32_bf16 v[24:27], v[234:237], v[174:177], 0
	v_mfma_f32_16x16x32_bf16 v[20:23], v[226:229], v[182:185], 0
	v_mfma_f32_16x16x32_bf16 v[16:19], v[234:237], v[182:185], 0
	v_mfma_f32_16x16x32_bf16 v[12:15], v[226:229], v[210:213], 0
	v_mfma_f32_16x16x32_bf16 v[8:11], v[234:237], v[210:213], 0
	v_mfma_f32_16x16x32_bf16 v[4:7], v[226:229], v[218:221], 0
	v_mfma_f32_16x16x32_bf16 v[0:3], v[234:237], v[218:221], 0
	v_mfma_f32_16x16x32_bf16 v[28:31], v[230:233], v[178:181], v[28:31]
	v_mfma_f32_16x16x32_bf16 v[24:27], v[238:241], v[178:181], v[24:27]
	v_mfma_f32_16x16x32_bf16 v[20:23], v[230:233], v[206:209], v[20:23]
	v_mfma_f32_16x16x32_bf16 v[16:19], v[238:241], v[206:209], v[16:19]
	v_mfma_f32_16x16x32_bf16 v[12:15], v[230:233], v[214:217], v[12:15]
	v_mfma_f32_16x16x32_bf16 v[8:11], v[238:241], v[214:217], v[8:11]
	v_mfma_f32_16x16x32_bf16 v[4:7], v[230:233], v[222:225], v[4:7]
	v_mfma_f32_16x16x32_bf16 v[0:3], v[238:241], v[222:225], v[0:3]
	s_setprio 0
	s_barrier
	s_add_i32 s6, 0, 0x18000
	v_add_u32_e32 v170, s6, v154
	ds_read_b128 v[158:161], v170
	ds_read_b128 v[162:165], v170 offset:1024
	ds_read_b128 v[166:169], v170 offset:2048
	ds_read_b128 v[170:173], v170 offset:3072
	s_add_u32 s58, s58, 0x40000
	s_addc_u32 s59, s59, 0
	s_mov_b32 m0, s70
	v_lshl_add_u64 v[226:227], s[58:59], 0, v[128:129]
	ds_read_b128 v[174:177], v157 offset:32768
	ds_read_b128 v[178:181], v157 offset:33792
	ds_read_b128 v[182:185], v157 offset:34816
	ds_read_b128 v[206:209], v157 offset:35840
	ds_read_b128 v[210:213], v157 offset:36864
	ds_read_b128 v[214:217], v157 offset:37888
	ds_read_b128 v[218:221], v157 offset:38912
	ds_read_b128 v[222:225], v157 offset:39936
	global_load_lds_dwordx4 v[226:227], off
	v_lshl_add_u64 v[226:227], s[58:59], 0, v[130:131]
	s_mov_b32 m0, s71
	s_nop 0
	global_load_lds_dwordx4 v[226:227], off
	s_add_i32 s19, 0, 0x1c000
	v_add_u32_e32 v192, s19, v154
	ds_read_b128 v[226:229], v192
	ds_read_b128 v[230:233], v192 offset:1024
	ds_read_b128 v[234:237], v192 offset:2048
	ds_read_b128 v[238:241], v192 offset:3072
	s_waitcnt vmcnt(8)
	s_waitcnt lgkmcnt(0)
	s_barrier
	s_setprio 1
	v_mfma_f32_16x16x32_bf16 v[124:127], v[158:161], v[174:177], v[124:127]
	v_mfma_f32_16x16x32_bf16 v[120:123], v[166:169], v[174:177], v[120:123]
	v_mfma_f32_16x16x32_bf16 v[116:119], v[158:161], v[182:185], v[116:119]
	v_mfma_f32_16x16x32_bf16 v[112:115], v[166:169], v[182:185], v[112:115]
	v_mfma_f32_16x16x32_bf16 v[108:111], v[158:161], v[210:213], v[108:111]
	v_mfma_f32_16x16x32_bf16 v[104:107], v[166:169], v[210:213], v[104:107]
	v_mfma_f32_16x16x32_bf16 v[100:103], v[158:161], v[218:221], v[100:103]
	v_mfma_f32_16x16x32_bf16 v[96:99], v[166:169], v[218:221], v[96:99]
	v_mfma_f32_16x16x32_bf16 v[124:127], v[162:165], v[178:181], v[124:127]
	v_mfma_f32_16x16x32_bf16 v[120:123], v[170:173], v[178:181], v[120:123]
	v_mfma_f32_16x16x32_bf16 v[116:119], v[162:165], v[206:209], v[116:119]
	v_mfma_f32_16x16x32_bf16 v[112:115], v[170:173], v[206:209], v[112:115]
	v_mfma_f32_16x16x32_bf16 v[108:111], v[162:165], v[214:217], v[108:111]
	v_mfma_f32_16x16x32_bf16 v[104:107], v[170:173], v[214:217], v[104:107]
	v_mfma_f32_16x16x32_bf16 v[100:103], v[162:165], v[222:225], v[100:103]
	v_mfma_f32_16x16x32_bf16 v[96:99], v[170:173], v[222:225], v[96:99]
	v_mfma_f32_16x16x32_bf16 v[92:95], v[226:229], v[174:177], v[92:95]
	v_mfma_f32_16x16x32_bf16 v[88:91], v[234:237], v[174:177], v[88:91]
	v_mfma_f32_16x16x32_bf16 v[84:87], v[226:229], v[182:185], v[84:87]
	v_mfma_f32_16x16x32_bf16 v[80:83], v[234:237], v[182:185], v[80:83]
	v_mfma_f32_16x16x32_bf16 v[76:79], v[226:229], v[210:213], v[76:79]
	v_mfma_f32_16x16x32_bf16 v[72:75], v[234:237], v[210:213], v[72:75]
	v_mfma_f32_16x16x32_bf16 v[68:71], v[226:229], v[218:221], v[68:71]
	v_mfma_f32_16x16x32_bf16 v[64:67], v[234:237], v[218:221], v[64:67]
	v_mfma_f32_16x16x32_bf16 v[92:95], v[230:233], v[178:181], v[92:95]
	v_mfma_f32_16x16x32_bf16 v[88:91], v[238:241], v[178:181], v[88:91]
	v_mfma_f32_16x16x32_bf16 v[84:87], v[230:233], v[206:209], v[84:87]
	v_mfma_f32_16x16x32_bf16 v[80:83], v[238:241], v[206:209], v[80:83]
	v_mfma_f32_16x16x32_bf16 v[76:79], v[230:233], v[214:217], v[76:79]
	v_mfma_f32_16x16x32_bf16 v[72:75], v[238:241], v[214:217], v[72:75]
	v_mfma_f32_16x16x32_bf16 v[68:71], v[230:233], v[222:225], v[68:71]
	v_mfma_f32_16x16x32_bf16 v[64:67], v[238:241], v[222:225], v[64:67]
	s_setprio 0
	s_barrier
	s_add_i32 s6, s6, s57
	v_lshl_add_u64 v[146:147], v[146:147], 0, s[36:37]
	s_mov_b32 m0, s6
	s_nop 0
	global_load_lds_dwordx4 v[146:147], off
	v_lshl_add_u64 v[146:147], v[148:149], 0, s[36:37]
	s_add_i32 m0, s6, 0x2000
	s_nop 0
	global_load_lds_dwordx4 v[146:147], off
	s_mov_b32 m0, s72
	v_lshl_add_u64 v[146:147], v[194:195], 0, s[36:37]
	ds_read_b128 v[174:177], v157 offset:49152
	ds_read_b128 v[178:181], v157 offset:50176
	ds_read_b128 v[182:185], v157 offset:51200
	ds_read_b128 v[206:209], v157 offset:52224
	ds_read_b128 v[210:213], v157 offset:53248
	ds_read_b128 v[214:217], v157 offset:54272
	ds_read_b128 v[218:221], v157 offset:55296
	ds_read_b128 v[222:225], v157 offset:56320
	global_load_lds_dwordx4 v[146:147], off
	v_lshl_add_u64 v[146:147], v[196:197], 0, s[36:37]
	s_mov_b32 m0, s73
	s_nop 0
	global_load_lds_dwordx4 v[146:147], off
	s_add_u32 s54, s54, 0x40080
	s_addc_u32 s55, s55, 0
	s_add_i32 s6, s19, s57
	v_lshl_add_u64 v[146:147], s[54:55], 0, v[140:141]
	s_mov_b32 m0, s6
	s_nop 0
	global_load_lds_dwordx4 v[146:147], off
	v_lshl_add_u64 v[146:147], s[54:55], 0, v[132:133]
	s_add_i32 m0, s6, 0x2000
	s_nop 0
	global_load_lds_dwordx4 v[146:147], off
	s_waitcnt vmcnt(8)
	s_waitcnt lgkmcnt(0)
	s_barrier
	s_setprio 1
	v_mfma_f32_16x16x32_bf16 v[60:63], v[158:161], v[174:177], v[60:63]
	v_mfma_f32_16x16x32_bf16 v[56:59], v[166:169], v[174:177], v[56:59]
	v_mfma_f32_16x16x32_bf16 v[52:55], v[158:161], v[182:185], v[52:55]
	v_mfma_f32_16x16x32_bf16 v[48:51], v[166:169], v[182:185], v[48:51]
	v_mfma_f32_16x16x32_bf16 v[44:47], v[158:161], v[210:213], v[44:47]
	v_mfma_f32_16x16x32_bf16 v[40:43], v[166:169], v[210:213], v[40:43]
	v_mfma_f32_16x16x32_bf16 v[36:39], v[158:161], v[218:221], v[36:39]
	v_mfma_f32_16x16x32_bf16 v[32:35], v[166:169], v[218:221], v[32:35]
	v_mfma_f32_16x16x32_bf16 v[60:63], v[162:165], v[178:181], v[60:63]
	v_mfma_f32_16x16x32_bf16 v[56:59], v[170:173], v[178:181], v[56:59]
	v_mfma_f32_16x16x32_bf16 v[52:55], v[162:165], v[206:209], v[52:55]
	v_mfma_f32_16x16x32_bf16 v[48:51], v[170:173], v[206:209], v[48:51]
	v_mfma_f32_16x16x32_bf16 v[44:47], v[162:165], v[214:217], v[44:47]
	v_mfma_f32_16x16x32_bf16 v[40:43], v[170:173], v[214:217], v[40:43]
	v_mfma_f32_16x16x32_bf16 v[36:39], v[162:165], v[222:225], v[36:39]
	v_mfma_f32_16x16x32_bf16 v[32:35], v[170:173], v[222:225], v[32:35]
	v_mfma_f32_16x16x32_bf16 v[28:31], v[226:229], v[174:177], v[28:31]
	v_mfma_f32_16x16x32_bf16 v[24:27], v[234:237], v[174:177], v[24:27]
	v_mfma_f32_16x16x32_bf16 v[20:23], v[226:229], v[182:185], v[20:23]
	v_mfma_f32_16x16x32_bf16 v[16:19], v[234:237], v[182:185], v[16:19]
	v_mfma_f32_16x16x32_bf16 v[12:15], v[226:229], v[210:213], v[12:15]
	v_mfma_f32_16x16x32_bf16 v[8:11], v[234:237], v[210:213], v[8:11]
	v_mfma_f32_16x16x32_bf16 v[4:7], v[226:229], v[218:221], v[4:7]
	v_mfma_f32_16x16x32_bf16 v[0:3], v[234:237], v[218:221], v[0:3]
	v_mfma_f32_16x16x32_bf16 v[28:31], v[230:233], v[178:181], v[28:31]
	v_mfma_f32_16x16x32_bf16 v[24:27], v[238:241], v[178:181], v[24:27]
	v_mfma_f32_16x16x32_bf16 v[20:23], v[230:233], v[206:209], v[20:23]
	v_mfma_f32_16x16x32_bf16 v[16:19], v[238:241], v[206:209], v[16:19]
	v_mfma_f32_16x16x32_bf16 v[12:15], v[230:233], v[214:217], v[12:15]
	v_mfma_f32_16x16x32_bf16 v[8:11], v[238:241], v[214:217], v[8:11]
	v_mfma_f32_16x16x32_bf16 v[4:7], v[230:233], v[222:225], v[4:7]
	v_mfma_f32_16x16x32_bf16 v[0:3], v[238:241], v[222:225], v[0:3]
	s_setprio 0
	s_add_i32 s81, s81, 2
	s_add_u32 s52, s52, 0x100
	s_addc_u32 s53, s53, 0
	s_cmp_gt_u32 s81, 13
	s_barrier
.LBB0_386:
	s_add_u32 s6, s28, s52
	s_addc_u32 s19, s29, s53
	s_add_u32 s6, s6, 0x100
	s_addc_u32 s19, s19, 0
	s_add_u32 s23, s10, s52
	s_addc_u32 s54, s11, s53
	s_add_i32 s82, 0, 0x10000
	v_add_u32_e32 v146, s82, v154
	ds_read_b128 v[158:161], v146
	ds_read_b128 v[162:165], v146 offset:1024
	ds_read_b128 v[166:169], v146 offset:2048
	ds_read_b128 v[170:173], v146 offset:3072
	s_cmpk_eq_i32 s52, 0x700
	s_cselect_b32 s59, s12, s19
	s_cselect_b32 s58, s35, s6
	s_cselect_b32 s55, s39, s54
	s_cselect_b32 s54, s47, s23
	v_lshl_add_u64 v[146:147], v[150:151], 0, s[52:53]
	s_add_i32 m0, s68, 0xc000
	ds_read_b128 v[174:177], v157
	ds_read_b128 v[178:181], v157 offset:1024
	ds_read_b128 v[182:185], v157 offset:2048
	ds_read_b128 v[206:209], v157 offset:3072
	ds_read_b128 v[210:213], v157 offset:4096
	ds_read_b128 v[214:217], v157 offset:5120
	ds_read_b128 v[218:221], v157 offset:6144
	ds_read_b128 v[222:225], v157 offset:7168
	global_load_lds_dwordx4 v[146:147], off
	v_lshl_add_u64 v[146:147], v[152:153], 0, s[52:53]
	s_add_i32 m0, s68, 0xe000
	s_nop 0
	global_load_lds_dwordx4 v[146:147], off
	s_add_i32 s6, 0, 0x14000
	v_add_u32_e32 v146, s6, v154
	ds_read_b128 v[226:229], v146
	ds_read_b128 v[230:233], v146 offset:1024
	ds_read_b128 v[234:237], v146 offset:2048
	ds_read_b128 v[238:241], v146 offset:3072
	s_waitcnt vmcnt(8)
	s_waitcnt lgkmcnt(0)
	s_barrier
	s_setprio 1
	v_mfma_f32_16x16x32_bf16 v[124:127], v[158:161], v[174:177], v[124:127]
	v_mfma_f32_16x16x32_bf16 v[120:123], v[166:169], v[174:177], v[120:123]
	v_mfma_f32_16x16x32_bf16 v[116:119], v[158:161], v[182:185], v[116:119]
	v_mfma_f32_16x16x32_bf16 v[112:115], v[166:169], v[182:185], v[112:115]
	v_mfma_f32_16x16x32_bf16 v[108:111], v[158:161], v[210:213], v[108:111]
	v_mfma_f32_16x16x32_bf16 v[104:107], v[166:169], v[210:213], v[104:107]
	v_mfma_f32_16x16x32_bf16 v[100:103], v[158:161], v[218:221], v[100:103]
	v_mfma_f32_16x16x32_bf16 v[96:99], v[166:169], v[218:221], v[96:99]
	v_mfma_f32_16x16x32_bf16 v[124:127], v[162:165], v[178:181], v[124:127]
	v_mfma_f32_16x16x32_bf16 v[120:123], v[170:173], v[178:181], v[120:123]
	v_mfma_f32_16x16x32_bf16 v[116:119], v[162:165], v[206:209], v[116:119]
	v_mfma_f32_16x16x32_bf16 v[112:115], v[170:173], v[206:209], v[112:115]
	v_mfma_f32_16x16x32_bf16 v[108:111], v[162:165], v[214:217], v[108:111]
	v_mfma_f32_16x16x32_bf16 v[104:107], v[170:173], v[214:217], v[104:107]
	v_mfma_f32_16x16x32_bf16 v[100:103], v[162:165], v[222:225], v[100:103]
	v_mfma_f32_16x16x32_bf16 v[96:99], v[170:173], v[222:225], v[96:99]
	v_mfma_f32_16x16x32_bf16 v[92:95], v[226:229], v[174:177], v[92:95]
	v_mfma_f32_16x16x32_bf16 v[88:91], v[234:237], v[174:177], v[88:91]
	v_mfma_f32_16x16x32_bf16 v[84:87], v[226:229], v[182:185], v[84:87]
	v_mfma_f32_16x16x32_bf16 v[80:83], v[234:237], v[182:185], v[80:83]
	v_mfma_f32_16x16x32_bf16 v[76:79], v[226:229], v[210:213], v[76:79]
	v_mfma_f32_16x16x32_bf16 v[72:75], v[234:237], v[210:213], v[72:75]
	v_mfma_f32_16x16x32_bf16 v[68:71], v[226:229], v[218:221], v[68:71]
	v_mfma_f32_16x16x32_bf16 v[64:67], v[234:237], v[218:221], v[64:67]
	v_mfma_f32_16x16x32_bf16 v[92:95], v[230:233], v[178:181], v[92:95]
	v_mfma_f32_16x16x32_bf16 v[88:91], v[238:241], v[178:181], v[88:91]
	v_mfma_f32_16x16x32_bf16 v[84:87], v[230:233], v[206:209], v[84:87]
	v_mfma_f32_16x16x32_bf16 v[80:83], v[238:241], v[206:209], v[80:83]
	v_mfma_f32_16x16x32_bf16 v[76:79], v[230:233], v[214:217], v[76:79]
	v_mfma_f32_16x16x32_bf16 v[72:75], v[238:241], v[214:217], v[72:75]
	v_mfma_f32_16x16x32_bf16 v[68:71], v[230:233], v[222:225], v[68:71]
	v_mfma_f32_16x16x32_bf16 v[64:67], v[238:241], v[222:225], v[64:67]
	s_setprio 0
	s_barrier
	s_add_i32 s19, s82, s57
	v_lshl_add_u64 v[146:147], s[54:55], 0, v[140:141]
	s_mov_b32 m0, s19
	v_lshl_add_u64 v[148:149], s[54:55], 0, v[132:133]
	global_load_lds_dwordx4 v[146:147], off
	s_add_i32 m0, s19, 0x2000
	s_nop 0
	global_load_lds_dwordx4 v[148:149], off
	s_mov_b32 m0, s68
	v_lshl_add_u64 v[194:195], s[58:59], 0, v[128:129]
	ds_read_b128 v[174:177], v157 offset:16384
	ds_read_b128 v[178:181], v157 offset:17408
	ds_read_b128 v[182:185], v157 offset:18432
	ds_read_b128 v[206:209], v157 offset:19456
	ds_read_b128 v[210:213], v157 offset:20480
	ds_read_b128 v[214:217], v157 offset:21504
	ds_read_b128 v[218:221], v157 offset:22528
	ds_read_b128 v[222:225], v157 offset:23552
	global_load_lds_dwordx4 v[194:195], off
	v_lshl_add_u64 v[196:197], s[58:59], 0, v[130:131]
	s_mov_b32 m0, s69
	s_nop 0
	global_load_lds_dwordx4 v[196:197], off
	s_add_u32 s82, s54, 0x40000
	s_addc_u32 s83, s55, 0
	s_add_i32 s6, s6, s57
	v_lshl_add_u64 v[250:251], s[82:83], 0, v[140:141]
	s_mov_b32 m0, s6
	s_nop 0
	global_load_lds_dwordx4 v[250:251], off
	v_lshl_add_u64 v[250:251], s[82:83], 0, v[132:133]
	s_add_i32 m0, s6, 0x2000
	s_nop 0
	global_load_lds_dwordx4 v[250:251], off
	s_waitcnt vmcnt(8)
	s_waitcnt lgkmcnt(0)
	s_barrier
	s_setprio 1
	v_mfma_f32_16x16x32_bf16 v[60:63], v[158:161], v[174:177], v[60:63]
	v_mfma_f32_16x16x32_bf16 v[56:59], v[166:169], v[174:177], v[56:59]
	v_mfma_f32_16x16x32_bf16 v[52:55], v[158:161], v[182:185], v[52:55]
	v_mfma_f32_16x16x32_bf16 v[48:51], v[166:169], v[182:185], v[48:51]
	v_mfma_f32_16x16x32_bf16 v[44:47], v[158:161], v[210:213], v[44:47]
	v_mfma_f32_16x16x32_bf16 v[40:43], v[166:169], v[210:213], v[40:43]
	v_mfma_f32_16x16x32_bf16 v[36:39], v[158:161], v[218:221], v[36:39]
	v_mfma_f32_16x16x32_bf16 v[32:35], v[166:169], v[218:221], v[32:35]
	v_mfma_f32_16x16x32_bf16 v[60:63], v[162:165], v[178:181], v[60:63]
	v_mfma_f32_16x16x32_bf16 v[56:59], v[170:173], v[178:181], v[56:59]
	v_mfma_f32_16x16x32_bf16 v[52:55], v[162:165], v[206:209], v[52:55]
	v_mfma_f32_16x16x32_bf16 v[48:51], v[170:173], v[206:209], v[48:51]
	v_mfma_f32_16x16x32_bf16 v[44:47], v[162:165], v[214:217], v[44:47]
	v_mfma_f32_16x16x32_bf16 v[40:43], v[170:173], v[214:217], v[40:43]
	v_mfma_f32_16x16x32_bf16 v[36:39], v[162:165], v[222:225], v[36:39]
	v_mfma_f32_16x16x32_bf16 v[32:35], v[170:173], v[222:225], v[32:35]
	v_mfma_f32_16x16x32_bf16 v[28:31], v[226:229], v[174:177], v[28:31]
	v_mfma_f32_16x16x32_bf16 v[24:27], v[234:237], v[174:177], v[24:27]
	v_mfma_f32_16x16x32_bf16 v[20:23], v[226:229], v[182:185], v[20:23]
	v_mfma_f32_16x16x32_bf16 v[16:19], v[234:237], v[182:185], v[16:19]
	v_mfma_f32_16x16x32_bf16 v[12:15], v[226:229], v[210:213], v[12:15]
	v_mfma_f32_16x16x32_bf16 v[8:11], v[234:237], v[210:213], v[8:11]
	v_mfma_f32_16x16x32_bf16 v[4:7], v[226:229], v[218:221], v[4:7]
	v_mfma_f32_16x16x32_bf16 v[0:3], v[234:237], v[218:221], v[0:3]
	v_mfma_f32_16x16x32_bf16 v[28:31], v[230:233], v[178:181], v[28:31]
	v_mfma_f32_16x16x32_bf16 v[24:27], v[238:241], v[178:181], v[24:27]
	v_mfma_f32_16x16x32_bf16 v[20:23], v[230:233], v[206:209], v[20:23]
	v_mfma_f32_16x16x32_bf16 v[16:19], v[238:241], v[206:209], v[16:19]
	v_mfma_f32_16x16x32_bf16 v[12:15], v[230:233], v[214:217], v[12:15]
	v_mfma_f32_16x16x32_bf16 v[8:11], v[238:241], v[214:217], v[8:11]
	v_mfma_f32_16x16x32_bf16 v[4:7], v[230:233], v[222:225], v[4:7]
	v_mfma_f32_16x16x32_bf16 v[0:3], v[238:241], v[222:225], v[0:3]
	s_setprio 0
	s_barrier
	s_add_i32 s6, 0, 0x18000
	v_add_u32_e32 v170, s6, v154
	ds_read_b128 v[158:161], v170
	ds_read_b128 v[162:165], v170 offset:1024
	ds_read_b128 v[166:169], v170 offset:2048
	ds_read_b128 v[170:173], v170 offset:3072
	s_add_u32 s58, s58, 0x40000
	s_addc_u32 s59, s59, 0
	s_mov_b32 m0, s70
	v_lshl_add_u64 v[226:227], s[58:59], 0, v[128:129]
	ds_read_b128 v[174:177], v157 offset:32768
	ds_read_b128 v[178:181], v157 offset:33792
	ds_read_b128 v[182:185], v157 offset:34816
	ds_read_b128 v[206:209], v157 offset:35840
	ds_read_b128 v[210:213], v157 offset:36864
	ds_read_b128 v[214:217], v157 offset:37888
	ds_read_b128 v[218:221], v157 offset:38912
	ds_read_b128 v[222:225], v157 offset:39936
	global_load_lds_dwordx4 v[226:227], off
	v_lshl_add_u64 v[226:227], s[58:59], 0, v[130:131]
	s_mov_b32 m0, s71
	s_nop 0
	global_load_lds_dwordx4 v[226:227], off
	s_add_i32 s19, 0, 0x1c000
	v_add_u32_e32 v192, s19, v154
	ds_read_b128 v[226:229], v192
	ds_read_b128 v[230:233], v192 offset:1024
	ds_read_b128 v[234:237], v192 offset:2048
	ds_read_b128 v[238:241], v192 offset:3072
	s_waitcnt vmcnt(8)
	s_waitcnt lgkmcnt(0)
	s_barrier
	s_setprio 1
	v_mfma_f32_16x16x32_bf16 v[124:127], v[158:161], v[174:177], v[124:127]
	v_mfma_f32_16x16x32_bf16 v[120:123], v[166:169], v[174:177], v[120:123]
	v_mfma_f32_16x16x32_bf16 v[116:119], v[158:161], v[182:185], v[116:119]
	v_mfma_f32_16x16x32_bf16 v[112:115], v[166:169], v[182:185], v[112:115]
	v_mfma_f32_16x16x32_bf16 v[108:111], v[158:161], v[210:213], v[108:111]
	v_mfma_f32_16x16x32_bf16 v[104:107], v[166:169], v[210:213], v[104:107]
	v_mfma_f32_16x16x32_bf16 v[100:103], v[158:161], v[218:221], v[100:103]
	v_mfma_f32_16x16x32_bf16 v[96:99], v[166:169], v[218:221], v[96:99]
	v_mfma_f32_16x16x32_bf16 v[124:127], v[162:165], v[178:181], v[124:127]
	v_mfma_f32_16x16x32_bf16 v[120:123], v[170:173], v[178:181], v[120:123]
	v_mfma_f32_16x16x32_bf16 v[116:119], v[162:165], v[206:209], v[116:119]
	v_mfma_f32_16x16x32_bf16 v[112:115], v[170:173], v[206:209], v[112:115]
	v_mfma_f32_16x16x32_bf16 v[108:111], v[162:165], v[214:217], v[108:111]
	v_mfma_f32_16x16x32_bf16 v[104:107], v[170:173], v[214:217], v[104:107]
	v_mfma_f32_16x16x32_bf16 v[100:103], v[162:165], v[222:225], v[100:103]
	v_mfma_f32_16x16x32_bf16 v[96:99], v[170:173], v[222:225], v[96:99]
	v_mfma_f32_16x16x32_bf16 v[92:95], v[226:229], v[174:177], v[92:95]
	v_mfma_f32_16x16x32_bf16 v[88:91], v[234:237], v[174:177], v[88:91]
	v_mfma_f32_16x16x32_bf16 v[84:87], v[226:229], v[182:185], v[84:87]
	v_mfma_f32_16x16x32_bf16 v[80:83], v[234:237], v[182:185], v[80:83]
	v_mfma_f32_16x16x32_bf16 v[76:79], v[226:229], v[210:213], v[76:79]
	v_mfma_f32_16x16x32_bf16 v[72:75], v[234:237], v[210:213], v[72:75]
	v_mfma_f32_16x16x32_bf16 v[68:71], v[226:229], v[218:221], v[68:71]
	v_mfma_f32_16x16x32_bf16 v[64:67], v[234:237], v[218:221], v[64:67]
	v_mfma_f32_16x16x32_bf16 v[92:95], v[230:233], v[178:181], v[92:95]
	v_mfma_f32_16x16x32_bf16 v[88:91], v[238:241], v[178:181], v[88:91]
	v_mfma_f32_16x16x32_bf16 v[84:87], v[230:233], v[206:209], v[84:87]
	v_mfma_f32_16x16x32_bf16 v[80:83], v[238:241], v[206:209], v[80:83]
	v_mfma_f32_16x16x32_bf16 v[76:79], v[230:233], v[214:217], v[76:79]
	v_mfma_f32_16x16x32_bf16 v[72:75], v[238:241], v[214:217], v[72:75]
	v_mfma_f32_16x16x32_bf16 v[68:71], v[230:233], v[222:225], v[68:71]
	v_mfma_f32_16x16x32_bf16 v[64:67], v[238:241], v[222:225], v[64:67]
	s_setprio 0
	s_barrier
	s_add_i32 s6, s6, s57
	v_lshl_add_u64 v[146:147], v[146:147], 0, s[36:37]
	s_mov_b32 m0, s6
	s_nop 0
	global_load_lds_dwordx4 v[146:147], off
	v_lshl_add_u64 v[146:147], v[148:149], 0, s[36:37]
	s_add_i32 m0, s6, 0x2000
	s_nop 0
	global_load_lds_dwordx4 v[146:147], off
	s_mov_b32 m0, s72
	v_lshl_add_u64 v[146:147], v[194:195], 0, s[36:37]
	ds_read_b128 v[174:177], v157 offset:49152
	ds_read_b128 v[178:181], v157 offset:50176
	ds_read_b128 v[182:185], v157 offset:51200
	ds_read_b128 v[206:209], v157 offset:52224
	ds_read_b128 v[210:213], v157 offset:53248
	ds_read_b128 v[214:217], v157 offset:54272
	ds_read_b128 v[218:221], v157 offset:55296
	ds_read_b128 v[222:225], v157 offset:56320
	global_load_lds_dwordx4 v[146:147], off
	v_lshl_add_u64 v[146:147], v[196:197], 0, s[36:37]
	s_mov_b32 m0, s73
	s_nop 0
	global_load_lds_dwordx4 v[146:147], off
	s_add_u32 s54, s54, 0x40080
	s_addc_u32 s55, s55, 0
	s_add_i32 s6, s19, s57
	v_lshl_add_u64 v[146:147], s[54:55], 0, v[140:141]
	s_mov_b32 m0, s6
	s_nop 0
	global_load_lds_dwordx4 v[146:147], off
	v_lshl_add_u64 v[146:147], s[54:55], 0, v[132:133]
	s_add_i32 m0, s6, 0x2000
	s_nop 0
	global_load_lds_dwordx4 v[146:147], off
	s_waitcnt vmcnt(8)
	s_waitcnt lgkmcnt(0)
	s_barrier
	s_setprio 1
	v_mfma_f32_16x16x32_bf16 v[60:63], v[158:161], v[174:177], v[60:63]
	v_mfma_f32_16x16x32_bf16 v[56:59], v[166:169], v[174:177], v[56:59]
	v_mfma_f32_16x16x32_bf16 v[52:55], v[158:161], v[182:185], v[52:55]
	v_mfma_f32_16x16x32_bf16 v[48:51], v[166:169], v[182:185], v[48:51]
	v_mfma_f32_16x16x32_bf16 v[44:47], v[158:161], v[210:213], v[44:47]
	v_mfma_f32_16x16x32_bf16 v[40:43], v[166:169], v[210:213], v[40:43]
	v_mfma_f32_16x16x32_bf16 v[36:39], v[158:161], v[218:221], v[36:39]
	v_mfma_f32_16x16x32_bf16 v[32:35], v[166:169], v[218:221], v[32:35]
	v_mfma_f32_16x16x32_bf16 v[60:63], v[162:165], v[178:181], v[60:63]
	v_mfma_f32_16x16x32_bf16 v[56:59], v[170:173], v[178:181], v[56:59]
	v_mfma_f32_16x16x32_bf16 v[52:55], v[162:165], v[206:209], v[52:55]
	v_mfma_f32_16x16x32_bf16 v[48:51], v[170:173], v[206:209], v[48:51]
	v_mfma_f32_16x16x32_bf16 v[44:47], v[162:165], v[214:217], v[44:47]
	v_mfma_f32_16x16x32_bf16 v[40:43], v[170:173], v[214:217], v[40:43]
	v_mfma_f32_16x16x32_bf16 v[36:39], v[162:165], v[222:225], v[36:39]
	v_mfma_f32_16x16x32_bf16 v[32:35], v[170:173], v[222:225], v[32:35]
	v_mfma_f32_16x16x32_bf16 v[28:31], v[226:229], v[174:177], v[28:31]
	v_mfma_f32_16x16x32_bf16 v[24:27], v[234:237], v[174:177], v[24:27]
	v_mfma_f32_16x16x32_bf16 v[20:23], v[226:229], v[182:185], v[20:23]
	v_mfma_f32_16x16x32_bf16 v[16:19], v[234:237], v[182:185], v[16:19]
	v_mfma_f32_16x16x32_bf16 v[12:15], v[226:229], v[210:213], v[12:15]
	v_mfma_f32_16x16x32_bf16 v[8:11], v[234:237], v[210:213], v[8:11]
	v_mfma_f32_16x16x32_bf16 v[4:7], v[226:229], v[218:221], v[4:7]
	v_mfma_f32_16x16x32_bf16 v[0:3], v[234:237], v[218:221], v[0:3]
	v_mfma_f32_16x16x32_bf16 v[28:31], v[230:233], v[178:181], v[28:31]
	v_mfma_f32_16x16x32_bf16 v[24:27], v[238:241], v[178:181], v[24:27]
	v_mfma_f32_16x16x32_bf16 v[20:23], v[230:233], v[206:209], v[20:23]
	v_mfma_f32_16x16x32_bf16 v[16:19], v[238:241], v[206:209], v[16:19]
	v_mfma_f32_16x16x32_bf16 v[12:15], v[230:233], v[214:217], v[12:15]
	v_mfma_f32_16x16x32_bf16 v[8:11], v[238:241], v[214:217], v[8:11]
	v_mfma_f32_16x16x32_bf16 v[4:7], v[230:233], v[222:225], v[4:7]
	v_mfma_f32_16x16x32_bf16 v[0:3], v[238:241], v[222:225], v[0:3]
	s_setprio 0
	s_add_i32 s81, s81, 2
	s_add_u32 s52, s52, 0x100
	s_addc_u32 s53, s53, 0
	s_cmp_gt_u32 s81, 13
	s_barrier
	s_cbranch_scc0 .LBB0_386
	s_mov_b32 s100, 1
	v_lshl_add_u32 v158, s75, 10, v155
	ds_read2_b32 v[146:147], v158 offset1:16
	s_add_u32 s52, s10, 0xffffff00
	s_addc_u32 s53, s11, -1
	s_ashr_i32 s35, s34, 31
	s_lshl_b64 s[10:11], s[34:35], 8
	s_waitcnt lgkmcnt(0)
	v_pk_mul_f32 v[148:149], v[124:125], v[146:147] op_sel_hi:[1,0]
	v_lshl_add_u64 v[152:153], v[134:135], 0, s[10:11]
	v_mul_f32_e32 v159, 0xbfb8aa3b, v148
	v_exp_f32_e32 v159, v159
	s_movk_i32 s6, 0x1600
	v_lshl_or_b32 v150, s74, 7, v156
	v_ashrrev_i32_e32 v151, 31, v150
	v_add_f32_e32 v159, 1.0, v159
	v_rcp_f32_e32 v160, v159
	v_mul_f32_e32 v159, 0xbfb8aa3b, v149
	v_exp_f32_e32 v159, v159
	s_nop 0
	v_add_f32_e32 v159, 1.0, v159
	v_rcp_f32_e32 v161, v159
	s_nop 0
	v_pk_mul_f32 v[148:149], v[148:149], v[160:161]
	v_pk_mul_f32 v[160:161], v[92:93], v[146:147] op_sel_hi:[1,0]
	s_nop 0
	v_pk_mul_f32 v[148:149], v[160:161], v[148:149]
	v_pk_mul_f32 v[160:161], v[126:127], v[146:147] op_sel_hi:[1,0]
	s_nop 0
	v_mul_f32_e32 v159, 0xbfb8aa3b, v160
	v_exp_f32_e32 v159, v159
	s_nop 0
	v_add_f32_e32 v159, 1.0, v159
	v_rcp_f32_e32 v162, v159
	v_mul_f32_e32 v159, 0xbfb8aa3b, v161
	v_exp_f32_e32 v159, v159
	s_nop 0
	v_add_f32_e32 v159, 1.0, v159
	v_rcp_f32_e32 v163, v159
	s_nop 0
	v_pk_mul_f32 v[160:161], v[160:161], v[162:163]
	v_pk_mul_f32 v[162:163], v[94:95], v[146:147] op_sel_hi:[1,0]
	s_nop 0
	v_pk_mul_f32 v[162:163], v[162:163], v[160:161]
	v_pk_mul_f32 v[160:161], v[120:121], v[146:147] op_sel_hi:[1,0]
	s_nop 0
	v_mul_f32_e32 v159, 0xbfb8aa3b, v160
	v_exp_f32_e32 v159, v159
	s_nop 0
	v_add_f32_e32 v159, 1.0, v159
	v_rcp_f32_e32 v164, v159
	v_mul_f32_e32 v159, 0xbfb8aa3b, v161
	v_exp_f32_e32 v159, v159
	s_nop 0
	v_add_f32_e32 v159, 1.0, v159
	v_rcp_f32_e32 v165, v159
	s_nop 0
	v_pk_mul_f32 v[160:161], v[160:161], v[164:165]
	v_pk_mul_f32 v[164:165], v[88:89], v[146:147] op_sel_hi:[1,0]
	s_nop 0
	v_pk_mul_f32 v[164:165], v[164:165], v[160:161]
	v_pk_mul_f32 v[160:161], v[122:123], v[146:147] op_sel_hi:[1,0]
	s_nop 0
	v_mul_f32_e32 v159, 0xbfb8aa3b, v160
	v_exp_f32_e32 v159, v159
	s_nop 0
	v_add_f32_e32 v159, 1.0, v159
	v_rcp_f32_e32 v166, v159
	v_mul_f32_e32 v159, 0xbfb8aa3b, v161
	v_exp_f32_e32 v159, v159
	s_nop 0
	v_add_f32_e32 v159, 1.0, v159
	v_rcp_f32_e32 v167, v159
	s_nop 0
	v_pk_mul_f32 v[160:161], v[160:161], v[166:167]
	v_pk_mul_f32 v[166:167], v[90:91], v[146:147] op_sel_hi:[1,0]
	s_nop 0
	v_pk_mul_f32 v[166:167], v[166:167], v[160:161]
	v_cvt_pk_bf16_f32 v160, v148, v149
	v_mov_b64_e32 v[148:149], s[30:31]
	v_mad_u64_u32 v[148:149], s[10:11], v152, s6, v[148:149]
	v_mov_b32_e32 v146, v149
	v_mad_u64_u32 v[152:153], s[10:11], v153, s6, v[146:147]
	v_mov_b32_e32 v149, v152
	v_mov_b32_e32 v146, v147
	v_lshl_add_u64 v[150:151], v[150:151], 1, v[148:149]
	v_pk_mul_f32 v[148:149], v[116:117], v[146:147] op_sel_hi:[1,0]
	v_cvt_pk_bf16_f32 v161, v162, v163
	v_mul_f32_e32 v147, 0xbfb8aa3b, v148
	v_exp_f32_e32 v147, v147
	v_cvt_pk_bf16_f32 v162, v164, v165
	v_cvt_pk_bf16_f32 v163, v166, v167
	global_store_dwordx4 v[150:151], v[160:163], off
	v_add_f32_e32 v147, 1.0, v147
	v_rcp_f32_e32 v152, v147
	v_mul_f32_e32 v147, 0xbfb8aa3b, v149
	v_exp_f32_e32 v147, v147
	s_mov_b32 s6, 0x16000
	v_add_f32_e32 v147, 1.0, v147
	v_rcp_f32_e32 v153, v147
	s_nop 0
	v_pk_mul_f32 v[148:149], v[148:149], v[152:153]
	v_pk_mul_f32 v[152:153], v[84:85], v[146:147] op_sel_hi:[1,0]
	s_nop 0
	v_pk_mul_f32 v[148:149], v[152:153], v[148:149]
	v_pk_mul_f32 v[152:153], v[118:119], v[146:147] op_sel_hi:[1,0]
	s_nop 0
	v_mul_f32_e32 v147, 0xbfb8aa3b, v152
	v_exp_f32_e32 v147, v147
	s_nop 0
	v_add_f32_e32 v147, 1.0, v147
	v_rcp_f32_e32 v160, v147
	v_mul_f32_e32 v147, 0xbfb8aa3b, v153
	v_exp_f32_e32 v147, v147
	s_nop 0
	v_add_f32_e32 v147, 1.0, v147
	v_rcp_f32_e32 v161, v147
	s_nop 0
	v_pk_mul_f32 v[152:153], v[152:153], v[160:161]
	v_pk_mul_f32 v[160:161], v[86:87], v[146:147] op_sel_hi:[1,0]
	s_nop 0
	v_pk_mul_f32 v[152:153], v[160:161], v[152:153]
	v_pk_mul_f32 v[160:161], v[112:113], v[146:147] op_sel_hi:[1,0]
	s_nop 0
	v_mul_f32_e32 v147, 0xbfb8aa3b, v160
	v_exp_f32_e32 v147, v147
	s_nop 0
	v_add_f32_e32 v147, 1.0, v147
	v_rcp_f32_e32 v162, v147
	v_mul_f32_e32 v147, 0xbfb8aa3b, v161
	v_exp_f32_e32 v147, v147
	s_nop 0
	v_add_f32_e32 v147, 1.0, v147
	v_rcp_f32_e32 v163, v147
	s_nop 0
	v_pk_mul_f32 v[160:161], v[160:161], v[162:163]
	v_pk_mul_f32 v[162:163], v[80:81], v[146:147] op_sel_hi:[1,0]
	s_nop 0
	v_pk_mul_f32 v[162:163], v[162:163], v[160:161]
	v_pk_mul_f32 v[160:161], v[114:115], v[146:147] op_sel_hi:[1,0]
	v_cvt_pk_bf16_f32 v162, v162, v163
	v_mul_f32_e32 v147, 0xbfb8aa3b, v160
	v_exp_f32_e32 v147, v147
	s_nop 0
	v_add_f32_e32 v147, 1.0, v147
	v_rcp_f32_e32 v164, v147
	v_mul_f32_e32 v147, 0xbfb8aa3b, v161
	v_exp_f32_e32 v147, v147
	s_nop 0
	v_add_f32_e32 v147, 1.0, v147
	v_rcp_f32_e32 v165, v147
	v_pk_mul_f32 v[146:147], v[82:83], v[146:147] op_sel_hi:[1,0]
	v_pk_mul_f32 v[160:161], v[160:161], v[164:165]
	s_nop 0
	v_pk_mul_f32 v[146:147], v[146:147], v[160:161]
	v_cvt_pk_bf16_f32 v160, v148, v149
	v_cvt_pk_bf16_f32 v163, v146, v147
	v_add_co_u32_e32 v146, vcc, s6, v150
	v_cvt_pk_bf16_f32 v161, v152, v153
	s_nop 0
	v_addc_co_u32_e32 v147, vcc, 0, v151, vcc
	global_store_dwordx4 v[146:147], v[160:163], off
	ds_read2_b32 v[146:147], v158 offset0:32 offset1:48
	s_mov_b32 s6, 0x2c000
	s_waitcnt lgkmcnt(0)
	v_pk_mul_f32 v[148:149], v[108:109], v[146:147] op_sel_hi:[1,0]
	s_nop 0
	v_mul_f32_e32 v152, 0xbfb8aa3b, v148
	v_mul_f32_e32 v153, 0xbfb8aa3b, v149
	v_exp_f32_e32 v152, v152
	v_exp_f32_e32 v153, v153
	v_add_f32_e32 v152, 1.0, v152
	v_add_f32_e32 v153, 1.0, v153
	v_rcp_f32_e32 v152, v152
	v_rcp_f32_e32 v153, v153
	s_nop 0
	v_pk_mul_f32 v[148:149], v[148:149], v[152:153]
	v_pk_mul_f32 v[152:153], v[76:77], v[146:147] op_sel_hi:[1,0]
	s_nop 0
	v_pk_mul_f32 v[148:149], v[152:153], v[148:149]
	v_pk_mul_f32 v[152:153], v[110:111], v[146:147] op_sel_hi:[1,0]
	s_nop 0
	v_mul_f32_e32 v159, 0xbfb8aa3b, v152
	v_exp_f32_e32 v159, v159
	s_nop 0
	v_add_f32_e32 v159, 1.0, v159
	v_rcp_f32_e32 v160, v159
	v_mul_f32_e32 v159, 0xbfb8aa3b, v153
	v_exp_f32_e32 v159, v159
	s_nop 0
	v_add_f32_e32 v159, 1.0, v159
	v_rcp_f32_e32 v161, v159
	s_nop 0
	v_pk_mul_f32 v[152:153], v[152:153], v[160:161]
	v_pk_mul_f32 v[160:161], v[78:79], v[146:147] op_sel_hi:[1,0]
	s_nop 0
	v_pk_mul_f32 v[152:153], v[160:161], v[152:153]
	v_pk_mul_f32 v[160:161], v[104:105], v[146:147] op_sel_hi:[1,0]
	s_nop 0
	v_mul_f32_e32 v159, 0xbfb8aa3b, v160
	v_exp_f32_e32 v159, v159
	s_nop 0
	v_add_f32_e32 v159, 1.0, v159
	v_rcp_f32_e32 v162, v159
	v_mul_f32_e32 v159, 0xbfb8aa3b, v161
	v_exp_f32_e32 v159, v159
	s_nop 0
	v_add_f32_e32 v159, 1.0, v159
	v_rcp_f32_e32 v163, v159
	s_nop 0
	v_pk_mul_f32 v[160:161], v[160:161], v[162:163]
	v_pk_mul_f32 v[162:163], v[72:73], v[146:147] op_sel_hi:[1,0]
	s_nop 0
	v_pk_mul_f32 v[162:163], v[162:163], v[160:161]
	v_pk_mul_f32 v[160:161], v[106:107], v[146:147] op_sel_hi:[1,0]
	v_cvt_pk_bf16_f32 v162, v162, v163
	v_mul_f32_e32 v159, 0xbfb8aa3b, v160
	v_exp_f32_e32 v159, v159
	s_nop 0
	v_add_f32_e32 v159, 1.0, v159
	v_rcp_f32_e32 v164, v159
	v_mul_f32_e32 v159, 0xbfb8aa3b, v161
	v_exp_f32_e32 v159, v159
	s_nop 0
	v_add_f32_e32 v159, 1.0, v159
	v_rcp_f32_e32 v165, v159
	s_nop 0
	v_pk_mul_f32 v[160:161], v[160:161], v[164:165]
	v_pk_mul_f32 v[164:165], v[74:75], v[146:147] op_sel_hi:[1,0]
	v_mov_b32_e32 v146, v147
	v_pk_mul_f32 v[164:165], v[164:165], v[160:161]
	v_cvt_pk_bf16_f32 v160, v148, v149
	v_add_co_u32_e32 v148, vcc, s6, v150
	v_cvt_pk_bf16_f32 v161, v152, v153
	v_cvt_pk_bf16_f32 v163, v164, v165
	v_addc_co_u32_e32 v149, vcc, 0, v151, vcc
	global_store_dwordx4 v[148:149], v[160:163], off
	v_pk_mul_f32 v[148:149], v[100:101], v[146:147] op_sel_hi:[1,0]
	s_mov_b32 s6, 0x42000
	v_mul_f32_e32 v147, 0xbfb8aa3b, v148
	v_exp_f32_e32 v147, v147
	s_nop 0
	v_add_f32_e32 v147, 1.0, v147
	v_rcp_f32_e32 v152, v147
	v_mul_f32_e32 v147, 0xbfb8aa3b, v149
	v_exp_f32_e32 v147, v147
	s_nop 0
	v_add_f32_e32 v147, 1.0, v147
	v_rcp_f32_e32 v153, v147
	s_nop 0
	v_pk_mul_f32 v[148:149], v[148:149], v[152:153]
	v_pk_mul_f32 v[152:153], v[68:69], v[146:147] op_sel_hi:[1,0]
	s_nop 0
	v_pk_mul_f32 v[148:149], v[152:153], v[148:149]
	v_pk_mul_f32 v[152:153], v[102:103], v[146:147] op_sel_hi:[1,0]
	s_nop 0
	v_mul_f32_e32 v147, 0xbfb8aa3b, v152
	v_exp_f32_e32 v147, v147
	s_nop 0
	v_add_f32_e32 v147, 1.0, v147
	v_rcp_f32_e32 v160, v147
	v_mul_f32_e32 v147, 0xbfb8aa3b, v153
	v_exp_f32_e32 v147, v147
	s_nop 0
	v_add_f32_e32 v147, 1.0, v147
	v_rcp_f32_e32 v161, v147
	s_nop 0
	v_pk_mul_f32 v[152:153], v[152:153], v[160:161]
	v_pk_mul_f32 v[160:161], v[70:71], v[146:147] op_sel_hi:[1,0]
	s_nop 0
	v_pk_mul_f32 v[152:153], v[160:161], v[152:153]
	v_pk_mul_f32 v[160:161], v[96:97], v[146:147] op_sel_hi:[1,0]
	s_nop 0
	v_mul_f32_e32 v147, 0xbfb8aa3b, v160
	v_exp_f32_e32 v147, v147
	s_nop 0
	v_add_f32_e32 v147, 1.0, v147
	v_rcp_f32_e32 v162, v147
	v_mul_f32_e32 v147, 0xbfb8aa3b, v161
	v_exp_f32_e32 v147, v147
	s_nop 0
	v_add_f32_e32 v147, 1.0, v147
	v_rcp_f32_e32 v163, v147
	s_nop 0
	v_pk_mul_f32 v[160:161], v[160:161], v[162:163]
	v_pk_mul_f32 v[162:163], v[64:65], v[146:147] op_sel_hi:[1,0]
	s_nop 0
	v_pk_mul_f32 v[162:163], v[162:163], v[160:161]
	v_pk_mul_f32 v[160:161], v[98:99], v[146:147] op_sel_hi:[1,0]
	v_cvt_pk_bf16_f32 v162, v162, v163
	v_mul_f32_e32 v147, 0xbfb8aa3b, v160
	v_exp_f32_e32 v147, v147
	s_nop 0
	v_add_f32_e32 v147, 1.0, v147
	v_rcp_f32_e32 v164, v147
	v_mul_f32_e32 v147, 0xbfb8aa3b, v161
	v_exp_f32_e32 v147, v147
	s_nop 0
	v_add_f32_e32 v147, 1.0, v147
	v_rcp_f32_e32 v165, v147
	v_pk_mul_f32 v[146:147], v[66:67], v[146:147] op_sel_hi:[1,0]
	v_pk_mul_f32 v[160:161], v[160:161], v[164:165]
	s_nop 0
	v_pk_mul_f32 v[146:147], v[146:147], v[160:161]
	v_cvt_pk_bf16_f32 v160, v148, v149
	v_cvt_pk_bf16_f32 v163, v146, v147
	v_add_co_u32_e32 v146, vcc, s6, v150
	v_cvt_pk_bf16_f32 v161, v152, v153
	s_nop 0
	v_addc_co_u32_e32 v147, vcc, 0, v151, vcc
	global_store_dwordx4 v[146:147], v[160:163], off
	ds_read2_b32 v[146:147], v158 offset0:128 offset1:144
	s_mov_b32 s6, 0xb0000
	s_waitcnt lgkmcnt(0)
	v_pk_mul_f32 v[148:149], v[60:61], v[146:147] op_sel_hi:[1,0]
	s_nop 0
	v_mul_f32_e32 v152, 0xbfb8aa3b, v148
	v_mul_f32_e32 v153, 0xbfb8aa3b, v149
	v_exp_f32_e32 v152, v152
	v_exp_f32_e32 v153, v153
	v_add_f32_e32 v152, 1.0, v152
	v_add_f32_e32 v153, 1.0, v153
	v_rcp_f32_e32 v152, v152
	v_rcp_f32_e32 v153, v153
	s_nop 0
	v_pk_mul_f32 v[148:149], v[148:149], v[152:153]
	v_pk_mul_f32 v[152:153], v[28:29], v[146:147] op_sel_hi:[1,0]
	s_nop 0
	v_pk_mul_f32 v[148:149], v[152:153], v[148:149]
	v_pk_mul_f32 v[152:153], v[62:63], v[146:147] op_sel_hi:[1,0]
	s_nop 0
	v_mul_f32_e32 v159, 0xbfb8aa3b, v152
	v_exp_f32_e32 v159, v159
	s_nop 0
	v_add_f32_e32 v159, 1.0, v159
	v_rcp_f32_e32 v160, v159
	v_mul_f32_e32 v159, 0xbfb8aa3b, v153
	v_exp_f32_e32 v159, v159
	s_nop 0
	v_add_f32_e32 v159, 1.0, v159
	v_rcp_f32_e32 v161, v159
	s_nop 0
	v_pk_mul_f32 v[152:153], v[152:153], v[160:161]
	v_pk_mul_f32 v[160:161], v[30:31], v[146:147] op_sel_hi:[1,0]
	s_nop 0
	v_pk_mul_f32 v[152:153], v[160:161], v[152:153]
	v_pk_mul_f32 v[160:161], v[56:57], v[146:147] op_sel_hi:[1,0]
	s_nop 0
	v_mul_f32_e32 v159, 0xbfb8aa3b, v160
	v_exp_f32_e32 v159, v159
	s_nop 0
	v_add_f32_e32 v159, 1.0, v159
	v_rcp_f32_e32 v162, v159
	v_mul_f32_e32 v159, 0xbfb8aa3b, v161
	v_exp_f32_e32 v159, v159
	s_nop 0
	v_add_f32_e32 v159, 1.0, v159
	v_rcp_f32_e32 v163, v159
	s_nop 0
	v_pk_mul_f32 v[160:161], v[160:161], v[162:163]
	v_pk_mul_f32 v[162:163], v[24:25], v[146:147] op_sel_hi:[1,0]
	s_nop 0
	v_pk_mul_f32 v[162:163], v[162:163], v[160:161]
	v_pk_mul_f32 v[160:161], v[58:59], v[146:147] op_sel_hi:[1,0]
	v_cvt_pk_bf16_f32 v162, v162, v163
	v_mul_f32_e32 v159, 0xbfb8aa3b, v160
	v_exp_f32_e32 v159, v159
	s_nop 0
	v_add_f32_e32 v159, 1.0, v159
	v_rcp_f32_e32 v164, v159
	v_mul_f32_e32 v159, 0xbfb8aa3b, v161
	v_exp_f32_e32 v159, v159
	s_nop 0
	v_add_f32_e32 v159, 1.0, v159
	v_rcp_f32_e32 v165, v159
	s_nop 0
	v_pk_mul_f32 v[160:161], v[160:161], v[164:165]
	v_pk_mul_f32 v[164:165], v[26:27], v[146:147] op_sel_hi:[1,0]
	v_mov_b32_e32 v146, v147
	v_pk_mul_f32 v[164:165], v[164:165], v[160:161]
	v_cvt_pk_bf16_f32 v160, v148, v149
	v_add_co_u32_e32 v148, vcc, s6, v150
	v_cvt_pk_bf16_f32 v161, v152, v153
	v_cvt_pk_bf16_f32 v163, v164, v165
	v_addc_co_u32_e32 v149, vcc, 0, v151, vcc
	global_store_dwordx4 v[148:149], v[160:163], off
	v_pk_mul_f32 v[148:149], v[52:53], v[146:147] op_sel_hi:[1,0]
	s_mov_b32 s6, 0xc6000
	v_mul_f32_e32 v147, 0xbfb8aa3b, v148
	v_exp_f32_e32 v147, v147
	s_nop 0
	v_add_f32_e32 v147, 1.0, v147
	v_rcp_f32_e32 v152, v147
	v_mul_f32_e32 v147, 0xbfb8aa3b, v149
	v_exp_f32_e32 v147, v147
	s_nop 0
	v_add_f32_e32 v147, 1.0, v147
	v_rcp_f32_e32 v153, v147
	s_nop 0
	v_pk_mul_f32 v[148:149], v[148:149], v[152:153]
	v_pk_mul_f32 v[152:153], v[20:21], v[146:147] op_sel_hi:[1,0]
	s_nop 0
	v_pk_mul_f32 v[148:149], v[152:153], v[148:149]
	v_pk_mul_f32 v[152:153], v[54:55], v[146:147] op_sel_hi:[1,0]
	s_nop 0
	v_mul_f32_e32 v147, 0xbfb8aa3b, v152
	v_exp_f32_e32 v147, v147
	s_nop 0
	v_add_f32_e32 v147, 1.0, v147
	v_rcp_f32_e32 v160, v147
	v_mul_f32_e32 v147, 0xbfb8aa3b, v153
	v_exp_f32_e32 v147, v147
	s_nop 0
	v_add_f32_e32 v147, 1.0, v147
	v_rcp_f32_e32 v161, v147
	s_nop 0
	v_pk_mul_f32 v[152:153], v[152:153], v[160:161]
	v_pk_mul_f32 v[160:161], v[22:23], v[146:147] op_sel_hi:[1,0]
	s_nop 0
	v_pk_mul_f32 v[152:153], v[160:161], v[152:153]
	v_pk_mul_f32 v[160:161], v[48:49], v[146:147] op_sel_hi:[1,0]
	s_nop 0
	v_mul_f32_e32 v147, 0xbfb8aa3b, v160
	v_exp_f32_e32 v147, v147
	s_nop 0
	v_add_f32_e32 v147, 1.0, v147
	v_rcp_f32_e32 v162, v147
	v_mul_f32_e32 v147, 0xbfb8aa3b, v161
	v_exp_f32_e32 v147, v147
	s_nop 0
	v_add_f32_e32 v147, 1.0, v147
	v_rcp_f32_e32 v163, v147
	s_nop 0
	v_pk_mul_f32 v[160:161], v[160:161], v[162:163]
	v_pk_mul_f32 v[162:163], v[16:17], v[146:147] op_sel_hi:[1,0]
	s_nop 0
	v_pk_mul_f32 v[162:163], v[162:163], v[160:161]
	v_pk_mul_f32 v[160:161], v[50:51], v[146:147] op_sel_hi:[1,0]
	v_cvt_pk_bf16_f32 v162, v162, v163
	v_mul_f32_e32 v147, 0xbfb8aa3b, v160
	v_exp_f32_e32 v147, v147
	s_nop 0
	v_add_f32_e32 v147, 1.0, v147
	v_rcp_f32_e32 v164, v147
	v_mul_f32_e32 v147, 0xbfb8aa3b, v161
	v_exp_f32_e32 v147, v147
	s_nop 0
	v_add_f32_e32 v147, 1.0, v147
	v_rcp_f32_e32 v165, v147
	v_pk_mul_f32 v[146:147], v[18:19], v[146:147] op_sel_hi:[1,0]
	v_pk_mul_f32 v[160:161], v[160:161], v[164:165]
	s_nop 0
	v_pk_mul_f32 v[146:147], v[146:147], v[160:161]
	v_cvt_pk_bf16_f32 v160, v148, v149
	v_cvt_pk_bf16_f32 v163, v146, v147
	v_add_co_u32_e32 v146, vcc, s6, v150
	v_cvt_pk_bf16_f32 v161, v152, v153
	s_nop 0
	v_addc_co_u32_e32 v147, vcc, 0, v151, vcc
	global_store_dwordx4 v[146:147], v[160:163], off
	ds_read2_b32 v[146:147], v158 offset0:160 offset1:176
	s_mov_b32 s6, 0xdc000
	s_waitcnt lgkmcnt(0)
	v_pk_mul_f32 v[148:149], v[44:45], v[146:147] op_sel_hi:[1,0]
	s_nop 0
	v_mul_f32_e32 v152, 0xbfb8aa3b, v148
	v_mul_f32_e32 v153, 0xbfb8aa3b, v149
	v_exp_f32_e32 v152, v152
	v_exp_f32_e32 v153, v153
	v_add_f32_e32 v152, 1.0, v152
	v_add_f32_e32 v153, 1.0, v153
	v_rcp_f32_e32 v152, v152
	v_rcp_f32_e32 v153, v153
	s_nop 0
	v_pk_mul_f32 v[148:149], v[148:149], v[152:153]
	v_pk_mul_f32 v[152:153], v[12:13], v[146:147] op_sel_hi:[1,0]
	s_nop 0
	v_pk_mul_f32 v[148:149], v[152:153], v[148:149]
	v_pk_mul_f32 v[152:153], v[46:47], v[146:147] op_sel_hi:[1,0]
	s_nop 0
	v_mul_f32_e32 v158, 0xbfb8aa3b, v152
	v_mul_f32_e32 v159, 0xbfb8aa3b, v153
	v_exp_f32_e32 v158, v158
	v_exp_f32_e32 v159, v159
	v_add_f32_e32 v158, 1.0, v158
	v_add_f32_e32 v159, 1.0, v159
	v_rcp_f32_e32 v158, v158
	v_rcp_f32_e32 v159, v159
	s_nop 0
	v_pk_mul_f32 v[152:153], v[152:153], v[158:159]
	v_pk_mul_f32 v[158:159], v[14:15], v[146:147] op_sel_hi:[1,0]
	s_nop 0
	v_pk_mul_f32 v[152:153], v[158:159], v[152:153]
	v_pk_mul_f32 v[158:159], v[40:41], v[146:147] op_sel_hi:[1,0]
	s_nop 0
	v_mul_f32_e32 v160, 0xbfb8aa3b, v158
	v_mul_f32_e32 v161, 0xbfb8aa3b, v159
	v_exp_f32_e32 v160, v160
	v_exp_f32_e32 v161, v161
	v_add_f32_e32 v160, 1.0, v160
	v_add_f32_e32 v161, 1.0, v161
	v_rcp_f32_e32 v160, v160
	v_rcp_f32_e32 v161, v161
	s_nop 0
	v_pk_mul_f32 v[158:159], v[158:159], v[160:161]
	v_pk_mul_f32 v[160:161], v[8:9], v[146:147] op_sel_hi:[1,0]
	s_nop 0
	v_pk_mul_f32 v[160:161], v[160:161], v[158:159]
	v_pk_mul_f32 v[158:159], v[42:43], v[146:147] op_sel_hi:[1,0]
	v_cvt_pk_bf16_f32 v160, v160, v161
	v_mul_f32_e32 v162, 0xbfb8aa3b, v158
	v_mul_f32_e32 v163, 0xbfb8aa3b, v159
	v_exp_f32_e32 v162, v162
	v_exp_f32_e32 v163, v163
	v_add_f32_e32 v162, 1.0, v162
	v_add_f32_e32 v163, 1.0, v163
	v_rcp_f32_e32 v162, v162
	v_rcp_f32_e32 v163, v163
	s_nop 0
	v_pk_mul_f32 v[158:159], v[158:159], v[162:163]
	v_pk_mul_f32 v[162:163], v[10:11], v[146:147] op_sel_hi:[1,0]
	v_mov_b32_e32 v146, v147
	v_pk_mul_f32 v[162:163], v[162:163], v[158:159]
	v_cvt_pk_bf16_f32 v158, v148, v149
	v_add_co_u32_e32 v148, vcc, s6, v150
	v_cvt_pk_bf16_f32 v159, v152, v153
	v_cvt_pk_bf16_f32 v161, v162, v163
	v_addc_co_u32_e32 v149, vcc, 0, v151, vcc
	global_store_dwordx4 v[148:149], v[158:161], off
	v_pk_mul_f32 v[148:149], v[36:37], v[146:147] op_sel_hi:[1,0]
	s_nop 0
	v_mul_f32_e32 v147, 0xbfb8aa3b, v148
	v_exp_f32_e32 v147, v147
	s_nop 0
	v_add_f32_e32 v147, 1.0, v147
	v_rcp_f32_e32 v152, v147
	v_mul_f32_e32 v147, 0xbfb8aa3b, v149
	v_exp_f32_e32 v147, v147
	s_nop 0
	v_add_f32_e32 v147, 1.0, v147
	v_rcp_f32_e32 v153, v147
	s_nop 0
	v_pk_mul_f32 v[148:149], v[148:149], v[152:153]
	v_pk_mul_f32 v[152:153], v[4:5], v[146:147] op_sel_hi:[1,0]
	s_nop 0
	v_pk_mul_f32 v[148:149], v[152:153], v[148:149]
	v_pk_mul_f32 v[152:153], v[38:39], v[146:147] op_sel_hi:[1,0]
	s_nop 0
	v_mul_f32_e32 v147, 0xbfb8aa3b, v152
	v_exp_f32_e32 v147, v147
	s_nop 0
	v_add_f32_e32 v147, 1.0, v147
	v_rcp_f32_e32 v158, v147
	v_mul_f32_e32 v147, 0xbfb8aa3b, v153
	v_exp_f32_e32 v147, v147
	s_nop 0
	v_add_f32_e32 v147, 1.0, v147
	v_rcp_f32_e32 v159, v147
	s_nop 0
	v_pk_mul_f32 v[152:153], v[152:153], v[158:159]
	v_pk_mul_f32 v[158:159], v[6:7], v[146:147] op_sel_hi:[1,0]
	s_nop 0
	v_pk_mul_f32 v[152:153], v[158:159], v[152:153]
	v_pk_mul_f32 v[158:159], v[32:33], v[146:147] op_sel_hi:[1,0]
	s_nop 0
	v_mul_f32_e32 v147, 0xbfb8aa3b, v158
	v_exp_f32_e32 v147, v147
	s_nop 0
	v_add_f32_e32 v147, 1.0, v147
	v_rcp_f32_e32 v160, v147
	v_mul_f32_e32 v147, 0xbfb8aa3b, v159
	v_exp_f32_e32 v147, v147
	s_nop 0
	v_add_f32_e32 v147, 1.0, v147
	v_rcp_f32_e32 v161, v147
	s_nop 0
	v_pk_mul_f32 v[158:159], v[158:159], v[160:161]
	v_pk_mul_f32 v[160:161], v[0:1], v[146:147] op_sel_hi:[1,0]
	s_nop 0
	v_pk_mul_f32 v[160:161], v[160:161], v[158:159]
	v_pk_mul_f32 v[158:159], v[34:35], v[146:147] op_sel_hi:[1,0]
	v_cvt_pk_bf16_f32 v160, v160, v161
	v_mul_f32_e32 v147, 0xbfb8aa3b, v158
	v_exp_f32_e32 v147, v147
	s_nop 0
	v_add_f32_e32 v147, 1.0, v147
	v_rcp_f32_e32 v162, v147
	v_mul_f32_e32 v147, 0xbfb8aa3b, v159
	v_exp_f32_e32 v147, v147
	s_nop 0
	v_add_f32_e32 v147, 1.0, v147
	v_rcp_f32_e32 v163, v147
	v_pk_mul_f32 v[146:147], v[2:3], v[146:147] op_sel_hi:[1,0]
	v_pk_mul_f32 v[158:159], v[158:159], v[162:163]
	s_nop 0
	v_pk_mul_f32 v[146:147], v[146:147], v[158:159]
	v_cvt_pk_bf16_f32 v158, v148, v149
	v_cvt_pk_bf16_f32 v161, v146, v147
	v_add_co_u32_e32 v146, vcc, 0xf2000, v150
	v_cvt_pk_bf16_f32 v159, v152, v153
	s_nop 0
	v_addc_co_u32_e32 v147, vcc, 0, v151, vcc
	s_andn2_b64 vcc, exec, s[44:45]
	global_store_dwordx4 v[146:147], v[158:161], off
	s_cbranch_vccz .LBB0_382
	s_mov_b64 s[48:49], s[52:53]
	s_andn2_b64 vcc, exec, s[42:43]
	s_mov_b64 s[52:53], s[48:49]
	s_cbranch_vccnz .LBB0_383

.LBB0_804:
	s_cmp_lg_u32 s22, 0
	s_waitcnt vmcnt(0)
	s_waitcnt vmcnt(0) lgkmcnt(0)
	s_barrier
	s_mov_b64 s[4:5], exec
	v_readlane_b32 s10, v252, 2
	v_readlane_b32 s11, v252, 3
	s_and_b64 s[10:11], s[4:5], s[10:11]
	s_mov_b64 exec, s[10:11]
	s_cbranch_execz .LBB0_858
	v_readlane_b32 s6, v255, 6
	s_waitcnt vmcnt(0) expcnt(0) lgkmcnt(0)
	s_nop 0
	v_mov_b32_e32 v0, s6
	ds_read_b32 v2, v0
	v_readlane_b32 s6, v255, 7
	s_waitcnt lgkmcnt(0)
	v_cmp_ne_u32_e32 vcc, 0, v2
	v_mov_b32_e32 v0, s6
	ds_read_b32 v0, v0
	s_cbranch_vccnz .LBB0_822
	s_mov_b32 s6, 1
	s_branch .LBB0_809

.LBB0_809:
	v_readlane_b32 s10, v252, 37
	v_readlane_b32 s11, v252, 38
	v_readlane_b32 s9, v253, 45
	s_mov_b64 s[26:27], -1
	s_mov_b64 s[28:29], -1
	s_waitcnt lgkmcnt(0)
	s_nop 2
	global_load_dword v0, v141, s[10:11] sc1
	global_load_dword v1, v141, s[10:11] offset:256 sc1
	global_load_dword v2, v141, s[10:11] offset:512 sc1
	global_load_dword v3, v141, s[10:11] offset:768 sc1
	global_load_dword v4, v141, s[10:11] offset:1024 sc1
	global_load_dword v5, v141, s[10:11] offset:1280 sc1
	global_load_dword v6, v141, s[10:11] offset:1536 sc1
	global_load_dword v7, v141, s[10:11] offset:1792 sc1
	global_load_dword v8, v141, s[10:11] offset:2048 sc1
	global_load_dword v9, v141, s[10:11] offset:2304 sc1
	global_load_dword v10, v141, s[10:11] offset:2560 sc1
	global_load_dword v11, v141, s[10:11] offset:2816 sc1
	global_load_dword v12, v141, s[10:11] offset:3072 sc1
	global_load_dword v13, v141, s[10:11] offset:3328 sc1
	global_load_dword v14, v141, s[10:11] offset:3584 sc1
	global_load_dword v15, v141, s[10:11] offset:3840 sc1
	s_waitcnt vmcnt(0)
	v_add_u32_e32 v16, v1, v0
	v_add_u32_e32 v16, v16, v2
	v_add_u32_e32 v16, v16, v3
	v_add_u32_e32 v16, v16, v4
	v_add_u32_e32 v16, v16, v5
	v_add_u32_e32 v16, v16, v6
	v_add_u32_e32 v16, v16, v7
	v_add_u32_e32 v16, v16, v8
	v_add_u32_e32 v16, v16, v9
	v_add_u32_e32 v16, v16, v10
	v_add_u32_e32 v16, v16, v11
	v_add_u32_e32 v16, v16, v12
	v_add_u32_e32 v16, v16, v13
	v_add_u32_e32 v16, v16, v14
	v_add_u32_e32 v16, v16, v15
	v_cmp_eq_u32_e32 vcc, s9, v16
	s_cbranch_vccnz .LBB0_808
	s_and_b32 s9, s6, 0xff
	s_cmp_eq_u32 s9, 0
	s_mov_b64 s[30:31], -1
	s_sleep 1
	s_cbranch_scc0 .LBB0_813
	v_readlane_b32 s10, v252, 35
	v_readlane_b32 s11, v252, 36
	s_nop 4
	global_load_dword v16, v141, s[10:11] sc1
	s_waitcnt vmcnt(0)
	v_cmp_eq_u32_e32 vcc, 0, v16
	s_cbranch_vccnz .LBB0_815
	s_mov_b64 s[30:31], 0
